# cooperative attention: the first K tiles of a block's next (b,h,row-block) unit are requested during the last tile of the current unit (cross-unit prefetch)
# baseline (speedup 1.0000x reference)
; #define PG8_STAGE(bufoff, gbase, voff) do { _Pragma("unroll") for (int _i = 0; _i < 2; ++_i) \
;         __builtin_amdgcn_global_load_lds((const unsigned*)((const char*)(gbase) + (voff)[_i]), (LAS unsigned*)(lds + (bufoff) + ldsw + _i * 8192), 16, 0, 0); } while (0)
; #define PG8_LDA(dst, b, h) do { _Pragma("unroll") for (int m = 0; m < 4; ++m) _Pragma("unroll") for (int k = 0; k < 2; ++k) dst[m][k] = *(const LAS bf16x8*)(lds + PG8_SA(b, h) + aoff + m * 2048 + k * 1024); } while (0)
; #define PG8_LDB(dst, b, h) do { _Pragma("unroll") for (int n = 0; n < 2; ++n) _Pragma("unroll") for (int k = 0; k < 2; ++k) dst[n][k] = *(const LAS bf16x8*)(lds + PG8_SB(b, h) + boff + n * 2048 + k * 1024); } while (0)
; #define PG8_MMA(ai, bj, At, Bt) do { __builtin_amdgcn_s_setprio(1); _Pragma("unroll") for (int m = 0; m < 4; ++m) _Pragma("unroll") for (int n = 0; n < 2; ++n) _Pragma("unroll") for (int k = 0; k < 2; ++k) \
;         acc[ai][bj][m][n] = __builtin_amdgcn_mfma_f32_16x16x32_bf16(Bt[n][k], At[m][k], acc[ai][bj][m][n], 0, 0, 0); __builtin_amdgcn_s_setprio(0); } while (0)
; #define PG8_WAIT_L(n) asm volatile("s_waitcnt lgkmcnt(" #n ")" ::: "memory")
; #define PG8_BAR __builtin_amdgcn_s_barrier()
; #define PG8_SCHED __builtin_amdgcn_sched_barrier(0)
; template <class Epi>
; __device__ __forceinline__ void gemm_phase(LAS unsigned char* lds, const Gemm g, const StaticOrder& S, const Epi& E) {
;     ...
;             PG8_LDB(B0, 0, 0); PG8_SCHED; PG8_LDA(At, 0, 0); PG8_STAGE(PG8_SA(1, 1), a1 + hstepA, voffA);
;             PG8_WAIT_L(8); PG8_BAR; PG8_WAIT_L(0); PG8_MMA(0, 0, At, B0); PG8_BAR; PG8_SCHED;
;             PG8_LDB(B1, 0, 1); PG8_STAGE(PG8_SB(0, 0), b2, voffB);
;             PG8_BAR; PG8_WAIT_L(0); PG8_MMA(0, 1, At, B1); PG8_BAR;
;             PG8_LDA(At, 0, 1); PG8_STAGE(PG8_SA(0, 0), a2, voffA);
;             PG8_BAR; PG8_WAIT_L(0); PG8_MMA(1, 0, At, B0); PG8_BAR; PG8_SCHED;
.LBB0_126:
	ds_read_b128 v[156:159], v152
	ds_read_b128 v[160:163], v152 offset:1024
	ds_read_b128 v[164:167], v152 offset:2048
	ds_read_b128 v[168:171], v152 offset:3072
	s_add_u32 s68, s66, 0xfff80080
	s_addc_u32 s69, s67, -1
	s_cmp_eq_u32 s93, 28
	s_cselect_b32 s71, s31, s69
	s_cselect_b32 s70, s65, s68
	s_cselect_b32 s69, s29, s92
	s_cselect_b32 s68, s90, s91
	v_lshl_add_u64 v[146:147], s[66:67], 0, v[138:139]
	s_add_i32 m0, s77, 0xc000
	ds_read_b128 v[172:175], v153
	ds_read_b128 v[176:179], v153 offset:1024
	ds_read_b128 v[180:183], v153 offset:2048
	ds_read_b128 v[184:187], v153 offset:3072
	ds_read_b128 v[190:193], v153 offset:4096
	ds_read_b128 v[194:197], v153 offset:5120
	ds_read_b128 v[198:201], v153 offset:6144
	ds_read_b128 v[202:205], v153 offset:7168
	global_load_lds_dwordx4 v[146:147], off
	v_lshl_add_u64 v[146:147], s[66:67], 0, v[140:141]
	s_add_i32 m0, s77, 0xe000
	s_nop 0
	global_load_lds_dwordx4 v[146:147], off
	s_waitcnt lgkmcnt(8)
	s_barrier
	s_setprio 1
	s_waitcnt lgkmcnt(12)
	s_waitcnt lgkmcnt(7)
	v_mfma_f32_16x16x32_bf16 v[124:127], v[156:159], v[172:175], v[124:127]
	v_mfma_f32_16x16x32_bf16 v[120:123], v[164:167], v[172:175], v[120:123]
	s_waitcnt lgkmcnt(5)
	v_mfma_f32_16x16x32_bf16 v[112:115], v[156:159], v[180:183], v[112:115]
	v_mfma_f32_16x16x32_bf16 v[104:107], v[164:167], v[180:183], v[104:107]
	s_waitcnt lgkmcnt(3)
	v_mfma_f32_16x16x32_bf16 v[96:99], v[156:159], v[190:193], v[96:99]
	v_mfma_f32_16x16x32_bf16 v[88:91], v[164:167], v[190:193], v[88:91]
	s_waitcnt lgkmcnt(1)
	v_mfma_f32_16x16x32_bf16 v[80:83], v[156:159], v[198:201], v[80:83]
	v_mfma_f32_16x16x32_bf16 v[72:75], v[164:167], v[198:201], v[72:75]
	v_mfma_f32_16x16x32_bf16 v[124:127], v[160:163], v[176:179], v[124:127]
	v_mfma_f32_16x16x32_bf16 v[120:123], v[168:171], v[176:179], v[120:123]
	v_mfma_f32_16x16x32_bf16 v[112:115], v[160:163], v[184:187], v[112:115]
	v_mfma_f32_16x16x32_bf16 v[104:107], v[168:171], v[184:187], v[104:107]
	v_mfma_f32_16x16x32_bf16 v[96:99], v[160:163], v[194:197], v[96:99]
	v_mfma_f32_16x16x32_bf16 v[88:91], v[168:171], v[194:197], v[88:91]
	s_waitcnt lgkmcnt(0)
	v_mfma_f32_16x16x32_bf16 v[80:83], v[160:163], v[202:205], v[80:83]
	v_mfma_f32_16x16x32_bf16 v[72:75], v[168:171], v[202:205], v[72:75]
	s_setprio 0
	s_barrier
	s_add_i32 s94, s87, s74
	v_lshl_add_u64 v[146:147], s[68:69], 0, v[132:133]
	s_mov_b32 m0, s94
	ds_read_b128 v[206:209], v154
	ds_read_b128 v[210:213], v154 offset:1024
	ds_read_b128 v[214:217], v154 offset:2048
	ds_read_b128 v[218:221], v154 offset:3072
	global_load_lds_dwordx4 v[146:147], off
	v_lshl_add_u64 v[222:223], s[68:69], 0, v[128:129]
	s_add_i32 m0, s94, 0x2000
	s_nop 0
	global_load_lds_dwordx4 v[222:223], off
	s_barrier
	s_setprio 1
	s_waitcnt lgkmcnt(3)
	v_mfma_f32_16x16x32_bf16 v[116:119], v[206:209], v[172:175], v[116:119]
	s_waitcnt lgkmcnt(1)
	v_mfma_f32_16x16x32_bf16 v[108:111], v[214:217], v[172:175], v[108:111]
	v_mfma_f32_16x16x32_bf16 v[100:103], v[206:209], v[180:183], v[100:103]
	v_mfma_f32_16x16x32_bf16 v[92:95], v[214:217], v[180:183], v[92:95]
	v_mfma_f32_16x16x32_bf16 v[84:87], v[206:209], v[190:193], v[84:87]
	v_mfma_f32_16x16x32_bf16 v[76:79], v[214:217], v[190:193], v[76:79]
	v_mfma_f32_16x16x32_bf16 v[68:71], v[206:209], v[198:201], v[68:71]
	v_mfma_f32_16x16x32_bf16 v[64:67], v[214:217], v[198:201], v[64:67]
	v_mfma_f32_16x16x32_bf16 v[116:119], v[210:213], v[176:179], v[116:119]
	s_waitcnt lgkmcnt(0)
	v_mfma_f32_16x16x32_bf16 v[108:111], v[218:221], v[176:179], v[108:111]
	v_mfma_f32_16x16x32_bf16 v[100:103], v[210:213], v[184:187], v[100:103]
	v_mfma_f32_16x16x32_bf16 v[92:95], v[218:221], v[184:187], v[92:95]
	v_mfma_f32_16x16x32_bf16 v[84:87], v[210:213], v[194:197], v[84:87]
	v_mfma_f32_16x16x32_bf16 v[76:79], v[218:221], v[194:197], v[76:79]
	v_mfma_f32_16x16x32_bf16 v[68:71], v[210:213], v[202:205], v[68:71]
	v_mfma_f32_16x16x32_bf16 v[64:67], v[218:221], v[202:205], v[64:67]
	s_setprio 0
	s_mov_b32 m0, s77
	v_lshl_add_u64 v[224:225], s[70:71], 0, v[134:135]
	s_barrier
	ds_read_b128 v[172:175], v153 offset:16384
	ds_read_b128 v[176:179], v153 offset:17408
	ds_read_b128 v[180:183], v153 offset:18432
	ds_read_b128 v[184:187], v153 offset:19456
	ds_read_b128 v[190:193], v153 offset:20480
	ds_read_b128 v[194:197], v153 offset:21504
	ds_read_b128 v[198:201], v153 offset:22528
	ds_read_b128 v[202:205], v153 offset:23552
	global_load_lds_dwordx4 v[224:225], off
	v_lshl_add_u64 v[226:227], s[70:71], 0, v[130:131]
	s_mov_b32 m0, s78
	s_nop 0
	global_load_lds_dwordx4 v[226:227], off
	s_barrier
	s_setprio 1
	s_waitcnt lgkmcnt(7)
	v_mfma_f32_16x16x32_bf16 v[60:63], v[156:159], v[172:175], v[60:63]
	v_mfma_f32_16x16x32_bf16 v[56:59], v[164:167], v[172:175], v[56:59]
	s_waitcnt lgkmcnt(5)
	v_mfma_f32_16x16x32_bf16 v[48:51], v[156:159], v[180:183], v[48:51]
	v_mfma_f32_16x16x32_bf16 v[40:43], v[164:167], v[180:183], v[40:43]
	s_waitcnt lgkmcnt(3)
	v_mfma_f32_16x16x32_bf16 v[36:39], v[156:159], v[190:193], v[36:39]
	v_mfma_f32_16x16x32_bf16 v[28:31], v[164:167], v[190:193], v[28:31]
	s_waitcnt lgkmcnt(1)
	v_mfma_f32_16x16x32_bf16 v[20:23], v[156:159], v[198:201], v[20:23]
	v_mfma_f32_16x16x32_bf16 v[12:15], v[164:167], v[198:201], v[12:15]
	v_mfma_f32_16x16x32_bf16 v[60:63], v[160:163], v[176:179], v[60:63]
	v_mfma_f32_16x16x32_bf16 v[56:59], v[168:171], v[176:179], v[56:59]
	v_mfma_f32_16x16x32_bf16 v[48:51], v[160:163], v[184:187], v[48:51]
	v_mfma_f32_16x16x32_bf16 v[40:43], v[168:171], v[184:187], v[40:43]
	v_mfma_f32_16x16x32_bf16 v[36:39], v[160:163], v[194:197], v[36:39]
	v_mfma_f32_16x16x32_bf16 v[28:31], v[168:171], v[194:197], v[28:31]
	s_waitcnt lgkmcnt(0)
	v_mfma_f32_16x16x32_bf16 v[20:23], v[160:163], v[202:205], v[20:23]
	v_mfma_f32_16x16x32_bf16 v[12:15], v[168:171], v[202:205], v[12:15]
	s_setprio 0
	s_barrier
; #define PG8_STAGE(bufoff, gbase, voff) do { _Pragma("unroll") for (int _i = 0; _i < 2; ++_i) \
;         __builtin_amdgcn_global_load_lds((const unsigned*)((const char*)(gbase) + (voff)[_i]), (LAS unsigned*)(lds + (bufoff) + ldsw + _i * 8192), 16, 0, 0); } while (0)
; #define PG8_LDA(dst, b, h) do { _Pragma("unroll") for (int m = 0; m < 4; ++m) _Pragma("unroll") for (int k = 0; k < 2; ++k) dst[m][k] = *(const LAS bf16x8*)(lds + PG8_SA(b, h) + aoff + m * 2048 + k * 1024); } while (0)
; #define PG8_LDB(dst, b, h) do { _Pragma("unroll") for (int n = 0; n < 2; ++n) _Pragma("unroll") for (int k = 0; k < 2; ++k) dst[n][k] = *(const LAS bf16x8*)(lds + PG8_SB(b, h) + boff + n * 2048 + k * 1024); } while (0)
; #define PG8_MMA(ai, bj, At, Bt) do { __builtin_amdgcn_s_setprio(1); _Pragma("unroll") for (int m = 0; m < 4; ++m) _Pragma("unroll") for (int n = 0; n < 2; ++n) _Pragma("unroll") for (int k = 0; k < 2; ++k) \
;         acc[ai][bj][m][n] = __builtin_amdgcn_mfma_f32_16x16x32_bf16(Bt[n][k], At[m][k], acc[ai][bj][m][n], 0, 0, 0); __builtin_amdgcn_s_setprio(0); } while (0)
; #define PG8_WAIT_V(n) asm volatile("s_waitcnt vmcnt(" #n ")" ::: "memory")
; #define PG8_WAIT_L(n) asm volatile("s_waitcnt lgkmcnt(" #n ")" ::: "memory")
; #define PG8_BAR __builtin_amdgcn_s_barrier()
; #define PG8_SCHED __builtin_amdgcn_sched_barrier(0)
; template <class Epi>
; __device__ __forceinline__ void gemm_phase(LAS unsigned char* lds, const Gemm g, const StaticOrder& S, const Epi& E) {
;     ...
;             PG8_STAGE(PG8_SB(0, 1), b2 + hstepB, voffB);
;             PG8_WAIT_V(6); PG8_BAR; PG8_MMA(1, 1, At, B1); PG8_BAR;
;             PG8_LDB(B0, 1, 0); PG8_SCHED; PG8_LDA(At, 1, 0); PG8_STAGE(PG8_SA(0, 1), a2 + hstepA, voffA);
;             PG8_WAIT_L(8); PG8_BAR; PG8_WAIT_L(0); PG8_MMA(0, 0, At, B0); PG8_BAR; PG8_SCHED;
;             PG8_LDB(B1, 1, 1); PG8_STAGE(PG8_SB(1, 0), b3, voffB);
;             PG8_BAR; PG8_WAIT_L(0); PG8_MMA(0, 1, At, B1); PG8_BAR;
	s_add_u32 s94, s68, 0x80000
	s_addc_u32 s95, s69, 0
	s_add_i32 vcc_lo, s88, s74
	v_lshl_add_u64 v[156:157], s[94:95], 0, v[132:133]
	s_mov_b32 m0, vcc_lo
	s_nop 0
	global_load_lds_dwordx4 v[156:157], off
	v_lshl_add_u64 v[156:157], s[94:95], 0, v[128:129]
	s_add_i32 m0, vcc_lo, 0x2000
	s_nop 0
	global_load_lds_dwordx4 v[156:157], off
	s_waitcnt vmcnt(6)
	s_barrier
	s_setprio 1
	v_mfma_f32_16x16x32_bf16 v[52:55], v[206:209], v[172:175], v[52:55]
	v_mfma_f32_16x16x32_bf16 v[44:47], v[214:217], v[172:175], v[44:47]
	v_mfma_f32_16x16x32_bf16 v[32:35], v[206:209], v[180:183], v[32:35]
	v_mfma_f32_16x16x32_bf16 v[24:27], v[214:217], v[180:183], v[24:27]
	v_mfma_f32_16x16x32_bf16 v[16:19], v[206:209], v[190:193], v[16:19]
	v_mfma_f32_16x16x32_bf16 v[8:11], v[214:217], v[190:193], v[8:11]
	v_mfma_f32_16x16x32_bf16 v[4:7], v[206:209], v[198:201], v[4:7]
	v_mfma_f32_16x16x32_bf16 v[0:3], v[214:217], v[198:201], v[0:3]
	v_mfma_f32_16x16x32_bf16 v[52:55], v[210:213], v[176:179], v[52:55]
	v_mfma_f32_16x16x32_bf16 v[44:47], v[218:221], v[176:179], v[44:47]
	v_mfma_f32_16x16x32_bf16 v[32:35], v[210:213], v[184:187], v[32:35]
	v_mfma_f32_16x16x32_bf16 v[24:27], v[218:221], v[184:187], v[24:27]
	v_mfma_f32_16x16x32_bf16 v[16:19], v[210:213], v[194:197], v[16:19]
	v_mfma_f32_16x16x32_bf16 v[8:11], v[218:221], v[194:197], v[8:11]
	v_mfma_f32_16x16x32_bf16 v[4:7], v[210:213], v[202:205], v[4:7]
	v_mfma_f32_16x16x32_bf16 v[0:3], v[218:221], v[202:205], v[0:3]
	s_setprio 0
	s_add_i32 s94, 0, 0x18000
	v_add_u32_e32 v136, s94, v149
	s_barrier
	ds_read_b128 v[156:159], v136
	ds_read_b128 v[160:163], v136 offset:1024
	ds_read_b128 v[164:167], v136 offset:2048
	ds_read_b128 v[168:171], v136 offset:3072
	s_add_u32 s70, s70, 0x80000
	s_addc_u32 s71, s71, 0
	s_mov_b32 m0, s79
	v_lshl_add_u64 v[206:207], s[70:71], 0, v[134:135]
	ds_read_b128 v[172:175], v153 offset:32768
	ds_read_b128 v[176:179], v153 offset:33792
	ds_read_b128 v[180:183], v153 offset:34816
	ds_read_b128 v[184:187], v153 offset:35840
	ds_read_b128 v[190:193], v153 offset:36864
	ds_read_b128 v[194:197], v153 offset:37888
	ds_read_b128 v[198:201], v153 offset:38912
	ds_read_b128 v[202:205], v153 offset:39936
	global_load_lds_dwordx4 v[206:207], off
	v_lshl_add_u64 v[206:207], s[70:71], 0, v[130:131]
	s_mov_b32 m0, s80
	s_nop 0
	global_load_lds_dwordx4 v[206:207], off
	s_waitcnt lgkmcnt(8)
	s_barrier
	s_setprio 1
	s_waitcnt lgkmcnt(7)
	v_mfma_f32_16x16x32_bf16 v[124:127], v[156:159], v[172:175], v[124:127]
	v_mfma_f32_16x16x32_bf16 v[120:123], v[164:167], v[172:175], v[120:123]
	s_waitcnt lgkmcnt(5)
	v_mfma_f32_16x16x32_bf16 v[112:115], v[156:159], v[180:183], v[112:115]
	v_mfma_f32_16x16x32_bf16 v[104:107], v[164:167], v[180:183], v[104:107]
	s_waitcnt lgkmcnt(3)
	v_mfma_f32_16x16x32_bf16 v[96:99], v[156:159], v[190:193], v[96:99]
	v_mfma_f32_16x16x32_bf16 v[88:91], v[164:167], v[190:193], v[88:91]
	s_waitcnt lgkmcnt(1)
	v_mfma_f32_16x16x32_bf16 v[80:83], v[156:159], v[198:201], v[80:83]
	v_mfma_f32_16x16x32_bf16 v[72:75], v[164:167], v[198:201], v[72:75]
	v_mfma_f32_16x16x32_bf16 v[124:127], v[160:163], v[176:179], v[124:127]
	v_mfma_f32_16x16x32_bf16 v[120:123], v[168:171], v[176:179], v[120:123]
	v_mfma_f32_16x16x32_bf16 v[112:115], v[160:163], v[184:187], v[112:115]
	v_mfma_f32_16x16x32_bf16 v[104:107], v[168:171], v[184:187], v[104:107]
	v_mfma_f32_16x16x32_bf16 v[96:99], v[160:163], v[194:197], v[96:99]
	v_mfma_f32_16x16x32_bf16 v[88:91], v[168:171], v[194:197], v[88:91]
	s_waitcnt lgkmcnt(0)
	v_mfma_f32_16x16x32_bf16 v[80:83], v[160:163], v[202:205], v[80:83]
	v_mfma_f32_16x16x32_bf16 v[72:75], v[168:171], v[202:205], v[72:75]
	s_setprio 0
	s_barrier
	s_add_i32 s70, 0, 0x1c000
	s_add_i32 s71, s94, s74
	v_add_u32_e32 v136, s70, v149
	v_lshl_add_u64 v[146:147], v[146:147], 0, s[26:27]
	s_mov_b32 m0, s71
	ds_read_b128 v[206:209], v136
	ds_read_b128 v[210:213], v136 offset:1024
	ds_read_b128 v[214:217], v136 offset:2048
	ds_read_b128 v[218:221], v136 offset:3072
	global_load_lds_dwordx4 v[146:147], off
	v_lshl_add_u64 v[146:147], v[222:223], 0, s[26:27]
	s_add_i32 m0, s71, 0x2000
	s_nop 0
	global_load_lds_dwordx4 v[146:147], off
	s_barrier
; __device__ __forceinline__ unsigned cvt_pk_bf16(float lo, float hi) { unsigned r; asm volatile("v_cvt_pk_bf16_f32 %0, %1, %2" : "=v"(r) : "v"(lo), "v"(hi)); return r; }
; #define PG8_STAGE(bufoff, gbase, voff) do { _Pragma("unroll") for (int _i = 0; _i < 2; ++_i) \
;         __builtin_amdgcn_global_load_lds((const unsigned*)((const char*)(gbase) + (voff)[_i]), (LAS unsigned*)(lds + (bufoff) + ldsw + _i * 8192), 16, 0, 0); } while (0)
; #define PG8_WAIT_V(n) asm volatile("s_waitcnt vmcnt(" #n ")" ::: "memory")
; template <class Epi>
; __device__ __forceinline__ void gemm_phase(LAS unsigned char* lds, const Gemm g, const StaticOrder& S, const Epi& E) {
;     ...
;             PG8_BAR; PG8_WAIT_L(0); PG8_MMA(0, 1, At, B1); PG8_BAR;
;             PG8_LDA(At, 1, 1); PG8_STAGE(PG8_SA(1, 0), a3, voffA);
;             PG8_BAR; PG8_WAIT_L(0); PG8_MMA(1, 0, At, B0); PG8_BAR; PG8_SCHED;
;             PG8_STAGE(PG8_SB(1, 1), b3 + hstepB, voffB);
;             PG8_WAIT_V(6); PG8_BAR; PG8_MMA(1, 1, At, B1); PG8_BAR;
;         }
;     __device__ __forceinline__ void operator()(const AccT& acc, const Unit& u, int wr, int wc, int fr, int fq) const {
;         const int row0 = u.pm * 256 + wr * 64 + fr; const int pn = u.pn;
;         if (pn >= 25 && pn < 29) {
;             const int cb = (pn - 25) * 256 + wc * 32 + 8 * fq;
; #pragma unroll
;             for (int ai = 0; ai < 2; ++ai)
; #pragma unroll
;                 for (int m = 0; m < 4; ++m) { const int row = row0 + ai * 128 + m * 16; const int b = row >> 14, tt = row & (SEQ - 1);
; #pragma unroll
;                     for (int bj = 0; bj < 2; ++bj)
; #pragma unroll
;                         for (int n = 0; n < 2; ++n)
; #pragma unroll
;                             for (int j = 0; j < 4; ++j) { const int ch = cb + bj * 128 + 4 * n + j;
;                                 vt[((size_t)(b * 1024 + ch)) * SEQ + tt] = (u16)(cvt_pk_bf16(acc[ai][bj][m][n][j], 0.f) & 0xffffu); } }
;             return;
;         }
;         u16* base; int ld, colt;
;         if (pn < 13) { base = zs; ld = 3328; colt = pn * 256; }
;         else if (pn < 17) { base = zg; ld = 1024; colt = (pn - 13) * 256; }
;         else if (pn < 21) { base = qn; ld = 1024; colt = (pn - 17) * 256; }
;         else if (pn < 25) { base = kn; ld = 1024; colt = (pn - 21) * 256; }
;         else { base = gn; ld = 1024; colt = (pn - 29) * 256; }
	s_setprio 1
	s_waitcnt lgkmcnt(3)
	v_mfma_f32_16x16x32_bf16 v[116:119], v[206:209], v[172:175], v[116:119]
	s_waitcnt lgkmcnt(1)
	v_mfma_f32_16x16x32_bf16 v[108:111], v[214:217], v[172:175], v[108:111]
	v_mfma_f32_16x16x32_bf16 v[100:103], v[206:209], v[180:183], v[100:103]
	v_mfma_f32_16x16x32_bf16 v[92:95], v[214:217], v[180:183], v[92:95]
	v_mfma_f32_16x16x32_bf16 v[84:87], v[206:209], v[190:193], v[84:87]
	v_mfma_f32_16x16x32_bf16 v[76:79], v[214:217], v[190:193], v[76:79]
	v_mfma_f32_16x16x32_bf16 v[68:71], v[206:209], v[198:201], v[68:71]
	v_mfma_f32_16x16x32_bf16 v[64:67], v[214:217], v[198:201], v[64:67]
	v_mfma_f32_16x16x32_bf16 v[116:119], v[210:213], v[176:179], v[116:119]
	s_waitcnt lgkmcnt(0)
	v_mfma_f32_16x16x32_bf16 v[108:111], v[218:221], v[176:179], v[108:111]
	v_mfma_f32_16x16x32_bf16 v[100:103], v[210:213], v[184:187], v[100:103]
	v_mfma_f32_16x16x32_bf16 v[92:95], v[218:221], v[184:187], v[92:95]
	v_mfma_f32_16x16x32_bf16 v[84:87], v[210:213], v[194:197], v[84:87]
	v_mfma_f32_16x16x32_bf16 v[76:79], v[218:221], v[194:197], v[76:79]
	v_mfma_f32_16x16x32_bf16 v[68:71], v[210:213], v[202:205], v[68:71]
	v_mfma_f32_16x16x32_bf16 v[64:67], v[218:221], v[202:205], v[64:67]
	s_setprio 0
	s_mov_b32 m0, s83
	v_lshl_add_u64 v[146:147], v[224:225], 0, s[26:27]
	s_barrier
	ds_read_b128 v[172:175], v153 offset:49152
	ds_read_b128 v[176:179], v153 offset:50176
	ds_read_b128 v[180:183], v153 offset:51200
	ds_read_b128 v[184:187], v153 offset:52224
	ds_read_b128 v[190:193], v153 offset:53248
	ds_read_b128 v[194:197], v153 offset:54272
	ds_read_b128 v[198:201], v153 offset:55296
	ds_read_b128 v[202:205], v153 offset:56320
	global_load_lds_dwordx4 v[146:147], off
	v_lshl_add_u64 v[146:147], v[226:227], 0, s[26:27]
	s_mov_b32 m0, s84
	s_nop 0
	global_load_lds_dwordx4 v[146:147], off
	s_barrier
	s_setprio 1
	s_waitcnt lgkmcnt(7)
	v_mfma_f32_16x16x32_bf16 v[60:63], v[156:159], v[172:175], v[60:63]
	v_mfma_f32_16x16x32_bf16 v[56:59], v[164:167], v[172:175], v[56:59]
	s_waitcnt lgkmcnt(5)
	v_mfma_f32_16x16x32_bf16 v[48:51], v[156:159], v[180:183], v[48:51]
	v_mfma_f32_16x16x32_bf16 v[40:43], v[164:167], v[180:183], v[40:43]
	s_waitcnt lgkmcnt(3)
	v_mfma_f32_16x16x32_bf16 v[36:39], v[156:159], v[190:193], v[36:39]
	v_mfma_f32_16x16x32_bf16 v[28:31], v[164:167], v[190:193], v[28:31]
	s_waitcnt lgkmcnt(1)
	v_mfma_f32_16x16x32_bf16 v[20:23], v[156:159], v[198:201], v[20:23]
	v_mfma_f32_16x16x32_bf16 v[12:15], v[164:167], v[198:201], v[12:15]
	v_mfma_f32_16x16x32_bf16 v[60:63], v[160:163], v[176:179], v[60:63]
	v_mfma_f32_16x16x32_bf16 v[56:59], v[168:171], v[176:179], v[56:59]
	v_mfma_f32_16x16x32_bf16 v[48:51], v[160:163], v[184:187], v[48:51]
	v_mfma_f32_16x16x32_bf16 v[40:43], v[168:171], v[184:187], v[40:43]
	v_mfma_f32_16x16x32_bf16 v[36:39], v[160:163], v[194:197], v[36:39]
	v_mfma_f32_16x16x32_bf16 v[28:31], v[168:171], v[194:197], v[28:31]
	s_waitcnt lgkmcnt(0)
	v_mfma_f32_16x16x32_bf16 v[20:23], v[160:163], v[202:205], v[20:23]
	v_mfma_f32_16x16x32_bf16 v[12:15], v[168:171], v[202:205], v[12:15]
	s_setprio 0
	s_barrier
	s_add_u32 s68, s68, 0x80080
	s_addc_u32 s69, s69, 0
	s_add_i32 s70, s70, s74
	v_lshl_add_u64 v[146:147], s[68:69], 0, v[132:133]
	s_mov_b32 m0, s70
	s_nop 0
	global_load_lds_dwordx4 v[146:147], off
	v_lshl_add_u64 v[146:147], s[68:69], 0, v[128:129]
	s_add_i32 m0, s70, 0x2000
	s_nop 0
	global_load_lds_dwordx4 v[146:147], off
	s_waitcnt vmcnt(6)
	s_barrier
	s_setprio 1
	v_mfma_f32_16x16x32_bf16 v[52:55], v[206:209], v[172:175], v[52:55]
	v_mfma_f32_16x16x32_bf16 v[44:47], v[214:217], v[172:175], v[44:47]
	v_mfma_f32_16x16x32_bf16 v[32:35], v[206:209], v[180:183], v[32:35]
	v_mfma_f32_16x16x32_bf16 v[24:27], v[214:217], v[180:183], v[24:27]
	v_mfma_f32_16x16x32_bf16 v[16:19], v[206:209], v[190:193], v[16:19]
	v_mfma_f32_16x16x32_bf16 v[8:11], v[214:217], v[190:193], v[8:11]
	v_mfma_f32_16x16x32_bf16 v[4:7], v[206:209], v[198:201], v[4:7]
	v_mfma_f32_16x16x32_bf16 v[0:3], v[214:217], v[198:201], v[0:3]
	v_mfma_f32_16x16x32_bf16 v[52:55], v[210:213], v[176:179], v[52:55]
	v_mfma_f32_16x16x32_bf16 v[44:47], v[218:221], v[176:179], v[44:47]
	v_mfma_f32_16x16x32_bf16 v[32:35], v[210:213], v[184:187], v[32:35]
	v_mfma_f32_16x16x32_bf16 v[24:27], v[218:221], v[184:187], v[24:27]
	v_mfma_f32_16x16x32_bf16 v[16:19], v[210:213], v[194:197], v[16:19]
	v_mfma_f32_16x16x32_bf16 v[8:11], v[218:221], v[194:197], v[8:11]
	v_mfma_f32_16x16x32_bf16 v[4:7], v[210:213], v[202:205], v[4:7]
	v_mfma_f32_16x16x32_bf16 v[0:3], v[218:221], v[202:205], v[0:3]
	s_setprio 0
	s_add_i32 s93, s93, 2
	s_add_u32 s66, s66, 0x100
	s_addc_u32 s67, s67, 0
	s_add_u32 s91, s91, 0x100
	s_addc_u32 s92, s92, 0
	s_cmp_gt_u32 s93, 29
	s_barrier
	s_cbranch_scc0 .LBB0_126
	s_lshl_b32 s29, s64, 8
	s_add_i32 s29, s29, s82
	s_sub_i32 s31, s89, 25
	v_or_b32_e32 v155, s29, v148
	s_cmp_gt_u32 s31, 3
	s_mov_b64 s[64:65], -1
	s_cbranch_scc0 .LBB0_145
	s_cmp_gt_i32 s89, 12
	s_cbranch_scc0 .LBB0_142
	s_lshl_b32 s68, s89, 8
	s_cmp_gt_u32 s89, 16
	s_cbranch_scc0 .LBB0_139
	s_cmp_gt_u32 s89, 20
	s_cbranch_scc0 .LBB0_136
	s_cmp_gt_u32 s89, 24
	s_cbranch_scc0 .LBB0_133
	s_add_i32 s31, s68, 0xffffe300
	s_mov_b64 s[64:65], 0

; #define PG8_STAGE(bufoff, gbase, voff) do { _Pragma("unroll") for (int _i = 0; _i < 2; ++_i) \
;         __builtin_amdgcn_global_load_lds((const unsigned*)((const char*)(gbase) + (voff)[_i]), (LAS unsigned*)(lds + (bufoff) + ldsw + _i * 8192), 16, 0, 0); } while (0)
; #define PG8_LDA(dst, b, h) do { _Pragma("unroll") for (int m = 0; m < 4; ++m) _Pragma("unroll") for (int k = 0; k < 2; ++k) dst[m][k] = *(const LAS bf16x8*)(lds + PG8_SA(b, h) + aoff + m * 2048 + k * 1024); } while (0)
; #define PG8_LDB(dst, b, h) do { _Pragma("unroll") for (int n = 0; n < 2; ++n) _Pragma("unroll") for (int k = 0; k < 2; ++k) dst[n][k] = *(const LAS bf16x8*)(lds + PG8_SB(b, h) + boff + n * 2048 + k * 1024); } while (0)
; #define PG8_MMA(ai, bj, At, Bt) do { __builtin_amdgcn_s_setprio(1); _Pragma("unroll") for (int m = 0; m < 4; ++m) _Pragma("unroll") for (int n = 0; n < 2; ++n) _Pragma("unroll") for (int k = 0; k < 2; ++k) \
;         acc[ai][bj][m][n] = __builtin_amdgcn_mfma_f32_16x16x32_bf16(Bt[n][k], At[m][k], acc[ai][bj][m][n], 0, 0, 0); __builtin_amdgcn_s_setprio(0); } while (0)
; #define PG8_WAIT_L(n) asm volatile("s_waitcnt lgkmcnt(" #n ")" ::: "memory")
; template <class Epi>
; __device__ __forceinline__ void gemm_phase(LAS unsigned char* lds, const Gemm g, const StaticOrder& S, const Epi& E) {
;     ...
;         const bool has_next = S.next(ui + 1, nxt);
;         const char* nA = has_next ? (const char*)g.A + (size_t)nxt.pm * tstepA : cA; const char* nB = has_next ? (const char*)g.Bt + (size_t)nxt.pn * tstepB : cB;
;         for (int t = 0; t < nt; t += 2) {
;             const bool last = (t == nt - 2);
;             const char* a1 = cA + (size_t)(t + 1) * kstep;
;             const char* a2 = last ? nA : cA + (size_t)(t + 2) * kstep; const char* b2 = last ? nB : cB + (size_t)(t + 2) * kstep;
;             const char* a3 = a2 + kstep; const char* b3 = b2 + kstep;
;             PG8_LDB(B0, 0, 0); PG8_SCHED; PG8_LDA(At, 0, 0); PG8_STAGE(PG8_SA(1, 1), a1 + hstepA, voffA);
;             PG8_WAIT_L(8); PG8_BAR; PG8_WAIT_L(0); PG8_MMA(0, 0, At, B0); PG8_BAR; PG8_SCHED;
;             PG8_LDB(B1, 0, 1); PG8_STAGE(PG8_SB(0, 0), b2, voffB);
;             PG8_BAR; PG8_WAIT_L(0); PG8_MMA(0, 1, At, B1); PG8_BAR;
;             PG8_LDA(At, 0, 1); PG8_STAGE(PG8_SA(0, 0), a2, voffA);
;             PG8_BAR; PG8_WAIT_L(0); PG8_MMA(1, 0, At, B0); PG8_BAR; PG8_SCHED;
.LBB0_352:
	s_ashr_i32 s31, s30, 31
	s_lshl_b64 s[38:39], s[30:31], 17
	v_mov_b64_e32 v[0:1], 0x400
	s_add_u32 s38, s71, s38
	v_cmp_lt_i64_e32 vcc, s[26:27], v[0:1]
	s_addc_u32 s39, s72, s39
	s_and_b64 s[40:41], vcc, exec
	s_cselect_b32 s67, s39, s65
	s_cselect_b32 s66, s38, s64
	s_ashr_i32 s29, s28, 31
	s_lshl_b64 s[40:41], s[28:29], 16
	s_add_u32 s40, s73, s40
	s_addc_u32 s41, s74, s41
	s_add_u32 s92, s64, 0x10080
	ds_read_b128 v[0:3], v171
	ds_read_b128 v[4:7], v171 offset:1024
	ds_read_b128 v[8:11], v171 offset:2048
	ds_read_b128 v[12:15], v171 offset:3072
	s_addc_u32 s93, s65, 0
	s_add_u32 s64, s66, 0x10000
	s_addc_u32 s65, s67, 0
	s_and_b64 s[68:69], vcc, exec
	s_cselect_b32 s60, s40, s60
	s_cselect_b32 s61, s41, s61
	s_add_u32 s68, s60, 0x8000
	s_addc_u32 s69, s61, 0
	v_lshl_add_u64 v[48:49], s[92:93], 0, v[132:133]
	s_add_i32 m0, s76, 0xc000
	ds_read_b128 v[16:19], v172
	ds_read_b128 v[20:23], v172 offset:1024
	ds_read_b128 v[24:27], v172 offset:2048
	ds_read_b128 v[28:31], v172 offset:3072
	ds_read_b128 v[32:35], v172 offset:4096
	ds_read_b128 v[36:39], v172 offset:5120
	ds_read_b128 v[40:43], v172 offset:6144
	ds_read_b128 v[44:47], v172 offset:7168
	global_load_lds_dwordx4 v[48:49], off
	v_lshl_add_u64 v[48:49], s[92:93], 0, v[136:137]
	s_add_i32 m0, s76, 0xe000
	s_nop 0
	global_load_lds_dwordx4 v[48:49], off
	s_waitcnt lgkmcnt(8)
	s_barrier
	s_setprio 1
	s_waitcnt lgkmcnt(12)
	s_waitcnt lgkmcnt(7)
	v_mfma_f32_16x16x32_bf16 v[48:51], v[0:3], v[16:19], 0
	v_mfma_f32_16x16x32_bf16 v[52:55], v[8:11], v[16:19], 0
	s_waitcnt lgkmcnt(5)
	v_mfma_f32_16x16x32_bf16 v[56:59], v[0:3], v[24:27], 0
	v_mfma_f32_16x16x32_bf16 v[60:63], v[8:11], v[24:27], 0
	s_waitcnt lgkmcnt(3)
	v_mfma_f32_16x16x32_bf16 v[64:67], v[0:3], v[32:35], 0
	v_mfma_f32_16x16x32_bf16 v[68:71], v[8:11], v[32:35], 0
	s_waitcnt lgkmcnt(1)
	v_mfma_f32_16x16x32_bf16 v[72:75], v[0:3], v[40:43], 0
	v_mfma_f32_16x16x32_bf16 v[76:79], v[8:11], v[40:43], 0
	v_mfma_f32_16x16x32_bf16 v[48:51], v[4:7], v[20:23], v[48:51]
	v_mfma_f32_16x16x32_bf16 v[52:55], v[12:15], v[20:23], v[52:55]
	v_mfma_f32_16x16x32_bf16 v[56:59], v[4:7], v[28:31], v[56:59]
	v_mfma_f32_16x16x32_bf16 v[60:63], v[12:15], v[28:31], v[60:63]
	v_mfma_f32_16x16x32_bf16 v[64:67], v[4:7], v[36:39], v[64:67]
	v_mfma_f32_16x16x32_bf16 v[68:71], v[12:15], v[36:39], v[68:71]
	s_waitcnt lgkmcnt(0)
	v_mfma_f32_16x16x32_bf16 v[72:75], v[4:7], v[44:47], v[72:75]
	v_mfma_f32_16x16x32_bf16 v[76:79], v[12:15], v[44:47], v[76:79]
	s_setprio 0
	s_barrier
	s_add_i32 s3, s85, s75
	v_lshl_add_u64 v[186:187], s[60:61], 0, v[134:135]
	s_mov_b32 m0, s3
	ds_read_b128 v[80:83], v173
	ds_read_b128 v[84:87], v173 offset:1024
	ds_read_b128 v[88:91], v173 offset:2048
	ds_read_b128 v[92:95], v173 offset:3072
	global_load_lds_dwordx4 v[186:187], off
	v_lshl_add_u64 v[242:243], s[60:61], 0, v[138:139]
	s_add_i32 m0, s3, 0x2000
	s_nop 0
	global_load_lds_dwordx4 v[242:243], off
	s_barrier
	s_setprio 1
	s_waitcnt lgkmcnt(3)
	v_mfma_f32_16x16x32_bf16 v[96:99], v[80:83], v[16:19], 0
	s_waitcnt lgkmcnt(1)
	v_mfma_f32_16x16x32_bf16 v[16:19], v[88:91], v[16:19], 0
	v_mfma_f32_16x16x32_bf16 v[96:99], v[84:87], v[20:23], v[96:99]
	s_waitcnt lgkmcnt(0)
	v_mfma_f32_16x16x32_bf16 v[16:19], v[92:95], v[20:23], v[16:19]
	v_mfma_f32_16x16x32_bf16 v[20:23], v[80:83], v[24:27], 0
	v_mfma_f32_16x16x32_bf16 v[24:27], v[88:91], v[24:27], 0
	v_mfma_f32_16x16x32_bf16 v[20:23], v[84:87], v[28:31], v[20:23]
	v_mfma_f32_16x16x32_bf16 v[24:27], v[92:95], v[28:31], v[24:27]
	v_mfma_f32_16x16x32_bf16 v[28:31], v[80:83], v[32:35], 0
	v_mfma_f32_16x16x32_bf16 v[100:103], v[84:87], v[36:39], v[28:31]
	v_mfma_f32_16x16x32_bf16 v[28:31], v[88:91], v[32:35], 0
	v_mfma_f32_16x16x32_bf16 v[32:35], v[92:95], v[36:39], v[28:31]
	v_mfma_f32_16x16x32_bf16 v[28:31], v[80:83], v[40:43], 0
	v_mfma_f32_16x16x32_bf16 v[36:39], v[84:87], v[44:47], v[28:31]
	v_mfma_f32_16x16x32_bf16 v[28:31], v[88:91], v[40:43], 0
	v_mfma_f32_16x16x32_bf16 v[40:43], v[92:95], v[44:47], v[28:31]
	s_setprio 0
	s_mov_b32 m0, s76
	v_lshl_add_u64 v[188:189], s[66:67], 0, v[132:133]
	s_barrier
	s_nop 2
	ds_read_b128 v[28:31], v172 offset:16384
	ds_read_b128 v[44:47], v172 offset:17408
	ds_read_b128 v[104:107], v172 offset:18432
	ds_read_b128 v[108:111], v172 offset:19456
	ds_read_b128 v[112:115], v172 offset:20480
	ds_read_b128 v[116:119], v172 offset:21504
	ds_read_b128 v[120:123], v172 offset:22528
	ds_read_b128 v[124:127], v172 offset:23552
	global_load_lds_dwordx4 v[188:189], off
	v_lshl_add_u64 v[140:141], s[66:67], 0, v[136:137]
	s_mov_b32 m0, s77
	s_nop 0
	global_load_lds_dwordx4 v[140:141], off
	s_barrier
	s_setprio 1
	s_waitcnt lgkmcnt(7)
	v_mfma_f32_16x16x32_bf16 v[128:131], v[0:3], v[28:31], 0
	s_waitcnt lgkmcnt(5)
	v_mfma_f32_16x16x32_bf16 v[148:151], v[0:3], v[104:107], 0
	s_waitcnt lgkmcnt(3)
	v_mfma_f32_16x16x32_bf16 v[156:159], v[0:3], v[112:115], 0
	s_waitcnt lgkmcnt(1)
	v_mfma_f32_16x16x32_bf16 v[0:3], v[0:3], v[120:123], 0
	v_mfma_f32_16x16x32_bf16 v[128:131], v[4:7], v[44:47], v[128:131]
	v_mfma_f32_16x16x32_bf16 v[144:147], v[8:11], v[28:31], 0
	v_mfma_f32_16x16x32_bf16 v[148:151], v[4:7], v[108:111], v[148:151]
	v_mfma_f32_16x16x32_bf16 v[152:155], v[8:11], v[104:107], 0
	v_mfma_f32_16x16x32_bf16 v[156:159], v[4:7], v[116:119], v[156:159]
	s_waitcnt lgkmcnt(0)
	v_mfma_f32_16x16x32_bf16 v[0:3], v[4:7], v[124:127], v[0:3]
	v_mfma_f32_16x16x32_bf16 v[4:7], v[8:11], v[120:123], 0
	v_mfma_f32_16x16x32_bf16 v[144:147], v[12:15], v[44:47], v[144:147]
	v_mfma_f32_16x16x32_bf16 v[152:155], v[12:15], v[108:111], v[152:155]
	v_mfma_f32_16x16x32_bf16 v[160:163], v[8:11], v[112:115], 0
	v_mfma_f32_16x16x32_bf16 v[4:7], v[12:15], v[124:127], v[4:7]
	v_mfma_f32_16x16x32_bf16 v[160:163], v[12:15], v[116:119], v[160:163]
	s_setprio 0
	s_barrier
; #define PG8_STAGE(bufoff, gbase, voff) do { _Pragma("unroll") for (int _i = 0; _i < 2; ++_i) \
;         __builtin_amdgcn_global_load_lds((const unsigned*)((const char*)(gbase) + (voff)[_i]), (LAS unsigned*)(lds + (bufoff) + ldsw + _i * 8192), 16, 0, 0); } while (0)
; #define PG8_LDA(dst, b, h) do { _Pragma("unroll") for (int m = 0; m < 4; ++m) _Pragma("unroll") for (int k = 0; k < 2; ++k) dst[m][k] = *(const LAS bf16x8*)(lds + PG8_SA(b, h) + aoff + m * 2048 + k * 1024); } while (0)
; #define PG8_LDB(dst, b, h) do { _Pragma("unroll") for (int n = 0; n < 2; ++n) _Pragma("unroll") for (int k = 0; k < 2; ++k) dst[n][k] = *(const LAS bf16x8*)(lds + PG8_SB(b, h) + boff + n * 2048 + k * 1024); } while (0)
; #define PG8_MMA(ai, bj, At, Bt) do { __builtin_amdgcn_s_setprio(1); _Pragma("unroll") for (int m = 0; m < 4; ++m) _Pragma("unroll") for (int n = 0; n < 2; ++n) _Pragma("unroll") for (int k = 0; k < 2; ++k) \
;         acc[ai][bj][m][n] = __builtin_amdgcn_mfma_f32_16x16x32_bf16(Bt[n][k], At[m][k], acc[ai][bj][m][n], 0, 0, 0); __builtin_amdgcn_s_setprio(0); } while (0)
; #define PG8_WAIT_V(n) asm volatile("s_waitcnt vmcnt(" #n ")" ::: "memory")
; #define PG8_WAIT_L(n) asm volatile("s_waitcnt lgkmcnt(" #n ")" ::: "memory")
; #define PG8_BAR __builtin_amdgcn_s_barrier()
; #define PG8_SCHED __builtin_amdgcn_sched_barrier(0)
; template <class Epi>
; __device__ __forceinline__ void gemm_phase(LAS unsigned char* lds, const Gemm g, const StaticOrder& S, const Epi& E) {
;     ...
;             PG8_STAGE(PG8_SB(0, 1), b2 + hstepB, voffB);
;             PG8_WAIT_V(6); PG8_BAR; PG8_MMA(1, 1, At, B1); PG8_BAR;
;             PG8_LDB(B0, 1, 0); PG8_SCHED; PG8_LDA(At, 1, 0); PG8_STAGE(PG8_SA(0, 1), a2 + hstepA, voffA);
;             PG8_WAIT_L(8); PG8_BAR; PG8_WAIT_L(0); PG8_MMA(0, 0, At, B0); PG8_BAR; PG8_SCHED;
;             PG8_LDB(B1, 1, 1); PG8_STAGE(PG8_SB(1, 0), b3, voffB);
;             PG8_BAR; PG8_WAIT_L(0); PG8_MMA(0, 1, At, B1); PG8_BAR;
;             PG8_LDA(At, 1, 1); PG8_STAGE(PG8_SA(1, 0), a3, voffA);
;             PG8_BAR; PG8_WAIT_L(0); PG8_MMA(1, 0, At, B0); PG8_BAR; PG8_SCHED;
	s_add_i32 s3, s86, s75
	v_lshl_add_u64 v[8:9], s[68:69], 0, v[134:135]
	s_mov_b32 m0, s3
	s_nop 0
	global_load_lds_dwordx4 v[8:9], off
	v_lshl_add_u64 v[8:9], s[68:69], 0, v[138:139]
	s_add_i32 m0, s3, 0x2000
	s_nop 0
	global_load_lds_dwordx4 v[8:9], off
	s_waitcnt vmcnt(6)
	s_barrier
	s_setprio 1
	v_mfma_f32_16x16x32_bf16 v[12:15], v[88:91], v[28:31], 0
	v_mfma_f32_16x16x32_bf16 v[164:167], v[92:95], v[44:47], v[12:15]
	v_mfma_f32_16x16x32_bf16 v[12:15], v[80:83], v[104:107], 0
	v_mfma_f32_16x16x32_bf16 v[174:177], v[84:87], v[108:111], v[12:15]
	v_mfma_f32_16x16x32_bf16 v[12:15], v[88:91], v[104:107], 0
	v_mfma_f32_16x16x32_bf16 v[178:181], v[92:95], v[108:111], v[12:15]
	v_mfma_f32_16x16x32_bf16 v[12:15], v[80:83], v[112:115], 0
	v_mfma_f32_16x16x32_bf16 v[182:185], v[84:87], v[116:119], v[12:15]
	v_mfma_f32_16x16x32_bf16 v[12:15], v[88:91], v[112:115], 0
	v_mfma_f32_16x16x32_bf16 v[8:11], v[80:83], v[28:31], 0
	v_mfma_f32_16x16x32_bf16 v[190:193], v[92:95], v[116:119], v[12:15]
	v_mfma_f32_16x16x32_bf16 v[12:15], v[80:83], v[120:123], 0
	v_mfma_f32_16x16x32_bf16 v[8:11], v[84:87], v[44:47], v[8:11]
	v_mfma_f32_16x16x32_bf16 v[194:197], v[84:87], v[124:127], v[12:15]
	v_mfma_f32_16x16x32_bf16 v[12:15], v[88:91], v[120:123], 0
	v_mfma_f32_16x16x32_bf16 v[198:201], v[92:95], v[124:127], v[12:15]
	s_setprio 0
	s_add_i32 s3, 0, 0x18000
	s_nop 4
	v_add_u32_e32 v12, s3, v169
	s_barrier
	ds_read_b128 v[202:205], v12
	ds_read_b128 v[206:209], v12 offset:1024
	ds_read_b128 v[210:213], v12 offset:2048
	ds_read_b128 v[214:217], v12 offset:3072
	s_mov_b32 m0, s78
	v_lshl_add_u64 v[84:85], s[64:65], 0, v[132:133]
	ds_read_b128 v[12:15], v172 offset:32768
	ds_read_b128 v[28:31], v172 offset:33792
	ds_read_b128 v[44:47], v172 offset:34816
	ds_read_b128 v[80:83], v172 offset:35840
	ds_read_b128 v[104:107], v172 offset:36864
	ds_read_b128 v[112:115], v172 offset:37888
	ds_read_b128 v[218:221], v172 offset:38912
	ds_read_b128 v[222:225], v172 offset:39936
	global_load_lds_dwordx4 v[84:85], off
	v_lshl_add_u64 v[84:85], s[64:65], 0, v[136:137]
	s_mov_b32 m0, s79
	s_nop 0
	global_load_lds_dwordx4 v[84:85], off
	s_waitcnt lgkmcnt(8)
	s_barrier
	s_setprio 1
	s_waitcnt lgkmcnt(7)
	v_mfma_f32_16x16x32_bf16 v[48:51], v[202:205], v[12:15], v[48:51]
	s_waitcnt lgkmcnt(6)
	v_mfma_f32_16x16x32_bf16 v[120:123], v[206:209], v[28:31], v[48:51]
	v_mfma_f32_16x16x32_bf16 v[48:51], v[210:213], v[12:15], v[52:55]
	v_mfma_f32_16x16x32_bf16 v[92:95], v[214:217], v[28:31], v[48:51]
	s_waitcnt lgkmcnt(5)
	v_mfma_f32_16x16x32_bf16 v[48:51], v[202:205], v[44:47], v[56:59]
	s_waitcnt lgkmcnt(4)
	v_mfma_f32_16x16x32_bf16 v[124:127], v[206:209], v[80:83], v[48:51]
	v_mfma_f32_16x16x32_bf16 v[48:51], v[210:213], v[44:47], v[60:63]
	v_mfma_f32_16x16x32_bf16 v[88:91], v[214:217], v[80:83], v[48:51]
	s_waitcnt lgkmcnt(3)
	v_mfma_f32_16x16x32_bf16 v[48:51], v[202:205], v[104:107], v[64:67]
	s_waitcnt lgkmcnt(2)
	v_mfma_f32_16x16x32_bf16 v[116:119], v[206:209], v[112:115], v[48:51]
	v_mfma_f32_16x16x32_bf16 v[48:51], v[210:213], v[104:107], v[68:71]
	v_mfma_f32_16x16x32_bf16 v[84:87], v[214:217], v[112:115], v[48:51]
	s_waitcnt lgkmcnt(1)
	v_mfma_f32_16x16x32_bf16 v[48:51], v[202:205], v[218:221], v[72:75]
	s_waitcnt lgkmcnt(0)
	v_mfma_f32_16x16x32_bf16 v[108:111], v[206:209], v[222:225], v[48:51]
	v_mfma_f32_16x16x32_bf16 v[48:51], v[210:213], v[218:221], v[76:79]
	v_mfma_f32_16x16x32_bf16 v[76:79], v[214:217], v[222:225], v[48:51]
	s_setprio 0
	s_barrier
	s_add_i32 s29, 0, 0x1c000
	s_nop 3
	v_add_u32_e32 v48, s29, v169
	s_add_i32 s3, s3, s75
	ds_read_b128 v[226:229], v48
	ds_read_b128 v[230:233], v48 offset:1024
	ds_read_b128 v[234:237], v48 offset:2048
	ds_read_b128 v[238:241], v48 offset:3072
	v_lshl_add_u64 v[48:49], v[186:187], 0, s[8:9]
	s_mov_b32 m0, s3
	s_nop 0
	global_load_lds_dwordx4 v[48:49], off
	v_lshl_add_u64 v[48:49], v[242:243], 0, s[8:9]
	s_add_i32 m0, s3, 0x2000
	s_nop 0
	global_load_lds_dwordx4 v[48:49], off
	s_barrier
	s_setprio 1
	s_waitcnt lgkmcnt(3)
	v_mfma_f32_16x16x32_bf16 v[48:51], v[226:229], v[12:15], v[96:99]
	s_waitcnt lgkmcnt(1)
	v_mfma_f32_16x16x32_bf16 v[12:15], v[234:237], v[12:15], v[16:19]
	v_mfma_f32_16x16x32_bf16 v[60:63], v[230:233], v[28:31], v[48:51]
	s_waitcnt lgkmcnt(0)
	v_mfma_f32_16x16x32_bf16 v[28:31], v[238:241], v[28:31], v[12:15]
	v_mfma_f32_16x16x32_bf16 v[12:15], v[226:229], v[44:47], v[20:23]
	v_mfma_f32_16x16x32_bf16 v[56:59], v[230:233], v[80:83], v[12:15]
	v_mfma_f32_16x16x32_bf16 v[12:15], v[234:237], v[44:47], v[24:27]
	v_mfma_f32_16x16x32_bf16 v[24:27], v[238:241], v[80:83], v[12:15]
	v_mfma_f32_16x16x32_bf16 v[12:15], v[226:229], v[104:107], v[100:103]
	v_mfma_f32_16x16x32_bf16 v[52:55], v[230:233], v[112:115], v[12:15]
	v_mfma_f32_16x16x32_bf16 v[12:15], v[234:237], v[104:107], v[32:35]
	v_mfma_f32_16x16x32_bf16 v[20:23], v[238:241], v[112:115], v[12:15]
	v_mfma_f32_16x16x32_bf16 v[12:15], v[226:229], v[218:221], v[36:39]
	v_mfma_f32_16x16x32_bf16 v[44:47], v[230:233], v[222:225], v[12:15]
	v_mfma_f32_16x16x32_bf16 v[12:15], v[234:237], v[218:221], v[40:43]
	v_mfma_f32_16x16x32_bf16 v[12:15], v[238:241], v[222:225], v[12:15]
	s_setprio 0
	s_mov_b32 m0, s80
	v_lshl_add_u64 v[40:41], v[188:189], 0, s[8:9]
	s_barrier
	ds_read_b128 v[16:19], v172 offset:49152
	ds_read_b128 v[32:35], v172 offset:50176
	ds_read_b128 v[36:39], v172 offset:51200
	ds_read_b128 v[218:221], v172 offset:52224
	ds_read_b128 v[222:225], v172 offset:53248
	ds_read_b128 v[242:245], v172 offset:54272
	ds_read_b128 v[246:249], v172 offset:55296
	ds_read_b128 v[250:253], v172 offset:56320
	global_load_lds_dwordx4 v[40:41], off
	v_lshl_add_u64 v[40:41], v[140:141], 0, s[8:9]
	s_mov_b32 m0, s81
	s_nop 0
	global_load_lds_dwordx4 v[40:41], off
	s_barrier
; __device__ __forceinline__ float sigmoidf_(float x) { return __builtin_amdgcn_rcpf(1.0f + __expf(-x)); }
; #define PG8_STAGE(bufoff, gbase, voff) do { _Pragma("unroll") for (int _i = 0; _i < 2; ++_i) \
;         __builtin_amdgcn_global_load_lds((const unsigned*)((const char*)(gbase) + (voff)[_i]), (LAS unsigned*)(lds + (bufoff) + ldsw + _i * 8192), 16, 0, 0); } while (0)
; #define PG8_WAIT_V(n) asm volatile("s_waitcnt vmcnt(" #n ")" ::: "memory")
; template <class Epi>
; __device__ __forceinline__ void gemm_phase(LAS unsigned char* lds, const Gemm g, const StaticOrder& S, const Epi& E) {
;     ...
;             PG8_BAR; PG8_WAIT_L(0); PG8_MMA(1, 0, At, B0); PG8_BAR; PG8_SCHED;
;             PG8_STAGE(PG8_SB(1, 1), b3 + hstepB, voffB);
;             PG8_WAIT_V(6); PG8_BAR; PG8_MMA(1, 1, At, B1); PG8_BAR;
;     __device__ __forceinline__ void operator()(const AccT& acc, const Unit& u, int wr, int wc, int fr, int fq) const {
;         const int row0 = u.pm * 256 + wr * 64 + fr, col0 = u.pn * 256 + wc * 32 + 4 * fq;
;         if (u.pn < 4) {
; #pragma unroll
;             for (int bj = 0; bj < 2; ++bj)
; #pragma unroll
;                 for (int n = 0; n < 2; ++n) { const int col = col0 + bj * 128 + n * 16; const f32x4 wv = *(const f32x4*)(w0 + col);
; #pragma unroll
;                     for (int ai = 0; ai < 2; ++ai)
; #pragma unroll
;                         for (int m = 0; m < 4; ++m) { const int row = row0 + ai * 128 + m * 16; f32x4 o;
; #pragma unroll
;                             for (int j = 0; j < 4; ++j) o[j] = __expf(-DECAY_SCALE * sigmoidf_(wv[j] + acc[ai][bj][m][n][j]));
;                             *(f32x4*)(Wd + (size_t)row * RW + col) = o; asm volatile("" ::: "memory"); } }
;         } else {
; #pragma unroll
;             for (int bj = 0; bj < 2; ++bj)
; #pragma unroll
;                 for (int n = 0; n < 2; ++n) { const int col = col0 - 1024 + bj * 128 + n * 16; const f32x4 av0 = *(const f32x4*)(a0 + col);
; #pragma unroll
;                     for (int ai = 0; ai < 2; ++ai)
; #pragma unroll
;                         for (int m = 0; m < 4; ++m) { const int row = row0 + ai * 128 + m * 16; f32x4 o;
; #pragma unroll
;                             for (int j = 0; j < 4; ++j) o[j] = sigmoidf_(av0[j] + acc[ai][bj][m][n][j]);
;                             *(f32x4*)(IC + (size_t)row * RW + col) = o; asm volatile("" ::: "memory"); } }
	s_waitcnt lgkmcnt(0)
	s_setprio 1
	s_waitcnt lgkmcnt(0)
	v_mfma_f32_16x16x32_bf16 v[40:43], v[202:205], v[16:19], v[128:131]
	s_add_u32 s60, s60, 0x8080
	s_addc_u32 s61, s61, 0
	v_mfma_f32_16x16x32_bf16 v[112:115], v[206:209], v[32:35], v[40:43]
	v_mfma_f32_16x16x32_bf16 v[40:43], v[210:213], v[16:19], v[144:147]
	v_mfma_f32_16x16x32_bf16 v[80:83], v[214:217], v[32:35], v[40:43]
	v_mfma_f32_16x16x32_bf16 v[40:43], v[202:205], v[36:39], v[148:151]
	v_mfma_f32_16x16x32_bf16 v[104:107], v[206:209], v[218:221], v[40:43]
	v_mfma_f32_16x16x32_bf16 v[40:43], v[210:213], v[36:39], v[152:155]
	v_mfma_f32_16x16x32_bf16 v[72:75], v[214:217], v[218:221], v[40:43]
	v_mfma_f32_16x16x32_bf16 v[40:43], v[202:205], v[222:225], v[156:159]
	v_mfma_f32_16x16x32_bf16 v[0:3], v[202:205], v[246:249], v[0:3]
	v_mfma_f32_16x16x32_bf16 v[100:103], v[206:209], v[242:245], v[40:43]
	v_mfma_f32_16x16x32_bf16 v[40:43], v[210:213], v[222:225], v[160:163]
	v_mfma_f32_16x16x32_bf16 v[96:99], v[206:209], v[250:253], v[0:3]
	v_mfma_f32_16x16x32_bf16 v[0:3], v[210:213], v[246:249], v[4:7]
	v_mfma_f32_16x16x32_bf16 v[68:71], v[214:217], v[242:245], v[40:43]
	v_mfma_f32_16x16x32_bf16 v[64:67], v[214:217], v[250:253], v[0:3]
	s_setprio 0
	s_barrier
	s_add_i32 s3, s29, s75
	s_nop 2
	v_lshl_add_u64 v[0:1], s[60:61], 0, v[134:135]
	s_mov_b32 m0, s3
	s_nop 0
	global_load_lds_dwordx4 v[0:1], off
	v_lshl_add_u64 v[0:1], s[60:61], 0, v[138:139]
	s_add_i32 m0, s3, 0x2000
	s_nop 0
	global_load_lds_dwordx4 v[0:1], off
	s_waitcnt vmcnt(6)
	s_barrier
	s_setprio 1
	v_mfma_f32_16x16x32_bf16 v[0:3], v[226:229], v[16:19], v[8:11]
	v_mfma_f32_16x16x32_bf16 v[48:51], v[230:233], v[32:35], v[0:3]
	v_mfma_f32_16x16x32_bf16 v[0:3], v[234:237], v[16:19], v[164:167]
	v_mfma_f32_16x16x32_bf16 v[16:19], v[238:241], v[32:35], v[0:3]
	v_mfma_f32_16x16x32_bf16 v[0:3], v[226:229], v[36:39], v[174:177]
	v_mfma_f32_16x16x32_bf16 v[40:43], v[230:233], v[218:221], v[0:3]
	v_mfma_f32_16x16x32_bf16 v[0:3], v[234:237], v[36:39], v[178:181]
	v_mfma_f32_16x16x32_bf16 v[8:11], v[238:241], v[218:221], v[0:3]
	v_mfma_f32_16x16x32_bf16 v[0:3], v[226:229], v[222:225], v[182:185]
	v_mfma_f32_16x16x32_bf16 v[36:39], v[230:233], v[242:245], v[0:3]
	v_mfma_f32_16x16x32_bf16 v[0:3], v[234:237], v[222:225], v[190:193]
	v_mfma_f32_16x16x32_bf16 v[4:7], v[238:241], v[242:245], v[0:3]
	v_mfma_f32_16x16x32_bf16 v[0:3], v[226:229], v[246:249], v[194:197]
	v_mfma_f32_16x16x32_bf16 v[32:35], v[230:233], v[250:253], v[0:3]
	v_mfma_f32_16x16x32_bf16 v[0:3], v[234:237], v[246:249], v[198:201]
	v_mfma_f32_16x16x32_bf16 v[0:3], v[238:241], v[250:253], v[0:3]
	s_setprio 0
	v_lshl_add_u32 v150, s44, 8, v168
	v_lshl_or_b32 v152, s91, 8, v170
	v_or_b32_e32 v148, 16, v150
	v_or_b32_e32 v146, 32, v150
	v_or_b32_e32 v144, 48, v150
	s_mov_b64 s[44:45], -1
	s_cmp_lt_i32 s91, 4
	v_ashrrev_i32_e32 v153, 31, v152
	v_ashrrev_i32_e32 v151, 31, v150
	v_ashrrev_i32_e32 v149, 31, v148
	v_ashrrev_i32_e32 v147, 31, v146
	v_ashrrev_i32_e32 v145, 31, v144
	s_barrier
	s_cbranch_scc1 .LBB0_354
	v_lshlrev_b64 v[140:141], 2, v[152:153]
	v_lshl_add_u64 v[156:157], s[36:37], 0, v[140:141]
	global_load_dwordx4 v[128:131], v[156:157], off offset:-4096
	v_lshlrev_b64 v[154:155], 12, v[150:151]
	v_lshlrev_b64 v[160:161], 12, v[146:147]
	v_lshl_add_u64 v[154:155], s[6:7], 0, v[154:155]
	v_lshl_add_u64 v[162:163], s[6:7], 0, v[160:161]
	v_lshl_add_u64 v[160:161], v[154:155], 0, v[140:141]
	v_lshl_add_u64 v[154:155], v[162:163], 0, v[140:141]
	v_lshlrev_b64 v[158:159], 12, v[148:149]
	v_lshl_add_u64 v[158:159], s[6:7], 0, v[158:159]
	v_lshl_add_u64 v[158:159], v[158:159], 0, v[140:141]
	s_mov_b64 s[44:45], 0
	s_waitcnt vmcnt(0)
	v_add_f32_e32 v162, v120, v128
	v_add_f32_e32 v163, v121, v129
	v_add_f32_e32 v164, v122, v130
	v_add_f32_e32 v165, v123, v131
	v_mul_f32_e32 v162, 0xbfb8aa3b, v162
	v_mul_f32_e32 v163, 0xbfb8aa3b, v163
	v_mul_f32_e32 v164, 0xbfb8aa3b, v164
	v_mul_f32_e32 v165, 0xbfb8aa3b, v165
	v_exp_f32_e32 v162, v162
	v_exp_f32_e32 v163, v163
	v_exp_f32_e32 v164, v164
	v_exp_f32_e32 v165, v165
	v_add_f32_e32 v162, 1.0, v162
	v_add_f32_e32 v163, 1.0, v163
	v_add_f32_e32 v164, 1.0, v164
	v_add_f32_e32 v165, 1.0, v165
	v_rcp_f32_e32 v162, v162
	v_rcp_f32_e32 v163, v163
	v_rcp_f32_e32 v164, v164
	v_rcp_f32_e32 v165, v165
	v_add_f32_e32 v166, v124, v128
	v_add_f32_e32 v167, v125, v129
	v_add_f32_e32 v174, v126, v130
	v_add_f32_e32 v175, v127, v131
	v_add_f32_e32 v176, v116, v128
	v_add_f32_e32 v177, v117, v129
	v_mul_f32_e32 v166, 0xbfb8aa3b, v166
	v_mul_f32_e32 v167, 0xbfb8aa3b, v167
	v_mul_f32_e32 v174, 0xbfb8aa3b, v174
	v_mul_f32_e32 v175, 0xbfb8aa3b, v175
	v_mul_f32_e32 v176, 0xbfb8aa3b, v176
	v_mul_f32_e32 v177, 0xbfb8aa3b, v177
	v_exp_f32_e32 v166, v166
	v_exp_f32_e32 v167, v167
	v_exp_f32_e32 v174, v174
	v_exp_f32_e32 v175, v175
	global_store_dwordx4 v[160:161], v[162:165], off offset:-4096
	v_exp_f32_e32 v176, v176
	v_exp_f32_e32 v177, v177
	v_lshlrev_b64 v[162:163], 12, v[144:145]
	v_lshl_add_u64 v[162:163], s[6:7], 0, v[162:163]
	v_lshl_add_u64 v[162:163], v[162:163], 0, v[140:141]
	v_add_f32_e32 v140, v112, v128
	v_mul_f32_e32 v140, 0xbfb8aa3b, v140
	v_add_f32_e32 v141, v113, v129
	v_add_f32_e32 v166, 1.0, v166
	v_add_f32_e32 v167, 1.0, v167
	v_add_f32_e32 v184, 1.0, v174
	v_add_f32_e32 v185, 1.0, v175
	v_exp_f32_e32 v140, v140
	v_mul_f32_e32 v141, 0xbfb8aa3b, v141
	v_add_f32_e32 v186, 1.0, v176
	v_add_f32_e32 v187, 1.0, v177
	v_rcp_f32_e32 v174, v166
	v_rcp_f32_e32 v175, v167
	v_rcp_f32_e32 v176, v184
	v_rcp_f32_e32 v177, v185
	v_exp_f32_e32 v141, v141
	v_add_f32_e32 v140, 1.0, v140
	global_store_dwordx4 v[158:159], v[174:177], off offset:-4096
; __device__ __forceinline__ float sigmoidf_(float x) { return __builtin_amdgcn_rcpf(1.0f + __expf(-x)); }
;     __device__ __forceinline__ void operator()(const AccT& acc, const Unit& u, int wr, int wc, int fr, int fq) const {
;     ...
;             for (int bj = 0; bj < 2; ++bj)
; #pragma unroll
;                 for (int n = 0; n < 2; ++n) { const int col = col0 - 1024 + bj * 128 + n * 16; const f32x4 av0 = *(const f32x4*)(a0 + col);
; #pragma unroll
;                     for (int ai = 0; ai < 2; ++ai)
; #pragma unroll
;                         for (int m = 0; m < 4; ++m) { const int row = row0 + ai * 128 + m * 16; f32x4 o;
; #pragma unroll
;                             for (int j = 0; j < 4; ++j) o[j] = sigmoidf_(av0[j] + acc[ai][bj][m][n][j]);
;                             *(f32x4*)(IC + (size_t)row * RW + col) = o; asm volatile("" ::: "memory"); } }
	v_add_f32_e32 v164, v115, v131
	v_mul_f32_e32 v164, 0xbfb8aa3b, v164
	v_rcp_f32_e32 v174, v140
	v_add_f32_e32 v140, 1.0, v141
	v_add_f32_e32 v141, v114, v130
	v_mul_f32_e32 v141, 0xbfb8aa3b, v141
	v_exp_f32_e32 v141, v141
	v_exp_f32_e32 v164, v164
	v_add_f32_e32 v178, v118, v130
	v_add_f32_e32 v179, v119, v131
	v_add_f32_e32 v180, v108, v128
	v_add_f32_e32 v181, v109, v129
	v_mul_f32_e32 v178, 0xbfb8aa3b, v178
	v_mul_f32_e32 v179, 0xbfb8aa3b, v179
	v_mul_f32_e32 v180, 0xbfb8aa3b, v180
	v_mul_f32_e32 v181, 0xbfb8aa3b, v181
	v_exp_f32_e32 v178, v178
	v_exp_f32_e32 v179, v179
	v_rcp_f32_e32 v175, v140
	v_add_f32_e32 v140, 1.0, v141
	v_exp_f32_e32 v180, v180
	v_exp_f32_e32 v181, v181
	v_rcp_f32_e32 v176, v140
	v_add_f32_e32 v140, 1.0, v164
	v_rcp_f32_e32 v177, v140
	v_add_f32_e32 v140, v104, v128
	v_mul_f32_e32 v140, 0xbfb8aa3b, v140
	v_add_f32_e32 v141, v105, v129
	v_add_f32_e32 v188, 1.0, v178
	v_add_f32_e32 v189, 1.0, v179
	v_exp_f32_e32 v140, v140
	v_mul_f32_e32 v141, 0xbfb8aa3b, v141
	v_add_f32_e32 v190, 1.0, v180
	v_add_f32_e32 v191, 1.0, v181
	v_rcp_f32_e32 v178, v186
	v_rcp_f32_e32 v179, v187
	v_rcp_f32_e32 v180, v188
	v_rcp_f32_e32 v181, v189
	v_exp_f32_e32 v141, v141
	v_add_f32_e32 v140, 1.0, v140
	global_store_dwordx4 v[154:155], v[178:181], off offset:-4096
	v_add_f32_e32 v164, v107, v131
	v_mul_f32_e32 v164, 0xbfb8aa3b, v164
	v_rcp_f32_e32 v178, v140
	v_add_f32_e32 v140, 1.0, v141
	v_add_f32_e32 v141, v106, v130
	v_mul_f32_e32 v141, 0xbfb8aa3b, v141
	v_exp_f32_e32 v141, v141
	v_add_f32_e32 v182, v110, v130
	v_add_f32_e32 v183, v111, v131
	v_exp_f32_e32 v164, v164
	v_mul_f32_e32 v182, 0xbfb8aa3b, v182
	v_mul_f32_e32 v183, 0xbfb8aa3b, v183
	v_exp_f32_e32 v182, v182
	v_exp_f32_e32 v183, v183
	v_rcp_f32_e32 v179, v140
	v_add_f32_e32 v140, 1.0, v141
	v_rcp_f32_e32 v180, v140
	v_add_f32_e32 v140, 1.0, v164
	v_rcp_f32_e32 v181, v140
	v_add_f32_e32 v140, v100, v128
	v_add_f32_e32 v192, 1.0, v182
	v_add_f32_e32 v193, 1.0, v183
	v_mul_f32_e32 v140, 0xbfb8aa3b, v140
	v_add_f32_e32 v141, v101, v129
	v_rcp_f32_e32 v182, v190
	v_rcp_f32_e32 v183, v191
	v_rcp_f32_e32 v184, v192
	v_rcp_f32_e32 v185, v193
	v_exp_f32_e32 v140, v140
	v_mul_f32_e32 v141, 0xbfb8aa3b, v141
	v_exp_f32_e32 v141, v141
	global_store_dwordx4 v[162:163], v[182:185], off offset:-4096
	v_lshl_add_u64 v[166:167], v[160:161], 0, s[16:17]
	v_add_f32_e32 v140, 1.0, v140
	global_store_dwordx4 v[166:167], v[174:177], off offset:-4096
	v_add_f32_e32 v128, v96, v128
	v_mul_f32_e32 v128, 0xbfb8aa3b, v128
	v_rcp_f32_e32 v174, v140
	v_add_f32_e32 v140, 1.0, v141
	v_add_f32_e32 v141, v102, v130
	v_mul_f32_e32 v141, 0xbfb8aa3b, v141
	v_add_f32_e32 v175, v103, v131
	v_exp_f32_e32 v141, v141
	v_mul_f32_e32 v175, 0xbfb8aa3b, v175
	v_exp_f32_e32 v177, v175
	v_rcp_f32_e32 v175, v140
	v_add_f32_e32 v140, 1.0, v141
	v_rcp_f32_e32 v176, v140
	v_add_f32_e32 v140, 1.0, v177
	v_add_f32_e32 v130, v98, v130
	v_rcp_f32_e32 v177, v140
	v_exp_f32_e32 v140, v128
	v_add_f32_e32 v128, v97, v129
	v_mul_f32_e32 v130, 0xbfb8aa3b, v130
	v_add_f32_e32 v131, v99, v131
	v_mul_f32_e32 v128, 0xbfb8aa3b, v128
	v_exp_f32_e32 v130, v130
	v_mul_f32_e32 v131, 0xbfb8aa3b, v131
	v_exp_f32_e32 v141, v128
	v_exp_f32_e32 v131, v131
	v_lshl_add_u64 v[164:165], v[160:161], 0, s[18:19]
	v_add_f32_e32 v140, 1.0, v140
	v_add_f32_e32 v130, 1.0, v130
	global_store_dwordx4 v[164:165], v[178:181], off offset:-4096
	v_lshl_add_u64 v[128:129], v[160:161], 0, s[20:21]
	global_store_dwordx4 v[128:129], v[174:177], off offset:-4096
	v_rcp_f32_e32 v178, v140
	v_add_f32_e32 v140, 1.0, v141
	v_rcp_f32_e32 v180, v130
	v_add_f32_e32 v130, 1.0, v131
	v_rcp_f32_e32 v179, v140
	v_rcp_f32_e32 v181, v130
	v_lshl_add_u64 v[130:131], v[160:161], 0, s[22:23]
	global_store_dwordx4 v[130:131], v[178:181], off offset:-4096
	global_load_dwordx4 v[174:177], v[156:157], off offset:-4032
	s_waitcnt vmcnt(0)
	v_add_f32_e32 v140, v92, v174
	v_mul_f32_e32 v140, 0xbfb8aa3b, v140
	v_add_f32_e32 v141, v93, v175
	v_exp_f32_e32 v140, v140
	v_mul_f32_e32 v141, 0xbfb8aa3b, v141
	v_exp_f32_e32 v141, v141
	v_add_f32_e32 v179, v95, v177
	v_add_f32_e32 v140, 1.0, v140
	v_rcp_f32_e32 v178, v140
	v_add_f32_e32 v140, 1.0, v141
	v_add_f32_e32 v141, v94, v176
	v_mul_f32_e32 v141, 0xbfb8aa3b, v141
	v_exp_f32_e32 v141, v141
	v_mul_f32_e32 v179, 0xbfb8aa3b, v179
	v_exp_f32_e32 v181, v179
	v_rcp_f32_e32 v179, v140
	v_add_f32_e32 v140, 1.0, v141
	v_add_f32_e32 v141, v88, v174
	v_rcp_f32_e32 v180, v140
	v_add_f32_e32 v140, 1.0, v181
	v_mul_f32_e32 v141, 0xbfb8aa3b, v141
	v_add_f32_e32 v181, v89, v175
	v_exp_f32_e32 v141, v141
	v_mul_f32_e32 v181, 0xbfb8aa3b, v181
	v_exp_f32_e32 v183, v181
	v_rcp_f32_e32 v181, v140
	v_add_f32_e32 v140, 1.0, v141
	v_add_f32_e32 v141, v90, v176
	v_rcp_f32_e32 v182, v140
	v_add_f32_e32 v140, 1.0, v183
	v_mul_f32_e32 v141, 0xbfb8aa3b, v141
	v_add_f32_e32 v183, v91, v177
	v_exp_f32_e32 v141, v141
	v_mul_f32_e32 v183, 0xbfb8aa3b, v183
	v_exp_f32_e32 v185, v183
	v_rcp_f32_e32 v183, v140
	v_add_f32_e32 v140, 1.0, v141
	v_rcp_f32_e32 v184, v140
	v_add_f32_e32 v140, 1.0, v185
	v_rcp_f32_e32 v185, v140
	v_add_f32_e32 v140, v84, v174
	v_mul_f32_e32 v140, 0xbfb8aa3b, v140
	v_add_f32_e32 v141, v85, v175
	v_exp_f32_e32 v140, v140
	v_mul_f32_e32 v141, 0xbfb8aa3b, v141
	v_exp_f32_e32 v141, v141
	global_store_dwordx4 v[160:161], v[178:181], off offset:-4032
	v_add_f32_e32 v140, 1.0, v140
	global_store_dwordx4 v[158:159], v[182:185], off offset:-4032
	v_rcp_f32_e32 v178, v140
	v_add_f32_e32 v140, 1.0, v141
	v_add_f32_e32 v141, v86, v176
	v_mul_f32_e32 v141, 0xbfb8aa3b, v141
	v_add_f32_e32 v179, v87, v177
	v_exp_f32_e32 v141, v141
	v_mul_f32_e32 v179, 0xbfb8aa3b, v179
; __device__ __forceinline__ float sigmoidf_(float x) { return __builtin_amdgcn_rcpf(1.0f + __expf(-x)); }
;     __device__ __forceinline__ void operator()(const AccT& acc, const Unit& u, int wr, int wc, int fr, int fq) const {
;     ...
;             for (int bj = 0; bj < 2; ++bj)
; #pragma unroll
;                 for (int n = 0; n < 2; ++n) { const int col = col0 - 1024 + bj * 128 + n * 16; const f32x4 av0 = *(const f32x4*)(a0 + col);
; #pragma unroll
;                     for (int ai = 0; ai < 2; ++ai)
; #pragma unroll
;                         for (int m = 0; m < 4; ++m) { const int row = row0 + ai * 128 + m * 16; f32x4 o;
; #pragma unroll
;                             for (int j = 0; j < 4; ++j) o[j] = sigmoidf_(av0[j] + acc[ai][bj][m][n][j]);
;                             *(f32x4*)(IC + (size_t)row * RW + col) = o; asm volatile("" ::: "memory"); } }
	v_exp_f32_e32 v181, v179
	v_rcp_f32_e32 v179, v140
	v_add_f32_e32 v140, 1.0, v141
	v_rcp_f32_e32 v180, v140
	v_add_f32_e32 v140, 1.0, v181
	v_rcp_f32_e32 v181, v140
	v_add_f32_e32 v140, v76, v174
	v_mul_f32_e32 v140, 0xbfb8aa3b, v140
	v_add_f32_e32 v141, v77, v175
	v_exp_f32_e32 v140, v140
	v_mul_f32_e32 v141, 0xbfb8aa3b, v141
	v_exp_f32_e32 v141, v141
	v_add_f32_e32 v140, 1.0, v140
	global_store_dwordx4 v[154:155], v[178:181], off offset:-4032
	s_nop 1
	v_rcp_f32_e32 v178, v140
	v_add_f32_e32 v140, 1.0, v141
	v_add_f32_e32 v141, v78, v176
	v_mul_f32_e32 v141, 0xbfb8aa3b, v141
	v_add_f32_e32 v179, v79, v177
	v_exp_f32_e32 v141, v141
	v_mul_f32_e32 v179, 0xbfb8aa3b, v179
	v_exp_f32_e32 v181, v179
	v_rcp_f32_e32 v179, v140
	v_add_f32_e32 v140, 1.0, v141
	v_add_f32_e32 v141, v80, v174
	v_rcp_f32_e32 v180, v140
	v_add_f32_e32 v140, 1.0, v181
	v_mul_f32_e32 v141, 0xbfb8aa3b, v141
	v_add_f32_e32 v181, v81, v175
	v_exp_f32_e32 v141, v141
	v_mul_f32_e32 v181, 0xbfb8aa3b, v181
	v_exp_f32_e32 v183, v181
	v_rcp_f32_e32 v181, v140
	v_add_f32_e32 v140, 1.0, v141
	v_add_f32_e32 v141, v82, v176
	v_rcp_f32_e32 v182, v140
	v_add_f32_e32 v140, 1.0, v183
	v_mul_f32_e32 v141, 0xbfb8aa3b, v141
	v_add_f32_e32 v183, v83, v177
	v_exp_f32_e32 v141, v141
	v_mul_f32_e32 v183, 0xbfb8aa3b, v183
	v_exp_f32_e32 v185, v183
	v_rcp_f32_e32 v183, v140
	v_add_f32_e32 v140, 1.0, v141
	v_rcp_f32_e32 v184, v140
	v_add_f32_e32 v140, 1.0, v185
	v_rcp_f32_e32 v185, v140
	v_add_f32_e32 v140, v72, v174
	v_mul_f32_e32 v140, 0xbfb8aa3b, v140
	v_add_f32_e32 v141, v73, v175
	v_exp_f32_e32 v140, v140
	v_mul_f32_e32 v141, 0xbfb8aa3b, v141
	v_exp_f32_e32 v141, v141
	global_store_dwordx4 v[162:163], v[178:181], off offset:-4032
	v_add_f32_e32 v140, 1.0, v140
	global_store_dwordx4 v[166:167], v[182:185], off offset:-4032
	v_rcp_f32_e32 v178, v140
	v_add_f32_e32 v140, 1.0, v141
	v_add_f32_e32 v141, v74, v176
	v_mul_f32_e32 v141, 0xbfb8aa3b, v141
	v_add_f32_e32 v179, v75, v177
	v_exp_f32_e32 v141, v141
	v_mul_f32_e32 v179, 0xbfb8aa3b, v179
	v_exp_f32_e32 v181, v179
	v_rcp_f32_e32 v179, v140
	v_add_f32_e32 v140, 1.0, v141
	v_rcp_f32_e32 v180, v140
	v_add_f32_e32 v140, 1.0, v181
	v_rcp_f32_e32 v181, v140
	v_add_f32_e32 v140, v68, v174
	v_mul_f32_e32 v140, 0xbfb8aa3b, v140
	v_add_f32_e32 v141, v69, v175
	v_exp_f32_e32 v140, v140
	v_mul_f32_e32 v141, 0xbfb8aa3b, v141
	v_exp_f32_e32 v141, v141
	v_add_f32_e32 v140, 1.0, v140
	global_store_dwordx4 v[164:165], v[178:181], off offset:-4032
	s_nop 1
	v_rcp_f32_e32 v178, v140
	v_add_f32_e32 v140, 1.0, v141
	v_add_f32_e32 v141, v70, v176
	v_mul_f32_e32 v141, 0xbfb8aa3b, v141
	v_exp_f32_e32 v141, v141
	v_add_f32_e32 v179, v71, v177
	v_mul_f32_e32 v179, 0xbfb8aa3b, v179
	v_exp_f32_e32 v181, v179
	v_rcp_f32_e32 v179, v140
	v_add_f32_e32 v140, 1.0, v141
	v_add_f32_e32 v141, v64, v174
	v_mul_f32_e32 v141, 0xbfb8aa3b, v141
	v_add_f32_e32 v174, v65, v175
	v_exp_f32_e32 v141, v141
	v_mul_f32_e32 v174, 0xbfb8aa3b, v174
	v_exp_f32_e32 v175, v174
	v_rcp_f32_e32 v180, v140
	v_add_f32_e32 v140, 1.0, v181
	v_rcp_f32_e32 v181, v140
	v_add_f32_e32 v140, 1.0, v141
	v_add_f32_e32 v141, v66, v176
	v_rcp_f32_e32 v174, v140
	v_add_f32_e32 v140, 1.0, v175
	v_mul_f32_e32 v141, 0xbfb8aa3b, v141
	v_add_f32_e32 v175, v67, v177
	v_exp_f32_e32 v141, v141
	v_mul_f32_e32 v175, 0xbfb8aa3b, v175
	v_exp_f32_e32 v177, v175
	v_rcp_f32_e32 v175, v140
	v_add_f32_e32 v140, 1.0, v141
	v_rcp_f32_e32 v176, v140
	v_add_f32_e32 v140, 1.0, v177
	v_rcp_f32_e32 v177, v140
	global_store_dwordx4 v[128:129], v[178:181], off offset:-4032
	global_store_dwordx4 v[130:131], v[174:177], off offset:-4032
	global_load_dwordx4 v[174:177], v[156:157], off offset:-3584
	s_waitcnt vmcnt(0)
	v_add_f32_e32 v140, v60, v174
	v_mul_f32_e32 v140, 0xbfb8aa3b, v140
	v_add_f32_e32 v141, v61, v175
	v_exp_f32_e32 v140, v140
	v_mul_f32_e32 v141, 0xbfb8aa3b, v141
	v_exp_f32_e32 v141, v141
	v_add_f32_e32 v179, v63, v177
	v_add_f32_e32 v140, 1.0, v140
	v_rcp_f32_e32 v178, v140
	v_add_f32_e32 v140, 1.0, v141
	v_add_f32_e32 v141, v62, v176
	v_mul_f32_e32 v141, 0xbfb8aa3b, v141
	v_exp_f32_e32 v141, v141
	v_mul_f32_e32 v179, 0xbfb8aa3b, v179
	v_exp_f32_e32 v181, v179
	v_rcp_f32_e32 v179, v140
	v_add_f32_e32 v140, 1.0, v141
	v_add_f32_e32 v141, v56, v174
	v_rcp_f32_e32 v180, v140
	v_add_f32_e32 v140, 1.0, v181
	v_mul_f32_e32 v141, 0xbfb8aa3b, v141
	v_add_f32_e32 v181, v57, v175
	v_exp_f32_e32 v141, v141
	v_mul_f32_e32 v181, 0xbfb8aa3b, v181
	v_exp_f32_e32 v183, v181
	v_rcp_f32_e32 v181, v140
	v_add_f32_e32 v140, 1.0, v141
	v_add_f32_e32 v141, v58, v176
	v_rcp_f32_e32 v182, v140
	v_add_f32_e32 v140, 1.0, v183
	v_mul_f32_e32 v141, 0xbfb8aa3b, v141
	v_add_f32_e32 v183, v59, v177
	v_exp_f32_e32 v141, v141
	v_mul_f32_e32 v183, 0xbfb8aa3b, v183
	v_exp_f32_e32 v185, v183
	v_rcp_f32_e32 v183, v140
	v_add_f32_e32 v140, 1.0, v141
	v_rcp_f32_e32 v184, v140
	v_add_f32_e32 v140, 1.0, v185
	v_rcp_f32_e32 v185, v140
	v_add_f32_e32 v140, v52, v174
	v_mul_f32_e32 v140, 0xbfb8aa3b, v140
	v_add_f32_e32 v141, v53, v175
	v_exp_f32_e32 v140, v140
	v_mul_f32_e32 v141, 0xbfb8aa3b, v141
	v_exp_f32_e32 v141, v141
	global_store_dwordx4 v[160:161], v[178:181], off offset:-3584
	v_add_f32_e32 v140, 1.0, v140
	global_store_dwordx4 v[158:159], v[182:185], off offset:-3584
	v_rcp_f32_e32 v178, v140
	v_add_f32_e32 v140, 1.0, v141
	v_add_f32_e32 v141, v54, v176
	v_mul_f32_e32 v141, 0xbfb8aa3b, v141
	v_add_f32_e32 v179, v55, v177
	v_exp_f32_e32 v141, v141
	v_mul_f32_e32 v179, 0xbfb8aa3b, v179
	v_exp_f32_e32 v181, v179
	v_rcp_f32_e32 v179, v140
	v_add_f32_e32 v140, 1.0, v141
	v_rcp_f32_e32 v180, v140
	v_add_f32_e32 v140, 1.0, v181
	v_rcp_f32_e32 v181, v140
; __device__ __forceinline__ float sigmoidf_(float x) { return __builtin_amdgcn_rcpf(1.0f + __expf(-x)); }
;     __device__ __forceinline__ void operator()(const AccT& acc, const Unit& u, int wr, int wc, int fr, int fq) const {
;     ...
;             for (int bj = 0; bj < 2; ++bj)
; #pragma unroll
;                 for (int n = 0; n < 2; ++n) { const int col = col0 - 1024 + bj * 128 + n * 16; const f32x4 av0 = *(const f32x4*)(a0 + col);
; #pragma unroll
;                     for (int ai = 0; ai < 2; ++ai)
; #pragma unroll
;                         for (int m = 0; m < 4; ++m) { const int row = row0 + ai * 128 + m * 16; f32x4 o;
; #pragma unroll
;                             for (int j = 0; j < 4; ++j) o[j] = sigmoidf_(av0[j] + acc[ai][bj][m][n][j]);
;                             *(f32x4*)(IC + (size_t)row * RW + col) = o; asm volatile("" ::: "memory"); } }
	v_add_f32_e32 v140, v44, v174
	v_mul_f32_e32 v140, 0xbfb8aa3b, v140
	v_add_f32_e32 v141, v45, v175
	v_exp_f32_e32 v140, v140
	v_mul_f32_e32 v141, 0xbfb8aa3b, v141
	v_exp_f32_e32 v141, v141
	v_add_f32_e32 v140, 1.0, v140
	global_store_dwordx4 v[154:155], v[178:181], off offset:-3584
	s_nop 1
	v_rcp_f32_e32 v178, v140
	v_add_f32_e32 v140, 1.0, v141
	v_add_f32_e32 v141, v46, v176
	v_mul_f32_e32 v141, 0xbfb8aa3b, v141
	v_add_f32_e32 v179, v47, v177
	v_exp_f32_e32 v141, v141
	v_mul_f32_e32 v179, 0xbfb8aa3b, v179
	v_exp_f32_e32 v181, v179
	v_rcp_f32_e32 v179, v140
	v_add_f32_e32 v140, 1.0, v141
	v_add_f32_e32 v141, v48, v174
	v_rcp_f32_e32 v180, v140
	v_add_f32_e32 v140, 1.0, v181
	v_mul_f32_e32 v141, 0xbfb8aa3b, v141
	v_add_f32_e32 v181, v49, v175
	v_exp_f32_e32 v141, v141
	v_mul_f32_e32 v181, 0xbfb8aa3b, v181
	v_exp_f32_e32 v183, v181
	v_rcp_f32_e32 v181, v140
	v_add_f32_e32 v140, 1.0, v141
	v_add_f32_e32 v141, v50, v176
	v_rcp_f32_e32 v182, v140
	v_add_f32_e32 v140, 1.0, v183
	v_mul_f32_e32 v141, 0xbfb8aa3b, v141
	v_add_f32_e32 v183, v51, v177
	v_exp_f32_e32 v141, v141
	v_mul_f32_e32 v183, 0xbfb8aa3b, v183
	v_exp_f32_e32 v185, v183
	v_rcp_f32_e32 v183, v140
	v_add_f32_e32 v140, 1.0, v141
	v_rcp_f32_e32 v184, v140
	v_add_f32_e32 v140, 1.0, v185
	v_rcp_f32_e32 v185, v140
	v_add_f32_e32 v140, v40, v174
	v_mul_f32_e32 v140, 0xbfb8aa3b, v140
	v_add_f32_e32 v141, v41, v175
	v_exp_f32_e32 v140, v140
	v_mul_f32_e32 v141, 0xbfb8aa3b, v141
	v_exp_f32_e32 v141, v141
	global_store_dwordx4 v[162:163], v[178:181], off offset:-3584
	v_add_f32_e32 v140, 1.0, v140
	global_store_dwordx4 v[166:167], v[182:185], off offset:-3584
	v_rcp_f32_e32 v178, v140
	v_add_f32_e32 v140, 1.0, v141
	v_add_f32_e32 v141, v42, v176
	v_mul_f32_e32 v141, 0xbfb8aa3b, v141
	v_add_f32_e32 v179, v43, v177
	v_exp_f32_e32 v141, v141
	v_mul_f32_e32 v179, 0xbfb8aa3b, v179
	v_exp_f32_e32 v181, v179
	v_rcp_f32_e32 v179, v140
	v_add_f32_e32 v140, 1.0, v141
	v_rcp_f32_e32 v180, v140
	v_add_f32_e32 v140, 1.0, v181
	v_rcp_f32_e32 v181, v140
	v_add_f32_e32 v140, v36, v174
	v_mul_f32_e32 v140, 0xbfb8aa3b, v140
	v_add_f32_e32 v141, v37, v175
	v_exp_f32_e32 v140, v140
	v_mul_f32_e32 v141, 0xbfb8aa3b, v141
	v_exp_f32_e32 v141, v141
	v_add_f32_e32 v140, 1.0, v140
	global_store_dwordx4 v[164:165], v[178:181], off offset:-3584
	s_nop 1
	v_rcp_f32_e32 v178, v140
	v_add_f32_e32 v140, 1.0, v141
	v_add_f32_e32 v141, v38, v176
	v_mul_f32_e32 v141, 0xbfb8aa3b, v141
	v_exp_f32_e32 v141, v141
	v_add_f32_e32 v179, v39, v177
	v_mul_f32_e32 v179, 0xbfb8aa3b, v179
	v_exp_f32_e32 v181, v179
	v_rcp_f32_e32 v179, v140
	v_add_f32_e32 v140, 1.0, v141
	v_add_f32_e32 v141, v32, v174
	v_mul_f32_e32 v141, 0xbfb8aa3b, v141
	v_add_f32_e32 v174, v33, v175
	v_exp_f32_e32 v141, v141
	v_mul_f32_e32 v174, 0xbfb8aa3b, v174
	v_exp_f32_e32 v175, v174
	v_rcp_f32_e32 v180, v140
	v_add_f32_e32 v140, 1.0, v181
	v_rcp_f32_e32 v181, v140
	v_add_f32_e32 v140, 1.0, v141
	v_add_f32_e32 v141, v34, v176
	v_rcp_f32_e32 v174, v140
	v_add_f32_e32 v140, 1.0, v175
	v_mul_f32_e32 v141, 0xbfb8aa3b, v141
	v_add_f32_e32 v175, v35, v177
	v_exp_f32_e32 v141, v141
	v_mul_f32_e32 v175, 0xbfb8aa3b, v175
	v_exp_f32_e32 v177, v175
	v_rcp_f32_e32 v175, v140
	v_add_f32_e32 v140, 1.0, v141
	v_rcp_f32_e32 v176, v140
	v_add_f32_e32 v140, 1.0, v177
	v_rcp_f32_e32 v177, v140
	global_store_dwordx4 v[128:129], v[178:181], off offset:-3584
	global_store_dwordx4 v[130:131], v[174:177], off offset:-3584
	global_load_dwordx4 v[174:177], v[156:157], off offset:-3520
	s_waitcnt vmcnt(0)
; __device__ __forceinline__ float sigmoidf_(float x) { return __builtin_amdgcn_rcpf(1.0f + __expf(-x)); }
;     __device__ __forceinline__ void operator()(const AccT& acc, const Unit& u, int wr, int wc, int fr, int fq) const {
;     ...
;             for (int bj = 0; bj < 2; ++bj)
; #pragma unroll
;                 for (int n = 0; n < 2; ++n) { const int col = col0 - 1024 + bj * 128 + n * 16; const f32x4 av0 = *(const f32x4*)(a0 + col);
; #pragma unroll
;                     for (int ai = 0; ai < 2; ++ai)
; #pragma unroll
;                         for (int m = 0; m < 4; ++m) { const int row = row0 + ai * 128 + m * 16; f32x4 o;
; #pragma unroll
;                             for (int j = 0; j < 4; ++j) o[j] = sigmoidf_(av0[j] + acc[ai][bj][m][n][j]);
;                             *(f32x4*)(IC + (size_t)row * RW + col) = o; asm volatile("" ::: "memory"); } }
	v_add_f32_e32 v140, v28, v174
	v_mul_f32_e32 v140, 0xbfb8aa3b, v140
	v_add_f32_e32 v141, v29, v175
	v_exp_f32_e32 v140, v140
	v_mul_f32_e32 v141, 0xbfb8aa3b, v141
	v_exp_f32_e32 v141, v141
	v_add_f32_e32 v156, v31, v177
	v_add_f32_e32 v140, 1.0, v140
	v_rcp_f32_e32 v178, v140
	v_add_f32_e32 v140, 1.0, v141
	v_add_f32_e32 v141, v30, v176
	v_mul_f32_e32 v141, 0xbfb8aa3b, v141
	v_exp_f32_e32 v141, v141
	v_mul_f32_e32 v156, 0xbfb8aa3b, v156
	v_exp_f32_e32 v156, v156
	v_rcp_f32_e32 v179, v140
	v_add_f32_e32 v140, 1.0, v141
	v_add_f32_e32 v141, v24, v174
	v_rcp_f32_e32 v180, v140
	v_add_f32_e32 v140, 1.0, v156
	v_mul_f32_e32 v141, 0xbfb8aa3b, v141
	v_add_f32_e32 v156, v25, v175
	v_exp_f32_e32 v141, v141
	v_mul_f32_e32 v156, 0xbfb8aa3b, v156
	v_exp_f32_e32 v156, v156
	v_rcp_f32_e32 v181, v140
	v_add_f32_e32 v140, 1.0, v141
	v_add_f32_e32 v141, v26, v176
	v_rcp_f32_e32 v182, v140
	v_add_f32_e32 v140, 1.0, v156
	v_mul_f32_e32 v141, 0xbfb8aa3b, v141
	v_add_f32_e32 v156, v27, v177
	v_exp_f32_e32 v141, v141
	v_mul_f32_e32 v156, 0xbfb8aa3b, v156
	v_exp_f32_e32 v156, v156
	v_rcp_f32_e32 v183, v140
	v_add_f32_e32 v140, 1.0, v141
	v_rcp_f32_e32 v184, v140
	v_add_f32_e32 v140, 1.0, v156
	v_rcp_f32_e32 v185, v140
	v_add_f32_e32 v140, v20, v174
	v_mul_f32_e32 v140, 0xbfb8aa3b, v140
	v_add_f32_e32 v141, v21, v175
	v_exp_f32_e32 v140, v140
	v_mul_f32_e32 v141, 0xbfb8aa3b, v141
	v_exp_f32_e32 v141, v141
	v_add_f32_e32 v157, v23, v177
	v_add_f32_e32 v140, 1.0, v140
	v_rcp_f32_e32 v156, v140
	v_add_f32_e32 v140, 1.0, v141
	v_add_f32_e32 v141, v22, v176
	v_mul_f32_e32 v141, 0xbfb8aa3b, v141
	global_store_dwordx4 v[160:161], v[178:181], off offset:-3520
	v_exp_f32_e32 v141, v141
	v_mul_f32_e32 v157, 0xbfb8aa3b, v157
	global_store_dwordx4 v[158:159], v[182:185], off offset:-3520
	v_exp_f32_e32 v159, v157
	v_rcp_f32_e32 v157, v140
	v_add_f32_e32 v140, 1.0, v141
	v_rcp_f32_e32 v158, v140
	v_add_f32_e32 v140, 1.0, v159
	v_rcp_f32_e32 v159, v140
	v_add_f32_e32 v140, v12, v174
	v_mul_f32_e32 v140, 0xbfb8aa3b, v140
	v_add_f32_e32 v141, v13, v175
	v_exp_f32_e32 v140, v140
	v_mul_f32_e32 v141, 0xbfb8aa3b, v141
	v_exp_f32_e32 v141, v141
	v_add_f32_e32 v140, 1.0, v140
	global_store_dwordx4 v[154:155], v[156:159], off offset:-3520
	v_rcp_f32_e32 v154, v140
	v_add_f32_e32 v140, 1.0, v141
	v_add_f32_e32 v141, v14, v176
	v_mul_f32_e32 v141, 0xbfb8aa3b, v141
	v_add_f32_e32 v155, v15, v177
	v_exp_f32_e32 v141, v141
	v_mul_f32_e32 v155, 0xbfb8aa3b, v155
	v_exp_f32_e32 v157, v155
	v_rcp_f32_e32 v155, v140
	v_add_f32_e32 v140, 1.0, v141
	v_add_f32_e32 v141, v16, v174
	v_rcp_f32_e32 v156, v140
	v_add_f32_e32 v140, 1.0, v157
	v_mul_f32_e32 v141, 0xbfb8aa3b, v141
	v_add_f32_e32 v157, v17, v175
	v_exp_f32_e32 v141, v141
	v_mul_f32_e32 v157, 0xbfb8aa3b, v157
	v_exp_f32_e32 v159, v157
	v_rcp_f32_e32 v157, v140
	v_add_f32_e32 v140, 1.0, v141
	v_add_f32_e32 v141, v18, v176
	v_rcp_f32_e32 v158, v140
	v_add_f32_e32 v140, 1.0, v159
	v_mul_f32_e32 v141, 0xbfb8aa3b, v141
	v_add_f32_e32 v159, v19, v177
	v_exp_f32_e32 v141, v141
	v_mul_f32_e32 v159, 0xbfb8aa3b, v159
	v_exp_f32_e32 v161, v159
	v_rcp_f32_e32 v159, v140
	v_add_f32_e32 v140, 1.0, v141
	v_rcp_f32_e32 v160, v140
	v_add_f32_e32 v140, 1.0, v161
	v_rcp_f32_e32 v161, v140
	v_add_f32_e32 v140, v8, v174
	v_mul_f32_e32 v140, 0xbfb8aa3b, v140
	v_add_f32_e32 v141, v9, v175
	v_exp_f32_e32 v140, v140
	v_mul_f32_e32 v141, 0xbfb8aa3b, v141
	v_exp_f32_e32 v141, v141
	v_add_f32_e32 v140, 1.0, v140
	global_store_dwordx4 v[162:163], v[154:157], off offset:-3520
	global_store_dwordx4 v[166:167], v[158:161], off offset:-3520
	s_nop 0
	v_rcp_f32_e32 v154, v140
	v_add_f32_e32 v140, 1.0, v141
	v_add_f32_e32 v141, v10, v176
	v_mul_f32_e32 v141, 0xbfb8aa3b, v141
	v_add_f32_e32 v155, v11, v177
	v_exp_f32_e32 v141, v141
	v_mul_f32_e32 v155, 0xbfb8aa3b, v155
	v_exp_f32_e32 v157, v155
	v_rcp_f32_e32 v155, v140
	v_add_f32_e32 v140, 1.0, v141
	v_rcp_f32_e32 v156, v140
	v_add_f32_e32 v140, 1.0, v157
	v_rcp_f32_e32 v157, v140
	v_add_f32_e32 v140, v4, v174
	v_mul_f32_e32 v140, 0xbfb8aa3b, v140
	v_add_f32_e32 v141, v5, v175
	v_exp_f32_e32 v140, v140
	v_mul_f32_e32 v141, 0xbfb8aa3b, v141
	v_exp_f32_e32 v141, v141
	global_store_dwordx4 v[164:165], v[154:157], off offset:-3520
	v_add_f32_e32 v140, 1.0, v140
	s_nop 0
	v_rcp_f32_e32 v154, v140
	v_add_f32_e32 v140, 1.0, v141
	v_add_f32_e32 v141, v6, v176
	v_mul_f32_e32 v141, 0xbfb8aa3b, v141
	v_add_f32_e32 v155, v7, v177
	v_exp_f32_e32 v141, v141
	v_mul_f32_e32 v155, 0xbfb8aa3b, v155
	v_exp_f32_e32 v157, v155
	v_rcp_f32_e32 v155, v140
	v_add_f32_e32 v140, 1.0, v141
	v_add_f32_e32 v141, v0, v174
	v_rcp_f32_e32 v156, v140
	v_add_f32_e32 v140, 1.0, v157
	v_mul_f32_e32 v141, 0xbfb8aa3b, v141
	v_add_f32_e32 v157, v1, v175
	v_exp_f32_e32 v141, v141
	v_mul_f32_e32 v157, 0xbfb8aa3b, v157
	v_exp_f32_e32 v159, v157
	v_rcp_f32_e32 v157, v140
	v_add_f32_e32 v140, 1.0, v141
	v_add_f32_e32 v141, v2, v176
	v_rcp_f32_e32 v158, v140
	v_add_f32_e32 v140, 1.0, v159
	v_mul_f32_e32 v141, 0xbfb8aa3b, v141
	v_add_f32_e32 v159, v3, v177
	v_exp_f32_e32 v141, v141
	v_mul_f32_e32 v159, 0xbfb8aa3b, v159
	v_exp_f32_e32 v161, v159
	v_rcp_f32_e32 v159, v140
	v_add_f32_e32 v140, 1.0, v141
	v_rcp_f32_e32 v160, v140
	v_add_f32_e32 v140, 1.0, v161
	v_rcp_f32_e32 v161, v140
	global_store_dwordx4 v[128:129], v[154:157], off offset:-3520
	global_store_dwordx4 v[130:131], v[158:161], off offset:-3520

; __device__ __forceinline__ void nat_phase(const Params& p, float* ldsf, int wave0, int nwaves) {
;     const int lane = threadIdx.x & 63, wid = __builtin_amdgcn_readfirstlane(threadIdx.x >> 6), l15 = lane & 15, lq = lane >> 4;
;     const u16* Qn = (const u16*)p.out; const u16* Kn = Qn + (size_t)NTOK * RW; const u16* VT = Kn + (size_t)NTOK * RW; const u16* Gn = VT + (size_t)NTOK * RW;
;     u16* MIX = (u16*)(p.ws + O_HN);
;     for (int item = wave0; item < 8192; item += nwaves) {
;         const int r = item & 255, h = (item >> 8) & 15, b = item >> 12;
;         const int rs = min(max(r - 4, 0), 248);
;         const u16* Qb = Qn + (size_t)(b * SEQ + r * 64) * RW + h * 64;
;         const u16* Kb = Kn + (size_t)(b * SEQ + rs * 64) * RW + h * 64;
;         const u16* Vb = VT + (size_t)((b * 16 + h) * 64) * SEQ + rs * 64;
;         float* tb = ldsf + wid * 256;
;         { const float* rpb = p.rpb + h * 465 + (rs - r + 7) * 31;
; #pragma unroll
;           for (int q = 0; q < 4; ++q) { const int e = lane + q * 64; if (e < 248) tb[e] = rpb[e]; } }
; template <bool MIX> __device__ __forceinline__ void scan_pass1(const Params& p, int d, float* ldsf) {
;     ...
;     if (MIX && wid >= 4) nat_phase(p, ldsf, blockIdx.x * 4 + (wid - 4), gridDim.x * 4);
.LBB0_413:
	s_cmp_lt_i32 s58, 5
	s_cselect_b64 s[0:1], -1, 0
	s_cmp_gt_i32 s59, 4
	s_cselect_b64 s[4:5], -1, 0
	s_and_b64 s[0:1], s[0:1], s[4:5]
	s_andn2_b64 vcc, exec, s[0:1]
	s_cbranch_vccnz .LBB0_628
	v_readfirstlane_b32 s0, v254
	v_and_b32_e32 v96, 63, v254
	s_cmp_lt_u32 s0, 0
	v_and_b32_e32 v65, 15, v254
	s_cbranch_scc1 .LBB0_555
	s_setprio 0
	s_lshr_b32 s1, s0, 6
	s_mov_b32 s64, s56
	s_and_b32 s65, s57, 0xffff
	s_brev_b32 s66, -2
	s_mov_b32 s67, 0x27000
	s_mov_b32 s68, s54
	s_and_b32 s69, s55, 0xffff
	s_mov_b32 s70, s66
	s_mov_b32 s71, s67
	s_mov_b32 s72, s50
	s_and_b32 s73, s51, 0xffff
	s_movk_i32 s74, 0x7440
	s_mov_b32 s75, s67
	v_and_b32_e32 v237, 15, v254
	v_bfe_u32 v238, v254, 4, 2
	v_and_b32_e32 v242, 63, v254
	v_lshlrev_b32_e32 v243, 4, v238
	v_lshl_add_u32 v224, v237, 11, v243
	v_lshl_add_u32 v226, v237, 15, v243
	v_lshrrev_b32_e32 v244, 2, v237
	v_and_b32_e32 v245, 3, v237
	v_lshl_add_u32 v244, v244, 3, v245
	v_lshl_add_u32 v225, v244, 11, v243
	v_lshlrev_b32_e32 v243, 3, v238
	v_lshl_add_u32 v227, v237, 11, v243
	v_lshl_add_u32 v228, v237, 12, v243
	v_xor_b32_e32 v248, 16, v242
	v_lshlrev_b32_e32 v248, 2, v248
	v_xor_b32_e32 v249, 32, v242
	v_lshlrev_b32_e32 v249, 2, v249
	s_cmp_lt_u32 s1, 4
	s_cselect_b64 vcc, -1, 0
	s_nop 3
	v_cndmask_b32_e32 v34, v226, v225, vcc
	s_and_b32 s4, s1, 3
	s_lshl_b32 s4, s4, 8
	s_add_u32 s4, s4, 0x1e800
	v_lshl_add_u32 v244, v242, 2, s4
	v_mov_b32_e32 v243, 0xf2c9f2ca
	ds_write_b32 v244, v243
	v_mov_b32_e32 v252, 0x3e38aa3b
	v_mov_b32_e32 v253, 0x3e38aa3b
	s_mov_b32 s95, 0
	s_mov_b32 s88, s2
	s_mov_b32 s94, s96
	s_cmpk_lg_u32 s96, 0x100
	s_cbranch_scc1 .Lmy_nat_unit
	s_and_b32 s88, s2, 7
	s_lshl_b32 s88, s88, 5
	s_lshr_b32 s4, s2, 3
	s_add_u32 s88, s88, s4
	s_movk_i32 s94, 0x100
	s_bfe_u32 s4, s2, 0x20003

; __device__ __forceinline__ void nat_phase(const Params& p, float* ldsf, int wave0, int nwaves) {
;     ...
;         for (int qt = 0; qt < 4; ++qt) {
;             const int c0 = qt * 16, cs0 = (qt == 0) ? 0 : (qt == 1 ? 8 : (qt == 2 ? 24 : 32));
;             const int c = c0 + l15, csq = min(max(c - 8, 0), 48);
;             const bf16x8 bq0 = *(const bf16x8*)(Qb + (size_t)c * RW + lq * 8), bq1 = *(const bf16x8*)(Qb + (size_t)c * RW + 32 + lq * 8);
;             f32x4 sc[8][2];
; #pragma unroll
;             for (int i = 0; i < 8; ++i)
; #pragma unroll
;                 for (int hf = 0; hf < 2; ++hf) { const u16* kp = Kb + (size_t)(i * 64 + cs0 + (l15 >> 2) * 8 + hf * 4 + (l15 & 3)) * RW + lq * 8;
;                     const bf16x8 a0 = *(const bf16x8*)kp, a1 = *(const bf16x8*)(kp + 32); f32x4 z = {0.f, 0.f, 0.f, 0.f};
;                     z = __builtin_amdgcn_mfma_f32_16x16x32_bf16(a0, bq0, z, 0, 0, 0); z = __builtin_amdgcn_mfma_f32_16x16x32_bf16(a1, bq1, z, 0, 0, 0); sc[i][hf] = z; }
.Lmy_nat_cqt:
	s_lshl_b32 s82, s16, 4
	s_add_i32 s83, s82, -8
	s_max_i32 s83, s83, 0
	s_min_i32 s83, s83, 32
	s_lshl_b32 s84, s82, 11
	s_add_u32 s84, s84, s76
	buffer_load_dwordx4 v[192:195], v224, s[68:71], s84 offen
	buffer_load_dwordx4 v[196:199], v224, s[68:71], s84 offen offset:64
	s_barrier
	s_cmp_lt_u32 s1, 4
	s_cbranch_scc0 .Lmy_nat_p1v
	s_cmp_eq_u32 s16, 0
	s_cbranch_scc0 .Lmy_nat_p1kw
	s_cmp_eq_u32 s95, 1
	s_cbranch_scc0 .Lmy_nat_p1k0
	s_mov_b32 s95, 0
	s_waitcnt vmcnt(2)
	s_branch .Lmy_nat_p1j
.Lmy_nat_p1k0:
	s_lshl_b32 s91, s83, 11
	s_add_u32 s91, s91, s77
	s_lshr_b32 s85, s1, 1
	s_lshl_b32 s85, s85, 13
	s_add_u32 s91, s91, s85
	s_and_b32 s85, s1, 1
	s_lshl_b32 s85, s85, 6
	s_add_u32 s91, s91, s85
	s_mov_b32 s93, 0x20000
	s_lshl_b32 s86, s1, 10
	s_mov_b32 m0, s86
	s_nop 0
	buffer_load_dwordx4 v34, s[68:71], s91 offen lds
	s_add_u32 m0, m0, 0x1000
	s_add_u32 s91, s91, s93
	buffer_load_dwordx4 v34, s[68:71], s91 offen lds
	s_add_u32 m0, m0, 0x1000
	s_add_u32 s91, s91, s93
	buffer_load_dwordx4 v34, s[68:71], s91 offen lds
	s_add_u32 m0, m0, 0x1000
	s_add_u32 s91, s91, s93
	buffer_load_dwordx4 v34, s[68:71], s91 offen lds
	s_add_u32 m0, m0, 0x1000
	s_add_u32 s91, s91, s93
	buffer_load_dwordx4 v34, s[68:71], s91 offen lds
	s_add_u32 m0, m0, 0x1000
	s_add_u32 s91, s91, s93
	buffer_load_dwordx4 v34, s[68:71], s91 offen lds
	s_add_u32 m0, m0, 0x1000
	s_add_u32 s91, s91, s93
	buffer_load_dwordx4 v34, s[68:71], s91 offen lds
	s_add_u32 m0, m0, 0x1000
	s_add_u32 s91, s91, s93
	buffer_load_dwordx4 v34, s[68:71], s91 offen lds
	s_add_u32 m0, m0, 0x1000
	s_add_u32 s91, s91, s93
	buffer_load_dwordx4 v34, s[68:71], s91 offen lds
	s_add_u32 m0, m0, 0x1000
	s_add_u32 s91, s91, s93
	buffer_load_dwordx4 v34, s[68:71], s91 offen lds
	s_add_u32 m0, m0, 0x1000
	s_add_u32 s91, s91, s93
	buffer_load_dwordx4 v34, s[68:71], s91 offen lds
	s_add_u32 m0, m0, 0x1000
	s_add_u32 s91, s91, s93
	buffer_load_dwordx4 v34, s[68:71], s91 offen lds
	s_add_u32 m0, m0, 0x1000
	s_add_u32 s91, s91, s93
	buffer_load_dwordx4 v34, s[68:71], s91 offen lds
	s_add_u32 m0, m0, 0x1000
	s_add_u32 s91, s91, s93
	buffer_load_dwordx4 v34, s[68:71], s91 offen lds
	s_add_u32 m0, m0, 0x1000
	s_add_u32 s91, s91, s93
	buffer_load_dwordx4 v34, s[68:71], s91 offen lds
	s_waitcnt vmcnt(0)
	s_branch .Lmy_nat_p1j

; __device__ __forceinline__ void nat_phase(const Params& p, float* ldsf, int wave0, int nwaves) {
;     ...
;     for (int item = wave0; item < 8192; item += nwaves) {
;         const int r = item & 255, h = (item >> 8) & 15, b = item >> 12;
;         const int rs = min(max(r - 4, 0), 248);
;         const u16* Qb = Qn + (size_t)(b * SEQ + r * 64) * RW + h * 64;
;         const u16* Kb = Kn + (size_t)(b * SEQ + rs * 64) * RW + h * 64;
;         const u16* Vb = VT + (size_t)((b * 16 + h) * 64) * SEQ + rs * 64;
;     ...
;                 for (int hf = 0; hf < 2; ++hf) { const u16* kp = Kb + (size_t)(i * 64 + cs0 + (l15 >> 2) * 8 + hf * 4 + (l15 & 3)) * RW + lq * 8;
;                     const bf16x8 a0 = *(const bf16x8*)kp, a1 = *(const bf16x8*)(kp + 32); f32x4 z = {0.f, 0.f, 0.f, 0.f};
.Lmy_nat_p3j:
	s_barrier
	s_mov_b32 s0, 0
	s_cmp_lt_u32 s1, 4
	s_cbranch_scc0 .Lmy_nat_p4j
	s_cmp_lt_u32 s16, 3
	s_cbranch_scc0 .Lmy_nat_p4x
	s_add_i32 s87, s82, 8
	s_min_i32 s87, s87, 32
	s_lshl_b32 s91, s87, 11
	s_add_u32 s91, s91, s77
	s_lshr_b32 s85, s1, 1
	s_lshl_b32 s85, s85, 13
	s_add_u32 s91, s91, s85
	s_and_b32 s85, s1, 1
	s_lshl_b32 s85, s85, 6
	s_add_u32 s91, s91, s85
	s_mov_b32 s93, 0x20000
	s_lshl_b32 s86, s1, 10
	s_mov_b32 m0, s86
	s_nop 0
	buffer_load_dwordx4 v34, s[68:71], s91 offen lds
	s_add_u32 m0, m0, 0x1000
	s_add_u32 s91, s91, s93
	buffer_load_dwordx4 v34, s[68:71], s91 offen lds
	s_add_u32 m0, m0, 0x1000
	s_add_u32 s91, s91, s93
	buffer_load_dwordx4 v34, s[68:71], s91 offen lds
	s_add_u32 m0, m0, 0x1000
	s_add_u32 s91, s91, s93
	buffer_load_dwordx4 v34, s[68:71], s91 offen lds
	s_add_u32 m0, m0, 0x1000
	s_add_u32 s91, s91, s93
	buffer_load_dwordx4 v34, s[68:71], s91 offen lds
	s_add_u32 m0, m0, 0x1000
	s_add_u32 s91, s91, s93
	buffer_load_dwordx4 v34, s[68:71], s91 offen lds
	s_add_u32 m0, m0, 0x1000
	s_add_u32 s91, s91, s93
	buffer_load_dwordx4 v34, s[68:71], s91 offen lds
	s_add_u32 m0, m0, 0x1000
	s_add_u32 s91, s91, s93
	buffer_load_dwordx4 v34, s[68:71], s91 offen lds
	s_add_u32 m0, m0, 0x1000
	s_add_u32 s91, s91, s93
	buffer_load_dwordx4 v34, s[68:71], s91 offen lds
	s_add_u32 m0, m0, 0x1000
	s_add_u32 s91, s91, s93
	buffer_load_dwordx4 v34, s[68:71], s91 offen lds
	s_add_u32 m0, m0, 0x1000
	s_add_u32 s91, s91, s93
	buffer_load_dwordx4 v34, s[68:71], s91 offen lds
	s_add_u32 m0, m0, 0x1000
	s_add_u32 s91, s91, s93
	buffer_load_dwordx4 v34, s[68:71], s91 offen lds
	s_add_u32 m0, m0, 0x1000
	s_add_u32 s91, s91, s93
	buffer_load_dwordx4 v34, s[68:71], s91 offen lds
	s_add_u32 m0, m0, 0x1000
	s_add_u32 s91, s91, s93
	buffer_load_dwordx4 v34, s[68:71], s91 offen lds
	s_add_u32 m0, m0, 0x1000
	s_add_u32 s91, s91, s93
	buffer_load_dwordx4 v34, s[68:71], s91 offen lds
	s_mov_b32 s0, 1
	s_branch .Lmy_nat_p4j
.Lmy_nat_p4x:
	s_add_u32 s4, s88, s94
	s_cmpk_gt_i32 s4, 0x3ff
	s_cbranch_scc1 .Lmy_nat_p4j
	s_lshr_b32 s5, s4, 5
	s_and_b32 s6, s5, 15
	s_lshl_b32 s6, s6, 7
	s_lshr_b32 s5, s5, 4
	s_lshl_b32 s5, s5, 14
	s_and_b32 s4, s4, 31
	s_lshl_b32 s4, s4, 3
	s_add_i32 s4, s4, -4
	s_max_i32 s4, s4, 0
	s_min_i32 s4, s4, 0xf1
	s_lshl_b32 s4, s4, 6
	s_add_u32 s4, s4, s5
	s_lshl_b32 s4, s4, 11
	s_add_u32 s4, s4, s6
	s_add_u32 s4, s4, 0x4000000
	s_mov_b32 s87, 0
	s_lshl_b32 s91, s87, 11
	s_add_u32 s91, s91, s4
	s_lshr_b32 s85, s1, 1
	s_lshl_b32 s85, s85, 13
	s_add_u32 s91, s91, s85
	s_and_b32 s85, s1, 1
	s_lshl_b32 s85, s85, 6
	s_add_u32 s91, s91, s85
	s_mov_b32 s93, 0x20000
	s_lshl_b32 s86, s1, 10
	s_mov_b32 m0, s86
	s_nop 0
	buffer_load_dwordx4 v34, s[68:71], s91 offen lds
	s_add_u32 m0, m0, 0x1000
	s_add_u32 s91, s91, s93
	buffer_load_dwordx4 v34, s[68:71], s91 offen lds
	s_add_u32 m0, m0, 0x1000
	s_add_u32 s91, s91, s93
	buffer_load_dwordx4 v34, s[68:71], s91 offen lds
	s_add_u32 m0, m0, 0x1000
	s_add_u32 s91, s91, s93
	buffer_load_dwordx4 v34, s[68:71], s91 offen lds
	s_add_u32 m0, m0, 0x1000
	s_add_u32 s91, s91, s93
	buffer_load_dwordx4 v34, s[68:71], s91 offen lds
	s_add_u32 m0, m0, 0x1000
	s_add_u32 s91, s91, s93
	buffer_load_dwordx4 v34, s[68:71], s91 offen lds
	s_add_u32 m0, m0, 0x1000
	s_add_u32 s91, s91, s93
	buffer_load_dwordx4 v34, s[68:71], s91 offen lds
	s_add_u32 m0, m0, 0x1000
	s_add_u32 s91, s91, s93
	buffer_load_dwordx4 v34, s[68:71], s91 offen lds
	s_add_u32 m0, m0, 0x1000
	s_add_u32 s91, s91, s93
	buffer_load_dwordx4 v34, s[68:71], s91 offen lds
	s_add_u32 m0, m0, 0x1000
	s_add_u32 s91, s91, s93
	buffer_load_dwordx4 v34, s[68:71], s91 offen lds
	s_add_u32 m0, m0, 0x1000
	s_add_u32 s91, s91, s93
	buffer_load_dwordx4 v34, s[68:71], s91 offen lds
	s_add_u32 m0, m0, 0x1000
	s_add_u32 s91, s91, s93
	buffer_load_dwordx4 v34, s[68:71], s91 offen lds
	s_add_u32 m0, m0, 0x1000
	s_add_u32 s91, s91, s93
	buffer_load_dwordx4 v34, s[68:71], s91 offen lds
	s_add_u32 m0, m0, 0x1000
	s_add_u32 s91, s91, s93
	buffer_load_dwordx4 v34, s[68:71], s91 offen lds
	s_add_u32 m0, m0, 0x1000
	s_add_u32 s91, s91, s93
	buffer_load_dwordx4 v34, s[68:71], s91 offen lds
	s_mov_b32 s0, 1
	s_mov_b32 s95, 1
; __device__ __forceinline__ unsigned cvt_pk_bf16(float lo, float hi) { unsigned r; asm volatile("v_cvt_pk_bf16_f32 %0, %1, %2" : "=v"(r) : "v"(lo), "v"(hi)); return r; }
; __device__ __forceinline__ void nat_phase(const Params& p, float* ldsf, int wave0, int nwaves) {
;     ...
;             for (int i = 0; i < 8; ++i) {
;                 u32x4 pw; pw.x = cvt_pk_bf16(sc[i][0][0] * inv, sc[i][0][1] * inv); pw.y = cvt_pk_bf16(sc[i][0][2] * inv, sc[i][0][3] * inv);
;                 pw.z = cvt_pk_bf16(sc[i][1][0] * inv, sc[i][1][1] * inv); pw.w = cvt_pk_bf16(sc[i][1][2] * inv, sc[i][1][3] * inv);
;                 const bf16x8 bp = __builtin_bit_cast(bf16x8, pw);
; #pragma unroll
;                 for (int mt = 0; mt < 4; ++mt) { const u16* vp = Vb + (size_t)(mt * 16 + l15) * SEQ + i * 64 + cs0 + lq * 8;
;                     o[mt] = __builtin_amdgcn_mfma_f32_16x16x32_bf16(*(const bf16x8*)vp, bp, o[mt], 0, 0, 0); }
;             }
.Lmy_nat_p4j:
	ds_read_b128 v[0:3], v33 offset:0
	ds_read_b128 v[4:7], v33 offset:1024
	ds_read_b128 v[8:11], v33 offset:2048
	ds_read_b128 v[12:15], v33 offset:3072
	ds_read_b128 v[16:19], v33 offset:4096
	ds_read_b128 v[20:23], v33 offset:5120
	ds_read_b128 v[24:27], v33 offset:6144
	ds_read_b128 v[28:31], v33 offset:7168
	s_waitcnt lgkmcnt(7)
	v_mfma_f32_16x16x32_bf16 v[200:203], v[0:3], v[128:131], 0
	ds_read_b128 v[0:3], v33 offset:8192
	s_waitcnt lgkmcnt(7)
	v_mfma_f32_16x16x32_bf16 v[204:207], v[4:7], v[128:131], 0
	ds_read_b128 v[4:7], v33 offset:9216
	s_waitcnt lgkmcnt(7)
	v_mfma_f32_16x16x32_bf16 v[208:211], v[8:11], v[128:131], 0
	ds_read_b128 v[8:11], v33 offset:10240
	s_waitcnt lgkmcnt(7)
	v_mfma_f32_16x16x32_bf16 v[212:215], v[12:15], v[128:131], 0
	ds_read_b128 v[12:15], v33 offset:11264
	s_waitcnt lgkmcnt(7)
	v_mfma_f32_16x16x32_bf16 v[200:203], v[16:19], v[136:139], v[200:203]
	ds_read_b128 v[16:19], v33 offset:12288
	s_waitcnt lgkmcnt(7)
	v_mfma_f32_16x16x32_bf16 v[204:207], v[20:23], v[136:139], v[204:207]
	ds_read_b128 v[20:23], v33 offset:13312
	s_waitcnt lgkmcnt(7)
	v_mfma_f32_16x16x32_bf16 v[208:211], v[24:27], v[136:139], v[208:211]
	ds_read_b128 v[24:27], v33 offset:14336
	s_waitcnt lgkmcnt(7)
	v_mfma_f32_16x16x32_bf16 v[212:215], v[28:31], v[136:139], v[212:215]
	ds_read_b128 v[28:31], v33 offset:15360
	s_waitcnt lgkmcnt(7)
	v_mfma_f32_16x16x32_bf16 v[200:203], v[0:3], v[144:147], v[200:203]
	ds_read_b128 v[0:3], v33 offset:16384
	s_waitcnt lgkmcnt(7)
	v_mfma_f32_16x16x32_bf16 v[204:207], v[4:7], v[144:147], v[204:207]
	ds_read_b128 v[4:7], v33 offset:17408
	s_waitcnt lgkmcnt(7)
	v_mfma_f32_16x16x32_bf16 v[208:211], v[8:11], v[144:147], v[208:211]
	ds_read_b128 v[8:11], v33 offset:18432
	s_waitcnt lgkmcnt(7)
	v_mfma_f32_16x16x32_bf16 v[212:215], v[12:15], v[144:147], v[212:215]
	ds_read_b128 v[12:15], v33 offset:19456
	s_waitcnt lgkmcnt(7)
	v_mfma_f32_16x16x32_bf16 v[200:203], v[16:19], v[152:155], v[200:203]
	ds_read_b128 v[16:19], v33 offset:20480
	s_waitcnt lgkmcnt(7)
	v_mfma_f32_16x16x32_bf16 v[204:207], v[20:23], v[152:155], v[204:207]
	ds_read_b128 v[20:23], v33 offset:21504
	s_waitcnt lgkmcnt(7)
	v_mfma_f32_16x16x32_bf16 v[208:211], v[24:27], v[152:155], v[208:211]
	ds_read_b128 v[24:27], v33 offset:22528
	s_waitcnt lgkmcnt(7)
	v_mfma_f32_16x16x32_bf16 v[212:215], v[28:31], v[152:155], v[212:215]
	ds_read_b128 v[28:31], v33 offset:23552
	s_waitcnt lgkmcnt(7)
	v_mfma_f32_16x16x32_bf16 v[200:203], v[0:3], v[160:163], v[200:203]
	ds_read_b128 v[0:3], v33 offset:24576
	s_waitcnt lgkmcnt(7)
	v_mfma_f32_16x16x32_bf16 v[204:207], v[4:7], v[160:163], v[204:207]
	ds_read_b128 v[4:7], v33 offset:25600
	s_waitcnt lgkmcnt(7)
	v_mfma_f32_16x16x32_bf16 v[208:211], v[8:11], v[160:163], v[208:211]
	ds_read_b128 v[8:11], v33 offset:26624
	s_waitcnt lgkmcnt(7)
	v_mfma_f32_16x16x32_bf16 v[212:215], v[12:15], v[160:163], v[212:215]
	ds_read_b128 v[12:15], v33 offset:27648
	s_waitcnt lgkmcnt(7)
	v_mfma_f32_16x16x32_bf16 v[200:203], v[16:19], v[168:171], v[200:203]
	ds_read_b128 v[16:19], v33 offset:28672
	s_waitcnt lgkmcnt(7)
	v_mfma_f32_16x16x32_bf16 v[204:207], v[20:23], v[168:171], v[204:207]
	ds_read_b128 v[20:23], v33 offset:29696
	s_waitcnt lgkmcnt(7)
	v_mfma_f32_16x16x32_bf16 v[208:211], v[24:27], v[168:171], v[208:211]
	ds_read_b128 v[24:27], v33 offset:30720
	s_waitcnt lgkmcnt(7)
	v_mfma_f32_16x16x32_bf16 v[212:215], v[28:31], v[168:171], v[212:215]
	ds_read_b128 v[28:31], v33 offset:31744
	s_waitcnt lgkmcnt(7)
	v_mfma_f32_16x16x32_bf16 v[200:203], v[0:3], v[176:179], v[200:203]
	s_waitcnt lgkmcnt(6)
	v_mfma_f32_16x16x32_bf16 v[204:207], v[4:7], v[176:179], v[204:207]
	s_waitcnt lgkmcnt(5)
	v_mfma_f32_16x16x32_bf16 v[208:211], v[8:11], v[176:179], v[208:211]
	s_waitcnt lgkmcnt(4)
	v_mfma_f32_16x16x32_bf16 v[212:215], v[12:15], v[176:179], v[212:215]
	s_waitcnt lgkmcnt(3)
	v_mfma_f32_16x16x32_bf16 v[200:203], v[16:19], v[184:187], v[200:203]
	s_waitcnt lgkmcnt(2)
	v_mfma_f32_16x16x32_bf16 v[204:207], v[20:23], v[184:187], v[204:207]
	s_waitcnt lgkmcnt(1)
	v_mfma_f32_16x16x32_bf16 v[208:211], v[24:27], v[184:187], v[208:211]
	s_waitcnt lgkmcnt(0)
	v_mfma_f32_16x16x32_bf16 v[212:215], v[28:31], v[184:187], v[212:215]
	s_cmp_eq_u32 s0, 1
	s_cbranch_scc0 .Lmy_nat_p5z
	s_waitcnt vmcnt(15)
	s_branch .Lmy_nat_p5j

; #define PG8_STAGE(bufoff, gbase, voff) do { _Pragma("unroll") for (int _i = 0; _i < 2; ++_i) \
;         __builtin_amdgcn_global_load_lds((const unsigned*)((const char*)(gbase) + (voff)[_i]), (LAS unsigned*)(lds + (bufoff) + ldsw + _i * 8192), 16, 0, 0); } while (0)
; #define PG8_LDA(dst, b, h) do { _Pragma("unroll") for (int m = 0; m < 4; ++m) _Pragma("unroll") for (int k = 0; k < 2; ++k) dst[m][k] = *(const LAS bf16x8*)(lds + PG8_SA(b, h) + aoff + m * 2048 + k * 1024); } while (0)
; #define PG8_LDB(dst, b, h) do { _Pragma("unroll") for (int n = 0; n < 2; ++n) _Pragma("unroll") for (int k = 0; k < 2; ++k) dst[n][k] = *(const LAS bf16x8*)(lds + PG8_SB(b, h) + boff + n * 2048 + k * 1024); } while (0)
; #define PG8_MMA(ai, bj, At, Bt) do { __builtin_amdgcn_s_setprio(1); _Pragma("unroll") for (int m = 0; m < 4; ++m) _Pragma("unroll") for (int n = 0; n < 2; ++n) _Pragma("unroll") for (int k = 0; k < 2; ++k) \
;         acc[ai][bj][m][n] = __builtin_amdgcn_mfma_f32_16x16x32_bf16(Bt[n][k], At[m][k], acc[ai][bj][m][n], 0, 0, 0); __builtin_amdgcn_s_setprio(0); } while (0)
; #define PG8_WAIT_L(n) asm volatile("s_waitcnt lgkmcnt(" #n ")" ::: "memory")
; #define PG8_BAR __builtin_amdgcn_s_barrier()
; #define PG8_SCHED __builtin_amdgcn_sched_barrier(0)
; template <class Epi>
; __device__ __forceinline__ void gemm_phase(LAS unsigned char* lds, const Gemm g, const StaticOrder& S, const Epi& E) {
;     ...
;             PG8_LDB(B0, 0, 0); PG8_SCHED; PG8_LDA(At, 0, 0); PG8_STAGE(PG8_SA(1, 1), a1 + hstepA, voffA);
;             PG8_WAIT_L(8); PG8_BAR; PG8_WAIT_L(0); PG8_MMA(0, 0, At, B0); PG8_BAR; PG8_SCHED;
;             PG8_LDB(B1, 0, 1); PG8_STAGE(PG8_SB(0, 0), b2, voffB);
;             PG8_BAR; PG8_WAIT_L(0); PG8_MMA(0, 1, At, B1); PG8_BAR;
;             PG8_LDA(At, 0, 1); PG8_STAGE(PG8_SA(0, 0), a2, voffA);
;             PG8_BAR; PG8_WAIT_L(0); PG8_MMA(1, 0, At, B0); PG8_BAR; PG8_SCHED;
.LBB0_766:
	s_ashr_i32 s31, s30, 31
	s_lshl_b64 s[38:39], s[30:31], 17
	v_mov_b64_e32 v[0:1], 0x400
	s_add_u32 s38, s69, s38
	v_cmp_lt_i64_e32 vcc, s[26:27], v[0:1]
	s_addc_u32 s39, s70, s39
	s_and_b64 s[40:41], vcc, exec
	s_cselect_b32 s65, s39, s61
	s_cselect_b32 s64, s38, s60
	s_ashr_i32 s29, s28, 31
	s_lshl_b64 s[40:41], s[28:29], 16
	s_add_u32 s40, s71, s40
	s_addc_u32 s41, s72, s41
	s_add_u32 s90, s60, 0x10080
	ds_read_b128 v[0:3], v171
	ds_read_b128 v[4:7], v171 offset:1024
	ds_read_b128 v[8:11], v171 offset:2048
	ds_read_b128 v[12:15], v171 offset:3072
	s_addc_u32 s91, s61, 0
	s_add_u32 s60, s64, 0x10000
	s_addc_u32 s61, s65, 0
	s_and_b64 s[66:67], vcc, exec
	s_cselect_b32 s50, s40, s50
	s_cselect_b32 s51, s41, s51
	s_add_u32 s66, s50, 0x8000
	s_addc_u32 s67, s51, 0
	v_lshl_add_u64 v[48:49], s[90:91], 0, v[132:133]
	s_add_i32 m0, s74, 0xc000
	ds_read_b128 v[16:19], v172
	ds_read_b128 v[20:23], v172 offset:1024
	ds_read_b128 v[24:27], v172 offset:2048
	ds_read_b128 v[28:31], v172 offset:3072
	ds_read_b128 v[32:35], v172 offset:4096
	ds_read_b128 v[36:39], v172 offset:5120
	ds_read_b128 v[40:43], v172 offset:6144
	ds_read_b128 v[44:47], v172 offset:7168
	global_load_lds_dwordx4 v[48:49], off
	v_lshl_add_u64 v[48:49], s[90:91], 0, v[136:137]
	s_add_i32 m0, s74, 0xe000
	s_nop 0
	global_load_lds_dwordx4 v[48:49], off
	s_waitcnt lgkmcnt(8)
	s_barrier
	s_setprio 1
	s_waitcnt lgkmcnt(12)
	s_waitcnt lgkmcnt(7)
	v_mfma_f32_16x16x32_bf16 v[48:51], v[0:3], v[16:19], 0
	v_mfma_f32_16x16x32_bf16 v[52:55], v[8:11], v[16:19], 0
	s_waitcnt lgkmcnt(5)
	v_mfma_f32_16x16x32_bf16 v[56:59], v[0:3], v[24:27], 0
	v_mfma_f32_16x16x32_bf16 v[60:63], v[8:11], v[24:27], 0
	s_waitcnt lgkmcnt(3)
	v_mfma_f32_16x16x32_bf16 v[64:67], v[0:3], v[32:35], 0
	v_mfma_f32_16x16x32_bf16 v[68:71], v[8:11], v[32:35], 0
	s_waitcnt lgkmcnt(1)
	v_mfma_f32_16x16x32_bf16 v[72:75], v[0:3], v[40:43], 0
	v_mfma_f32_16x16x32_bf16 v[76:79], v[8:11], v[40:43], 0
	v_mfma_f32_16x16x32_bf16 v[48:51], v[4:7], v[20:23], v[48:51]
	v_mfma_f32_16x16x32_bf16 v[52:55], v[12:15], v[20:23], v[52:55]
	v_mfma_f32_16x16x32_bf16 v[56:59], v[4:7], v[28:31], v[56:59]
	v_mfma_f32_16x16x32_bf16 v[60:63], v[12:15], v[28:31], v[60:63]
	v_mfma_f32_16x16x32_bf16 v[64:67], v[4:7], v[36:39], v[64:67]
	v_mfma_f32_16x16x32_bf16 v[68:71], v[12:15], v[36:39], v[68:71]
	s_waitcnt lgkmcnt(0)
	v_mfma_f32_16x16x32_bf16 v[72:75], v[4:7], v[44:47], v[72:75]
	v_mfma_f32_16x16x32_bf16 v[76:79], v[12:15], v[44:47], v[76:79]
	s_setprio 0
	s_barrier
	s_add_i32 s3, s83, s73
	v_lshl_add_u64 v[186:187], s[50:51], 0, v[134:135]
	s_mov_b32 m0, s3
	ds_read_b128 v[80:83], v173
	ds_read_b128 v[84:87], v173 offset:1024
	ds_read_b128 v[88:91], v173 offset:2048
	ds_read_b128 v[92:95], v173 offset:3072
	global_load_lds_dwordx4 v[186:187], off
	v_lshl_add_u64 v[188:189], s[50:51], 0, v[138:139]
	s_add_i32 m0, s3, 0x2000
	s_nop 0
	global_load_lds_dwordx4 v[188:189], off
	s_barrier
	s_setprio 1
	s_waitcnt lgkmcnt(3)
	v_mfma_f32_16x16x32_bf16 v[96:99], v[80:83], v[16:19], 0
	s_waitcnt lgkmcnt(1)
	v_mfma_f32_16x16x32_bf16 v[16:19], v[88:91], v[16:19], 0
	v_mfma_f32_16x16x32_bf16 v[96:99], v[84:87], v[20:23], v[96:99]
	s_waitcnt lgkmcnt(0)
	v_mfma_f32_16x16x32_bf16 v[16:19], v[92:95], v[20:23], v[16:19]
	v_mfma_f32_16x16x32_bf16 v[20:23], v[80:83], v[24:27], 0
	v_mfma_f32_16x16x32_bf16 v[24:27], v[88:91], v[24:27], 0
	v_mfma_f32_16x16x32_bf16 v[20:23], v[84:87], v[28:31], v[20:23]
	v_mfma_f32_16x16x32_bf16 v[24:27], v[92:95], v[28:31], v[24:27]
	v_mfma_f32_16x16x32_bf16 v[28:31], v[80:83], v[32:35], 0
	v_mfma_f32_16x16x32_bf16 v[100:103], v[84:87], v[36:39], v[28:31]
	v_mfma_f32_16x16x32_bf16 v[28:31], v[88:91], v[32:35], 0
	v_mfma_f32_16x16x32_bf16 v[32:35], v[92:95], v[36:39], v[28:31]
	v_mfma_f32_16x16x32_bf16 v[28:31], v[80:83], v[40:43], 0
	v_mfma_f32_16x16x32_bf16 v[36:39], v[84:87], v[44:47], v[28:31]
	v_mfma_f32_16x16x32_bf16 v[28:31], v[88:91], v[40:43], 0
	v_mfma_f32_16x16x32_bf16 v[40:43], v[92:95], v[44:47], v[28:31]
	s_setprio 0
	s_mov_b32 m0, s74
	v_lshl_add_u64 v[140:141], s[64:65], 0, v[132:133]
	s_barrier
	s_nop 2
	ds_read_b128 v[28:31], v172 offset:16384
	ds_read_b128 v[44:47], v172 offset:17408
	ds_read_b128 v[104:107], v172 offset:18432
	ds_read_b128 v[108:111], v172 offset:19456
	ds_read_b128 v[112:115], v172 offset:20480
	ds_read_b128 v[116:119], v172 offset:21504
	ds_read_b128 v[120:123], v172 offset:22528
	ds_read_b128 v[124:127], v172 offset:23552
	global_load_lds_dwordx4 v[140:141], off
	v_lshl_add_u64 v[142:143], s[64:65], 0, v[136:137]
	s_mov_b32 m0, s75
	s_nop 0
	global_load_lds_dwordx4 v[142:143], off
	s_barrier
	s_setprio 1
	s_waitcnt lgkmcnt(7)
	v_mfma_f32_16x16x32_bf16 v[128:131], v[0:3], v[28:31], 0
	s_waitcnt lgkmcnt(5)
	v_mfma_f32_16x16x32_bf16 v[148:151], v[0:3], v[104:107], 0
	s_waitcnt lgkmcnt(3)
	v_mfma_f32_16x16x32_bf16 v[156:159], v[0:3], v[112:115], 0
	s_waitcnt lgkmcnt(1)
	v_mfma_f32_16x16x32_bf16 v[0:3], v[0:3], v[120:123], 0
	v_mfma_f32_16x16x32_bf16 v[128:131], v[4:7], v[44:47], v[128:131]
	v_mfma_f32_16x16x32_bf16 v[144:147], v[8:11], v[28:31], 0
	v_mfma_f32_16x16x32_bf16 v[148:151], v[4:7], v[108:111], v[148:151]
	v_mfma_f32_16x16x32_bf16 v[152:155], v[8:11], v[104:107], 0
	v_mfma_f32_16x16x32_bf16 v[156:159], v[4:7], v[116:119], v[156:159]
	s_waitcnt lgkmcnt(0)
	v_mfma_f32_16x16x32_bf16 v[0:3], v[4:7], v[124:127], v[0:3]
	v_mfma_f32_16x16x32_bf16 v[4:7], v[8:11], v[120:123], 0
	v_mfma_f32_16x16x32_bf16 v[144:147], v[12:15], v[44:47], v[144:147]
	v_mfma_f32_16x16x32_bf16 v[152:155], v[12:15], v[108:111], v[152:155]
	v_mfma_f32_16x16x32_bf16 v[160:163], v[8:11], v[112:115], 0
	v_mfma_f32_16x16x32_bf16 v[4:7], v[12:15], v[124:127], v[4:7]
	v_mfma_f32_16x16x32_bf16 v[160:163], v[12:15], v[116:119], v[160:163]
	s_setprio 0
	s_barrier
; #define PG8_STAGE(bufoff, gbase, voff) do { _Pragma("unroll") for (int _i = 0; _i < 2; ++_i) \
;         __builtin_amdgcn_global_load_lds((const unsigned*)((const char*)(gbase) + (voff)[_i]), (LAS unsigned*)(lds + (bufoff) + ldsw + _i * 8192), 16, 0, 0); } while (0)
; #define PG8_LDA(dst, b, h) do { _Pragma("unroll") for (int m = 0; m < 4; ++m) _Pragma("unroll") for (int k = 0; k < 2; ++k) dst[m][k] = *(const LAS bf16x8*)(lds + PG8_SA(b, h) + aoff + m * 2048 + k * 1024); } while (0)
; #define PG8_LDB(dst, b, h) do { _Pragma("unroll") for (int n = 0; n < 2; ++n) _Pragma("unroll") for (int k = 0; k < 2; ++k) dst[n][k] = *(const LAS bf16x8*)(lds + PG8_SB(b, h) + boff + n * 2048 + k * 1024); } while (0)
; #define PG8_MMA(ai, bj, At, Bt) do { __builtin_amdgcn_s_setprio(1); _Pragma("unroll") for (int m = 0; m < 4; ++m) _Pragma("unroll") for (int n = 0; n < 2; ++n) _Pragma("unroll") for (int k = 0; k < 2; ++k) \
;         acc[ai][bj][m][n] = __builtin_amdgcn_mfma_f32_16x16x32_bf16(Bt[n][k], At[m][k], acc[ai][bj][m][n], 0, 0, 0); __builtin_amdgcn_s_setprio(0); } while (0)
; #define PG8_WAIT_V(n) asm volatile("s_waitcnt vmcnt(" #n ")" ::: "memory")
; #define PG8_WAIT_L(n) asm volatile("s_waitcnt lgkmcnt(" #n ")" ::: "memory")
; #define PG8_BAR __builtin_amdgcn_s_barrier()
; #define PG8_SCHED __builtin_amdgcn_sched_barrier(0)
; template <class Epi>
; __device__ __forceinline__ void gemm_phase(LAS unsigned char* lds, const Gemm g, const StaticOrder& S, const Epi& E) {
;     ...
;             PG8_LDA(At, 0, 1); PG8_STAGE(PG8_SA(0, 0), a2, voffA);
;             PG8_BAR; PG8_WAIT_L(0); PG8_MMA(1, 0, At, B0); PG8_BAR; PG8_SCHED;
;             PG8_STAGE(PG8_SB(0, 1), b2 + hstepB, voffB);
;             PG8_WAIT_V(6); PG8_BAR; PG8_MMA(1, 1, At, B1); PG8_BAR;
;             PG8_LDB(B0, 1, 0); PG8_SCHED; PG8_LDA(At, 1, 0); PG8_STAGE(PG8_SA(0, 1), a2 + hstepA, voffA);
;             PG8_WAIT_L(8); PG8_BAR; PG8_WAIT_L(0); PG8_MMA(0, 0, At, B0); PG8_BAR; PG8_SCHED;
;             PG8_LDB(B1, 1, 1); PG8_STAGE(PG8_SB(1, 0), b3, voffB);
;             PG8_BAR; PG8_WAIT_L(0); PG8_MMA(0, 1, At, B1); PG8_BAR;
;             PG8_LDA(At, 1, 1); PG8_STAGE(PG8_SA(1, 0), a3, voffA);
;             PG8_BAR; PG8_WAIT_L(0); PG8_MMA(1, 0, At, B0); PG8_BAR; PG8_SCHED;
	s_add_i32 s3, s84, s73
	v_lshl_add_u64 v[8:9], s[66:67], 0, v[134:135]
	s_mov_b32 m0, s3
	s_nop 0
	global_load_lds_dwordx4 v[8:9], off
	v_lshl_add_u64 v[8:9], s[66:67], 0, v[138:139]
	s_add_i32 m0, s3, 0x2000
	s_nop 0
	global_load_lds_dwordx4 v[8:9], off
	s_waitcnt vmcnt(6)
	s_barrier
	s_setprio 1
	v_mfma_f32_16x16x32_bf16 v[12:15], v[88:91], v[28:31], 0
	v_mfma_f32_16x16x32_bf16 v[164:167], v[92:95], v[44:47], v[12:15]
	v_mfma_f32_16x16x32_bf16 v[12:15], v[80:83], v[104:107], 0
	v_mfma_f32_16x16x32_bf16 v[174:177], v[84:87], v[108:111], v[12:15]
	v_mfma_f32_16x16x32_bf16 v[12:15], v[88:91], v[104:107], 0
	v_mfma_f32_16x16x32_bf16 v[178:181], v[92:95], v[108:111], v[12:15]
	v_mfma_f32_16x16x32_bf16 v[12:15], v[80:83], v[112:115], 0
	v_mfma_f32_16x16x32_bf16 v[182:185], v[84:87], v[116:119], v[12:15]
	v_mfma_f32_16x16x32_bf16 v[12:15], v[88:91], v[112:115], 0
	v_mfma_f32_16x16x32_bf16 v[8:11], v[80:83], v[28:31], 0
	v_mfma_f32_16x16x32_bf16 v[190:193], v[92:95], v[116:119], v[12:15]
	v_mfma_f32_16x16x32_bf16 v[12:15], v[80:83], v[120:123], 0
	v_mfma_f32_16x16x32_bf16 v[8:11], v[84:87], v[44:47], v[8:11]
	v_mfma_f32_16x16x32_bf16 v[194:197], v[84:87], v[124:127], v[12:15]
	v_mfma_f32_16x16x32_bf16 v[12:15], v[88:91], v[120:123], 0
	v_mfma_f32_16x16x32_bf16 v[198:201], v[92:95], v[124:127], v[12:15]
	s_setprio 0
	s_add_i32 s3, 0, 0x18000
	s_nop 4
	v_add_u32_e32 v12, s3, v169
	s_barrier
	ds_read_b128 v[202:205], v12
	ds_read_b128 v[206:209], v12 offset:1024
	ds_read_b128 v[210:213], v12 offset:2048
	ds_read_b128 v[214:217], v12 offset:3072
	s_mov_b32 m0, s76
	v_lshl_add_u64 v[84:85], s[60:61], 0, v[132:133]
	ds_read_b128 v[12:15], v172 offset:32768
	ds_read_b128 v[28:31], v172 offset:33792
	ds_read_b128 v[44:47], v172 offset:34816
	ds_read_b128 v[80:83], v172 offset:35840
	ds_read_b128 v[104:107], v172 offset:36864
	ds_read_b128 v[112:115], v172 offset:37888
	ds_read_b128 v[218:221], v172 offset:38912
	ds_read_b128 v[222:225], v172 offset:39936
	global_load_lds_dwordx4 v[84:85], off
	v_lshl_add_u64 v[84:85], s[60:61], 0, v[136:137]
	s_mov_b32 m0, s77
	s_nop 0
	global_load_lds_dwordx4 v[84:85], off
	s_waitcnt lgkmcnt(8)
	s_barrier
	s_setprio 1
	s_waitcnt lgkmcnt(7)
	v_mfma_f32_16x16x32_bf16 v[48:51], v[202:205], v[12:15], v[48:51]
	s_waitcnt lgkmcnt(6)
	v_mfma_f32_16x16x32_bf16 v[120:123], v[206:209], v[28:31], v[48:51]
	v_mfma_f32_16x16x32_bf16 v[48:51], v[210:213], v[12:15], v[52:55]
	v_mfma_f32_16x16x32_bf16 v[92:95], v[214:217], v[28:31], v[48:51]
	s_waitcnt lgkmcnt(5)
	v_mfma_f32_16x16x32_bf16 v[48:51], v[202:205], v[44:47], v[56:59]
	s_waitcnt lgkmcnt(4)
	v_mfma_f32_16x16x32_bf16 v[124:127], v[206:209], v[80:83], v[48:51]
	v_mfma_f32_16x16x32_bf16 v[48:51], v[210:213], v[44:47], v[60:63]
	v_mfma_f32_16x16x32_bf16 v[88:91], v[214:217], v[80:83], v[48:51]
	s_waitcnt lgkmcnt(3)
	v_mfma_f32_16x16x32_bf16 v[48:51], v[202:205], v[104:107], v[64:67]
	s_waitcnt lgkmcnt(2)
	v_mfma_f32_16x16x32_bf16 v[116:119], v[206:209], v[112:115], v[48:51]
	v_mfma_f32_16x16x32_bf16 v[48:51], v[210:213], v[104:107], v[68:71]
	v_mfma_f32_16x16x32_bf16 v[84:87], v[214:217], v[112:115], v[48:51]
	s_waitcnt lgkmcnt(1)
	v_mfma_f32_16x16x32_bf16 v[48:51], v[202:205], v[218:221], v[72:75]
	s_waitcnt lgkmcnt(0)
	v_mfma_f32_16x16x32_bf16 v[108:111], v[206:209], v[222:225], v[48:51]
	v_mfma_f32_16x16x32_bf16 v[48:51], v[210:213], v[218:221], v[76:79]
	v_mfma_f32_16x16x32_bf16 v[76:79], v[214:217], v[222:225], v[48:51]
	s_setprio 0
	s_barrier
	s_add_i32 s29, 0, 0x1c000
	s_nop 3
	v_add_u32_e32 v48, s29, v169
	s_add_i32 s3, s3, s73
	ds_read_b128 v[226:229], v48
	ds_read_b128 v[230:233], v48 offset:1024
	ds_read_b128 v[234:237], v48 offset:2048
	ds_read_b128 v[238:241], v48 offset:3072
	v_lshl_add_u64 v[48:49], v[186:187], 0, s[16:17]
	s_mov_b32 m0, s3
	s_nop 0
	global_load_lds_dwordx4 v[48:49], off
	v_lshl_add_u64 v[48:49], v[188:189], 0, s[16:17]
	s_add_i32 m0, s3, 0x2000
	s_nop 0
	global_load_lds_dwordx4 v[48:49], off
	s_barrier
	s_setprio 1
	s_waitcnt lgkmcnt(3)
	v_mfma_f32_16x16x32_bf16 v[48:51], v[226:229], v[12:15], v[96:99]
	s_waitcnt lgkmcnt(1)
	v_mfma_f32_16x16x32_bf16 v[12:15], v[234:237], v[12:15], v[16:19]
	v_mfma_f32_16x16x32_bf16 v[60:63], v[230:233], v[28:31], v[48:51]
	s_waitcnt lgkmcnt(0)
	v_mfma_f32_16x16x32_bf16 v[28:31], v[238:241], v[28:31], v[12:15]
	v_mfma_f32_16x16x32_bf16 v[12:15], v[226:229], v[44:47], v[20:23]
	v_mfma_f32_16x16x32_bf16 v[56:59], v[230:233], v[80:83], v[12:15]
	v_mfma_f32_16x16x32_bf16 v[12:15], v[234:237], v[44:47], v[24:27]
	v_mfma_f32_16x16x32_bf16 v[24:27], v[238:241], v[80:83], v[12:15]
	v_mfma_f32_16x16x32_bf16 v[12:15], v[226:229], v[104:107], v[100:103]
	v_mfma_f32_16x16x32_bf16 v[52:55], v[230:233], v[112:115], v[12:15]
	v_mfma_f32_16x16x32_bf16 v[12:15], v[234:237], v[104:107], v[32:35]
	v_mfma_f32_16x16x32_bf16 v[20:23], v[238:241], v[112:115], v[12:15]
	v_mfma_f32_16x16x32_bf16 v[12:15], v[226:229], v[218:221], v[36:39]
	v_mfma_f32_16x16x32_bf16 v[44:47], v[230:233], v[222:225], v[12:15]
	v_mfma_f32_16x16x32_bf16 v[12:15], v[234:237], v[218:221], v[40:43]
	v_mfma_f32_16x16x32_bf16 v[12:15], v[238:241], v[222:225], v[12:15]
	s_setprio 0
	s_mov_b32 m0, s78
	v_lshl_add_u64 v[40:41], v[140:141], 0, s[16:17]
	s_barrier
	ds_read_b128 v[16:19], v172 offset:49152
	ds_read_b128 v[32:35], v172 offset:50176
	ds_read_b128 v[36:39], v172 offset:51200
	ds_read_b128 v[218:221], v172 offset:52224
	ds_read_b128 v[222:225], v172 offset:53248
	ds_read_b128 v[242:245], v172 offset:54272
	ds_read_b128 v[246:249], v172 offset:55296
	ds_read_b128 v[250:253], v172 offset:56320
	global_load_lds_dwordx4 v[40:41], off
	v_lshl_add_u64 v[40:41], v[142:143], 0, s[16:17]
	s_mov_b32 m0, s79
	s_nop 0
	global_load_lds_dwordx4 v[40:41], off
	s_barrier
; __device__ __forceinline__ float sigmoidf_(float x) { return __builtin_amdgcn_rcpf(1.0f + __expf(-x)); }
; #define PG8_STAGE(bufoff, gbase, voff) do { _Pragma("unroll") for (int _i = 0; _i < 2; ++_i) \
;         __builtin_amdgcn_global_load_lds((const unsigned*)((const char*)(gbase) + (voff)[_i]), (LAS unsigned*)(lds + (bufoff) + ldsw + _i * 8192), 16, 0, 0); } while (0)
; #define PG8_LDA(dst, b, h) do { _Pragma("unroll") for (int m = 0; m < 4; ++m) _Pragma("unroll") for (int k = 0; k < 2; ++k) dst[m][k] = *(const LAS bf16x8*)(lds + PG8_SA(b, h) + aoff + m * 2048 + k * 1024); } while (0)
; #define PG8_WAIT_V(n) asm volatile("s_waitcnt vmcnt(" #n ")" ::: "memory")
; #define PG8_WAIT_L(n) asm volatile("s_waitcnt lgkmcnt(" #n ")" ::: "memory")
; #define PG8_BAR __builtin_amdgcn_s_barrier()
; template <class Epi>
; __device__ __forceinline__ void gemm_phase(LAS unsigned char* lds, const Gemm g, const StaticOrder& S, const Epi& E) {
;     ...
;             PG8_WAIT_V(6); PG8_BAR; PG8_MMA(1, 1, At, B1); PG8_BAR;
;             PG8_LDB(B0, 1, 0); PG8_SCHED; PG8_LDA(At, 1, 0); PG8_STAGE(PG8_SA(0, 1), a2 + hstepA, voffA);
;             PG8_WAIT_L(8); PG8_BAR; PG8_WAIT_L(0); PG8_MMA(0, 0, At, B0); PG8_BAR; PG8_SCHED;
;             PG8_LDB(B1, 1, 1); PG8_STAGE(PG8_SB(1, 0), b3, voffB);
;             PG8_BAR; PG8_WAIT_L(0); PG8_MMA(0, 1, At, B1); PG8_BAR;
;             PG8_LDA(At, 1, 1); PG8_STAGE(PG8_SA(1, 0), a3, voffA);
;             PG8_BAR; PG8_WAIT_L(0); PG8_MMA(1, 0, At, B0); PG8_BAR; PG8_SCHED;
;             PG8_STAGE(PG8_SB(1, 1), b3 + hstepB, voffB);
;             PG8_WAIT_V(6); PG8_BAR; PG8_MMA(1, 1, At, B1); PG8_BAR;
;     __device__ __forceinline__ void operator()(const AccT& acc, const Unit& u, int wr, int wc, int fr, int fq) const {
;     ...
;             for (int bj = 0; bj < 2; ++bj)
; #pragma unroll
;                 for (int n = 0; n < 2; ++n) { const int col = col0 - 1024 + bj * 128 + n * 16; const f32x4 av0 = *(const f32x4*)(a0 + col);
; #pragma unroll
;                     for (int ai = 0; ai < 2; ++ai)
; #pragma unroll
;                         for (int m = 0; m < 4; ++m) { const int row = row0 + ai * 128 + m * 16; f32x4 o;
; #pragma unroll
;                             for (int j = 0; j < 4; ++j) o[j] = sigmoidf_(av0[j] + acc[ai][bj][m][n][j]);
;                             *(f32x4*)(IC + (size_t)row * RW + col) = o; asm volatile("" ::: "memory"); } }
	s_waitcnt lgkmcnt(0)
	s_setprio 1
	s_waitcnt lgkmcnt(0)
	v_mfma_f32_16x16x32_bf16 v[40:43], v[202:205], v[16:19], v[128:131]
	s_add_u32 s50, s50, 0x8080
	s_addc_u32 s51, s51, 0
	v_mfma_f32_16x16x32_bf16 v[112:115], v[206:209], v[32:35], v[40:43]
	v_mfma_f32_16x16x32_bf16 v[40:43], v[210:213], v[16:19], v[144:147]
	v_mfma_f32_16x16x32_bf16 v[80:83], v[214:217], v[32:35], v[40:43]
	v_mfma_f32_16x16x32_bf16 v[40:43], v[202:205], v[36:39], v[148:151]
	v_mfma_f32_16x16x32_bf16 v[104:107], v[206:209], v[218:221], v[40:43]
	v_mfma_f32_16x16x32_bf16 v[40:43], v[210:213], v[36:39], v[152:155]
	v_mfma_f32_16x16x32_bf16 v[72:75], v[214:217], v[218:221], v[40:43]
	v_mfma_f32_16x16x32_bf16 v[40:43], v[202:205], v[222:225], v[156:159]
	v_mfma_f32_16x16x32_bf16 v[0:3], v[202:205], v[246:249], v[0:3]
	v_mfma_f32_16x16x32_bf16 v[100:103], v[206:209], v[242:245], v[40:43]
	v_mfma_f32_16x16x32_bf16 v[40:43], v[210:213], v[222:225], v[160:163]
	v_mfma_f32_16x16x32_bf16 v[96:99], v[206:209], v[250:253], v[0:3]
	v_mfma_f32_16x16x32_bf16 v[0:3], v[210:213], v[246:249], v[4:7]
	v_mfma_f32_16x16x32_bf16 v[68:71], v[214:217], v[242:245], v[40:43]
	v_mfma_f32_16x16x32_bf16 v[64:67], v[214:217], v[250:253], v[0:3]
	s_setprio 0
	s_barrier
	s_add_i32 s3, s29, s73
	s_nop 2
	v_lshl_add_u64 v[0:1], s[50:51], 0, v[134:135]
	s_mov_b32 m0, s3
	s_nop 0
	global_load_lds_dwordx4 v[0:1], off
	v_lshl_add_u64 v[0:1], s[50:51], 0, v[138:139]
	s_add_i32 m0, s3, 0x2000
	s_nop 0
	global_load_lds_dwordx4 v[0:1], off
	s_waitcnt vmcnt(6)
	s_barrier
	s_setprio 1
	v_mfma_f32_16x16x32_bf16 v[0:3], v[226:229], v[16:19], v[8:11]
	v_mfma_f32_16x16x32_bf16 v[48:51], v[230:233], v[32:35], v[0:3]
	v_mfma_f32_16x16x32_bf16 v[0:3], v[234:237], v[16:19], v[164:167]
	v_mfma_f32_16x16x32_bf16 v[16:19], v[238:241], v[32:35], v[0:3]
	v_mfma_f32_16x16x32_bf16 v[0:3], v[226:229], v[36:39], v[174:177]
	v_mfma_f32_16x16x32_bf16 v[40:43], v[230:233], v[218:221], v[0:3]
	v_mfma_f32_16x16x32_bf16 v[0:3], v[234:237], v[36:39], v[178:181]
	v_mfma_f32_16x16x32_bf16 v[8:11], v[238:241], v[218:221], v[0:3]
	v_mfma_f32_16x16x32_bf16 v[0:3], v[226:229], v[222:225], v[182:185]
	v_mfma_f32_16x16x32_bf16 v[36:39], v[230:233], v[242:245], v[0:3]
	v_mfma_f32_16x16x32_bf16 v[0:3], v[234:237], v[222:225], v[190:193]
	v_mfma_f32_16x16x32_bf16 v[4:7], v[238:241], v[242:245], v[0:3]
	v_mfma_f32_16x16x32_bf16 v[0:3], v[226:229], v[246:249], v[194:197]
	v_mfma_f32_16x16x32_bf16 v[32:35], v[230:233], v[250:253], v[0:3]
	v_mfma_f32_16x16x32_bf16 v[0:3], v[234:237], v[246:249], v[198:201]
	v_mfma_f32_16x16x32_bf16 v[0:3], v[238:241], v[250:253], v[0:3]
	s_setprio 0
	v_lshl_add_u32 v152, s44, 8, v168
	v_lshl_or_b32 v144, s89, 8, v170
	v_or_b32_e32 v150, 16, v152
	v_or_b32_e32 v148, 32, v152
	v_or_b32_e32 v146, 48, v152
	s_mov_b64 s[44:45], -1
	s_cmp_lt_i32 s89, 4
	v_ashrrev_i32_e32 v145, 31, v144
	v_ashrrev_i32_e32 v153, 31, v152
	v_ashrrev_i32_e32 v151, 31, v150
	v_ashrrev_i32_e32 v149, 31, v148
	v_ashrrev_i32_e32 v147, 31, v146
	s_barrier
	s_cbranch_scc1 .LBB0_768
	v_lshlrev_b64 v[140:141], 2, v[144:145]
	v_lshl_add_u64 v[156:157], s[36:37], 0, v[140:141]
	global_load_dwordx4 v[128:131], v[156:157], off
	v_lshlrev_b64 v[142:143], 12, v[152:153]
	v_lshlrev_b64 v[154:155], 12, v[150:151]
	v_lshlrev_b64 v[158:159], 12, v[148:149]
	v_lshl_add_u64 v[142:143], s[8:9], 0, v[142:143]
	v_lshl_add_u64 v[154:155], s[8:9], 0, v[154:155]
	v_lshl_add_u64 v[162:163], s[8:9], 0, v[158:159]
	v_lshl_add_u64 v[160:161], v[142:143], 0, v[140:141]
	v_lshl_add_u64 v[158:159], v[154:155], 0, v[140:141]
	v_lshl_add_u64 v[154:155], v[162:163], 0, v[140:141]
	s_mov_b64 s[44:45], 0
	s_waitcnt vmcnt(0)
	v_add_f32_e32 v142, v120, v128
	v_add_f32_e32 v143, v121, v129
	v_add_f32_e32 v162, v122, v130
	v_add_f32_e32 v163, v123, v131
	v_add_f32_e32 v164, v124, v128
	v_add_f32_e32 v165, v125, v129
	v_mul_f32_e32 v142, 0xbfb8aa3b, v142
	v_mul_f32_e32 v143, 0xbfb8aa3b, v143
	v_mul_f32_e32 v162, 0xbfb8aa3b, v162
	v_mul_f32_e32 v163, 0xbfb8aa3b, v163
	v_mul_f32_e32 v164, 0xbfb8aa3b, v164
	v_mul_f32_e32 v165, 0xbfb8aa3b, v165
	v_exp_f32_e32 v142, v142
	v_exp_f32_e32 v143, v143
	v_exp_f32_e32 v162, v162
	v_exp_f32_e32 v163, v163
	v_exp_f32_e32 v164, v164
	v_exp_f32_e32 v165, v165
	v_add_f32_e32 v142, 1.0, v142
	v_add_f32_e32 v143, 1.0, v143
	v_add_f32_e32 v182, 1.0, v162
	v_add_f32_e32 v183, 1.0, v163
	v_add_f32_e32 v166, v126, v130
	v_add_f32_e32 v167, v127, v131
	v_add_f32_e32 v184, 1.0, v164
	v_add_f32_e32 v185, 1.0, v165
	v_rcp_f32_e32 v162, v142
	v_rcp_f32_e32 v163, v143
	v_rcp_f32_e32 v164, v182
	v_rcp_f32_e32 v165, v183
	v_add_f32_e32 v174, v116, v128
	v_add_f32_e32 v175, v117, v129
	v_add_f32_e32 v176, v118, v130
	v_add_f32_e32 v177, v119, v131
	v_mul_f32_e32 v166, 0xbfb8aa3b, v166
	v_mul_f32_e32 v167, 0xbfb8aa3b, v167
	v_mul_f32_e32 v174, 0xbfb8aa3b, v174
	v_mul_f32_e32 v175, 0xbfb8aa3b, v175
	v_mul_f32_e32 v176, 0xbfb8aa3b, v176
	v_mul_f32_e32 v177, 0xbfb8aa3b, v177
	v_exp_f32_e32 v166, v166
	v_exp_f32_e32 v167, v167
	v_lshlrev_b64 v[142:143], 12, v[146:147]
	v_exp_f32_e32 v174, v174
	v_exp_f32_e32 v175, v175
	v_exp_f32_e32 v176, v176
	v_exp_f32_e32 v177, v177
	v_lshl_add_u64 v[142:143], s[8:9], 0, v[142:143]
	global_store_dwordx4 v[160:161], v[162:165], off offset:-4096
	v_add_f32_e32 v166, 1.0, v166
	v_add_f32_e32 v167, 1.0, v167
	v_lshl_add_u64 v[162:163], v[142:143], 0, v[140:141]
	v_add_f32_e32 v140, v112, v128
	v_mul_f32_e32 v140, 0xbfb8aa3b, v140
	v_add_f32_e32 v141, v113, v129
	v_exp_f32_e32 v140, v140
	v_mul_f32_e32 v141, 0xbfb8aa3b, v141
	v_add_f32_e32 v186, 1.0, v174
	v_add_f32_e32 v187, 1.0, v175
	v_add_f32_e32 v188, 1.0, v176
	v_add_f32_e32 v189, 1.0, v177
; __device__ __forceinline__ float sigmoidf_(float x) { return __builtin_amdgcn_rcpf(1.0f + __expf(-x)); }
;     __device__ __forceinline__ void operator()(const AccT& acc, const Unit& u, int wr, int wc, int fr, int fq) const {
;     ...
;             for (int bj = 0; bj < 2; ++bj)
; #pragma unroll
;                 for (int n = 0; n < 2; ++n) { const int col = col0 - 1024 + bj * 128 + n * 16; const f32x4 av0 = *(const f32x4*)(a0 + col);
; #pragma unroll
;                     for (int ai = 0; ai < 2; ++ai)
; #pragma unroll
;                         for (int m = 0; m < 4; ++m) { const int row = row0 + ai * 128 + m * 16; f32x4 o;
; #pragma unroll
;                             for (int j = 0; j < 4; ++j) o[j] = sigmoidf_(av0[j] + acc[ai][bj][m][n][j]);
;                             *(f32x4*)(IC + (size_t)row * RW + col) = o; asm volatile("" ::: "memory"); } }
	v_rcp_f32_e32 v174, v184
	v_rcp_f32_e32 v175, v185
	v_rcp_f32_e32 v176, v166
	v_rcp_f32_e32 v177, v167
	v_exp_f32_e32 v141, v141
	v_add_f32_e32 v140, 1.0, v140
	global_store_dwordx4 v[158:159], v[174:177], off offset:-4096
	v_add_f32_e32 v142, v115, v131
	v_mul_f32_e32 v142, 0xbfb8aa3b, v142
	v_rcp_f32_e32 v174, v140
	v_add_f32_e32 v140, 1.0, v141
	v_add_f32_e32 v141, v114, v130
	v_mul_f32_e32 v141, 0xbfb8aa3b, v141
	v_exp_f32_e32 v141, v141
	v_exp_f32_e32 v142, v142
	v_add_f32_e32 v178, v108, v128
	v_add_f32_e32 v179, v109, v129
	v_add_f32_e32 v180, v110, v130
	v_add_f32_e32 v181, v111, v131
	v_mul_f32_e32 v178, 0xbfb8aa3b, v178
	v_mul_f32_e32 v179, 0xbfb8aa3b, v179
	v_mul_f32_e32 v180, 0xbfb8aa3b, v180
	v_mul_f32_e32 v181, 0xbfb8aa3b, v181
	v_rcp_f32_e32 v175, v140
	v_add_f32_e32 v140, 1.0, v141
	v_exp_f32_e32 v178, v178
	v_exp_f32_e32 v179, v179
	v_exp_f32_e32 v180, v180
	v_exp_f32_e32 v181, v181
	v_rcp_f32_e32 v176, v140
	v_add_f32_e32 v140, 1.0, v142
	v_rcp_f32_e32 v177, v140
	v_add_f32_e32 v140, v104, v128
	v_mul_f32_e32 v140, 0xbfb8aa3b, v140
	v_add_f32_e32 v141, v105, v129
	v_exp_f32_e32 v140, v140
	v_mul_f32_e32 v141, 0xbfb8aa3b, v141
	v_add_f32_e32 v190, 1.0, v178
	v_add_f32_e32 v191, 1.0, v179
	v_add_f32_e32 v192, 1.0, v180
	v_add_f32_e32 v193, 1.0, v181
	v_rcp_f32_e32 v178, v186
	v_rcp_f32_e32 v179, v187
	v_rcp_f32_e32 v180, v188
	v_rcp_f32_e32 v181, v189
	v_exp_f32_e32 v141, v141
	v_add_f32_e32 v140, 1.0, v140
	global_store_dwordx4 v[154:155], v[178:181], off offset:-4096
	v_add_f32_e32 v142, v107, v131
	v_mul_f32_e32 v142, 0xbfb8aa3b, v142
	v_rcp_f32_e32 v178, v140
	v_add_f32_e32 v140, 1.0, v141
	v_add_f32_e32 v141, v106, v130
	v_mul_f32_e32 v141, 0xbfb8aa3b, v141
	v_exp_f32_e32 v141, v141
	v_exp_f32_e32 v142, v142
	v_rcp_f32_e32 v179, v140
	v_rcp_f32_e32 v182, v190
	v_add_f32_e32 v140, 1.0, v141
	v_rcp_f32_e32 v180, v140
	v_add_f32_e32 v140, 1.0, v142
	v_rcp_f32_e32 v181, v140
	v_add_f32_e32 v140, v100, v128
	v_mul_f32_e32 v140, 0xbfb8aa3b, v140
	v_add_f32_e32 v141, v101, v129
	v_rcp_f32_e32 v183, v191
	v_rcp_f32_e32 v184, v192
	v_rcp_f32_e32 v185, v193
	v_exp_f32_e32 v140, v140
	v_mul_f32_e32 v141, 0xbfb8aa3b, v141
	v_exp_f32_e32 v141, v141
	global_store_dwordx4 v[162:163], v[182:185], off offset:-4096
	v_lshl_add_u64 v[166:167], v[160:161], 0, s[18:19]
	v_add_f32_e32 v140, 1.0, v140
	global_store_dwordx4 v[166:167], v[174:177], off offset:-4096
	v_add_f32_e32 v142, v103, v131
	v_mul_f32_e32 v142, 0xbfb8aa3b, v142
	v_rcp_f32_e32 v174, v140
	v_add_f32_e32 v140, 1.0, v141
	v_add_f32_e32 v141, v102, v130
	v_mul_f32_e32 v141, 0xbfb8aa3b, v141
	v_exp_f32_e32 v141, v141
	v_exp_f32_e32 v142, v142
	v_rcp_f32_e32 v175, v140
	v_add_f32_e32 v128, v96, v128
	v_add_f32_e32 v140, 1.0, v141
	v_rcp_f32_e32 v176, v140
	v_add_f32_e32 v140, 1.0, v142
	v_mul_f32_e32 v128, 0xbfb8aa3b, v128
	v_add_f32_e32 v130, v98, v130
	v_rcp_f32_e32 v177, v140
	v_exp_f32_e32 v140, v128
	v_add_f32_e32 v128, v97, v129
	v_mul_f32_e32 v130, 0xbfb8aa3b, v130
	v_add_f32_e32 v131, v99, v131
	v_mul_f32_e32 v128, 0xbfb8aa3b, v128
	v_exp_f32_e32 v130, v130
	v_mul_f32_e32 v131, 0xbfb8aa3b, v131
	v_exp_f32_e32 v141, v128
	v_exp_f32_e32 v131, v131
	v_lshl_add_u64 v[164:165], v[160:161], 0, s[20:21]
	v_add_f32_e32 v140, 1.0, v140
	v_add_f32_e32 v130, 1.0, v130
	global_store_dwordx4 v[164:165], v[178:181], off offset:-4096
	v_lshl_add_u64 v[128:129], v[160:161], 0, s[22:23]
	global_store_dwordx4 v[128:129], v[174:177], off offset:-4096
	v_rcp_f32_e32 v178, v140
	v_add_f32_e32 v140, 1.0, v141
	v_rcp_f32_e32 v180, v130
	v_add_f32_e32 v130, 1.0, v131
	v_rcp_f32_e32 v179, v140
	v_rcp_f32_e32 v181, v130
	v_lshl_add_u64 v[130:131], v[160:161], 0, s[24:25]
	global_store_dwordx4 v[130:131], v[178:181], off offset:-4096
	global_load_dwordx4 v[174:177], v[156:157], off offset:64
	s_waitcnt vmcnt(0)
	v_add_f32_e32 v140, v92, v174
	v_mul_f32_e32 v140, 0xbfb8aa3b, v140
	v_add_f32_e32 v141, v93, v175
	v_exp_f32_e32 v140, v140
	v_mul_f32_e32 v141, 0xbfb8aa3b, v141
	v_exp_f32_e32 v141, v141
	v_add_f32_e32 v142, v95, v177
	v_add_f32_e32 v140, 1.0, v140
	v_rcp_f32_e32 v178, v140
	v_add_f32_e32 v140, 1.0, v141
	v_add_f32_e32 v141, v94, v176
	v_mul_f32_e32 v141, 0xbfb8aa3b, v141
	v_exp_f32_e32 v141, v141
	v_mul_f32_e32 v142, 0xbfb8aa3b, v142
	v_exp_f32_e32 v142, v142
	v_rcp_f32_e32 v179, v140
	v_add_f32_e32 v140, 1.0, v141
	v_add_f32_e32 v141, v88, v174
	v_rcp_f32_e32 v180, v140
	v_add_f32_e32 v140, 1.0, v142
	v_mul_f32_e32 v141, 0xbfb8aa3b, v141
	v_add_f32_e32 v142, v89, v175
	v_exp_f32_e32 v141, v141
	v_mul_f32_e32 v142, 0xbfb8aa3b, v142
	v_exp_f32_e32 v142, v142
	v_rcp_f32_e32 v181, v140
	v_add_f32_e32 v140, 1.0, v141
	v_add_f32_e32 v141, v90, v176
	v_rcp_f32_e32 v182, v140
	v_add_f32_e32 v140, 1.0, v142
	v_mul_f32_e32 v141, 0xbfb8aa3b, v141
	v_add_f32_e32 v142, v91, v177
	v_exp_f32_e32 v141, v141
	v_mul_f32_e32 v142, 0xbfb8aa3b, v142
	v_exp_f32_e32 v142, v142
	v_rcp_f32_e32 v183, v140
	v_add_f32_e32 v140, 1.0, v141
	v_rcp_f32_e32 v184, v140
	v_add_f32_e32 v140, 1.0, v142
	v_rcp_f32_e32 v185, v140
	v_add_f32_e32 v140, v84, v174
	v_mul_f32_e32 v140, 0xbfb8aa3b, v140
	v_add_f32_e32 v141, v85, v175
	v_exp_f32_e32 v140, v140
	v_mul_f32_e32 v141, 0xbfb8aa3b, v141
	v_exp_f32_e32 v141, v141
	global_store_dwordx4 v[160:161], v[178:181], off offset:-4032
	v_add_f32_e32 v140, 1.0, v140
	v_add_f32_e32 v142, v87, v177
	v_rcp_f32_e32 v178, v140
	v_add_f32_e32 v140, 1.0, v141
	v_add_f32_e32 v141, v86, v176
	v_mul_f32_e32 v141, 0xbfb8aa3b, v141
	v_exp_f32_e32 v141, v141
	v_mul_f32_e32 v142, 0xbfb8aa3b, v142
	v_exp_f32_e32 v142, v142
	v_rcp_f32_e32 v179, v140
	v_add_f32_e32 v140, 1.0, v141
; __device__ __forceinline__ float sigmoidf_(float x) { return __builtin_amdgcn_rcpf(1.0f + __expf(-x)); }
;     __device__ __forceinline__ void operator()(const AccT& acc, const Unit& u, int wr, int wc, int fr, int fq) const {
;     ...
;             for (int bj = 0; bj < 2; ++bj)
; #pragma unroll
;                 for (int n = 0; n < 2; ++n) { const int col = col0 - 1024 + bj * 128 + n * 16; const f32x4 av0 = *(const f32x4*)(a0 + col);
; #pragma unroll
;                     for (int ai = 0; ai < 2; ++ai)
; #pragma unroll
;                         for (int m = 0; m < 4; ++m) { const int row = row0 + ai * 128 + m * 16; f32x4 o;
; #pragma unroll
;                             for (int j = 0; j < 4; ++j) o[j] = sigmoidf_(av0[j] + acc[ai][bj][m][n][j]);
;                             *(f32x4*)(IC + (size_t)row * RW + col) = o; asm volatile("" ::: "memory"); } }
	v_rcp_f32_e32 v180, v140
	v_add_f32_e32 v140, 1.0, v142
	v_rcp_f32_e32 v181, v140
	v_add_f32_e32 v140, v76, v174
	v_mul_f32_e32 v140, 0xbfb8aa3b, v140
	v_add_f32_e32 v141, v77, v175
	v_exp_f32_e32 v140, v140
	v_mul_f32_e32 v141, 0xbfb8aa3b, v141
	v_exp_f32_e32 v141, v141
	global_store_dwordx4 v[158:159], v[182:185], off offset:-4032
	v_add_f32_e32 v140, 1.0, v140
	global_store_dwordx4 v[154:155], v[178:181], off offset:-4032
	v_add_f32_e32 v142, v79, v177
	v_mul_f32_e32 v142, 0xbfb8aa3b, v142
	v_rcp_f32_e32 v178, v140
	v_add_f32_e32 v140, 1.0, v141
	v_add_f32_e32 v141, v78, v176
	v_mul_f32_e32 v141, 0xbfb8aa3b, v141
	v_exp_f32_e32 v141, v141
	v_exp_f32_e32 v142, v142
	v_rcp_f32_e32 v179, v140
	v_add_f32_e32 v140, 1.0, v141
	v_add_f32_e32 v141, v80, v174
	v_rcp_f32_e32 v180, v140
	v_add_f32_e32 v140, 1.0, v142
	v_mul_f32_e32 v141, 0xbfb8aa3b, v141
	v_add_f32_e32 v142, v81, v175
	v_exp_f32_e32 v141, v141
	v_mul_f32_e32 v142, 0xbfb8aa3b, v142
	v_exp_f32_e32 v142, v142
	v_rcp_f32_e32 v181, v140
	v_add_f32_e32 v140, 1.0, v141
	v_add_f32_e32 v141, v82, v176
	v_rcp_f32_e32 v182, v140
	v_add_f32_e32 v140, 1.0, v142
	v_mul_f32_e32 v141, 0xbfb8aa3b, v141
	v_add_f32_e32 v142, v83, v177
	v_exp_f32_e32 v141, v141
	v_mul_f32_e32 v142, 0xbfb8aa3b, v142
	v_exp_f32_e32 v142, v142
	v_rcp_f32_e32 v183, v140
	v_add_f32_e32 v140, 1.0, v141
	v_rcp_f32_e32 v184, v140
	v_add_f32_e32 v140, 1.0, v142
	v_rcp_f32_e32 v185, v140
	v_add_f32_e32 v140, v72, v174
	v_mul_f32_e32 v140, 0xbfb8aa3b, v140
	v_add_f32_e32 v141, v73, v175
	v_exp_f32_e32 v140, v140
	v_mul_f32_e32 v141, 0xbfb8aa3b, v141
	v_exp_f32_e32 v141, v141
	global_store_dwordx4 v[162:163], v[178:181], off offset:-4032
	v_add_f32_e32 v140, 1.0, v140
	v_add_f32_e32 v142, v75, v177
	v_rcp_f32_e32 v178, v140
	v_add_f32_e32 v140, 1.0, v141
	v_add_f32_e32 v141, v74, v176
	v_mul_f32_e32 v141, 0xbfb8aa3b, v141
	v_exp_f32_e32 v141, v141
	v_mul_f32_e32 v142, 0xbfb8aa3b, v142
	v_exp_f32_e32 v142, v142
	v_rcp_f32_e32 v179, v140
	v_add_f32_e32 v140, 1.0, v141
	v_rcp_f32_e32 v180, v140
	v_add_f32_e32 v140, 1.0, v142
	v_rcp_f32_e32 v181, v140
	v_add_f32_e32 v140, v68, v174
	v_mul_f32_e32 v140, 0xbfb8aa3b, v140
	v_add_f32_e32 v141, v69, v175
	v_exp_f32_e32 v140, v140
	v_mul_f32_e32 v141, 0xbfb8aa3b, v141
	v_exp_f32_e32 v141, v141
	global_store_dwordx4 v[166:167], v[182:185], off offset:-4032
	v_add_f32_e32 v140, 1.0, v140
	global_store_dwordx4 v[164:165], v[178:181], off offset:-4032
	v_add_f32_e32 v142, v71, v177
	v_mul_f32_e32 v142, 0xbfb8aa3b, v142
	v_rcp_f32_e32 v178, v140
	v_add_f32_e32 v140, 1.0, v141
	v_add_f32_e32 v141, v70, v176
	v_mul_f32_e32 v141, 0xbfb8aa3b, v141
	v_exp_f32_e32 v141, v141
	v_exp_f32_e32 v142, v142
	v_rcp_f32_e32 v179, v140
	v_add_f32_e32 v140, 1.0, v141
	v_add_f32_e32 v141, v64, v174
	v_rcp_f32_e32 v180, v140
	v_add_f32_e32 v140, 1.0, v142
	v_mul_f32_e32 v141, 0xbfb8aa3b, v141
	v_add_f32_e32 v142, v65, v175
	v_exp_f32_e32 v141, v141
	v_mul_f32_e32 v142, 0xbfb8aa3b, v142
	v_exp_f32_e32 v142, v142
	v_rcp_f32_e32 v181, v140
	v_add_f32_e32 v140, 1.0, v141
	v_add_f32_e32 v141, v66, v176
	v_rcp_f32_e32 v174, v140
	v_add_f32_e32 v140, 1.0, v142
	v_mul_f32_e32 v141, 0xbfb8aa3b, v141
	v_add_f32_e32 v142, v67, v177
	v_exp_f32_e32 v141, v141
	v_mul_f32_e32 v142, 0xbfb8aa3b, v142
	v_exp_f32_e32 v142, v142
	v_rcp_f32_e32 v175, v140
	v_add_f32_e32 v140, 1.0, v141
	v_rcp_f32_e32 v176, v140
	v_add_f32_e32 v140, 1.0, v142
	v_rcp_f32_e32 v177, v140
	global_store_dwordx4 v[128:129], v[178:181], off offset:-4032
	global_store_dwordx4 v[130:131], v[174:177], off offset:-4032
	global_load_dwordx4 v[174:177], v[156:157], off offset:512
	s_waitcnt vmcnt(0)
	v_add_f32_e32 v140, v60, v174
	v_mul_f32_e32 v140, 0xbfb8aa3b, v140
	v_add_f32_e32 v141, v61, v175
	v_exp_f32_e32 v140, v140
	v_mul_f32_e32 v141, 0xbfb8aa3b, v141
	v_exp_f32_e32 v141, v141
	v_add_f32_e32 v142, v63, v177
	v_add_f32_e32 v140, 1.0, v140
	v_rcp_f32_e32 v178, v140
	v_add_f32_e32 v140, 1.0, v141
	v_add_f32_e32 v141, v62, v176
	v_mul_f32_e32 v141, 0xbfb8aa3b, v141
	v_exp_f32_e32 v141, v141
	v_mul_f32_e32 v142, 0xbfb8aa3b, v142
	v_exp_f32_e32 v142, v142
	v_rcp_f32_e32 v179, v140
	v_add_f32_e32 v140, 1.0, v141
	v_add_f32_e32 v141, v56, v174
	v_rcp_f32_e32 v180, v140
	v_add_f32_e32 v140, 1.0, v142
	v_mul_f32_e32 v141, 0xbfb8aa3b, v141
	v_add_f32_e32 v142, v57, v175
	v_exp_f32_e32 v141, v141
	v_mul_f32_e32 v142, 0xbfb8aa3b, v142
	v_exp_f32_e32 v142, v142
	v_rcp_f32_e32 v181, v140
	v_add_f32_e32 v140, 1.0, v141
	v_add_f32_e32 v141, v58, v176
	v_rcp_f32_e32 v182, v140
	v_add_f32_e32 v140, 1.0, v142
	v_mul_f32_e32 v141, 0xbfb8aa3b, v141
	v_add_f32_e32 v142, v59, v177
	v_exp_f32_e32 v141, v141
	v_mul_f32_e32 v142, 0xbfb8aa3b, v142
	v_exp_f32_e32 v142, v142
	v_rcp_f32_e32 v183, v140
	v_add_f32_e32 v140, 1.0, v141
	v_rcp_f32_e32 v184, v140
	v_add_f32_e32 v140, 1.0, v142
	v_rcp_f32_e32 v185, v140
	v_add_f32_e32 v140, v52, v174
	v_mul_f32_e32 v140, 0xbfb8aa3b, v140
	v_add_f32_e32 v141, v53, v175
	v_exp_f32_e32 v140, v140
	v_mul_f32_e32 v141, 0xbfb8aa3b, v141
	v_exp_f32_e32 v141, v141
	global_store_dwordx4 v[160:161], v[178:181], off offset:-3584
	v_add_f32_e32 v140, 1.0, v140
	v_add_f32_e32 v142, v55, v177
	v_rcp_f32_e32 v178, v140
	v_add_f32_e32 v140, 1.0, v141
	v_add_f32_e32 v141, v54, v176
	v_mul_f32_e32 v141, 0xbfb8aa3b, v141
	v_exp_f32_e32 v141, v141
	v_mul_f32_e32 v142, 0xbfb8aa3b, v142
	v_exp_f32_e32 v142, v142
	v_rcp_f32_e32 v179, v140
	v_add_f32_e32 v140, 1.0, v141
	v_rcp_f32_e32 v180, v140
	v_add_f32_e32 v140, 1.0, v142
	v_rcp_f32_e32 v181, v140
	v_add_f32_e32 v140, v44, v174
	v_mul_f32_e32 v140, 0xbfb8aa3b, v140
	v_add_f32_e32 v141, v45, v175
; __device__ __forceinline__ float sigmoidf_(float x) { return __builtin_amdgcn_rcpf(1.0f + __expf(-x)); }
;     __device__ __forceinline__ void operator()(const AccT& acc, const Unit& u, int wr, int wc, int fr, int fq) const {
;     ...
;             for (int bj = 0; bj < 2; ++bj)
; #pragma unroll
;                 for (int n = 0; n < 2; ++n) { const int col = col0 - 1024 + bj * 128 + n * 16; const f32x4 av0 = *(const f32x4*)(a0 + col);
; #pragma unroll
;                     for (int ai = 0; ai < 2; ++ai)
; #pragma unroll
;                         for (int m = 0; m < 4; ++m) { const int row = row0 + ai * 128 + m * 16; f32x4 o;
; #pragma unroll
;                             for (int j = 0; j < 4; ++j) o[j] = sigmoidf_(av0[j] + acc[ai][bj][m][n][j]);
;                             *(f32x4*)(IC + (size_t)row * RW + col) = o; asm volatile("" ::: "memory"); } }
	v_exp_f32_e32 v140, v140
	v_mul_f32_e32 v141, 0xbfb8aa3b, v141
	v_exp_f32_e32 v141, v141
	global_store_dwordx4 v[158:159], v[182:185], off offset:-3584
	v_add_f32_e32 v140, 1.0, v140
	global_store_dwordx4 v[154:155], v[178:181], off offset:-3584
	v_add_f32_e32 v142, v47, v177
	v_mul_f32_e32 v142, 0xbfb8aa3b, v142
	v_rcp_f32_e32 v178, v140
	v_add_f32_e32 v140, 1.0, v141
	v_add_f32_e32 v141, v46, v176
	v_mul_f32_e32 v141, 0xbfb8aa3b, v141
	v_exp_f32_e32 v141, v141
	v_exp_f32_e32 v142, v142
	v_rcp_f32_e32 v179, v140
	v_add_f32_e32 v140, 1.0, v141
	v_add_f32_e32 v141, v48, v174
	v_rcp_f32_e32 v180, v140
	v_add_f32_e32 v140, 1.0, v142
	v_mul_f32_e32 v141, 0xbfb8aa3b, v141
	v_add_f32_e32 v142, v49, v175
	v_exp_f32_e32 v141, v141
	v_mul_f32_e32 v142, 0xbfb8aa3b, v142
	v_exp_f32_e32 v142, v142
	v_rcp_f32_e32 v181, v140
	v_add_f32_e32 v140, 1.0, v141
	v_add_f32_e32 v141, v50, v176
	v_rcp_f32_e32 v182, v140
	v_add_f32_e32 v140, 1.0, v142
	v_mul_f32_e32 v141, 0xbfb8aa3b, v141
	v_add_f32_e32 v142, v51, v177
	v_exp_f32_e32 v141, v141
	v_mul_f32_e32 v142, 0xbfb8aa3b, v142
	v_exp_f32_e32 v142, v142
	v_rcp_f32_e32 v183, v140
	v_add_f32_e32 v140, 1.0, v141
	v_rcp_f32_e32 v184, v140
	v_add_f32_e32 v140, 1.0, v142
	v_rcp_f32_e32 v185, v140
	v_add_f32_e32 v140, v40, v174
	v_mul_f32_e32 v140, 0xbfb8aa3b, v140
	v_add_f32_e32 v141, v41, v175
	v_exp_f32_e32 v140, v140
	v_mul_f32_e32 v141, 0xbfb8aa3b, v141
	v_exp_f32_e32 v141, v141
	global_store_dwordx4 v[162:163], v[178:181], off offset:-3584
	v_add_f32_e32 v140, 1.0, v140
	v_add_f32_e32 v142, v43, v177
	v_rcp_f32_e32 v178, v140
	v_add_f32_e32 v140, 1.0, v141
	v_add_f32_e32 v141, v42, v176
	v_mul_f32_e32 v141, 0xbfb8aa3b, v141
	v_exp_f32_e32 v141, v141
	v_mul_f32_e32 v142, 0xbfb8aa3b, v142
	v_exp_f32_e32 v142, v142
	v_rcp_f32_e32 v179, v140
	v_add_f32_e32 v140, 1.0, v141
	v_rcp_f32_e32 v180, v140
	v_add_f32_e32 v140, 1.0, v142
	v_rcp_f32_e32 v181, v140
	v_add_f32_e32 v140, v36, v174
	v_mul_f32_e32 v140, 0xbfb8aa3b, v140
	v_add_f32_e32 v141, v37, v175
	v_exp_f32_e32 v140, v140
	v_mul_f32_e32 v141, 0xbfb8aa3b, v141
	v_exp_f32_e32 v141, v141
	global_store_dwordx4 v[166:167], v[182:185], off offset:-3584
	v_add_f32_e32 v140, 1.0, v140
	global_store_dwordx4 v[164:165], v[178:181], off offset:-3584
	v_add_f32_e32 v142, v39, v177
	v_mul_f32_e32 v142, 0xbfb8aa3b, v142
	v_rcp_f32_e32 v178, v140
	v_add_f32_e32 v140, 1.0, v141
	v_add_f32_e32 v141, v38, v176
	v_mul_f32_e32 v141, 0xbfb8aa3b, v141
	v_exp_f32_e32 v141, v141
	v_exp_f32_e32 v142, v142
	v_rcp_f32_e32 v179, v140
	v_add_f32_e32 v140, 1.0, v141
	v_add_f32_e32 v141, v32, v174
	v_rcp_f32_e32 v180, v140
	v_add_f32_e32 v140, 1.0, v142
	v_mul_f32_e32 v141, 0xbfb8aa3b, v141
	v_add_f32_e32 v142, v33, v175
	v_exp_f32_e32 v141, v141
	v_mul_f32_e32 v142, 0xbfb8aa3b, v142
	v_exp_f32_e32 v142, v142
	v_rcp_f32_e32 v181, v140
	v_add_f32_e32 v140, 1.0, v141
	v_add_f32_e32 v141, v34, v176
	v_rcp_f32_e32 v174, v140
	v_add_f32_e32 v140, 1.0, v142
	v_mul_f32_e32 v141, 0xbfb8aa3b, v141
	v_add_f32_e32 v142, v35, v177
	v_exp_f32_e32 v141, v141
	v_mul_f32_e32 v142, 0xbfb8aa3b, v142
	v_exp_f32_e32 v142, v142
	v_rcp_f32_e32 v175, v140
	v_add_f32_e32 v140, 1.0, v141
	v_rcp_f32_e32 v176, v140
	v_add_f32_e32 v140, 1.0, v142
	v_rcp_f32_e32 v177, v140
	global_store_dwordx4 v[128:129], v[178:181], off offset:-3584
	global_store_dwordx4 v[130:131], v[174:177], off offset:-3584
	global_load_dwordx4 v[174:177], v[156:157], off offset:576
	s_waitcnt vmcnt(0)
; __device__ __forceinline__ float sigmoidf_(float x) { return __builtin_amdgcn_rcpf(1.0f + __expf(-x)); }
;     __device__ __forceinline__ void operator()(const AccT& acc, const Unit& u, int wr, int wc, int fr, int fq) const {
;     ...
;             for (int bj = 0; bj < 2; ++bj)
; #pragma unroll
;                 for (int n = 0; n < 2; ++n) { const int col = col0 - 1024 + bj * 128 + n * 16; const f32x4 av0 = *(const f32x4*)(a0 + col);
; #pragma unroll
;                     for (int ai = 0; ai < 2; ++ai)
; #pragma unroll
;                         for (int m = 0; m < 4; ++m) { const int row = row0 + ai * 128 + m * 16; f32x4 o;
; #pragma unroll
;                             for (int j = 0; j < 4; ++j) o[j] = sigmoidf_(av0[j] + acc[ai][bj][m][n][j]);
;                             *(f32x4*)(IC + (size_t)row * RW + col) = o; asm volatile("" ::: "memory"); } }
	v_add_f32_e32 v140, v28, v174
	v_mul_f32_e32 v140, 0xbfb8aa3b, v140
	v_add_f32_e32 v141, v29, v175
	v_exp_f32_e32 v140, v140
	v_mul_f32_e32 v141, 0xbfb8aa3b, v141
	v_exp_f32_e32 v141, v141
	v_add_f32_e32 v142, v31, v177
	v_add_f32_e32 v140, 1.0, v140
	v_rcp_f32_e32 v178, v140
	v_add_f32_e32 v140, 1.0, v141
	v_add_f32_e32 v141, v30, v176
	v_mul_f32_e32 v141, 0xbfb8aa3b, v141
	v_exp_f32_e32 v141, v141
	v_mul_f32_e32 v142, 0xbfb8aa3b, v142
	v_exp_f32_e32 v142, v142
	v_rcp_f32_e32 v179, v140
	v_add_f32_e32 v140, 1.0, v141
	v_add_f32_e32 v141, v24, v174
	v_rcp_f32_e32 v180, v140
	v_add_f32_e32 v140, 1.0, v142
	v_mul_f32_e32 v141, 0xbfb8aa3b, v141
	v_add_f32_e32 v142, v25, v175
	v_exp_f32_e32 v141, v141
	v_mul_f32_e32 v142, 0xbfb8aa3b, v142
	v_exp_f32_e32 v142, v142
	v_rcp_f32_e32 v181, v140
	v_add_f32_e32 v140, 1.0, v141
	v_add_f32_e32 v141, v26, v176
	v_rcp_f32_e32 v182, v140
	v_add_f32_e32 v140, 1.0, v142
	v_mul_f32_e32 v141, 0xbfb8aa3b, v141
	v_add_f32_e32 v142, v27, v177
	v_exp_f32_e32 v141, v141
	v_mul_f32_e32 v142, 0xbfb8aa3b, v142
	v_exp_f32_e32 v142, v142
	v_rcp_f32_e32 v183, v140
	v_add_f32_e32 v140, 1.0, v141
	v_rcp_f32_e32 v184, v140
	v_add_f32_e32 v140, 1.0, v142
	v_rcp_f32_e32 v185, v140
	v_add_f32_e32 v140, v20, v174
	v_mul_f32_e32 v140, 0xbfb8aa3b, v140
	v_add_f32_e32 v141, v21, v175
	v_exp_f32_e32 v140, v140
	v_mul_f32_e32 v141, 0xbfb8aa3b, v141
	v_exp_f32_e32 v141, v141
	v_add_f32_e32 v142, v23, v177
	v_add_f32_e32 v140, 1.0, v140
	v_rcp_f32_e32 v156, v140
	v_add_f32_e32 v140, 1.0, v141
	v_add_f32_e32 v141, v22, v176
	v_mul_f32_e32 v141, 0xbfb8aa3b, v141
	v_exp_f32_e32 v141, v141
	v_mul_f32_e32 v142, 0xbfb8aa3b, v142
	v_exp_f32_e32 v142, v142
	global_store_dwordx4 v[160:161], v[178:181], off offset:-3520
	v_rcp_f32_e32 v157, v140
	v_add_f32_e32 v140, 1.0, v141
	global_store_dwordx4 v[158:159], v[182:185], off offset:-3520
	v_rcp_f32_e32 v158, v140
	v_add_f32_e32 v140, 1.0, v142
	v_rcp_f32_e32 v159, v140
	v_add_f32_e32 v140, v12, v174
	v_mul_f32_e32 v140, 0xbfb8aa3b, v140
	v_add_f32_e32 v141, v13, v175
	v_exp_f32_e32 v140, v140
	v_mul_f32_e32 v141, 0xbfb8aa3b, v141
	v_exp_f32_e32 v141, v141
	v_add_f32_e32 v140, 1.0, v140
	global_store_dwordx4 v[154:155], v[156:159], off offset:-3520
	v_rcp_f32_e32 v154, v140
	v_add_f32_e32 v140, 1.0, v141
	v_add_f32_e32 v141, v14, v176
	v_mul_f32_e32 v141, 0xbfb8aa3b, v141
	v_add_f32_e32 v142, v15, v177
	v_exp_f32_e32 v141, v141
	v_mul_f32_e32 v142, 0xbfb8aa3b, v142
	v_exp_f32_e32 v142, v142
	v_rcp_f32_e32 v155, v140
	v_add_f32_e32 v140, 1.0, v141
	v_add_f32_e32 v141, v16, v174
	v_rcp_f32_e32 v156, v140
	v_add_f32_e32 v140, 1.0, v142
	v_mul_f32_e32 v141, 0xbfb8aa3b, v141
	v_add_f32_e32 v142, v17, v175
	v_exp_f32_e32 v141, v141
	v_mul_f32_e32 v142, 0xbfb8aa3b, v142
	v_exp_f32_e32 v142, v142
	v_rcp_f32_e32 v157, v140
	v_add_f32_e32 v140, 1.0, v141
	v_add_f32_e32 v141, v18, v176
	v_rcp_f32_e32 v158, v140
	v_add_f32_e32 v140, 1.0, v142
	v_mul_f32_e32 v141, 0xbfb8aa3b, v141
	v_add_f32_e32 v142, v19, v177
	v_exp_f32_e32 v141, v141
	v_mul_f32_e32 v142, 0xbfb8aa3b, v142
	v_exp_f32_e32 v142, v142
	v_rcp_f32_e32 v159, v140
	v_add_f32_e32 v140, 1.0, v141
	v_rcp_f32_e32 v160, v140
	v_add_f32_e32 v140, 1.0, v142
	v_rcp_f32_e32 v161, v140
	v_add_f32_e32 v140, v8, v174
	v_mul_f32_e32 v140, 0xbfb8aa3b, v140
	v_add_f32_e32 v141, v9, v175
	v_exp_f32_e32 v140, v140
	v_mul_f32_e32 v141, 0xbfb8aa3b, v141
	v_exp_f32_e32 v141, v141
	v_add_f32_e32 v140, 1.0, v140
	global_store_dwordx4 v[162:163], v[154:157], off offset:-3520
	v_add_f32_e32 v142, v11, v177
	v_mul_f32_e32 v142, 0xbfb8aa3b, v142
	v_rcp_f32_e32 v154, v140
	v_add_f32_e32 v140, 1.0, v141
	v_add_f32_e32 v141, v10, v176
	v_mul_f32_e32 v141, 0xbfb8aa3b, v141
	v_exp_f32_e32 v141, v141
	v_exp_f32_e32 v142, v142
	v_rcp_f32_e32 v155, v140
	v_add_f32_e32 v140, 1.0, v141
	v_rcp_f32_e32 v156, v140
	v_add_f32_e32 v140, 1.0, v142
	v_rcp_f32_e32 v157, v140
	v_add_f32_e32 v140, v4, v174
	v_mul_f32_e32 v140, 0xbfb8aa3b, v140
	v_add_f32_e32 v141, v5, v175
	v_exp_f32_e32 v140, v140
	v_mul_f32_e32 v141, 0xbfb8aa3b, v141
	v_exp_f32_e32 v141, v141
	global_store_dwordx4 v[166:167], v[158:161], off offset:-3520
	v_add_f32_e32 v140, 1.0, v140
	global_store_dwordx4 v[164:165], v[154:157], off offset:-3520
	v_add_f32_e32 v142, v7, v177
	v_mul_f32_e32 v142, 0xbfb8aa3b, v142
	v_rcp_f32_e32 v154, v140
	v_add_f32_e32 v140, 1.0, v141
	v_add_f32_e32 v141, v6, v176
	v_mul_f32_e32 v141, 0xbfb8aa3b, v141
	v_exp_f32_e32 v141, v141
	v_exp_f32_e32 v142, v142
	v_rcp_f32_e32 v155, v140
	v_add_f32_e32 v140, 1.0, v141
	v_add_f32_e32 v141, v0, v174
	v_rcp_f32_e32 v156, v140
	v_add_f32_e32 v140, 1.0, v142
	v_mul_f32_e32 v141, 0xbfb8aa3b, v141
	v_add_f32_e32 v142, v1, v175
	v_exp_f32_e32 v141, v141
	v_mul_f32_e32 v142, 0xbfb8aa3b, v142
	v_exp_f32_e32 v142, v142
	v_rcp_f32_e32 v157, v140
	v_add_f32_e32 v140, 1.0, v141
	v_add_f32_e32 v141, v2, v176
	v_rcp_f32_e32 v158, v140
	v_add_f32_e32 v140, 1.0, v142
	v_mul_f32_e32 v141, 0xbfb8aa3b, v141
	v_add_f32_e32 v142, v3, v177
	v_exp_f32_e32 v141, v141
	v_mul_f32_e32 v142, 0xbfb8aa3b, v142
	v_exp_f32_e32 v142, v142
	v_rcp_f32_e32 v159, v140
	v_add_f32_e32 v140, 1.0, v141
	v_rcp_f32_e32 v160, v140
	v_add_f32_e32 v140, 1.0, v142
	v_rcp_f32_e32 v161, v140
	global_store_dwordx4 v[128:129], v[154:157], off offset:-3520
	global_store_dwordx4 v[130:131], v[158:161], off offset:-3520

; #define PG8_STAGE(bufoff, gbase, voff) do { _Pragma("unroll") for (int _i = 0; _i < 2; ++_i) \
;         __builtin_amdgcn_global_load_lds((const unsigned*)((const char*)(gbase) + (voff)[_i]), (LAS unsigned*)(lds + (bufoff) + ldsw + _i * 8192), 16, 0, 0); } while (0)
; #define PG8_LDA(dst, b, h) do { _Pragma("unroll") for (int m = 0; m < 4; ++m) _Pragma("unroll") for (int k = 0; k < 2; ++k) dst[m][k] = *(const LAS bf16x8*)(lds + PG8_SA(b, h) + aoff + m * 2048 + k * 1024); } while (0)
; #define PG8_LDB(dst, b, h) do { _Pragma("unroll") for (int n = 0; n < 2; ++n) _Pragma("unroll") for (int k = 0; k < 2; ++k) dst[n][k] = *(const LAS bf16x8*)(lds + PG8_SB(b, h) + boff + n * 2048 + k * 1024); } while (0)
; #define PG8_MMA(ai, bj, At, Bt) do { __builtin_amdgcn_s_setprio(1); _Pragma("unroll") for (int m = 0; m < 4; ++m) _Pragma("unroll") for (int n = 0; n < 2; ++n) _Pragma("unroll") for (int k = 0; k < 2; ++k) \
;         acc[ai][bj][m][n] = __builtin_amdgcn_mfma_f32_16x16x32_bf16(Bt[n][k], At[m][k], acc[ai][bj][m][n], 0, 0, 0); __builtin_amdgcn_s_setprio(0); } while (0)
; #define PG8_WAIT_L(n) asm volatile("s_waitcnt lgkmcnt(" #n ")" ::: "memory")
; #define PG8_BAR __builtin_amdgcn_s_barrier()
; #define PG8_SCHED __builtin_amdgcn_sched_barrier(0)
; template <class Epi>
; __device__ __forceinline__ void gemm_phase(LAS unsigned char* lds, const Gemm g, const StaticOrder& S, const Epi& E) {
;     ...
;             PG8_LDB(B0, 0, 0); PG8_SCHED; PG8_LDA(At, 0, 0); PG8_STAGE(PG8_SA(1, 1), a1 + hstepA, voffA);
;             PG8_WAIT_L(8); PG8_BAR; PG8_WAIT_L(0); PG8_MMA(0, 0, At, B0); PG8_BAR; PG8_SCHED;
;             PG8_LDB(B1, 0, 1); PG8_STAGE(PG8_SB(0, 0), b2, voffB);
;             PG8_BAR; PG8_WAIT_L(0); PG8_MMA(0, 1, At, B1); PG8_BAR;
;             PG8_LDA(At, 0, 1); PG8_STAGE(PG8_SA(0, 0), a2, voffA);
;             PG8_BAR; PG8_WAIT_L(0); PG8_MMA(1, 0, At, B0); PG8_BAR; PG8_SCHED;
.LBB0_1089:
	ds_read_b128 v[158:161], v154
	ds_read_b128 v[162:165], v154 offset:1024
	ds_read_b128 v[166:169], v154 offset:2048
	ds_read_b128 v[170:173], v154 offset:3072
	s_add_u32 s36, s30, 0xfff80080
	s_addc_u32 s37, s31, -1
	s_cmp_eq_u32 s71, 28
	s_cselect_b32 s39, s23, s37
	s_cselect_b32 s38, s67, s36
	s_cselect_b32 s37, s21, s70
	s_cselect_b32 s36, s68, s69
	v_lshl_add_u64 v[140:141], s[30:31], 0, v[132:133]
	s_add_i32 m0, s29, 0xc000
	ds_read_b128 v[174:177], v155
	ds_read_b128 v[178:181], v155 offset:1024
	ds_read_b128 v[182:185], v155 offset:2048
	ds_read_b128 v[190:193], v155 offset:3072
	ds_read_b128 v[194:197], v155 offset:4096
	ds_read_b128 v[198:201], v155 offset:5120
	ds_read_b128 v[202:205], v155 offset:6144
	ds_read_b128 v[206:209], v155 offset:7168
	global_load_lds_dwordx4 v[140:141], off
	v_lshl_add_u64 v[140:141], s[30:31], 0, v[134:135]
	s_add_i32 m0, s29, 0xe000
	s_nop 0
	global_load_lds_dwordx4 v[140:141], off
	s_waitcnt lgkmcnt(8)
	s_barrier
	s_setprio 1
	s_waitcnt lgkmcnt(12)
	s_waitcnt lgkmcnt(7)
	v_mfma_f32_16x16x32_bf16 v[124:127], v[158:161], v[174:177], v[124:127]
	v_mfma_f32_16x16x32_bf16 v[120:123], v[166:169], v[174:177], v[120:123]
	s_waitcnt lgkmcnt(5)
	v_mfma_f32_16x16x32_bf16 v[112:115], v[158:161], v[182:185], v[112:115]
	v_mfma_f32_16x16x32_bf16 v[104:107], v[166:169], v[182:185], v[104:107]
	s_waitcnt lgkmcnt(3)
	v_mfma_f32_16x16x32_bf16 v[96:99], v[158:161], v[194:197], v[96:99]
	v_mfma_f32_16x16x32_bf16 v[88:91], v[166:169], v[194:197], v[88:91]
	s_waitcnt lgkmcnt(1)
	v_mfma_f32_16x16x32_bf16 v[80:83], v[158:161], v[202:205], v[80:83]
	v_mfma_f32_16x16x32_bf16 v[72:75], v[166:169], v[202:205], v[72:75]
	v_mfma_f32_16x16x32_bf16 v[124:127], v[162:165], v[178:181], v[124:127]
	v_mfma_f32_16x16x32_bf16 v[120:123], v[170:173], v[178:181], v[120:123]
	v_mfma_f32_16x16x32_bf16 v[112:115], v[162:165], v[190:193], v[112:115]
	v_mfma_f32_16x16x32_bf16 v[104:107], v[170:173], v[190:193], v[104:107]
	v_mfma_f32_16x16x32_bf16 v[96:99], v[162:165], v[198:201], v[96:99]
	v_mfma_f32_16x16x32_bf16 v[88:91], v[170:173], v[198:201], v[88:91]
	s_waitcnt lgkmcnt(0)
	v_mfma_f32_16x16x32_bf16 v[80:83], v[162:165], v[206:209], v[80:83]
	v_mfma_f32_16x16x32_bf16 v[72:75], v[170:173], v[206:209], v[72:75]
	s_setprio 0
	s_barrier
	s_add_i32 s72, s64, s45
	v_lshl_add_u64 v[140:141], s[36:37], 0, v[128:129]
	s_mov_b32 m0, s72
	ds_read_b128 v[210:213], v156
	ds_read_b128 v[214:217], v156 offset:1024
	ds_read_b128 v[218:221], v156 offset:2048
	ds_read_b128 v[222:225], v156 offset:3072
	global_load_lds_dwordx4 v[140:141], off
	v_lshl_add_u64 v[186:187], s[36:37], 0, v[130:131]
	s_add_i32 m0, s72, 0x2000
	s_nop 0
	global_load_lds_dwordx4 v[186:187], off
	s_barrier
	s_setprio 1
	s_waitcnt lgkmcnt(3)
	v_mfma_f32_16x16x32_bf16 v[116:119], v[210:213], v[174:177], v[116:119]
	s_waitcnt lgkmcnt(1)
	v_mfma_f32_16x16x32_bf16 v[108:111], v[218:221], v[174:177], v[108:111]
	v_mfma_f32_16x16x32_bf16 v[100:103], v[210:213], v[182:185], v[100:103]
	v_mfma_f32_16x16x32_bf16 v[92:95], v[218:221], v[182:185], v[92:95]
	v_mfma_f32_16x16x32_bf16 v[84:87], v[210:213], v[194:197], v[84:87]
	v_mfma_f32_16x16x32_bf16 v[76:79], v[218:221], v[194:197], v[76:79]
	v_mfma_f32_16x16x32_bf16 v[68:71], v[210:213], v[202:205], v[68:71]
	v_mfma_f32_16x16x32_bf16 v[64:67], v[218:221], v[202:205], v[64:67]
	v_mfma_f32_16x16x32_bf16 v[116:119], v[214:217], v[178:181], v[116:119]
	s_waitcnt lgkmcnt(0)
	v_mfma_f32_16x16x32_bf16 v[108:111], v[222:225], v[178:181], v[108:111]
	v_mfma_f32_16x16x32_bf16 v[100:103], v[214:217], v[190:193], v[100:103]
	v_mfma_f32_16x16x32_bf16 v[92:95], v[222:225], v[190:193], v[92:95]
	v_mfma_f32_16x16x32_bf16 v[84:87], v[214:217], v[198:201], v[84:87]
	v_mfma_f32_16x16x32_bf16 v[76:79], v[222:225], v[198:201], v[76:79]
	v_mfma_f32_16x16x32_bf16 v[68:71], v[214:217], v[206:209], v[68:71]
	v_mfma_f32_16x16x32_bf16 v[64:67], v[222:225], v[206:209], v[64:67]
	s_setprio 0
	s_mov_b32 m0, s29
	v_lshl_add_u64 v[188:189], s[38:39], 0, v[128:129]
	s_barrier
	ds_read_b128 v[174:177], v155 offset:16384
	ds_read_b128 v[178:181], v155 offset:17408
	ds_read_b128 v[182:185], v155 offset:18432
	ds_read_b128 v[190:193], v155 offset:19456
	ds_read_b128 v[194:197], v155 offset:20480
	ds_read_b128 v[198:201], v155 offset:21504
	ds_read_b128 v[202:205], v155 offset:22528
	ds_read_b128 v[206:209], v155 offset:23552
	global_load_lds_dwordx4 v[188:189], off
	v_lshl_add_u64 v[226:227], s[38:39], 0, v[130:131]
	s_mov_b32 m0, s46
	s_nop 0
	global_load_lds_dwordx4 v[226:227], off
	s_barrier
	s_setprio 1
	s_waitcnt lgkmcnt(7)
	v_mfma_f32_16x16x32_bf16 v[60:63], v[158:161], v[174:177], v[60:63]
	v_mfma_f32_16x16x32_bf16 v[56:59], v[166:169], v[174:177], v[56:59]
	s_waitcnt lgkmcnt(5)
	v_mfma_f32_16x16x32_bf16 v[48:51], v[158:161], v[182:185], v[48:51]
	v_mfma_f32_16x16x32_bf16 v[44:47], v[166:169], v[182:185], v[44:47]
	s_waitcnt lgkmcnt(3)
	v_mfma_f32_16x16x32_bf16 v[32:35], v[158:161], v[194:197], v[32:35]
	v_mfma_f32_16x16x32_bf16 v[28:31], v[166:169], v[194:197], v[28:31]
	s_waitcnt lgkmcnt(1)
	v_mfma_f32_16x16x32_bf16 v[16:19], v[158:161], v[202:205], v[16:19]
	v_mfma_f32_16x16x32_bf16 v[12:15], v[166:169], v[202:205], v[12:15]
	v_mfma_f32_16x16x32_bf16 v[60:63], v[162:165], v[178:181], v[60:63]
	v_mfma_f32_16x16x32_bf16 v[56:59], v[170:173], v[178:181], v[56:59]
	v_mfma_f32_16x16x32_bf16 v[48:51], v[162:165], v[190:193], v[48:51]
	v_mfma_f32_16x16x32_bf16 v[44:47], v[170:173], v[190:193], v[44:47]
	v_mfma_f32_16x16x32_bf16 v[32:35], v[162:165], v[198:201], v[32:35]
	v_mfma_f32_16x16x32_bf16 v[28:31], v[170:173], v[198:201], v[28:31]
	s_waitcnt lgkmcnt(0)
	v_mfma_f32_16x16x32_bf16 v[16:19], v[162:165], v[206:209], v[16:19]
	v_mfma_f32_16x16x32_bf16 v[12:15], v[170:173], v[206:209], v[12:15]
	s_setprio 0
	s_barrier
; #define PG8_STAGE(bufoff, gbase, voff) do { _Pragma("unroll") for (int _i = 0; _i < 2; ++_i) \
;         __builtin_amdgcn_global_load_lds((const unsigned*)((const char*)(gbase) + (voff)[_i]), (LAS unsigned*)(lds + (bufoff) + ldsw + _i * 8192), 16, 0, 0); } while (0)
; #define PG8_LDA(dst, b, h) do { _Pragma("unroll") for (int m = 0; m < 4; ++m) _Pragma("unroll") for (int k = 0; k < 2; ++k) dst[m][k] = *(const LAS bf16x8*)(lds + PG8_SA(b, h) + aoff + m * 2048 + k * 1024); } while (0)
; #define PG8_LDB(dst, b, h) do { _Pragma("unroll") for (int n = 0; n < 2; ++n) _Pragma("unroll") for (int k = 0; k < 2; ++k) dst[n][k] = *(const LAS bf16x8*)(lds + PG8_SB(b, h) + boff + n * 2048 + k * 1024); } while (0)
; #define PG8_MMA(ai, bj, At, Bt) do { __builtin_amdgcn_s_setprio(1); _Pragma("unroll") for (int m = 0; m < 4; ++m) _Pragma("unroll") for (int n = 0; n < 2; ++n) _Pragma("unroll") for (int k = 0; k < 2; ++k) \
;         acc[ai][bj][m][n] = __builtin_amdgcn_mfma_f32_16x16x32_bf16(Bt[n][k], At[m][k], acc[ai][bj][m][n], 0, 0, 0); __builtin_amdgcn_s_setprio(0); } while (0)
; #define PG8_WAIT_V(n) asm volatile("s_waitcnt vmcnt(" #n ")" ::: "memory")
; #define PG8_WAIT_L(n) asm volatile("s_waitcnt lgkmcnt(" #n ")" ::: "memory")
; #define PG8_BAR __builtin_amdgcn_s_barrier()
; #define PG8_SCHED __builtin_amdgcn_sched_barrier(0)
; template <class Epi>
; __device__ __forceinline__ void gemm_phase(LAS unsigned char* lds, const Gemm g, const StaticOrder& S, const Epi& E) {
;     ...
;             PG8_STAGE(PG8_SB(0, 1), b2 + hstepB, voffB);
;             PG8_WAIT_V(6); PG8_BAR; PG8_MMA(1, 1, At, B1); PG8_BAR;
;             PG8_LDB(B0, 1, 0); PG8_SCHED; PG8_LDA(At, 1, 0); PG8_STAGE(PG8_SA(0, 1), a2 + hstepA, voffA);
;             PG8_WAIT_L(8); PG8_BAR; PG8_WAIT_L(0); PG8_MMA(0, 0, At, B0); PG8_BAR; PG8_SCHED;
;             PG8_LDB(B1, 1, 1); PG8_STAGE(PG8_SB(1, 0), b3, voffB);
;             PG8_BAR; PG8_WAIT_L(0); PG8_MMA(0, 1, At, B1); PG8_BAR;
	s_add_u32 s72, s36, 0x80000
	s_addc_u32 s73, s37, 0
	s_add_i32 s74, s65, s45
	v_lshl_add_u64 v[158:159], s[72:73], 0, v[128:129]
	s_mov_b32 m0, s74
	s_nop 0
	global_load_lds_dwordx4 v[158:159], off
	v_lshl_add_u64 v[158:159], s[72:73], 0, v[130:131]
	s_add_i32 m0, s74, 0x2000
	s_nop 0
	global_load_lds_dwordx4 v[158:159], off
	s_waitcnt vmcnt(6)
	s_barrier
	s_setprio 1
	v_mfma_f32_16x16x32_bf16 v[52:55], v[210:213], v[174:177], v[52:55]
	v_mfma_f32_16x16x32_bf16 v[40:43], v[218:221], v[174:177], v[40:43]
	v_mfma_f32_16x16x32_bf16 v[36:39], v[210:213], v[182:185], v[36:39]
	v_mfma_f32_16x16x32_bf16 v[24:27], v[218:221], v[182:185], v[24:27]
	v_mfma_f32_16x16x32_bf16 v[20:23], v[210:213], v[194:197], v[20:23]
	v_mfma_f32_16x16x32_bf16 v[8:11], v[218:221], v[194:197], v[8:11]
	v_mfma_f32_16x16x32_bf16 v[4:7], v[210:213], v[202:205], v[4:7]
	v_mfma_f32_16x16x32_bf16 v[0:3], v[218:221], v[202:205], v[0:3]
	v_mfma_f32_16x16x32_bf16 v[52:55], v[214:217], v[178:181], v[52:55]
	v_mfma_f32_16x16x32_bf16 v[40:43], v[222:225], v[178:181], v[40:43]
	v_mfma_f32_16x16x32_bf16 v[36:39], v[214:217], v[190:193], v[36:39]
	v_mfma_f32_16x16x32_bf16 v[24:27], v[222:225], v[190:193], v[24:27]
	v_mfma_f32_16x16x32_bf16 v[20:23], v[214:217], v[198:201], v[20:23]
	v_mfma_f32_16x16x32_bf16 v[8:11], v[222:225], v[198:201], v[8:11]
	v_mfma_f32_16x16x32_bf16 v[4:7], v[214:217], v[206:209], v[4:7]
	v_mfma_f32_16x16x32_bf16 v[0:3], v[222:225], v[206:209], v[0:3]
	s_setprio 0
	s_add_i32 s72, 0, 0x18000
	v_add_u32_e32 v157, s72, v152
	s_barrier
	ds_read_b128 v[158:161], v157
	ds_read_b128 v[162:165], v157 offset:1024
	ds_read_b128 v[166:169], v157 offset:2048
	ds_read_b128 v[170:173], v157 offset:3072
	s_add_u32 s38, s38, 0x80000
	s_addc_u32 s39, s39, 0
	s_mov_b32 m0, s47
	v_lshl_add_u64 v[210:211], s[38:39], 0, v[128:129]
	ds_read_b128 v[174:177], v155 offset:32768
	ds_read_b128 v[178:181], v155 offset:33792
	ds_read_b128 v[182:185], v155 offset:34816
	ds_read_b128 v[190:193], v155 offset:35840
	ds_read_b128 v[194:197], v155 offset:36864
	ds_read_b128 v[198:201], v155 offset:37888
	ds_read_b128 v[202:205], v155 offset:38912
	ds_read_b128 v[206:209], v155 offset:39936
	global_load_lds_dwordx4 v[210:211], off
	v_lshl_add_u64 v[210:211], s[38:39], 0, v[130:131]
	s_mov_b32 m0, s48
	s_nop 0
	global_load_lds_dwordx4 v[210:211], off
	s_waitcnt lgkmcnt(8)
	s_barrier
	s_setprio 1
	s_waitcnt lgkmcnt(7)
	v_mfma_f32_16x16x32_bf16 v[124:127], v[158:161], v[174:177], v[124:127]
	v_mfma_f32_16x16x32_bf16 v[120:123], v[166:169], v[174:177], v[120:123]
	s_waitcnt lgkmcnt(5)
	v_mfma_f32_16x16x32_bf16 v[112:115], v[158:161], v[182:185], v[112:115]
	v_mfma_f32_16x16x32_bf16 v[104:107], v[166:169], v[182:185], v[104:107]
	s_waitcnt lgkmcnt(3)
	v_mfma_f32_16x16x32_bf16 v[96:99], v[158:161], v[194:197], v[96:99]
	v_mfma_f32_16x16x32_bf16 v[88:91], v[166:169], v[194:197], v[88:91]
	s_waitcnt lgkmcnt(1)
	v_mfma_f32_16x16x32_bf16 v[80:83], v[158:161], v[202:205], v[80:83]
	v_mfma_f32_16x16x32_bf16 v[72:75], v[166:169], v[202:205], v[72:75]
	v_mfma_f32_16x16x32_bf16 v[124:127], v[162:165], v[178:181], v[124:127]
	v_mfma_f32_16x16x32_bf16 v[120:123], v[170:173], v[178:181], v[120:123]
	v_mfma_f32_16x16x32_bf16 v[112:115], v[162:165], v[190:193], v[112:115]
	v_mfma_f32_16x16x32_bf16 v[104:107], v[170:173], v[190:193], v[104:107]
	v_mfma_f32_16x16x32_bf16 v[96:99], v[162:165], v[198:201], v[96:99]
	v_mfma_f32_16x16x32_bf16 v[88:91], v[170:173], v[198:201], v[88:91]
	s_waitcnt lgkmcnt(0)
	v_mfma_f32_16x16x32_bf16 v[80:83], v[162:165], v[206:209], v[80:83]
	v_mfma_f32_16x16x32_bf16 v[72:75], v[170:173], v[206:209], v[72:75]
	s_setprio 0
	s_barrier
	s_add_i32 s38, 0, 0x1c000
	s_add_i32 s39, s72, s45
	v_add_u32_e32 v157, s38, v152
	v_lshl_add_u64 v[140:141], v[140:141], 0, s[6:7]
	s_mov_b32 m0, s39
	ds_read_b128 v[210:213], v157
	ds_read_b128 v[214:217], v157 offset:1024
	ds_read_b128 v[218:221], v157 offset:2048
	ds_read_b128 v[222:225], v157 offset:3072
	global_load_lds_dwordx4 v[140:141], off
	v_lshl_add_u64 v[140:141], v[186:187], 0, s[6:7]
	s_add_i32 m0, s39, 0x2000
	s_nop 0
	global_load_lds_dwordx4 v[140:141], off
	s_barrier
	s_setprio 1
	s_waitcnt lgkmcnt(3)
	v_mfma_f32_16x16x32_bf16 v[116:119], v[210:213], v[174:177], v[116:119]
	s_waitcnt lgkmcnt(1)
	v_mfma_f32_16x16x32_bf16 v[108:111], v[218:221], v[174:177], v[108:111]
	v_mfma_f32_16x16x32_bf16 v[100:103], v[210:213], v[182:185], v[100:103]
	v_mfma_f32_16x16x32_bf16 v[92:95], v[218:221], v[182:185], v[92:95]
	v_mfma_f32_16x16x32_bf16 v[84:87], v[210:213], v[194:197], v[84:87]
	v_mfma_f32_16x16x32_bf16 v[76:79], v[218:221], v[194:197], v[76:79]
	v_mfma_f32_16x16x32_bf16 v[68:71], v[210:213], v[202:205], v[68:71]
	v_mfma_f32_16x16x32_bf16 v[64:67], v[218:221], v[202:205], v[64:67]
	v_mfma_f32_16x16x32_bf16 v[116:119], v[214:217], v[178:181], v[116:119]
	s_waitcnt lgkmcnt(0)
	v_mfma_f32_16x16x32_bf16 v[108:111], v[222:225], v[178:181], v[108:111]
	v_mfma_f32_16x16x32_bf16 v[100:103], v[214:217], v[190:193], v[100:103]
	v_mfma_f32_16x16x32_bf16 v[92:95], v[222:225], v[190:193], v[92:95]
	v_mfma_f32_16x16x32_bf16 v[84:87], v[214:217], v[198:201], v[84:87]
	v_mfma_f32_16x16x32_bf16 v[76:79], v[222:225], v[198:201], v[76:79]
	v_mfma_f32_16x16x32_bf16 v[68:71], v[214:217], v[206:209], v[68:71]
	v_mfma_f32_16x16x32_bf16 v[64:67], v[222:225], v[206:209], v[64:67]
	s_setprio 0
	s_mov_b32 m0, s50
	v_lshl_add_u64 v[140:141], v[188:189], 0, s[6:7]
	s_barrier
; #define PG8_STAGE(bufoff, gbase, voff) do { _Pragma("unroll") for (int _i = 0; _i < 2; ++_i) \
;         __builtin_amdgcn_global_load_lds((const unsigned*)((const char*)(gbase) + (voff)[_i]), (LAS unsigned*)(lds + (bufoff) + ldsw + _i * 8192), 16, 0, 0); } while (0)
; #define PG8_LDA(dst, b, h) do { _Pragma("unroll") for (int m = 0; m < 4; ++m) _Pragma("unroll") for (int k = 0; k < 2; ++k) dst[m][k] = *(const LAS bf16x8*)(lds + PG8_SA(b, h) + aoff + m * 2048 + k * 1024); } while (0)
; #define PG8_MMA(ai, bj, At, Bt) do { __builtin_amdgcn_s_setprio(1); _Pragma("unroll") for (int m = 0; m < 4; ++m) _Pragma("unroll") for (int n = 0; n < 2; ++n) _Pragma("unroll") for (int k = 0; k < 2; ++k) \
;         acc[ai][bj][m][n] = __builtin_amdgcn_mfma_f32_16x16x32_bf16(Bt[n][k], At[m][k], acc[ai][bj][m][n], 0, 0, 0); __builtin_amdgcn_s_setprio(0); } while (0)
; #define PG8_WAIT_V(n) asm volatile("s_waitcnt vmcnt(" #n ")" ::: "memory")
; #define PG8_WAIT_L(n) asm volatile("s_waitcnt lgkmcnt(" #n ")" ::: "memory")
; #define PG8_BAR __builtin_amdgcn_s_barrier()
; #define PG8_SCHED __builtin_amdgcn_sched_barrier(0)
; template <class Epi>
; __device__ __forceinline__ void gemm_phase(LAS unsigned char* lds, const Gemm g, const StaticOrder& S, const Epi& E) {
;     ...
;             PG8_BAR; PG8_WAIT_L(0); PG8_MMA(0, 1, At, B1); PG8_BAR;
;             PG8_LDA(At, 1, 1); PG8_STAGE(PG8_SA(1, 0), a3, voffA);
;             PG8_BAR; PG8_WAIT_L(0); PG8_MMA(1, 0, At, B0); PG8_BAR; PG8_SCHED;
;             PG8_STAGE(PG8_SB(1, 1), b3 + hstepB, voffB);
;             PG8_WAIT_V(6); PG8_BAR; PG8_MMA(1, 1, At, B1); PG8_BAR;
;         }
;     __device__ __forceinline__ void operator()(const AccT& acc, const Unit& u, int wr, int wc, int fr, int fq) const {
;         const int row0 = u.pm * 256 + wr * 64 + fr, col0 = u.pn * 256 + wc * 32 + 4 * fq;
; #pragma unroll
;         for (int ai = 0; ai < 2; ++ai)
; #pragma unroll
;             for (int m = 0; m < 4; ++m) { const size_t ro = (size_t)(row0 + ai * 128 + m * 16) * DM + col0;
; #pragma unroll
;                 for (int bj = 0; bj < 2; ++bj)
; #pragma unroll
;                     for (int n = 0; n < 2; ++n) { const size_t o = ro + bj * 128 + n * 16; *(f32x4*)(H + o) = acc[ai][bj][m][n] + *(const f32x4*)(X + o); } asm volatile("" ::: "memory"); }
	ds_read_b128 v[174:177], v155 offset:49152
	ds_read_b128 v[178:181], v155 offset:50176
	ds_read_b128 v[182:185], v155 offset:51200
	ds_read_b128 v[190:193], v155 offset:52224
	ds_read_b128 v[194:197], v155 offset:53248
	ds_read_b128 v[198:201], v155 offset:54272
	ds_read_b128 v[202:205], v155 offset:55296
	ds_read_b128 v[206:209], v155 offset:56320
	global_load_lds_dwordx4 v[140:141], off
	v_lshl_add_u64 v[140:141], v[226:227], 0, s[6:7]
	s_mov_b32 m0, s51
	s_nop 0
	global_load_lds_dwordx4 v[140:141], off
	s_barrier
	s_setprio 1
	s_waitcnt lgkmcnt(7)
	v_mfma_f32_16x16x32_bf16 v[60:63], v[158:161], v[174:177], v[60:63]
	v_mfma_f32_16x16x32_bf16 v[56:59], v[166:169], v[174:177], v[56:59]
	s_waitcnt lgkmcnt(5)
	v_mfma_f32_16x16x32_bf16 v[48:51], v[158:161], v[182:185], v[48:51]
	v_mfma_f32_16x16x32_bf16 v[44:47], v[166:169], v[182:185], v[44:47]
	s_waitcnt lgkmcnt(3)
	v_mfma_f32_16x16x32_bf16 v[32:35], v[158:161], v[194:197], v[32:35]
	v_mfma_f32_16x16x32_bf16 v[28:31], v[166:169], v[194:197], v[28:31]
	s_waitcnt lgkmcnt(1)
	v_mfma_f32_16x16x32_bf16 v[16:19], v[158:161], v[202:205], v[16:19]
	v_mfma_f32_16x16x32_bf16 v[12:15], v[166:169], v[202:205], v[12:15]
	v_mfma_f32_16x16x32_bf16 v[60:63], v[162:165], v[178:181], v[60:63]
	v_mfma_f32_16x16x32_bf16 v[56:59], v[170:173], v[178:181], v[56:59]
	v_mfma_f32_16x16x32_bf16 v[48:51], v[162:165], v[190:193], v[48:51]
	v_mfma_f32_16x16x32_bf16 v[44:47], v[170:173], v[190:193], v[44:47]
	v_mfma_f32_16x16x32_bf16 v[32:35], v[162:165], v[198:201], v[32:35]
	v_mfma_f32_16x16x32_bf16 v[28:31], v[170:173], v[198:201], v[28:31]
	s_waitcnt lgkmcnt(0)
	v_mfma_f32_16x16x32_bf16 v[16:19], v[162:165], v[206:209], v[16:19]
	v_mfma_f32_16x16x32_bf16 v[12:15], v[170:173], v[206:209], v[12:15]
	s_setprio 0
	s_barrier
	s_add_u32 s36, s36, 0x80080
	s_addc_u32 s37, s37, 0
	s_add_i32 s38, s38, s45
	v_lshl_add_u64 v[140:141], s[36:37], 0, v[128:129]
	s_mov_b32 m0, s38
	s_nop 0
	global_load_lds_dwordx4 v[140:141], off
	v_lshl_add_u64 v[140:141], s[36:37], 0, v[130:131]
	s_add_i32 m0, s38, 0x2000
	s_nop 0
	global_load_lds_dwordx4 v[140:141], off
	s_waitcnt vmcnt(6)
	s_barrier
	s_setprio 1
	v_mfma_f32_16x16x32_bf16 v[52:55], v[210:213], v[174:177], v[52:55]
	v_mfma_f32_16x16x32_bf16 v[40:43], v[218:221], v[174:177], v[40:43]
	v_mfma_f32_16x16x32_bf16 v[36:39], v[210:213], v[182:185], v[36:39]
	v_mfma_f32_16x16x32_bf16 v[24:27], v[218:221], v[182:185], v[24:27]
	v_mfma_f32_16x16x32_bf16 v[20:23], v[210:213], v[194:197], v[20:23]
	v_mfma_f32_16x16x32_bf16 v[8:11], v[218:221], v[194:197], v[8:11]
	v_mfma_f32_16x16x32_bf16 v[4:7], v[210:213], v[202:205], v[4:7]
	v_mfma_f32_16x16x32_bf16 v[0:3], v[218:221], v[202:205], v[0:3]
	v_mfma_f32_16x16x32_bf16 v[52:55], v[214:217], v[178:181], v[52:55]
	v_mfma_f32_16x16x32_bf16 v[40:43], v[222:225], v[178:181], v[40:43]
	v_mfma_f32_16x16x32_bf16 v[36:39], v[214:217], v[190:193], v[36:39]
	v_mfma_f32_16x16x32_bf16 v[24:27], v[222:225], v[190:193], v[24:27]
	v_mfma_f32_16x16x32_bf16 v[20:23], v[214:217], v[198:201], v[20:23]
	v_mfma_f32_16x16x32_bf16 v[8:11], v[222:225], v[198:201], v[8:11]
	v_mfma_f32_16x16x32_bf16 v[4:7], v[214:217], v[206:209], v[4:7]
	v_mfma_f32_16x16x32_bf16 v[0:3], v[222:225], v[206:209], v[0:3]
	s_setprio 0
	s_add_i32 s71, s71, 2
	s_add_u32 s30, s30, 0x100
	s_addc_u32 s31, s31, 0
	s_add_u32 s69, s69, 0x100
	s_addc_u32 s70, s70, 0
	s_cmp_gt_u32 s71, 29
	s_barrier
	s_cbranch_scc0 .LBB0_1089
	v_lshl_add_u32 v162, s28, 8, v151
	v_lshl_or_b32 v164, s66, 8, v153
	v_ashrrev_i32_e32 v163, 31, v162
	v_ashrrev_i32_e32 v165, 31, v164
	v_lshlrev_b64 v[140:141], 11, v[162:163]
	v_lshl_add_u64 v[140:141], v[140:141], 0, v[164:165]
	v_lshlrev_b64 v[140:141], 2, v[140:141]
	v_lshl_add_u64 v[166:167], s[12:13], 0, v[140:141]
	global_load_dwordx4 v[158:161], v[166:167], off
	v_lshl_add_u64 v[168:169], s[54:55], 0, v[140:141]
	s_and_b64 vcc, exec, s[4:5]
	s_mov_b32 s66, s20
	s_mov_b32 s28, s22
	s_mov_b64 s[36:37], s[26:27]
	s_mov_b64 s[30:31], s[24:25]
	s_waitcnt vmcnt(0)
	v_pk_add_f32 v[126:127], v[126:127], v[160:161]
	v_pk_add_f32 v[124:125], v[124:125], v[158:159]
	global_store_dwordx4 v[168:169], v[124:127], off
	global_load_dwordx4 v[124:127], v[166:167], off offset:64
	s_waitcnt vmcnt(0)
	v_pk_add_f32 v[122:123], v[122:123], v[126:127]
	v_pk_add_f32 v[120:121], v[120:121], v[124:125]
	global_store_dwordx4 v[168:169], v[120:123], off offset:64
	global_load_dwordx4 v[120:123], v[166:167], off offset:512
	s_waitcnt vmcnt(0)
	v_pk_add_f32 v[118:119], v[118:119], v[122:123]
	v_pk_add_f32 v[116:117], v[116:117], v[120:121]
	global_store_dwordx4 v[168:169], v[116:119], off offset:512
	global_load_dwordx4 v[116:119], v[166:167], off offset:576
	v_or_b32_e32 v120, 16, v162
	v_ashrrev_i32_e32 v121, 31, v120
	v_lshlrev_b64 v[120:121], 11, v[120:121]
	v_lshl_add_u64 v[120:121], v[120:121], 0, v[164:165]
	v_lshlrev_b64 v[120:121], 2, v[120:121]
	v_lshl_add_u64 v[122:123], s[12:13], 0, v[120:121]
	s_waitcnt vmcnt(0)
	v_pk_add_f32 v[110:111], v[110:111], v[118:119]
	v_pk_add_f32 v[108:109], v[108:109], v[116:117]
	global_store_dwordx4 v[168:169], v[108:111], off offset:576
	global_load_dwordx4 v[108:111], v[122:123], off
	v_lshl_add_u64 v[116:117], s[54:55], 0, v[120:121]
	s_waitcnt vmcnt(0)
	v_pk_add_f32 v[110:111], v[114:115], v[110:111]
	v_pk_add_f32 v[108:109], v[112:113], v[108:109]
	global_store_dwordx4 v[116:117], v[108:111], off
	global_load_dwordx4 v[108:111], v[122:123], off offset:64
	s_waitcnt vmcnt(0)
	v_pk_add_f32 v[106:107], v[106:107], v[110:111]
	v_pk_add_f32 v[104:105], v[104:105], v[108:109]
	global_store_dwordx4 v[116:117], v[104:107], off offset:64
	global_load_dwordx4 v[104:107], v[122:123], off offset:512
	s_waitcnt vmcnt(0)
; #define PG8_WAIT_V(n) asm volatile("s_waitcnt vmcnt(" #n ")" ::: "memory")
; #define PG8_BAR __builtin_amdgcn_s_barrier()
; template <class Epi>
; __device__ __forceinline__ void gemm_phase(LAS unsigned char* lds, const Gemm g, const StaticOrder& S, const Epi& E) {
;     ...
;         E(acc, cur, wr, wc, fr, fq);
;         if (!has_next) break;
; #pragma unroll
;         for (int a = 0; a < 2; ++a)
; #pragma unroll
;             for (int b = 0; b < 2; ++b)
; #pragma unroll
;                 for (int m = 0; m < 4; ++m)
; #pragma unroll
;                     for (int n = 0; n < 2; ++n) acc[a][b][m][n] = (f32x4){0.f, 0.f, 0.f, 0.f};
;         cur = nxt; cA = nA; cB = nB; ++ui;
;     }
;     PG8_WAIT_V(0);
;     if (wr == 0) PG8_BAR;
;     PG8_BAR;
;     __device__ __forceinline__ void operator()(const AccT& acc, const Unit& u, int wr, int wc, int fr, int fq) const {
;         const int row0 = u.pm * 256 + wr * 64 + fr, col0 = u.pn * 256 + wc * 32 + 4 * fq;
; #pragma unroll
;         for (int ai = 0; ai < 2; ++ai)
; #pragma unroll
;             for (int m = 0; m < 4; ++m) { const size_t ro = (size_t)(row0 + ai * 128 + m * 16) * DM + col0;
; #pragma unroll
;                 for (int bj = 0; bj < 2; ++bj)
; #pragma unroll
;                     for (int n = 0; n < 2; ++n) { const size_t o = ro + bj * 128 + n * 16; *(f32x4*)(H + o) = acc[ai][bj][m][n] + *(const f32x4*)(X + o); } asm volatile("" ::: "memory"); }
	v_pk_add_f32 v[102:103], v[102:103], v[106:107]
	v_pk_add_f32 v[100:101], v[100:101], v[104:105]
	global_store_dwordx4 v[116:117], v[100:103], off offset:512
	global_load_dwordx4 v[100:103], v[122:123], off offset:576
	v_or_b32_e32 v104, 32, v162
	v_ashrrev_i32_e32 v105, 31, v104
	v_lshlrev_b64 v[104:105], 11, v[104:105]
	v_lshl_add_u64 v[104:105], v[104:105], 0, v[164:165]
	v_lshlrev_b64 v[104:105], 2, v[104:105]
	v_lshl_add_u64 v[106:107], s[12:13], 0, v[104:105]
	s_waitcnt vmcnt(0)
	v_pk_add_f32 v[94:95], v[94:95], v[102:103]
	v_pk_add_f32 v[92:93], v[92:93], v[100:101]
	global_store_dwordx4 v[116:117], v[92:95], off offset:576
	global_load_dwordx4 v[92:95], v[106:107], off
	v_lshl_add_u64 v[100:101], s[54:55], 0, v[104:105]
	s_waitcnt vmcnt(0)
	v_pk_add_f32 v[94:95], v[98:99], v[94:95]
	v_pk_add_f32 v[92:93], v[96:97], v[92:93]
	global_store_dwordx4 v[100:101], v[92:95], off
	global_load_dwordx4 v[92:95], v[106:107], off offset:64
	s_waitcnt vmcnt(0)
	v_pk_add_f32 v[90:91], v[90:91], v[94:95]
	v_pk_add_f32 v[88:89], v[88:89], v[92:93]
	global_store_dwordx4 v[100:101], v[88:91], off offset:64
	global_load_dwordx4 v[88:91], v[106:107], off offset:512
	s_waitcnt vmcnt(0)
	v_pk_add_f32 v[86:87], v[86:87], v[90:91]
	v_pk_add_f32 v[84:85], v[84:85], v[88:89]
	global_store_dwordx4 v[100:101], v[84:87], off offset:512
	global_load_dwordx4 v[84:87], v[106:107], off offset:576
	v_or_b32_e32 v88, 48, v162
	v_ashrrev_i32_e32 v89, 31, v88
	v_lshlrev_b64 v[88:89], 11, v[88:89]
	v_lshl_add_u64 v[88:89], v[88:89], 0, v[164:165]
	v_lshlrev_b64 v[88:89], 2, v[88:89]
	v_lshl_add_u64 v[90:91], s[12:13], 0, v[88:89]
	s_waitcnt vmcnt(0)
	v_pk_add_f32 v[78:79], v[78:79], v[86:87]
	v_pk_add_f32 v[76:77], v[76:77], v[84:85]
	global_store_dwordx4 v[100:101], v[76:79], off offset:576
	global_load_dwordx4 v[76:79], v[90:91], off
	v_lshl_add_u64 v[84:85], s[54:55], 0, v[88:89]
	s_waitcnt vmcnt(0)
	v_pk_add_f32 v[78:79], v[82:83], v[78:79]
	v_pk_add_f32 v[76:77], v[80:81], v[76:77]
	global_store_dwordx4 v[84:85], v[76:79], off
	global_load_dwordx4 v[76:79], v[90:91], off offset:64
	s_waitcnt vmcnt(0)
	v_pk_add_f32 v[74:75], v[74:75], v[78:79]
	v_pk_add_f32 v[72:73], v[72:73], v[76:77]
	global_store_dwordx4 v[84:85], v[72:75], off offset:64
	global_load_dwordx4 v[72:75], v[90:91], off offset:512
	s_waitcnt vmcnt(0)
	v_pk_add_f32 v[70:71], v[70:71], v[74:75]
	v_pk_add_f32 v[68:69], v[68:69], v[72:73]
	global_store_dwordx4 v[84:85], v[68:71], off offset:512
	global_load_dwordx4 v[68:71], v[90:91], off offset:576
	v_lshl_add_u64 v[72:73], v[140:141], 0, s[8:9]
	v_lshl_add_u64 v[74:75], s[12:13], 0, v[72:73]
	s_waitcnt vmcnt(0)
	v_pk_add_f32 v[66:67], v[66:67], v[70:71]
	v_pk_add_f32 v[64:65], v[64:65], v[68:69]
	global_store_dwordx4 v[84:85], v[64:67], off offset:576
	global_load_dwordx4 v[64:67], v[74:75], off
	v_lshl_add_u64 v[68:69], s[54:55], 0, v[72:73]
	s_waitcnt vmcnt(0)
	v_pk_add_f32 v[62:63], v[62:63], v[66:67]
	v_pk_add_f32 v[60:61], v[60:61], v[64:65]
	global_store_dwordx4 v[68:69], v[60:63], off
	global_load_dwordx4 v[60:63], v[74:75], off offset:64
	s_waitcnt vmcnt(0)
	v_pk_add_f32 v[58:59], v[58:59], v[62:63]
	v_pk_add_f32 v[56:57], v[56:57], v[60:61]
	global_store_dwordx4 v[68:69], v[56:59], off offset:64
	global_load_dwordx4 v[56:59], v[74:75], off offset:512
	s_waitcnt vmcnt(0)
	v_pk_add_f32 v[54:55], v[54:55], v[58:59]
	v_pk_add_f32 v[52:53], v[52:53], v[56:57]
	global_store_dwordx4 v[68:69], v[52:55], off offset:512
	global_load_dwordx4 v[52:55], v[74:75], off offset:576
	v_lshl_add_u64 v[56:57], v[140:141], 0, s[14:15]
	v_lshl_add_u64 v[58:59], s[12:13], 0, v[56:57]
	s_waitcnt vmcnt(0)
	v_pk_add_f32 v[42:43], v[42:43], v[54:55]
	v_pk_add_f32 v[40:41], v[40:41], v[52:53]
	global_store_dwordx4 v[68:69], v[40:43], off offset:576
	global_load_dwordx4 v[40:43], v[58:59], off
	v_lshl_add_u64 v[52:53], s[54:55], 0, v[56:57]
	s_waitcnt vmcnt(0)
	v_pk_add_f32 v[42:43], v[50:51], v[42:43]
	v_pk_add_f32 v[40:41], v[48:49], v[40:41]
	global_store_dwordx4 v[52:53], v[40:43], off
	global_load_dwordx4 v[40:43], v[58:59], off offset:64
	s_waitcnt vmcnt(0)
	v_pk_add_f32 v[42:43], v[46:47], v[42:43]
	v_pk_add_f32 v[40:41], v[44:45], v[40:41]
	global_store_dwordx4 v[52:53], v[40:43], off offset:64
	global_load_dwordx4 v[40:43], v[58:59], off offset:512
	s_waitcnt vmcnt(0)
	v_pk_add_f32 v[38:39], v[38:39], v[42:43]
	v_pk_add_f32 v[36:37], v[36:37], v[40:41]
	global_store_dwordx4 v[52:53], v[36:39], off offset:512
	global_load_dwordx4 v[36:39], v[58:59], off offset:576
	v_lshl_add_u64 v[40:41], v[140:141], 0, s[16:17]
	v_lshl_add_u64 v[42:43], s[12:13], 0, v[40:41]
	s_waitcnt vmcnt(0)
	v_pk_add_f32 v[26:27], v[26:27], v[38:39]
	v_pk_add_f32 v[24:25], v[24:25], v[36:37]
	global_store_dwordx4 v[52:53], v[24:27], off offset:576
	global_load_dwordx4 v[24:27], v[42:43], off
	v_lshl_add_u64 v[36:37], s[54:55], 0, v[40:41]
	s_waitcnt vmcnt(0)
	v_pk_add_f32 v[26:27], v[34:35], v[26:27]
	v_pk_add_f32 v[24:25], v[32:33], v[24:25]
	global_store_dwordx4 v[36:37], v[24:27], off
	global_load_dwordx4 v[24:27], v[42:43], off offset:64
	s_waitcnt vmcnt(0)
	v_pk_add_f32 v[26:27], v[30:31], v[26:27]
	v_pk_add_f32 v[24:25], v[28:29], v[24:25]
	global_store_dwordx4 v[36:37], v[24:27], off offset:64
	global_load_dwordx4 v[24:27], v[42:43], off offset:512
	s_waitcnt vmcnt(0)
	v_pk_add_f32 v[22:23], v[22:23], v[26:27]
	v_pk_add_f32 v[20:21], v[20:21], v[24:25]
	global_store_dwordx4 v[36:37], v[20:23], off offset:512
	global_load_dwordx4 v[20:23], v[42:43], off offset:576
	v_lshl_add_u64 v[24:25], v[140:141], 0, s[18:19]
	v_lshl_add_u64 v[26:27], s[12:13], 0, v[24:25]
	s_waitcnt vmcnt(0)
	v_pk_add_f32 v[10:11], v[10:11], v[22:23]
	v_pk_add_f32 v[8:9], v[8:9], v[20:21]
	global_store_dwordx4 v[36:37], v[8:11], off offset:576
	global_load_dwordx4 v[8:11], v[26:27], off
	v_lshl_add_u64 v[20:21], s[54:55], 0, v[24:25]
	s_waitcnt vmcnt(0)
	v_pk_add_f32 v[10:11], v[18:19], v[10:11]
	v_pk_add_f32 v[8:9], v[16:17], v[8:9]
	global_store_dwordx4 v[20:21], v[8:11], off
	global_load_dwordx4 v[8:11], v[26:27], off offset:64
	s_waitcnt vmcnt(0)
	v_pk_add_f32 v[10:11], v[14:15], v[10:11]
	v_pk_add_f32 v[8:9], v[12:13], v[8:9]
	global_store_dwordx4 v[20:21], v[8:11], off offset:64
	global_load_dwordx4 v[8:11], v[26:27], off offset:512
	s_waitcnt vmcnt(0)
	v_pk_add_f32 v[6:7], v[6:7], v[10:11]
	v_pk_add_f32 v[4:5], v[4:5], v[8:9]
	global_store_dwordx4 v[20:21], v[4:7], off offset:512
	global_load_dwordx4 v[4:7], v[26:27], off offset:576
	s_waitcnt vmcnt(0)
	v_pk_add_f32 v[2:3], v[2:3], v[6:7]
	v_pk_add_f32 v[0:1], v[0:1], v[4:5]
	global_store_dwordx4 v[20:21], v[0:3], off offset:576
	s_cbranch_vccz .LBB0_1082
	s_waitcnt vmcnt(0)
	s_cmpk_gt_u32 s3, 0xff
	s_cbranch_scc1 .LBB0_1093
	s_barrier

; #define PG8_STAGE(bufoff, gbase, voff) do { _Pragma("unroll") for (int _i = 0; _i < 2; ++_i) \
;         __builtin_amdgcn_global_load_lds((const unsigned*)((const char*)(gbase) + (voff)[_i]), (LAS unsigned*)(lds + (bufoff) + ldsw + _i * 8192), 16, 0, 0); } while (0)
; #define PG8_LDA(dst, b, h) do { _Pragma("unroll") for (int m = 0; m < 4; ++m) _Pragma("unroll") for (int k = 0; k < 2; ++k) dst[m][k] = *(const LAS bf16x8*)(lds + PG8_SA(b, h) + aoff + m * 2048 + k * 1024); } while (0)
; #define PG8_LDB(dst, b, h) do { _Pragma("unroll") for (int n = 0; n < 2; ++n) _Pragma("unroll") for (int k = 0; k < 2; ++k) dst[n][k] = *(const LAS bf16x8*)(lds + PG8_SB(b, h) + boff + n * 2048 + k * 1024); } while (0)
; #define PG8_MMA(ai, bj, At, Bt) do { __builtin_amdgcn_s_setprio(1); _Pragma("unroll") for (int m = 0; m < 4; ++m) _Pragma("unroll") for (int n = 0; n < 2; ++n) _Pragma("unroll") for (int k = 0; k < 2; ++k) \
;         acc[ai][bj][m][n] = __builtin_amdgcn_mfma_f32_16x16x32_bf16(Bt[n][k], At[m][k], acc[ai][bj][m][n], 0, 0, 0); __builtin_amdgcn_s_setprio(0); } while (0)
; #define PG8_WAIT_L(n) asm volatile("s_waitcnt lgkmcnt(" #n ")" ::: "memory")
; #define PG8_BAR __builtin_amdgcn_s_barrier()
; #define PG8_SCHED __builtin_amdgcn_sched_barrier(0)
; template <class Epi>
; __device__ __forceinline__ void gemm_phase(LAS unsigned char* lds, const Gemm g, const StaticOrder& S, const Epi& E) {
;     ...
;             PG8_LDB(B0, 0, 0); PG8_SCHED; PG8_LDA(At, 0, 0); PG8_STAGE(PG8_SA(1, 1), a1 + hstepA, voffA);
;             PG8_WAIT_L(8); PG8_BAR; PG8_WAIT_L(0); PG8_MMA(0, 0, At, B0); PG8_BAR; PG8_SCHED;
;             PG8_LDB(B1, 0, 1); PG8_STAGE(PG8_SB(0, 0), b2, voffB);
;             PG8_BAR; PG8_WAIT_L(0); PG8_MMA(0, 1, At, B1); PG8_BAR;
;             PG8_LDA(At, 0, 1); PG8_STAGE(PG8_SA(0, 0), a2, voffA);
;             PG8_BAR; PG8_WAIT_L(0); PG8_MMA(1, 0, At, B0); PG8_BAR; PG8_SCHED;
.LBB0_1103:
	s_ashr_i32 s27, s26, 31
	s_lshl_b64 s[28:29], s[26:27], 17
	s_add_u32 s28, s47, s28
	v_cmp_lt_i64_e32 vcc, s[22:23], v[48:49]
	s_addc_u32 s29, s48, s29
	ds_read_b128 v[0:3], v57
	ds_read_b128 v[4:7], v57 offset:1024
	ds_read_b128 v[8:11], v57 offset:2048
	ds_read_b128 v[12:15], v57 offset:3072
	s_and_b64 s[30:31], vcc, exec
	s_cselect_b32 s45, s29, s39
	s_cselect_b32 s44, s28, s38
	s_ashr_i32 s25, s24, 31
	s_lshl_b64 s[30:31], s[24:25], 17
	s_add_u32 s30, s49, s30
	s_addc_u32 s31, s50, s31
	s_and_b64 s[42:43], vcc, exec
	s_cselect_b32 s43, s31, s41
	s_cselect_b32 s42, s30, s40
	s_add_u32 s78, s38, 0x10080
	s_addc_u32 s79, s39, 0
	s_add_i32 s80, s37, 0xc000
	v_lshl_add_u64 v[52:53], s[78:79], 0, v[40:41]
	s_mov_b32 m0, s80
	s_add_i32 s3, s37, 0xe000
	ds_read_b128 v[16:19], v58
	ds_read_b128 v[20:23], v58 offset:1024
	ds_read_b128 v[24:27], v58 offset:2048
	ds_read_b128 v[28:31], v58 offset:3072
	ds_read_b128 v[32:35], v58 offset:4096
	ds_read_b128 v[36:39], v58 offset:5120
	ds_read_b128 v[60:63], v58 offset:6144
	ds_read_b128 v[64:67], v58 offset:7168
	global_load_lds_dwordx4 v[52:53], off
	v_lshl_add_u64 v[52:53], s[78:79], 0, v[44:45]
	s_mov_b32 m0, s3
	s_nop 0
	global_load_lds_dwordx4 v[52:53], off
	s_waitcnt lgkmcnt(8)
	s_barrier
	s_setprio 1
	s_waitcnt lgkmcnt(12)
	s_waitcnt lgkmcnt(7)
	v_mfma_f32_16x16x32_bf16 v[68:71], v[0:3], v[16:19], 0
	v_mfma_f32_16x16x32_bf16 v[72:75], v[8:11], v[16:19], 0
	s_waitcnt lgkmcnt(5)
	v_mfma_f32_16x16x32_bf16 v[76:79], v[0:3], v[24:27], 0
	v_mfma_f32_16x16x32_bf16 v[80:83], v[8:11], v[24:27], 0
	s_waitcnt lgkmcnt(3)
	v_mfma_f32_16x16x32_bf16 v[84:87], v[0:3], v[32:35], 0
	v_mfma_f32_16x16x32_bf16 v[88:91], v[8:11], v[32:35], 0
	s_waitcnt lgkmcnt(1)
	v_mfma_f32_16x16x32_bf16 v[92:95], v[0:3], v[60:63], 0
	v_mfma_f32_16x16x32_bf16 v[96:99], v[8:11], v[60:63], 0
	v_mfma_f32_16x16x32_bf16 v[68:71], v[4:7], v[20:23], v[68:71]
	v_mfma_f32_16x16x32_bf16 v[72:75], v[12:15], v[20:23], v[72:75]
	v_mfma_f32_16x16x32_bf16 v[76:79], v[4:7], v[28:31], v[76:79]
	v_mfma_f32_16x16x32_bf16 v[80:83], v[12:15], v[28:31], v[80:83]
	v_mfma_f32_16x16x32_bf16 v[84:87], v[4:7], v[36:39], v[84:87]
	v_mfma_f32_16x16x32_bf16 v[88:91], v[12:15], v[36:39], v[88:91]
	s_waitcnt lgkmcnt(0)
	v_mfma_f32_16x16x32_bf16 v[92:95], v[4:7], v[64:67], v[92:95]
	v_mfma_f32_16x16x32_bf16 v[96:99], v[12:15], v[64:67], v[96:99]
	s_setprio 0
	s_barrier
	v_lshl_add_u64 v[52:53], s[40:41], 0, v[42:43]
	s_add_i32 s77, s70, s51
	v_lshl_add_u64 v[116:117], v[52:53], 0, s[8:9]
	s_mov_b32 m0, s77
	v_lshl_add_u64 v[186:187], s[40:41], 0, v[46:47]
	s_add_i32 s25, s77, 0x2000
	ds_read_b128 v[100:103], v59
	ds_read_b128 v[104:107], v59 offset:1024
	ds_read_b128 v[108:111], v59 offset:2048
	ds_read_b128 v[112:115], v59 offset:3072
	global_load_lds_dwordx4 v[116:117], off
	v_lshl_add_u64 v[116:117], v[186:187], 0, s[8:9]
	s_mov_b32 m0, s25
	s_nop 0
	global_load_lds_dwordx4 v[116:117], off
	s_barrier
	s_setprio 1
	s_waitcnt lgkmcnt(3)
	v_mfma_f32_16x16x32_bf16 v[116:119], v[100:103], v[16:19], 0
	s_waitcnt lgkmcnt(1)
	v_mfma_f32_16x16x32_bf16 v[16:19], v[108:111], v[16:19], 0
	v_mfma_f32_16x16x32_bf16 v[116:119], v[104:107], v[20:23], v[116:119]
	s_waitcnt lgkmcnt(0)
	v_mfma_f32_16x16x32_bf16 v[16:19], v[112:115], v[20:23], v[16:19]
	v_mfma_f32_16x16x32_bf16 v[20:23], v[100:103], v[24:27], 0
	v_mfma_f32_16x16x32_bf16 v[24:27], v[108:111], v[24:27], 0
	v_mfma_f32_16x16x32_bf16 v[20:23], v[104:107], v[28:31], v[20:23]
	v_mfma_f32_16x16x32_bf16 v[24:27], v[112:115], v[28:31], v[24:27]
	v_mfma_f32_16x16x32_bf16 v[28:31], v[100:103], v[32:35], 0
	v_mfma_f32_16x16x32_bf16 v[32:35], v[108:111], v[32:35], 0
	v_mfma_f32_16x16x32_bf16 v[28:31], v[104:107], v[36:39], v[28:31]
	v_mfma_f32_16x16x32_bf16 v[32:35], v[112:115], v[36:39], v[32:35]
	v_mfma_f32_16x16x32_bf16 v[36:39], v[100:103], v[60:63], 0
	v_mfma_f32_16x16x32_bf16 v[60:63], v[108:111], v[60:63], 0
	v_mfma_f32_16x16x32_bf16 v[36:39], v[104:107], v[64:67], v[36:39]
	v_mfma_f32_16x16x32_bf16 v[60:63], v[112:115], v[64:67], v[60:63]
	s_setprio 0
	v_lshl_add_u64 v[188:189], s[38:39], 0, v[40:41]
	s_mov_b32 m0, s37
	v_lshl_add_u64 v[150:151], v[188:189], 0, s[8:9]
	v_lshl_add_u64 v[218:219], s[38:39], 0, v[44:45]
	s_barrier
	ds_read_b128 v[64:67], v58 offset:16384
	ds_read_b128 v[120:123], v58 offset:17408
	ds_read_b128 v[124:127], v58 offset:18432
	ds_read_b128 v[128:131], v58 offset:19456
	ds_read_b128 v[132:135], v58 offset:20480
	ds_read_b128 v[136:139], v58 offset:21504
	ds_read_b128 v[140:143], v58 offset:22528
	ds_read_b128 v[144:147], v58 offset:23552
	global_load_lds_dwordx4 v[150:151], off
	v_lshl_add_u64 v[150:151], v[218:219], 0, s[8:9]
	s_mov_b32 m0, s60
	s_nop 0
	global_load_lds_dwordx4 v[150:151], off
	s_barrier
	s_setprio 1
	s_waitcnt lgkmcnt(7)
	v_mfma_f32_16x16x32_bf16 v[150:153], v[0:3], v[64:67], 0
	s_waitcnt lgkmcnt(5)
	v_mfma_f32_16x16x32_bf16 v[158:161], v[0:3], v[124:127], 0
	s_waitcnt lgkmcnt(3)
	v_mfma_f32_16x16x32_bf16 v[166:169], v[0:3], v[132:135], 0
	s_waitcnt lgkmcnt(1)
	v_mfma_f32_16x16x32_bf16 v[0:3], v[0:3], v[140:143], 0
	v_mfma_f32_16x16x32_bf16 v[150:153], v[4:7], v[120:123], v[150:153]
	v_mfma_f32_16x16x32_bf16 v[154:157], v[8:11], v[64:67], 0
	v_mfma_f32_16x16x32_bf16 v[158:161], v[4:7], v[128:131], v[158:161]
	v_mfma_f32_16x16x32_bf16 v[162:165], v[8:11], v[124:127], 0
	v_mfma_f32_16x16x32_bf16 v[166:169], v[4:7], v[136:139], v[166:169]
	v_mfma_f32_16x16x32_bf16 v[170:173], v[8:11], v[132:135], 0
	s_waitcnt lgkmcnt(0)
	v_mfma_f32_16x16x32_bf16 v[0:3], v[4:7], v[144:147], v[0:3]
	v_mfma_f32_16x16x32_bf16 v[4:7], v[8:11], v[140:143], 0
	v_mfma_f32_16x16x32_bf16 v[154:157], v[12:15], v[120:123], v[154:157]
	v_mfma_f32_16x16x32_bf16 v[162:165], v[12:15], v[128:131], v[162:165]
	v_mfma_f32_16x16x32_bf16 v[170:173], v[12:15], v[136:139], v[170:173]
	v_mfma_f32_16x16x32_bf16 v[4:7], v[12:15], v[144:147], v[4:7]
	s_setprio 0
	s_barrier
; #define PG8_STAGE(bufoff, gbase, voff) do { _Pragma("unroll") for (int _i = 0; _i < 2; ++_i) \
;         __builtin_amdgcn_global_load_lds((const unsigned*)((const char*)(gbase) + (voff)[_i]), (LAS unsigned*)(lds + (bufoff) + ldsw + _i * 8192), 16, 0, 0); } while (0)
; #define PG8_LDA(dst, b, h) do { _Pragma("unroll") for (int m = 0; m < 4; ++m) _Pragma("unroll") for (int k = 0; k < 2; ++k) dst[m][k] = *(const LAS bf16x8*)(lds + PG8_SA(b, h) + aoff + m * 2048 + k * 1024); } while (0)
; #define PG8_LDB(dst, b, h) do { _Pragma("unroll") for (int n = 0; n < 2; ++n) _Pragma("unroll") for (int k = 0; k < 2; ++k) dst[n][k] = *(const LAS bf16x8*)(lds + PG8_SB(b, h) + boff + n * 2048 + k * 1024); } while (0)
; #define PG8_MMA(ai, bj, At, Bt) do { __builtin_amdgcn_s_setprio(1); _Pragma("unroll") for (int m = 0; m < 4; ++m) _Pragma("unroll") for (int n = 0; n < 2; ++n) _Pragma("unroll") for (int k = 0; k < 2; ++k) \
;         acc[ai][bj][m][n] = __builtin_amdgcn_mfma_f32_16x16x32_bf16(Bt[n][k], At[m][k], acc[ai][bj][m][n], 0, 0, 0); __builtin_amdgcn_s_setprio(0); } while (0)
; #define PG8_WAIT_V(n) asm volatile("s_waitcnt vmcnt(" #n ")" ::: "memory")
; #define PG8_WAIT_L(n) asm volatile("s_waitcnt lgkmcnt(" #n ")" ::: "memory")
; #define PG8_BAR __builtin_amdgcn_s_barrier()
; #define PG8_SCHED __builtin_amdgcn_sched_barrier(0)
; template <class Epi>
; __device__ __forceinline__ void gemm_phase(LAS unsigned char* lds, const Gemm g, const StaticOrder& S, const Epi& E) {
;     ...
;             PG8_STAGE(PG8_SB(0, 1), b2 + hstepB, voffB);
;             PG8_WAIT_V(6); PG8_BAR; PG8_MMA(1, 1, At, B1); PG8_BAR;
;             PG8_LDB(B0, 1, 0); PG8_SCHED; PG8_LDA(At, 1, 0); PG8_STAGE(PG8_SA(0, 1), a2 + hstepA, voffA);
;             PG8_WAIT_L(8); PG8_BAR; PG8_WAIT_L(0); PG8_MMA(0, 0, At, B0); PG8_BAR; PG8_SCHED;
;             PG8_LDB(B1, 1, 1); PG8_STAGE(PG8_SB(1, 0), b3, voffB);
;             PG8_BAR; PG8_WAIT_L(0); PG8_MMA(0, 1, At, B1); PG8_BAR;
	s_add_u32 s82, s40, 0x10100
	s_addc_u32 s83, s41, 0
	s_add_i32 s78, s71, s51
	v_lshl_add_u64 v[8:9], s[82:83], 0, v[42:43]
	s_mov_b32 m0, s78
	s_add_i32 s27, s78, 0x2000
	global_load_lds_dwordx4 v[8:9], off
	v_lshl_add_u64 v[8:9], s[82:83], 0, v[46:47]
	s_mov_b32 m0, s27
	s_nop 0
	global_load_lds_dwordx4 v[8:9], off
	s_waitcnt vmcnt(6)
	s_barrier
	s_setprio 1
	v_mfma_f32_16x16x32_bf16 v[8:11], v[100:103], v[64:67], 0
	v_mfma_f32_16x16x32_bf16 v[12:15], v[108:111], v[64:67], 0
	v_mfma_f32_16x16x32_bf16 v[8:11], v[104:107], v[120:123], v[8:11]
	v_mfma_f32_16x16x32_bf16 v[12:15], v[112:115], v[120:123], v[12:15]
	v_mfma_f32_16x16x32_bf16 v[64:67], v[100:103], v[124:127], 0
	v_mfma_f32_16x16x32_bf16 v[120:123], v[108:111], v[124:127], 0
	v_mfma_f32_16x16x32_bf16 v[124:127], v[100:103], v[132:135], 0
	v_mfma_f32_16x16x32_bf16 v[100:103], v[100:103], v[140:143], 0
	v_mfma_f32_16x16x32_bf16 v[64:67], v[104:107], v[128:131], v[64:67]
	v_mfma_f32_16x16x32_bf16 v[120:123], v[112:115], v[128:131], v[120:123]
	v_mfma_f32_16x16x32_bf16 v[124:127], v[104:107], v[136:139], v[124:127]
	v_mfma_f32_16x16x32_bf16 v[128:131], v[108:111], v[132:135], 0
	v_mfma_f32_16x16x32_bf16 v[100:103], v[104:107], v[144:147], v[100:103]
	v_mfma_f32_16x16x32_bf16 v[104:107], v[108:111], v[140:143], 0
	v_mfma_f32_16x16x32_bf16 v[128:131], v[112:115], v[136:139], v[128:131]
	v_mfma_f32_16x16x32_bf16 v[104:107], v[112:115], v[144:147], v[104:107]
	s_setprio 0
	s_add_i32 s81, 0, 0x18000
	v_add_u32_e32 v149, s81, v55
	s_barrier
	ds_read_b128 v[108:111], v149
	ds_read_b128 v[112:115], v149 offset:1024
	ds_read_b128 v[132:135], v149 offset:2048
	ds_read_b128 v[136:139], v149 offset:3072
	s_add_u32 s82, s38, 0x10100
	s_addc_u32 s83, s39, 0
	s_mov_b32 m0, s61
	v_lshl_add_u64 v[202:203], s[82:83], 0, v[40:41]
	ds_read_b128 v[140:143], v58 offset:32768
	ds_read_b128 v[144:147], v58 offset:33792
	ds_read_b128 v[174:177], v58 offset:34816
	ds_read_b128 v[178:181], v58 offset:35840
	ds_read_b128 v[182:185], v58 offset:36864
	ds_read_b128 v[190:193], v58 offset:37888
	ds_read_b128 v[194:197], v58 offset:38912
	ds_read_b128 v[198:201], v58 offset:39936
	global_load_lds_dwordx4 v[202:203], off
	v_lshl_add_u64 v[202:203], s[82:83], 0, v[44:45]
	s_mov_b32 m0, s64
	s_nop 0
	global_load_lds_dwordx4 v[202:203], off
	s_waitcnt lgkmcnt(8)
	s_barrier
	s_setprio 1
	s_waitcnt lgkmcnt(7)
	v_mfma_f32_16x16x32_bf16 v[68:71], v[108:111], v[140:143], v[68:71]
	v_mfma_f32_16x16x32_bf16 v[72:75], v[132:135], v[140:143], v[72:75]
	s_waitcnt lgkmcnt(5)
	v_mfma_f32_16x16x32_bf16 v[76:79], v[108:111], v[174:177], v[76:79]
	v_mfma_f32_16x16x32_bf16 v[80:83], v[132:135], v[174:177], v[80:83]
	s_waitcnt lgkmcnt(3)
	v_mfma_f32_16x16x32_bf16 v[84:87], v[108:111], v[182:185], v[84:87]
	v_mfma_f32_16x16x32_bf16 v[88:91], v[132:135], v[182:185], v[88:91]
	s_waitcnt lgkmcnt(1)
	v_mfma_f32_16x16x32_bf16 v[92:95], v[108:111], v[194:197], v[92:95]
	v_mfma_f32_16x16x32_bf16 v[96:99], v[132:135], v[194:197], v[96:99]
	v_mfma_f32_16x16x32_bf16 v[68:71], v[112:115], v[144:147], v[68:71]
	v_mfma_f32_16x16x32_bf16 v[72:75], v[136:139], v[144:147], v[72:75]
	v_mfma_f32_16x16x32_bf16 v[76:79], v[112:115], v[178:181], v[76:79]
	v_mfma_f32_16x16x32_bf16 v[80:83], v[136:139], v[178:181], v[80:83]
	v_mfma_f32_16x16x32_bf16 v[84:87], v[112:115], v[190:193], v[84:87]
	v_mfma_f32_16x16x32_bf16 v[88:91], v[136:139], v[190:193], v[88:91]
	s_waitcnt lgkmcnt(0)
	v_mfma_f32_16x16x32_bf16 v[92:95], v[112:115], v[198:201], v[92:95]
	v_mfma_f32_16x16x32_bf16 v[96:99], v[136:139], v[198:201], v[96:99]
	s_setprio 0
	s_barrier
	s_add_i32 s84, 0, 0x1c000
	s_add_i32 s81, s81, s51
	v_add_u32_e32 v220, s84, v55
	v_lshl_add_u64 v[52:53], v[52:53], 0, s[12:13]
	s_mov_b32 m0, s81
	s_add_i32 s79, s81, 0x2000
	ds_read_b128 v[202:205], v220
	ds_read_b128 v[206:209], v220 offset:1024
	ds_read_b128 v[210:213], v220 offset:2048
	ds_read_b128 v[214:217], v220 offset:3072
	global_load_lds_dwordx4 v[52:53], off
	v_lshl_add_u64 v[52:53], v[186:187], 0, s[12:13]
	s_mov_b32 m0, s79
	s_nop 0
	global_load_lds_dwordx4 v[52:53], off
	s_barrier
	s_setprio 1
	s_waitcnt lgkmcnt(3)
	v_mfma_f32_16x16x32_bf16 v[116:119], v[202:205], v[140:143], v[116:119]
	s_waitcnt lgkmcnt(1)
	v_mfma_f32_16x16x32_bf16 v[16:19], v[210:213], v[140:143], v[16:19]
	v_mfma_f32_16x16x32_bf16 v[20:23], v[202:205], v[174:177], v[20:23]
	v_mfma_f32_16x16x32_bf16 v[24:27], v[210:213], v[174:177], v[24:27]
	v_mfma_f32_16x16x32_bf16 v[28:31], v[202:205], v[182:185], v[28:31]
	v_mfma_f32_16x16x32_bf16 v[32:35], v[210:213], v[182:185], v[32:35]
	v_mfma_f32_16x16x32_bf16 v[36:39], v[202:205], v[194:197], v[36:39]
	v_mfma_f32_16x16x32_bf16 v[60:63], v[210:213], v[194:197], v[60:63]
	v_mfma_f32_16x16x32_bf16 v[116:119], v[206:209], v[144:147], v[116:119]
	s_waitcnt lgkmcnt(0)
	v_mfma_f32_16x16x32_bf16 v[16:19], v[214:217], v[144:147], v[16:19]
	v_mfma_f32_16x16x32_bf16 v[20:23], v[206:209], v[178:181], v[20:23]
	v_mfma_f32_16x16x32_bf16 v[24:27], v[214:217], v[178:181], v[24:27]
	v_mfma_f32_16x16x32_bf16 v[28:31], v[206:209], v[190:193], v[28:31]
	v_mfma_f32_16x16x32_bf16 v[32:35], v[214:217], v[190:193], v[32:35]
	v_mfma_f32_16x16x32_bf16 v[36:39], v[206:209], v[198:201], v[36:39]
	v_mfma_f32_16x16x32_bf16 v[60:63], v[214:217], v[198:201], v[60:63]
	s_setprio 0
	s_mov_b32 m0, s65
	v_lshl_add_u64 v[52:53], v[188:189], 0, s[12:13]
	s_barrier
	ds_read_b128 v[140:143], v58 offset:49152
	ds_read_b128 v[144:147], v58 offset:50176
	ds_read_b128 v[174:177], v58 offset:51200
	ds_read_b128 v[178:181], v58 offset:52224
	ds_read_b128 v[182:185], v58 offset:53248
	ds_read_b128 v[190:193], v58 offset:54272
	ds_read_b128 v[194:197], v58 offset:55296
	ds_read_b128 v[198:201], v58 offset:56320
	global_load_lds_dwordx4 v[52:53], off
	v_lshl_add_u64 v[52:53], v[218:219], 0, s[12:13]
	s_mov_b32 m0, s66
	s_nop 0
	global_load_lds_dwordx4 v[52:53], off
	s_barrier
; #define PG8_STAGE(bufoff, gbase, voff) do { _Pragma("unroll") for (int _i = 0; _i < 2; ++_i) \
;         __builtin_amdgcn_global_load_lds((const unsigned*)((const char*)(gbase) + (voff)[_i]), (LAS unsigned*)(lds + (bufoff) + ldsw + _i * 8192), 16, 0, 0); } while (0)
; #define PG8_LDA(dst, b, h) do { _Pragma("unroll") for (int m = 0; m < 4; ++m) _Pragma("unroll") for (int k = 0; k < 2; ++k) dst[m][k] = *(const LAS bf16x8*)(lds + PG8_SA(b, h) + aoff + m * 2048 + k * 1024); } while (0)
; #define PG8_LDB(dst, b, h) do { _Pragma("unroll") for (int n = 0; n < 2; ++n) _Pragma("unroll") for (int k = 0; k < 2; ++k) dst[n][k] = *(const LAS bf16x8*)(lds + PG8_SB(b, h) + boff + n * 2048 + k * 1024); } while (0)
; #define PG8_WAIT_V(n) asm volatile("s_waitcnt vmcnt(" #n ")" ::: "memory")
; #define PG8_WAIT_L(n) asm volatile("s_waitcnt lgkmcnt(" #n ")" ::: "memory")
; #define PG8_BAR __builtin_amdgcn_s_barrier()
; #define PG8_SCHED __builtin_amdgcn_sched_barrier(0)
; template <class Epi>
; __device__ __forceinline__ void gemm_phase(LAS unsigned char* lds, const Gemm g, const StaticOrder& S, const Epi& E) {
;     ...
;             PG8_LDB(B0, 0, 0); PG8_SCHED; PG8_LDA(At, 0, 0); PG8_STAGE(PG8_SA(1, 1), a1 + hstepA, voffA);
;             PG8_WAIT_L(8); PG8_BAR; PG8_WAIT_L(0); PG8_MMA(0, 0, At, B0); PG8_BAR; PG8_SCHED;
;             PG8_LDB(B1, 0, 1); PG8_STAGE(PG8_SB(0, 0), b2, voffB);
;             PG8_BAR; PG8_WAIT_L(0); PG8_MMA(0, 1, At, B1); PG8_BAR;
;             PG8_LDA(At, 0, 1); PG8_STAGE(PG8_SA(0, 0), a2, voffA);
;             PG8_BAR; PG8_WAIT_L(0); PG8_MMA(1, 0, At, B0); PG8_BAR; PG8_SCHED;
;             PG8_STAGE(PG8_SB(0, 1), b2 + hstepB, voffB);
;             PG8_WAIT_V(6); PG8_BAR; PG8_MMA(1, 1, At, B1); PG8_BAR;
;             PG8_LDB(B0, 1, 0); PG8_SCHED; PG8_LDA(At, 1, 0); PG8_STAGE(PG8_SA(0, 1), a2 + hstepA, voffA);
;             PG8_WAIT_L(8); PG8_BAR; PG8_WAIT_L(0); PG8_MMA(0, 0, At, B0); PG8_BAR; PG8_SCHED;
;             PG8_LDB(B1, 1, 1); PG8_STAGE(PG8_SB(1, 0), b3, voffB);
;             PG8_BAR; PG8_WAIT_L(0); PG8_MMA(0, 1, At, B1); PG8_BAR;
;             PG8_LDA(At, 1, 1); PG8_STAGE(PG8_SA(1, 0), a3, voffA);
;             PG8_BAR; PG8_WAIT_L(0); PG8_MMA(1, 0, At, B0); PG8_BAR; PG8_SCHED;
;             PG8_STAGE(PG8_SB(1, 1), b3 + hstepB, voffB);
;             PG8_WAIT_V(6); PG8_BAR; PG8_MMA(1, 1, At, B1); PG8_BAR;
	s_setprio 1
	s_waitcnt lgkmcnt(7)
	v_mfma_f32_16x16x32_bf16 v[150:153], v[108:111], v[140:143], v[150:153]
	v_mfma_f32_16x16x32_bf16 v[154:157], v[132:135], v[140:143], v[154:157]
	s_waitcnt lgkmcnt(5)
	v_mfma_f32_16x16x32_bf16 v[158:161], v[108:111], v[174:177], v[158:161]
	v_mfma_f32_16x16x32_bf16 v[162:165], v[132:135], v[174:177], v[162:165]
	s_waitcnt lgkmcnt(3)
	v_mfma_f32_16x16x32_bf16 v[166:169], v[108:111], v[182:185], v[166:169]
	v_mfma_f32_16x16x32_bf16 v[170:173], v[132:135], v[182:185], v[170:173]
	s_waitcnt lgkmcnt(1)
	v_mfma_f32_16x16x32_bf16 v[0:3], v[108:111], v[194:197], v[0:3]
	v_mfma_f32_16x16x32_bf16 v[4:7], v[132:135], v[194:197], v[4:7]
	v_mfma_f32_16x16x32_bf16 v[150:153], v[112:115], v[144:147], v[150:153]
	v_mfma_f32_16x16x32_bf16 v[154:157], v[136:139], v[144:147], v[154:157]
	v_mfma_f32_16x16x32_bf16 v[158:161], v[112:115], v[178:181], v[158:161]
	v_mfma_f32_16x16x32_bf16 v[162:165], v[136:139], v[178:181], v[162:165]
	v_mfma_f32_16x16x32_bf16 v[166:169], v[112:115], v[190:193], v[166:169]
	v_mfma_f32_16x16x32_bf16 v[170:173], v[136:139], v[190:193], v[170:173]
	s_waitcnt lgkmcnt(0)
	v_mfma_f32_16x16x32_bf16 v[0:3], v[112:115], v[198:201], v[0:3]
	v_mfma_f32_16x16x32_bf16 v[4:7], v[136:139], v[198:201], v[4:7]
	s_setprio 0
	s_barrier
	s_add_u32 s82, s40, 0x10180
	s_addc_u32 s83, s41, 0
	s_add_i32 s41, s84, s51
	v_lshl_add_u64 v[52:53], s[82:83], 0, v[42:43]
	s_mov_b32 m0, s41
	s_add_i32 s40, s41, 0x2000
	global_load_lds_dwordx4 v[52:53], off
	v_lshl_add_u64 v[52:53], s[82:83], 0, v[46:47]
	s_mov_b32 m0, s40
	s_nop 0
	global_load_lds_dwordx4 v[52:53], off
	s_waitcnt vmcnt(6)
	s_barrier
	s_setprio 1
	v_mfma_f32_16x16x32_bf16 v[8:11], v[202:205], v[140:143], v[8:11]
	v_mfma_f32_16x16x32_bf16 v[12:15], v[210:213], v[140:143], v[12:15]
	v_mfma_f32_16x16x32_bf16 v[64:67], v[202:205], v[174:177], v[64:67]
	v_mfma_f32_16x16x32_bf16 v[108:111], v[210:213], v[174:177], v[120:123]
	v_mfma_f32_16x16x32_bf16 v[112:115], v[202:205], v[182:185], v[124:127]
	v_mfma_f32_16x16x32_bf16 v[120:123], v[210:213], v[182:185], v[128:131]
	v_mfma_f32_16x16x32_bf16 v[100:103], v[202:205], v[194:197], v[100:103]
	v_mfma_f32_16x16x32_bf16 v[104:107], v[210:213], v[194:197], v[104:107]
	v_mfma_f32_16x16x32_bf16 v[8:11], v[206:209], v[144:147], v[8:11]
	v_mfma_f32_16x16x32_bf16 v[12:15], v[214:217], v[144:147], v[12:15]
	v_mfma_f32_16x16x32_bf16 v[64:67], v[206:209], v[178:181], v[64:67]
	v_mfma_f32_16x16x32_bf16 v[108:111], v[214:217], v[178:181], v[108:111]
	v_mfma_f32_16x16x32_bf16 v[112:115], v[206:209], v[190:193], v[112:115]
	v_mfma_f32_16x16x32_bf16 v[120:123], v[214:217], v[190:193], v[120:123]
	v_mfma_f32_16x16x32_bf16 v[100:103], v[206:209], v[198:201], v[100:103]
	v_mfma_f32_16x16x32_bf16 v[104:107], v[214:217], v[198:201], v[104:107]
	s_setprio 0
	s_barrier
	ds_read_b128 v[124:127], v57
	ds_read_b128 v[128:131], v57 offset:1024
	ds_read_b128 v[132:135], v57 offset:2048
	ds_read_b128 v[136:139], v57 offset:3072
	s_add_u32 s38, s38, 0x10180
	s_addc_u32 s39, s39, 0
	s_mov_b32 m0, s80
	v_lshl_add_u64 v[52:53], s[38:39], 0, v[40:41]
	ds_read_b128 v[140:143], v58
	ds_read_b128 v[144:147], v58 offset:1024
	ds_read_b128 v[174:177], v58 offset:2048
	ds_read_b128 v[178:181], v58 offset:3072
	ds_read_b128 v[182:185], v58 offset:4096
	ds_read_b128 v[190:193], v58 offset:5120
	ds_read_b128 v[194:197], v58 offset:6144
	ds_read_b128 v[198:201], v58 offset:7168
	global_load_lds_dwordx4 v[52:53], off
	v_lshl_add_u64 v[52:53], s[38:39], 0, v[44:45]
	s_mov_b32 m0, s3
	s_nop 0
	global_load_lds_dwordx4 v[52:53], off
	s_waitcnt lgkmcnt(8)
	s_barrier
	s_setprio 1
	s_waitcnt lgkmcnt(7)
	v_mfma_f32_16x16x32_bf16 v[68:71], v[124:127], v[140:143], v[68:71]
	v_mfma_f32_16x16x32_bf16 v[72:75], v[132:135], v[140:143], v[72:75]
	s_waitcnt lgkmcnt(5)
	v_mfma_f32_16x16x32_bf16 v[76:79], v[124:127], v[174:177], v[76:79]
	v_mfma_f32_16x16x32_bf16 v[80:83], v[132:135], v[174:177], v[80:83]
	s_waitcnt lgkmcnt(3)
	v_mfma_f32_16x16x32_bf16 v[84:87], v[124:127], v[182:185], v[84:87]
	v_mfma_f32_16x16x32_bf16 v[88:91], v[132:135], v[182:185], v[88:91]
	s_waitcnt lgkmcnt(1)
	v_mfma_f32_16x16x32_bf16 v[92:95], v[124:127], v[194:197], v[92:95]
	v_mfma_f32_16x16x32_bf16 v[96:99], v[132:135], v[194:197], v[96:99]
	v_mfma_f32_16x16x32_bf16 v[68:71], v[128:131], v[144:147], v[68:71]
	v_mfma_f32_16x16x32_bf16 v[72:75], v[136:139], v[144:147], v[72:75]
	v_mfma_f32_16x16x32_bf16 v[76:79], v[128:131], v[178:181], v[76:79]
	v_mfma_f32_16x16x32_bf16 v[80:83], v[136:139], v[178:181], v[80:83]
	v_mfma_f32_16x16x32_bf16 v[84:87], v[128:131], v[190:193], v[84:87]
	v_mfma_f32_16x16x32_bf16 v[88:91], v[136:139], v[190:193], v[88:91]
	s_waitcnt lgkmcnt(0)
	v_mfma_f32_16x16x32_bf16 v[92:95], v[128:131], v[198:201], v[92:95]
	v_mfma_f32_16x16x32_bf16 v[96:99], v[136:139], v[198:201], v[96:99]
	s_setprio 0
	s_barrier
	s_mov_b32 m0, s77
	v_lshl_add_u64 v[52:53], s[42:43], 0, v[42:43]
	ds_read_b128 v[202:205], v59
	ds_read_b128 v[206:209], v59 offset:1024
	ds_read_b128 v[210:213], v59 offset:2048
	ds_read_b128 v[214:217], v59 offset:3072
	global_load_lds_dwordx4 v[52:53], off
	v_lshl_add_u64 v[186:187], s[42:43], 0, v[46:47]
	s_mov_b32 m0, s25
	s_nop 0
	global_load_lds_dwordx4 v[186:187], off
	s_barrier
; #define PG8_STAGE(bufoff, gbase, voff) do { _Pragma("unroll") for (int _i = 0; _i < 2; ++_i) \
;         __builtin_amdgcn_global_load_lds((const unsigned*)((const char*)(gbase) + (voff)[_i]), (LAS unsigned*)(lds + (bufoff) + ldsw + _i * 8192), 16, 0, 0); } while (0)
; #define PG8_LDA(dst, b, h) do { _Pragma("unroll") for (int m = 0; m < 4; ++m) _Pragma("unroll") for (int k = 0; k < 2; ++k) dst[m][k] = *(const LAS bf16x8*)(lds + PG8_SA(b, h) + aoff + m * 2048 + k * 1024); } while (0)
; #define PG8_LDB(dst, b, h) do { _Pragma("unroll") for (int n = 0; n < 2; ++n) _Pragma("unroll") for (int k = 0; k < 2; ++k) dst[n][k] = *(const LAS bf16x8*)(lds + PG8_SB(b, h) + boff + n * 2048 + k * 1024); } while (0)
; #define PG8_MMA(ai, bj, At, Bt) do { __builtin_amdgcn_s_setprio(1); _Pragma("unroll") for (int m = 0; m < 4; ++m) _Pragma("unroll") for (int n = 0; n < 2; ++n) _Pragma("unroll") for (int k = 0; k < 2; ++k) \
;         acc[ai][bj][m][n] = __builtin_amdgcn_mfma_f32_16x16x32_bf16(Bt[n][k], At[m][k], acc[ai][bj][m][n], 0, 0, 0); __builtin_amdgcn_s_setprio(0); } while (0)
; #define PG8_WAIT_V(n) asm volatile("s_waitcnt vmcnt(" #n ")" ::: "memory")
; #define PG8_WAIT_L(n) asm volatile("s_waitcnt lgkmcnt(" #n ")" ::: "memory")
; #define PG8_BAR __builtin_amdgcn_s_barrier()
; #define PG8_SCHED __builtin_amdgcn_sched_barrier(0)
; template <class Epi>
; __device__ __forceinline__ void gemm_phase(LAS unsigned char* lds, const Gemm g, const StaticOrder& S, const Epi& E) {
;     ...
;             PG8_LDB(B0, 0, 0); PG8_SCHED; PG8_LDA(At, 0, 0); PG8_STAGE(PG8_SA(1, 1), a1 + hstepA, voffA);
;             PG8_WAIT_L(8); PG8_BAR; PG8_WAIT_L(0); PG8_MMA(0, 0, At, B0); PG8_BAR; PG8_SCHED;
;             PG8_LDB(B1, 0, 1); PG8_STAGE(PG8_SB(0, 0), b2, voffB);
;             PG8_BAR; PG8_WAIT_L(0); PG8_MMA(0, 1, At, B1); PG8_BAR;
;             PG8_LDA(At, 0, 1); PG8_STAGE(PG8_SA(0, 0), a2, voffA);
;             PG8_BAR; PG8_WAIT_L(0); PG8_MMA(1, 0, At, B0); PG8_BAR; PG8_SCHED;
;             PG8_STAGE(PG8_SB(0, 1), b2 + hstepB, voffB);
;             PG8_WAIT_V(6); PG8_BAR; PG8_MMA(1, 1, At, B1); PG8_BAR;
;             PG8_LDB(B0, 1, 0); PG8_SCHED; PG8_LDA(At, 1, 0); PG8_STAGE(PG8_SA(0, 1), a2 + hstepA, voffA);
;             PG8_WAIT_L(8); PG8_BAR; PG8_WAIT_L(0); PG8_MMA(0, 0, At, B0); PG8_BAR; PG8_SCHED;
	s_setprio 1
	s_waitcnt lgkmcnt(3)
	v_mfma_f32_16x16x32_bf16 v[116:119], v[202:205], v[140:143], v[116:119]
	s_waitcnt lgkmcnt(1)
	v_mfma_f32_16x16x32_bf16 v[16:19], v[210:213], v[140:143], v[16:19]
	v_mfma_f32_16x16x32_bf16 v[20:23], v[202:205], v[174:177], v[20:23]
	v_mfma_f32_16x16x32_bf16 v[24:27], v[210:213], v[174:177], v[24:27]
	v_mfma_f32_16x16x32_bf16 v[28:31], v[202:205], v[182:185], v[28:31]
	v_mfma_f32_16x16x32_bf16 v[32:35], v[210:213], v[182:185], v[32:35]
	v_mfma_f32_16x16x32_bf16 v[36:39], v[202:205], v[194:197], v[36:39]
	v_mfma_f32_16x16x32_bf16 v[60:63], v[210:213], v[194:197], v[60:63]
	v_mfma_f32_16x16x32_bf16 v[116:119], v[206:209], v[144:147], v[116:119]
	s_waitcnt lgkmcnt(0)
	v_mfma_f32_16x16x32_bf16 v[16:19], v[214:217], v[144:147], v[16:19]
	v_mfma_f32_16x16x32_bf16 v[20:23], v[206:209], v[178:181], v[20:23]
	v_mfma_f32_16x16x32_bf16 v[24:27], v[214:217], v[178:181], v[24:27]
	v_mfma_f32_16x16x32_bf16 v[28:31], v[206:209], v[190:193], v[28:31]
	v_mfma_f32_16x16x32_bf16 v[32:35], v[214:217], v[190:193], v[32:35]
	v_mfma_f32_16x16x32_bf16 v[36:39], v[206:209], v[198:201], v[36:39]
	v_mfma_f32_16x16x32_bf16 v[60:63], v[214:217], v[198:201], v[60:63]
	s_setprio 0
	s_mov_b32 m0, s37
	v_lshl_add_u64 v[188:189], s[44:45], 0, v[40:41]
	s_barrier
	ds_read_b128 v[140:143], v58 offset:16384
	ds_read_b128 v[144:147], v58 offset:17408
	ds_read_b128 v[174:177], v58 offset:18432
	ds_read_b128 v[178:181], v58 offset:19456
	ds_read_b128 v[182:185], v58 offset:20480
	ds_read_b128 v[190:193], v58 offset:21504
	ds_read_b128 v[194:197], v58 offset:22528
	ds_read_b128 v[198:201], v58 offset:23552
	global_load_lds_dwordx4 v[188:189], off
	v_lshl_add_u64 v[234:235], s[44:45], 0, v[44:45]
	s_mov_b32 m0, s60
	s_nop 0
	global_load_lds_dwordx4 v[234:235], off
	s_barrier
	s_setprio 1
	s_waitcnt lgkmcnt(7)
	v_mfma_f32_16x16x32_bf16 v[150:153], v[124:127], v[140:143], v[150:153]
	v_mfma_f32_16x16x32_bf16 v[154:157], v[132:135], v[140:143], v[154:157]
	s_waitcnt lgkmcnt(5)
	v_mfma_f32_16x16x32_bf16 v[158:161], v[124:127], v[174:177], v[158:161]
	v_mfma_f32_16x16x32_bf16 v[162:165], v[132:135], v[174:177], v[162:165]
	s_waitcnt lgkmcnt(3)
	v_mfma_f32_16x16x32_bf16 v[166:169], v[124:127], v[182:185], v[166:169]
	v_mfma_f32_16x16x32_bf16 v[170:173], v[132:135], v[182:185], v[170:173]
	s_waitcnt lgkmcnt(1)
	v_mfma_f32_16x16x32_bf16 v[0:3], v[124:127], v[194:197], v[0:3]
	v_mfma_f32_16x16x32_bf16 v[4:7], v[132:135], v[194:197], v[4:7]
	v_mfma_f32_16x16x32_bf16 v[150:153], v[128:131], v[144:147], v[150:153]
	v_mfma_f32_16x16x32_bf16 v[154:157], v[136:139], v[144:147], v[154:157]
	v_mfma_f32_16x16x32_bf16 v[158:161], v[128:131], v[178:181], v[158:161]
	v_mfma_f32_16x16x32_bf16 v[162:165], v[136:139], v[178:181], v[162:165]
	v_mfma_f32_16x16x32_bf16 v[166:169], v[128:131], v[190:193], v[166:169]
	v_mfma_f32_16x16x32_bf16 v[170:173], v[136:139], v[190:193], v[170:173]
	s_waitcnt lgkmcnt(0)
	v_mfma_f32_16x16x32_bf16 v[0:3], v[128:131], v[198:201], v[0:3]
	v_mfma_f32_16x16x32_bf16 v[124:127], v[136:139], v[198:201], v[4:7]
	s_setprio 0
	s_barrier
	s_add_u32 s38, s42, 0x10000
	s_addc_u32 s39, s43, 0
	s_mov_b32 m0, s78
	v_lshl_add_u64 v[4:5], s[38:39], 0, v[42:43]
	global_load_lds_dwordx4 v[4:5], off
	v_lshl_add_u64 v[4:5], s[38:39], 0, v[46:47]
	s_mov_b32 m0, s27
	s_nop 0
	global_load_lds_dwordx4 v[4:5], off
	s_waitcnt vmcnt(6)
	s_barrier
	s_setprio 1
	v_mfma_f32_16x16x32_bf16 v[4:7], v[202:205], v[140:143], v[8:11]
	v_mfma_f32_16x16x32_bf16 v[8:11], v[206:209], v[144:147], v[4:7]
	v_mfma_f32_16x16x32_bf16 v[4:7], v[210:213], v[140:143], v[12:15]
	v_mfma_f32_16x16x32_bf16 v[12:15], v[214:217], v[144:147], v[4:7]
	v_mfma_f32_16x16x32_bf16 v[4:7], v[202:205], v[174:177], v[64:67]
	v_mfma_f32_16x16x32_bf16 v[64:67], v[206:209], v[178:181], v[4:7]
	v_mfma_f32_16x16x32_bf16 v[4:7], v[210:213], v[174:177], v[108:111]
	v_mfma_f32_16x16x32_bf16 v[108:111], v[214:217], v[178:181], v[4:7]
	v_mfma_f32_16x16x32_bf16 v[4:7], v[202:205], v[182:185], v[112:115]
	v_mfma_f32_16x16x32_bf16 v[112:115], v[206:209], v[190:193], v[4:7]
	v_mfma_f32_16x16x32_bf16 v[4:7], v[210:213], v[182:185], v[120:123]
	v_mfma_f32_16x16x32_bf16 v[120:123], v[214:217], v[190:193], v[4:7]
	v_mfma_f32_16x16x32_bf16 v[4:7], v[202:205], v[194:197], v[100:103]
	v_mfma_f32_16x16x32_bf16 v[100:103], v[206:209], v[198:201], v[4:7]
	v_mfma_f32_16x16x32_bf16 v[4:7], v[210:213], v[194:197], v[104:107]
	v_mfma_f32_16x16x32_bf16 v[104:107], v[214:217], v[198:201], v[4:7]
	s_setprio 0
	s_barrier
	s_nop 4
	ds_read_b128 v[4:7], v149
	ds_read_b128 v[128:131], v149 offset:1024
	ds_read_b128 v[132:135], v149 offset:2048
	ds_read_b128 v[136:139], v149 offset:3072
	s_add_u32 s38, s44, 0x10000
	s_addc_u32 s39, s45, 0
	s_mov_b32 m0, s61
	v_lshl_add_u64 v[202:203], s[38:39], 0, v[40:41]
	ds_read_b128 v[140:143], v58 offset:32768
	ds_read_b128 v[144:147], v58 offset:33792
	ds_read_b128 v[174:177], v58 offset:34816
	ds_read_b128 v[178:181], v58 offset:35840
	ds_read_b128 v[182:185], v58 offset:36864
	ds_read_b128 v[190:193], v58 offset:37888
	ds_read_b128 v[194:197], v58 offset:38912
	ds_read_b128 v[198:201], v58 offset:39936
	global_load_lds_dwordx4 v[202:203], off
	v_lshl_add_u64 v[202:203], s[38:39], 0, v[44:45]
	s_mov_b32 m0, s64
	s_nop 0
	global_load_lds_dwordx4 v[202:203], off
	s_waitcnt lgkmcnt(8)
	s_barrier
; #define PG8_STAGE(bufoff, gbase, voff) do { _Pragma("unroll") for (int _i = 0; _i < 2; ++_i) \
;         __builtin_amdgcn_global_load_lds((const unsigned*)((const char*)(gbase) + (voff)[_i]), (LAS unsigned*)(lds + (bufoff) + ldsw + _i * 8192), 16, 0, 0); } while (0)
; #define PG8_LDA(dst, b, h) do { _Pragma("unroll") for (int m = 0; m < 4; ++m) _Pragma("unroll") for (int k = 0; k < 2; ++k) dst[m][k] = *(const LAS bf16x8*)(lds + PG8_SA(b, h) + aoff + m * 2048 + k * 1024); } while (0)
; #define PG8_LDB(dst, b, h) do { _Pragma("unroll") for (int n = 0; n < 2; ++n) _Pragma("unroll") for (int k = 0; k < 2; ++k) dst[n][k] = *(const LAS bf16x8*)(lds + PG8_SB(b, h) + boff + n * 2048 + k * 1024); } while (0)
; #define PG8_MMA(ai, bj, At, Bt) do { __builtin_amdgcn_s_setprio(1); _Pragma("unroll") for (int m = 0; m < 4; ++m) _Pragma("unroll") for (int n = 0; n < 2; ++n) _Pragma("unroll") for (int k = 0; k < 2; ++k) \
;         acc[ai][bj][m][n] = __builtin_amdgcn_mfma_f32_16x16x32_bf16(Bt[n][k], At[m][k], acc[ai][bj][m][n], 0, 0, 0); __builtin_amdgcn_s_setprio(0); } while (0)
; #define PG8_WAIT_V(n) asm volatile("s_waitcnt vmcnt(" #n ")" ::: "memory")
; #define PG8_WAIT_L(n) asm volatile("s_waitcnt lgkmcnt(" #n ")" ::: "memory")
; #define PG8_BAR __builtin_amdgcn_s_barrier()
; #define PG8_SCHED __builtin_amdgcn_sched_barrier(0)
; template <class Epi>
; __device__ __forceinline__ void gemm_phase(LAS unsigned char* lds, const Gemm g, const StaticOrder& S, const Epi& E) {
;     ...
;             PG8_WAIT_L(8); PG8_BAR; PG8_WAIT_L(0); PG8_MMA(0, 0, At, B0); PG8_BAR; PG8_SCHED;
;             PG8_LDB(B1, 1, 1); PG8_STAGE(PG8_SB(1, 0), b3, voffB);
;             PG8_BAR; PG8_WAIT_L(0); PG8_MMA(0, 1, At, B1); PG8_BAR;
;             PG8_LDA(At, 1, 1); PG8_STAGE(PG8_SA(1, 0), a3, voffA);
;             PG8_BAR; PG8_WAIT_L(0); PG8_MMA(1, 0, At, B0); PG8_BAR; PG8_SCHED;
;             PG8_STAGE(PG8_SB(1, 1), b3 + hstepB, voffB);
;             PG8_WAIT_V(6); PG8_BAR; PG8_MMA(1, 1, At, B1); PG8_BAR;
	s_setprio 1
	s_waitcnt lgkmcnt(7)
	v_mfma_f32_16x16x32_bf16 v[68:71], v[4:7], v[140:143], v[68:71]
	v_mfma_f32_16x16x32_bf16 v[72:75], v[132:135], v[140:143], v[72:75]
	s_waitcnt lgkmcnt(5)
	v_mfma_f32_16x16x32_bf16 v[76:79], v[4:7], v[174:177], v[76:79]
	v_mfma_f32_16x16x32_bf16 v[80:83], v[132:135], v[174:177], v[80:83]
	s_waitcnt lgkmcnt(3)
	v_mfma_f32_16x16x32_bf16 v[84:87], v[4:7], v[182:185], v[84:87]
	v_mfma_f32_16x16x32_bf16 v[88:91], v[132:135], v[182:185], v[88:91]
	s_waitcnt lgkmcnt(1)
	v_mfma_f32_16x16x32_bf16 v[92:95], v[4:7], v[194:197], v[92:95]
	v_mfma_f32_16x16x32_bf16 v[96:99], v[132:135], v[194:197], v[96:99]
	v_mfma_f32_16x16x32_bf16 v[68:71], v[128:131], v[144:147], v[68:71]
	v_mfma_f32_16x16x32_bf16 v[72:75], v[136:139], v[144:147], v[72:75]
	v_mfma_f32_16x16x32_bf16 v[76:79], v[128:131], v[178:181], v[76:79]
	v_mfma_f32_16x16x32_bf16 v[80:83], v[136:139], v[178:181], v[80:83]
	v_mfma_f32_16x16x32_bf16 v[84:87], v[128:131], v[190:193], v[84:87]
	v_mfma_f32_16x16x32_bf16 v[88:91], v[136:139], v[190:193], v[88:91]
	s_waitcnt lgkmcnt(0)
	v_mfma_f32_16x16x32_bf16 v[92:95], v[128:131], v[198:201], v[92:95]
	v_mfma_f32_16x16x32_bf16 v[96:99], v[136:139], v[198:201], v[96:99]
	s_setprio 0
	s_barrier
	s_mov_b32 m0, s81
	v_lshl_add_u64 v[52:53], v[52:53], 0, s[6:7]
	ds_read_b128 v[202:205], v220
	ds_read_b128 v[206:209], v220 offset:1024
	ds_read_b128 v[210:213], v220 offset:2048
	ds_read_b128 v[214:217], v220 offset:3072
	global_load_lds_dwordx4 v[52:53], off
	v_lshl_add_u64 v[52:53], v[186:187], 0, s[6:7]
	s_mov_b32 m0, s79
	s_nop 0
	global_load_lds_dwordx4 v[52:53], off
	s_barrier
	s_setprio 1
	s_waitcnt lgkmcnt(1)
	v_mfma_f32_16x16x32_bf16 v[16:19], v[210:213], v[140:143], v[16:19]
	v_mfma_f32_16x16x32_bf16 v[116:119], v[202:205], v[140:143], v[116:119]
	s_waitcnt lgkmcnt(0)
	v_mfma_f32_16x16x32_bf16 v[140:143], v[214:217], v[144:147], v[16:19]
	v_mfma_f32_16x16x32_bf16 v[16:19], v[202:205], v[174:177], v[20:23]
	v_mfma_f32_16x16x32_bf16 v[116:119], v[206:209], v[144:147], v[116:119]
	v_mfma_f32_16x16x32_bf16 v[144:147], v[206:209], v[178:181], v[16:19]
	v_mfma_f32_16x16x32_bf16 v[16:19], v[210:213], v[174:177], v[24:27]
	v_mfma_f32_16x16x32_bf16 v[174:177], v[214:217], v[178:181], v[16:19]
	v_mfma_f32_16x16x32_bf16 v[16:19], v[202:205], v[182:185], v[28:31]
	v_mfma_f32_16x16x32_bf16 v[178:181], v[206:209], v[190:193], v[16:19]
	v_mfma_f32_16x16x32_bf16 v[16:19], v[210:213], v[182:185], v[32:35]
	v_mfma_f32_16x16x32_bf16 v[182:185], v[214:217], v[190:193], v[16:19]
	v_mfma_f32_16x16x32_bf16 v[16:19], v[202:205], v[194:197], v[36:39]
	v_mfma_f32_16x16x32_bf16 v[190:193], v[206:209], v[198:201], v[16:19]
	v_mfma_f32_16x16x32_bf16 v[16:19], v[210:213], v[194:197], v[60:63]
	v_mfma_f32_16x16x32_bf16 v[60:63], v[214:217], v[198:201], v[16:19]
	s_setprio 0
	s_mov_b32 m0, s65
	s_nop 4
	v_lshl_add_u64 v[16:17], v[188:189], 0, s[6:7]
	s_barrier
	ds_read_b128 v[24:27], v58 offset:49152
	ds_read_b128 v[28:31], v58 offset:50176
	ds_read_b128 v[194:197], v58 offset:51200
	ds_read_b128 v[198:201], v58 offset:52224
	ds_read_b128 v[218:221], v58 offset:53248
	ds_read_b128 v[222:225], v58 offset:54272
	ds_read_b128 v[226:229], v58 offset:55296
	ds_read_b128 v[230:233], v58 offset:56320
	global_load_lds_dwordx4 v[16:17], off
	v_lshl_add_u64 v[16:17], v[234:235], 0, s[6:7]
	s_mov_b32 m0, s66
	s_nop 0
	global_load_lds_dwordx4 v[16:17], off
	s_barrier
	s_setprio 1
	s_waitcnt lgkmcnt(7)
	v_mfma_f32_16x16x32_bf16 v[16:19], v[4:7], v[24:27], v[150:153]
	s_waitcnt lgkmcnt(6)
	v_mfma_f32_16x16x32_bf16 v[150:153], v[128:131], v[28:31], v[16:19]
	v_mfma_f32_16x16x32_bf16 v[16:19], v[132:135], v[24:27], v[154:157]
	v_mfma_f32_16x16x32_bf16 v[154:157], v[136:139], v[28:31], v[16:19]
	s_waitcnt lgkmcnt(5)
	v_mfma_f32_16x16x32_bf16 v[16:19], v[4:7], v[194:197], v[158:161]
	s_waitcnt lgkmcnt(4)
	v_mfma_f32_16x16x32_bf16 v[36:39], v[128:131], v[198:201], v[16:19]
	v_mfma_f32_16x16x32_bf16 v[16:19], v[132:135], v[194:197], v[162:165]
	v_mfma_f32_16x16x32_bf16 v[32:35], v[136:139], v[198:201], v[16:19]
	s_waitcnt lgkmcnt(3)
	v_mfma_f32_16x16x32_bf16 v[16:19], v[4:7], v[218:221], v[166:169]
	s_waitcnt lgkmcnt(1)
	v_mfma_f32_16x16x32_bf16 v[0:3], v[4:7], v[226:229], v[0:3]
	v_mfma_f32_16x16x32_bf16 v[20:23], v[128:131], v[222:225], v[16:19]
	v_mfma_f32_16x16x32_bf16 v[16:19], v[132:135], v[218:221], v[170:173]
	s_waitcnt lgkmcnt(0)
	v_mfma_f32_16x16x32_bf16 v[4:7], v[128:131], v[230:233], v[0:3]
	v_mfma_f32_16x16x32_bf16 v[0:3], v[132:135], v[226:229], v[124:127]
	v_mfma_f32_16x16x32_bf16 v[16:19], v[136:139], v[222:225], v[16:19]
	v_mfma_f32_16x16x32_bf16 v[0:3], v[136:139], v[230:233], v[0:3]
	s_setprio 0
	s_barrier
	s_add_u32 s38, s42, 0x10080
	s_addc_u32 s39, s43, 0
	s_mov_b32 m0, s41
	v_lshl_add_u64 v[52:53], s[38:39], 0, v[42:43]
	global_load_lds_dwordx4 v[52:53], off
	v_lshl_add_u64 v[52:53], s[38:39], 0, v[46:47]
	s_mov_b32 m0, s40
	s_nop 0
	global_load_lds_dwordx4 v[52:53], off
	s_waitcnt vmcnt(6)
	s_barrier
; __device__ __forceinline__ unsigned cvt_pk_bf16(float lo, float hi) { unsigned r; asm volatile("v_cvt_pk_bf16_f32 %0, %1, %2" : "=v"(r) : "v"(lo), "v"(hi)); return r; }
; #define PG8_MMA(ai, bj, At, Bt) do { __builtin_amdgcn_s_setprio(1); _Pragma("unroll") for (int m = 0; m < 4; ++m) _Pragma("unroll") for (int n = 0; n < 2; ++n) _Pragma("unroll") for (int k = 0; k < 2; ++k) \
;         acc[ai][bj][m][n] = __builtin_amdgcn_mfma_f32_16x16x32_bf16(Bt[n][k], At[m][k], acc[ai][bj][m][n], 0, 0, 0); __builtin_amdgcn_s_setprio(0); } while (0)
; #define PG8_WAIT_V(n) asm volatile("s_waitcnt vmcnt(" #n ")" ::: "memory")
; #define PG8_BAR __builtin_amdgcn_s_barrier()
; template <class Epi>
; __device__ __forceinline__ void gemm_phase(LAS unsigned char* lds, const Gemm g, const StaticOrder& S, const Epi& E) {
;     ...
;             PG8_WAIT_V(6); PG8_BAR; PG8_MMA(1, 1, At, B1); PG8_BAR;
;     __device__ __forceinline__ void operator()(const AccT& acc, const Unit& u, int wr, int wc, int fr, int fq) const {
;         const int row0 = u.pm * 256 + wr * 64 + fr, col0 = u.pn * 256 + wc * 32 + 8 * fq;
; #pragma unroll
;         for (int ai = 0; ai < 2; ++ai)
; #pragma unroll
;             for (int m = 0; m < 4; ++m) { u16* rowp = O + (size_t)(row0 + ai * 128 + m * 16) * ld + col0;
; #pragma unroll
;                 for (int bj = 0; bj < 2; ++bj) { const f32x4 v0 = acc[ai][bj][m][0], v1 = acc[ai][bj][m][1];
;                     u32x4 w; w.x = cvt_pk_bf16(v0[0], v0[1]); w.y = cvt_pk_bf16(v0[2], v0[3]); w.z = cvt_pk_bf16(v1[0], v1[1]); w.w = cvt_pk_bf16(v1[2], v1[3]);
;                     *(u32x4*)(rowp + bj * 128) = w; } }
	s_setprio 1
	v_mfma_f32_16x16x32_bf16 v[8:11], v[202:205], v[24:27], v[8:11]
	v_mfma_f32_16x16x32_bf16 v[124:127], v[206:209], v[28:31], v[8:11]
	v_mfma_f32_16x16x32_bf16 v[8:11], v[210:213], v[24:27], v[12:15]
	v_mfma_f32_16x16x32_bf16 v[128:131], v[214:217], v[28:31], v[8:11]
	v_mfma_f32_16x16x32_bf16 v[8:11], v[202:205], v[194:197], v[64:67]
	v_mfma_f32_16x16x32_bf16 v[64:67], v[206:209], v[198:201], v[8:11]
	v_mfma_f32_16x16x32_bf16 v[8:11], v[210:213], v[194:197], v[108:111]
	v_mfma_f32_16x16x32_bf16 v[108:111], v[214:217], v[198:201], v[8:11]
	v_mfma_f32_16x16x32_bf16 v[8:11], v[202:205], v[218:221], v[112:115]
	v_mfma_f32_16x16x32_bf16 v[28:31], v[206:209], v[222:225], v[8:11]
	v_mfma_f32_16x16x32_bf16 v[8:11], v[210:213], v[218:221], v[120:123]
	v_mfma_f32_16x16x32_bf16 v[24:27], v[214:217], v[222:225], v[8:11]
	v_mfma_f32_16x16x32_bf16 v[8:11], v[202:205], v[226:229], v[100:103]
	v_mfma_f32_16x16x32_bf16 v[12:15], v[206:209], v[230:233], v[8:11]
	v_mfma_f32_16x16x32_bf16 v[8:11], v[210:213], v[226:229], v[104:107]
	v_mfma_f32_16x16x32_bf16 v[8:11], v[214:217], v[230:233], v[8:11]
	s_setprio 0
	v_lshl_add_u32 v100, s36, 8, v54
	v_lshl_or_b32 v52, s76, 8, v56
	v_ashrrev_i32_e32 v101, 31, v100
	v_ashrrev_i32_e32 v53, 31, v52
	v_lshlrev_b64 v[102:103], 12, v[100:101]
	v_lshl_add_u64 v[102:103], s[0:1], 0, v[102:103]
	v_lshlrev_b64 v[104:105], 1, v[52:53]
	s_barrier
	v_lshl_add_u64 v[52:53], v[102:103], 0, v[104:105]
	v_cvt_pk_bf16_f32 v68, v68, v69
	v_cvt_pk_bf16_f32 v69, v70, v71
	v_cvt_pk_bf16_f32 v70, v72, v73
	v_cvt_pk_bf16_f32 v71, v74, v75
	global_store_dwordx4 v[52:53], v[68:71], off
	s_add_i32 s69, s69, s96
	s_mov_b32 s76, s24
	v_cvt_pk_bf16_f32 v68, v116, v117
	v_cvt_pk_bf16_f32 v69, v118, v119
	v_cvt_pk_bf16_f32 v70, v140, v141
	v_cvt_pk_bf16_f32 v71, v142, v143
	global_store_dwordx4 v[52:53], v[68:71], off offset:256
	s_mov_b32 s36, s26
	s_mov_b64 s[40:41], s[30:31]
	v_or_b32_e32 v68, 16, v100
	v_ashrrev_i32_e32 v69, 31, v68
	v_lshlrev_b64 v[68:69], 12, v[68:69]
	v_lshl_add_u64 v[68:69], s[0:1], 0, v[68:69]
	v_lshl_add_u64 v[72:73], v[68:69], 0, v[104:105]
	v_cvt_pk_bf16_f32 v68, v76, v77
	v_cvt_pk_bf16_f32 v69, v78, v79
	v_cvt_pk_bf16_f32 v70, v80, v81
	v_cvt_pk_bf16_f32 v71, v82, v83
	global_store_dwordx4 v[72:73], v[68:71], off
	s_mov_b64 s[38:39], s[28:29]
	s_nop 0
	v_cvt_pk_bf16_f32 v68, v144, v145
	v_cvt_pk_bf16_f32 v69, v146, v147
	v_cvt_pk_bf16_f32 v70, v174, v175
	v_cvt_pk_bf16_f32 v71, v176, v177
	global_store_dwordx4 v[72:73], v[68:71], off offset:256
	s_nop 1
	v_or_b32_e32 v68, 32, v100
	v_ashrrev_i32_e32 v69, 31, v68
	v_lshlrev_b64 v[68:69], 12, v[68:69]
	v_lshl_add_u64 v[68:69], s[0:1], 0, v[68:69]
	v_lshl_add_u64 v[72:73], v[68:69], 0, v[104:105]
	v_cvt_pk_bf16_f32 v68, v84, v85
	v_cvt_pk_bf16_f32 v69, v86, v87
	v_cvt_pk_bf16_f32 v70, v88, v89
	v_cvt_pk_bf16_f32 v71, v90, v91
	global_store_dwordx4 v[72:73], v[68:71], off
	s_nop 1
	v_cvt_pk_bf16_f32 v68, v178, v179
	v_cvt_pk_bf16_f32 v69, v180, v181
	v_cvt_pk_bf16_f32 v70, v182, v183
	v_cvt_pk_bf16_f32 v71, v184, v185
	global_store_dwordx4 v[72:73], v[68:71], off offset:256
	s_nop 1
	v_or_b32_e32 v68, 48, v100
	v_ashrrev_i32_e32 v69, 31, v68
	v_lshlrev_b64 v[68:69], 12, v[68:69]
	v_lshl_add_u64 v[68:69], s[0:1], 0, v[68:69]
	v_lshl_add_u64 v[72:73], v[68:69], 0, v[104:105]
	v_cvt_pk_bf16_f32 v68, v92, v93
	v_cvt_pk_bf16_f32 v69, v94, v95
	v_cvt_pk_bf16_f32 v70, v96, v97
	v_cvt_pk_bf16_f32 v71, v98, v99
	global_store_dwordx4 v[72:73], v[68:71], off
	s_nop 1
	v_cvt_pk_bf16_f32 v68, v190, v191
	v_cvt_pk_bf16_f32 v69, v192, v193
	v_cvt_pk_bf16_f32 v70, v60, v61
	v_cvt_pk_bf16_f32 v71, v62, v63
	global_store_dwordx4 v[72:73], v[68:71], off offset:256
	v_cvt_pk_bf16_f32 v60, v150, v151
	v_cvt_pk_bf16_f32 v61, v152, v153
	v_cvt_pk_bf16_f32 v62, v154, v155
	v_cvt_pk_bf16_f32 v63, v156, v157
	s_nop 1
	v_add_co_u32_e32 v70, vcc, s72, v52
	v_lshl_add_u64 v[68:69], v[52:53], 0, s[14:15]
	s_nop 0
	v_addc_co_u32_e32 v71, vcc, 0, v53, vcc
	global_store_dwordx4 v[70:71], v[60:63], off
	s_nop 1
	v_cvt_pk_bf16_f32 v60, v124, v125
	v_cvt_pk_bf16_f32 v61, v126, v127
	v_cvt_pk_bf16_f32 v62, v128, v129
	v_cvt_pk_bf16_f32 v63, v130, v131
	global_store_dwordx4 v[68:69], v[60:63], off offset:256
	v_cvt_pk_bf16_f32 v36, v36, v37
	v_cvt_pk_bf16_f32 v37, v38, v39
	v_cvt_pk_bf16_f32 v38, v32, v33
	v_add_co_u32_e32 v32, vcc, s73, v52
	s_nop 0
	v_lshl_add_u64 v[60:61], v[52:53], 0, s[16:17]
	v_addc_co_u32_e32 v33, vcc, 0, v53, vcc
	v_cvt_pk_bf16_f32 v39, v34, v35
	global_store_dwordx4 v[32:33], v[36:39], off
	v_cvt_pk_bf16_f32 v32, v64, v65
	v_cvt_pk_bf16_f32 v33, v66, v67
	v_cvt_pk_bf16_f32 v34, v108, v109
	v_cvt_pk_bf16_f32 v35, v110, v111
	global_store_dwordx4 v[60:61], v[32:35], off offset:256
	v_cvt_pk_bf16_f32 v20, v20, v21
	v_cvt_pk_bf16_f32 v21, v22, v23
	v_cvt_pk_bf16_f32 v22, v16, v17
	v_add_co_u32_e32 v16, vcc, s74, v52
	s_nop 0
	v_lshl_add_u64 v[32:33], v[52:53], 0, s[18:19]
	v_addc_co_u32_e32 v17, vcc, 0, v53, vcc
	v_cvt_pk_bf16_f32 v23, v18, v19
	global_store_dwordx4 v[16:17], v[20:23], off
	v_cvt_pk_bf16_f32 v16, v28, v29
	v_cvt_pk_bf16_f32 v17, v30, v31
	v_cvt_pk_bf16_f32 v18, v24, v25
	v_cvt_pk_bf16_f32 v19, v26, v27
	global_store_dwordx4 v[32:33], v[16:19], off offset:256
	v_cvt_pk_bf16_f32 v4, v4, v5
	v_cvt_pk_bf16_f32 v5, v6, v7
	v_cvt_pk_bf16_f32 v6, v0, v1
	v_add_co_u32_e32 v0, vcc, s75, v52
	s_nop 0
	v_lshl_add_u64 v[16:17], v[52:53], 0, s[20:21]
	v_addc_co_u32_e32 v1, vcc, 0, v53, vcc
	s_andn2_b64 vcc, exec, s[4:5]
	v_cvt_pk_bf16_f32 v7, v2, v3
	global_store_dwordx4 v[0:1], v[4:7], off
	v_cvt_pk_bf16_f32 v0, v12, v13
	v_cvt_pk_bf16_f32 v1, v14, v15
	v_cvt_pk_bf16_f32 v2, v8, v9
	v_cvt_pk_bf16_f32 v3, v10, v11
	global_store_dwordx4 v[16:17], v[0:3], off offset:256
	s_cbranch_vccz .LBB0_1109

; #define PG8_STAGE(bufoff, gbase, voff) do { _Pragma("unroll") for (int _i = 0; _i < 2; ++_i) \
;         __builtin_amdgcn_global_load_lds((const unsigned*)((const char*)(gbase) + (voff)[_i]), (LAS unsigned*)(lds + (bufoff) + ldsw + _i * 8192), 16, 0, 0); } while (0)
; #define PG8_LDA(dst, b, h) do { _Pragma("unroll") for (int m = 0; m < 4; ++m) _Pragma("unroll") for (int k = 0; k < 2; ++k) dst[m][k] = *(const LAS bf16x8*)(lds + PG8_SA(b, h) + aoff + m * 2048 + k * 1024); } while (0)
; #define PG8_LDB(dst, b, h) do { _Pragma("unroll") for (int n = 0; n < 2; ++n) _Pragma("unroll") for (int k = 0; k < 2; ++k) dst[n][k] = *(const LAS bf16x8*)(lds + PG8_SB(b, h) + boff + n * 2048 + k * 1024); } while (0)
; #define PG8_MMA(ai, bj, At, Bt) do { __builtin_amdgcn_s_setprio(1); _Pragma("unroll") for (int m = 0; m < 4; ++m) _Pragma("unroll") for (int n = 0; n < 2; ++n) _Pragma("unroll") for (int k = 0; k < 2; ++k) \
;         acc[ai][bj][m][n] = __builtin_amdgcn_mfma_f32_16x16x32_bf16(Bt[n][k], At[m][k], acc[ai][bj][m][n], 0, 0, 0); __builtin_amdgcn_s_setprio(0); } while (0)
; #define PG8_WAIT_L(n) asm volatile("s_waitcnt lgkmcnt(" #n ")" ::: "memory")
; #define PG8_BAR __builtin_amdgcn_s_barrier()
; #define PG8_SCHED __builtin_amdgcn_sched_barrier(0)
; template <class Epi>
; __device__ __forceinline__ void gemm_phase(LAS unsigned char* lds, const Gemm g, const StaticOrder& S, const Epi& E) {
;     ...
;             PG8_LDB(B0, 0, 0); PG8_SCHED; PG8_LDA(At, 0, 0); PG8_STAGE(PG8_SA(1, 1), a1 + hstepA, voffA);
;             PG8_WAIT_L(8); PG8_BAR; PG8_WAIT_L(0); PG8_MMA(0, 0, At, B0); PG8_BAR; PG8_SCHED;
;             PG8_LDB(B1, 0, 1); PG8_STAGE(PG8_SB(0, 0), b2, voffB);
;             PG8_BAR; PG8_WAIT_L(0); PG8_MMA(0, 1, At, B1); PG8_BAR;
;             PG8_LDA(At, 0, 1); PG8_STAGE(PG8_SA(0, 0), a2, voffA);
;             PG8_BAR; PG8_WAIT_L(0); PG8_MMA(1, 0, At, B0); PG8_BAR; PG8_SCHED;
.LBB0_1240:
	ds_read_b128 v[140:143], v152
	ds_read_b128 v[144:147], v152 offset:1024
	ds_read_b128 v[156:159], v152 offset:2048
	ds_read_b128 v[160:163], v152 offset:3072
	s_add_u32 s30, s28, 0xfff80080
	s_addc_u32 s31, s29, -1
	s_cmp_eq_u32 s67, 28
	s_cselect_b32 s37, s21, s31
	s_cselect_b32 s36, s63, s30
	s_cselect_b32 s31, s19, s66
	s_cselect_b32 s30, s64, s65
	v_lshl_add_u64 v[188:189], s[28:29], 0, v[132:133]
	s_add_i32 m0, s27, 0xc000
	ds_read_b128 v[164:167], v153
	ds_read_b128 v[168:171], v153 offset:1024
	ds_read_b128 v[172:175], v153 offset:2048
	ds_read_b128 v[176:179], v153 offset:3072
	ds_read_b128 v[180:183], v153 offset:4096
	ds_read_b128 v[184:187], v153 offset:5120
	ds_read_b128 v[190:193], v153 offset:6144
	ds_read_b128 v[194:197], v153 offset:7168
	global_load_lds_dwordx4 v[188:189], off
	v_lshl_add_u64 v[188:189], s[28:29], 0, v[134:135]
	s_add_i32 m0, s27, 0xe000
	s_nop 0
	global_load_lds_dwordx4 v[188:189], off
	s_waitcnt lgkmcnt(8)
	s_barrier
	s_setprio 1
	s_waitcnt lgkmcnt(12)
	s_waitcnt lgkmcnt(7)
	v_mfma_f32_16x16x32_bf16 v[124:127], v[140:143], v[164:167], v[124:127]
	v_mfma_f32_16x16x32_bf16 v[120:123], v[156:159], v[164:167], v[120:123]
	s_waitcnt lgkmcnt(5)
	v_mfma_f32_16x16x32_bf16 v[108:111], v[140:143], v[172:175], v[108:111]
	v_mfma_f32_16x16x32_bf16 v[104:107], v[156:159], v[172:175], v[104:107]
	s_waitcnt lgkmcnt(3)
	v_mfma_f32_16x16x32_bf16 v[92:95], v[140:143], v[180:183], v[92:95]
	v_mfma_f32_16x16x32_bf16 v[88:91], v[156:159], v[180:183], v[88:91]
	s_waitcnt lgkmcnt(1)
	v_mfma_f32_16x16x32_bf16 v[76:79], v[140:143], v[190:193], v[76:79]
	v_mfma_f32_16x16x32_bf16 v[72:75], v[156:159], v[190:193], v[72:75]
	v_mfma_f32_16x16x32_bf16 v[124:127], v[144:147], v[168:171], v[124:127]
	v_mfma_f32_16x16x32_bf16 v[120:123], v[160:163], v[168:171], v[120:123]
	v_mfma_f32_16x16x32_bf16 v[108:111], v[144:147], v[176:179], v[108:111]
	v_mfma_f32_16x16x32_bf16 v[104:107], v[160:163], v[176:179], v[104:107]
	v_mfma_f32_16x16x32_bf16 v[92:95], v[144:147], v[184:187], v[92:95]
	v_mfma_f32_16x16x32_bf16 v[88:91], v[160:163], v[184:187], v[88:91]
	s_waitcnt lgkmcnt(0)
	v_mfma_f32_16x16x32_bf16 v[76:79], v[144:147], v[194:197], v[76:79]
	v_mfma_f32_16x16x32_bf16 v[72:75], v[160:163], v[194:197], v[72:75]
	s_setprio 0
	s_barrier
	s_add_i32 s68, s60, s43
	v_lshl_add_u64 v[188:189], s[30:31], 0, v[128:129]
	s_mov_b32 m0, s68
	ds_read_b128 v[198:201], v154
	ds_read_b128 v[202:205], v154 offset:1024
	ds_read_b128 v[206:209], v154 offset:2048
	ds_read_b128 v[210:213], v154 offset:3072
	global_load_lds_dwordx4 v[188:189], off
	v_lshl_add_u64 v[214:215], s[30:31], 0, v[130:131]
	s_add_i32 m0, s68, 0x2000
	s_nop 0
	global_load_lds_dwordx4 v[214:215], off
	s_barrier
	s_setprio 1
	s_waitcnt lgkmcnt(3)
	v_mfma_f32_16x16x32_bf16 v[116:119], v[198:201], v[164:167], v[116:119]
	s_waitcnt lgkmcnt(1)
	v_mfma_f32_16x16x32_bf16 v[112:115], v[206:209], v[164:167], v[112:115]
	v_mfma_f32_16x16x32_bf16 v[100:103], v[198:201], v[172:175], v[100:103]
	v_mfma_f32_16x16x32_bf16 v[96:99], v[206:209], v[172:175], v[96:99]
	v_mfma_f32_16x16x32_bf16 v[84:87], v[198:201], v[180:183], v[84:87]
	v_mfma_f32_16x16x32_bf16 v[80:83], v[206:209], v[180:183], v[80:83]
	v_mfma_f32_16x16x32_bf16 v[68:71], v[198:201], v[190:193], v[68:71]
	v_mfma_f32_16x16x32_bf16 v[64:67], v[206:209], v[190:193], v[64:67]
	v_mfma_f32_16x16x32_bf16 v[116:119], v[202:205], v[168:171], v[116:119]
	s_waitcnt lgkmcnt(0)
	v_mfma_f32_16x16x32_bf16 v[112:115], v[210:213], v[168:171], v[112:115]
	v_mfma_f32_16x16x32_bf16 v[100:103], v[202:205], v[176:179], v[100:103]
	v_mfma_f32_16x16x32_bf16 v[96:99], v[210:213], v[176:179], v[96:99]
	v_mfma_f32_16x16x32_bf16 v[84:87], v[202:205], v[184:187], v[84:87]
	v_mfma_f32_16x16x32_bf16 v[80:83], v[210:213], v[184:187], v[80:83]
	v_mfma_f32_16x16x32_bf16 v[68:71], v[202:205], v[194:197], v[68:71]
	v_mfma_f32_16x16x32_bf16 v[64:67], v[210:213], v[194:197], v[64:67]
	s_setprio 0
	s_mov_b32 m0, s27
	v_lshl_add_u64 v[216:217], s[36:37], 0, v[128:129]
	s_barrier
	ds_read_b128 v[164:167], v153 offset:16384
	ds_read_b128 v[168:171], v153 offset:17408
	ds_read_b128 v[172:175], v153 offset:18432
	ds_read_b128 v[176:179], v153 offset:19456
	ds_read_b128 v[180:183], v153 offset:20480
	ds_read_b128 v[184:187], v153 offset:21504
	ds_read_b128 v[190:193], v153 offset:22528
	ds_read_b128 v[194:197], v153 offset:23552
	global_load_lds_dwordx4 v[216:217], off
	v_lshl_add_u64 v[218:219], s[36:37], 0, v[130:131]
	s_mov_b32 m0, s44
	s_nop 0
	global_load_lds_dwordx4 v[218:219], off
	s_barrier
	s_setprio 1
	s_waitcnt lgkmcnt(7)
	v_mfma_f32_16x16x32_bf16 v[60:63], v[140:143], v[164:167], v[60:63]
	v_mfma_f32_16x16x32_bf16 v[56:59], v[156:159], v[164:167], v[56:59]
	s_waitcnt lgkmcnt(5)
	v_mfma_f32_16x16x32_bf16 v[44:47], v[140:143], v[172:175], v[44:47]
	v_mfma_f32_16x16x32_bf16 v[40:43], v[156:159], v[172:175], v[40:43]
	s_waitcnt lgkmcnt(3)
	v_mfma_f32_16x16x32_bf16 v[28:31], v[140:143], v[180:183], v[28:31]
	v_mfma_f32_16x16x32_bf16 v[24:27], v[156:159], v[180:183], v[24:27]
	s_waitcnt lgkmcnt(1)
	v_mfma_f32_16x16x32_bf16 v[12:15], v[140:143], v[190:193], v[12:15]
	v_mfma_f32_16x16x32_bf16 v[8:11], v[156:159], v[190:193], v[8:11]
	v_mfma_f32_16x16x32_bf16 v[60:63], v[144:147], v[168:171], v[60:63]
	v_mfma_f32_16x16x32_bf16 v[56:59], v[160:163], v[168:171], v[56:59]
	v_mfma_f32_16x16x32_bf16 v[44:47], v[144:147], v[176:179], v[44:47]
	v_mfma_f32_16x16x32_bf16 v[40:43], v[160:163], v[176:179], v[40:43]
	v_mfma_f32_16x16x32_bf16 v[28:31], v[144:147], v[184:187], v[28:31]
	v_mfma_f32_16x16x32_bf16 v[24:27], v[160:163], v[184:187], v[24:27]
	s_waitcnt lgkmcnt(0)
	v_mfma_f32_16x16x32_bf16 v[12:15], v[144:147], v[194:197], v[12:15]
	v_mfma_f32_16x16x32_bf16 v[8:11], v[160:163], v[194:197], v[8:11]
	s_setprio 0
	s_barrier
; #define PG8_STAGE(bufoff, gbase, voff) do { _Pragma("unroll") for (int _i = 0; _i < 2; ++_i) \
;         __builtin_amdgcn_global_load_lds((const unsigned*)((const char*)(gbase) + (voff)[_i]), (LAS unsigned*)(lds + (bufoff) + ldsw + _i * 8192), 16, 0, 0); } while (0)
; #define PG8_LDA(dst, b, h) do { _Pragma("unroll") for (int m = 0; m < 4; ++m) _Pragma("unroll") for (int k = 0; k < 2; ++k) dst[m][k] = *(const LAS bf16x8*)(lds + PG8_SA(b, h) + aoff + m * 2048 + k * 1024); } while (0)
; #define PG8_LDB(dst, b, h) do { _Pragma("unroll") for (int n = 0; n < 2; ++n) _Pragma("unroll") for (int k = 0; k < 2; ++k) dst[n][k] = *(const LAS bf16x8*)(lds + PG8_SB(b, h) + boff + n * 2048 + k * 1024); } while (0)
; #define PG8_MMA(ai, bj, At, Bt) do { __builtin_amdgcn_s_setprio(1); _Pragma("unroll") for (int m = 0; m < 4; ++m) _Pragma("unroll") for (int n = 0; n < 2; ++n) _Pragma("unroll") for (int k = 0; k < 2; ++k) \
;         acc[ai][bj][m][n] = __builtin_amdgcn_mfma_f32_16x16x32_bf16(Bt[n][k], At[m][k], acc[ai][bj][m][n], 0, 0, 0); __builtin_amdgcn_s_setprio(0); } while (0)
; #define PG8_WAIT_V(n) asm volatile("s_waitcnt vmcnt(" #n ")" ::: "memory")
; #define PG8_WAIT_L(n) asm volatile("s_waitcnt lgkmcnt(" #n ")" ::: "memory")
; #define PG8_BAR __builtin_amdgcn_s_barrier()
; #define PG8_SCHED __builtin_amdgcn_sched_barrier(0)
; template <class Epi>
; __device__ __forceinline__ void gemm_phase(LAS unsigned char* lds, const Gemm g, const StaticOrder& S, const Epi& E) {
;     ...
;             PG8_STAGE(PG8_SB(0, 1), b2 + hstepB, voffB);
;             PG8_WAIT_V(6); PG8_BAR; PG8_MMA(1, 1, At, B1); PG8_BAR;
;             PG8_LDB(B0, 1, 0); PG8_SCHED; PG8_LDA(At, 1, 0); PG8_STAGE(PG8_SA(0, 1), a2 + hstepA, voffA);
;             PG8_WAIT_L(8); PG8_BAR; PG8_WAIT_L(0); PG8_MMA(0, 0, At, B0); PG8_BAR; PG8_SCHED;
;             PG8_LDB(B1, 1, 1); PG8_STAGE(PG8_SB(1, 0), b3, voffB);
;             PG8_BAR; PG8_WAIT_L(0); PG8_MMA(0, 1, At, B1); PG8_BAR;
;             PG8_LDA(At, 1, 1); PG8_STAGE(PG8_SA(1, 0), a3, voffA);
	s_add_u32 s68, s30, 0x80000
	s_addc_u32 s69, s31, 0
	s_add_i32 s70, s61, s43
	v_lshl_add_u64 v[140:141], s[68:69], 0, v[128:129]
	s_mov_b32 m0, s70
	s_nop 0
	global_load_lds_dwordx4 v[140:141], off
	v_lshl_add_u64 v[140:141], s[68:69], 0, v[130:131]
	s_add_i32 m0, s70, 0x2000
	s_nop 0
	global_load_lds_dwordx4 v[140:141], off
	s_waitcnt vmcnt(6)
	s_barrier
	s_setprio 1
	v_mfma_f32_16x16x32_bf16 v[52:55], v[198:201], v[164:167], v[52:55]
	v_mfma_f32_16x16x32_bf16 v[48:51], v[206:209], v[164:167], v[48:51]
	v_mfma_f32_16x16x32_bf16 v[36:39], v[198:201], v[172:175], v[36:39]
	v_mfma_f32_16x16x32_bf16 v[32:35], v[206:209], v[172:175], v[32:35]
	v_mfma_f32_16x16x32_bf16 v[20:23], v[198:201], v[180:183], v[20:23]
	v_mfma_f32_16x16x32_bf16 v[16:19], v[206:209], v[180:183], v[16:19]
	v_mfma_f32_16x16x32_bf16 v[4:7], v[198:201], v[190:193], v[4:7]
	v_mfma_f32_16x16x32_bf16 v[0:3], v[206:209], v[190:193], v[0:3]
	v_mfma_f32_16x16x32_bf16 v[52:55], v[202:205], v[168:171], v[52:55]
	v_mfma_f32_16x16x32_bf16 v[48:51], v[210:213], v[168:171], v[48:51]
	v_mfma_f32_16x16x32_bf16 v[36:39], v[202:205], v[176:179], v[36:39]
	v_mfma_f32_16x16x32_bf16 v[32:35], v[210:213], v[176:179], v[32:35]
	v_mfma_f32_16x16x32_bf16 v[20:23], v[202:205], v[184:187], v[20:23]
	v_mfma_f32_16x16x32_bf16 v[16:19], v[210:213], v[184:187], v[16:19]
	v_mfma_f32_16x16x32_bf16 v[4:7], v[202:205], v[194:197], v[4:7]
	v_mfma_f32_16x16x32_bf16 v[0:3], v[210:213], v[194:197], v[0:3]
	s_setprio 0
	s_add_i32 s68, 0, 0x18000
	v_add_u32_e32 v155, s68, v150
	s_barrier
	ds_read_b128 v[140:143], v155
	ds_read_b128 v[144:147], v155 offset:1024
	ds_read_b128 v[156:159], v155 offset:2048
	ds_read_b128 v[160:163], v155 offset:3072
	s_add_u32 s36, s36, 0x80000
	s_addc_u32 s37, s37, 0
	s_mov_b32 m0, s45
	v_lshl_add_u64 v[198:199], s[36:37], 0, v[128:129]
	ds_read_b128 v[164:167], v153 offset:32768
	ds_read_b128 v[168:171], v153 offset:33792
	ds_read_b128 v[172:175], v153 offset:34816
	ds_read_b128 v[176:179], v153 offset:35840
	ds_read_b128 v[180:183], v153 offset:36864
	ds_read_b128 v[184:187], v153 offset:37888
	ds_read_b128 v[190:193], v153 offset:38912
	ds_read_b128 v[194:197], v153 offset:39936
	global_load_lds_dwordx4 v[198:199], off
	v_lshl_add_u64 v[198:199], s[36:37], 0, v[130:131]
	s_mov_b32 m0, s46
	s_nop 0
	global_load_lds_dwordx4 v[198:199], off
	s_waitcnt lgkmcnt(8)
	s_barrier
	s_setprio 1
	s_waitcnt lgkmcnt(7)
	v_mfma_f32_16x16x32_bf16 v[124:127], v[140:143], v[164:167], v[124:127]
	v_mfma_f32_16x16x32_bf16 v[120:123], v[156:159], v[164:167], v[120:123]
	s_waitcnt lgkmcnt(5)
	v_mfma_f32_16x16x32_bf16 v[108:111], v[140:143], v[172:175], v[108:111]
	v_mfma_f32_16x16x32_bf16 v[104:107], v[156:159], v[172:175], v[104:107]
	s_waitcnt lgkmcnt(3)
	v_mfma_f32_16x16x32_bf16 v[92:95], v[140:143], v[180:183], v[92:95]
	v_mfma_f32_16x16x32_bf16 v[88:91], v[156:159], v[180:183], v[88:91]
	s_waitcnt lgkmcnt(1)
	v_mfma_f32_16x16x32_bf16 v[76:79], v[140:143], v[190:193], v[76:79]
	v_mfma_f32_16x16x32_bf16 v[72:75], v[156:159], v[190:193], v[72:75]
	v_mfma_f32_16x16x32_bf16 v[124:127], v[144:147], v[168:171], v[124:127]
	v_mfma_f32_16x16x32_bf16 v[120:123], v[160:163], v[168:171], v[120:123]
	v_mfma_f32_16x16x32_bf16 v[108:111], v[144:147], v[176:179], v[108:111]
	v_mfma_f32_16x16x32_bf16 v[104:107], v[160:163], v[176:179], v[104:107]
	v_mfma_f32_16x16x32_bf16 v[92:95], v[144:147], v[184:187], v[92:95]
	v_mfma_f32_16x16x32_bf16 v[88:91], v[160:163], v[184:187], v[88:91]
	s_waitcnt lgkmcnt(0)
	v_mfma_f32_16x16x32_bf16 v[76:79], v[144:147], v[194:197], v[76:79]
	v_mfma_f32_16x16x32_bf16 v[72:75], v[160:163], v[194:197], v[72:75]
	s_setprio 0
	s_barrier
	s_add_i32 s36, 0, 0x1c000
	s_add_i32 s37, s68, s43
	v_add_u32_e32 v155, s36, v150
	v_lshl_add_u64 v[188:189], v[188:189], 0, s[6:7]
	s_mov_b32 m0, s37
	ds_read_b128 v[198:201], v155
	ds_read_b128 v[202:205], v155 offset:1024
	ds_read_b128 v[206:209], v155 offset:2048
	ds_read_b128 v[210:213], v155 offset:3072
	global_load_lds_dwordx4 v[188:189], off
	v_lshl_add_u64 v[188:189], v[214:215], 0, s[6:7]
	s_add_i32 m0, s37, 0x2000
	s_nop 0
	global_load_lds_dwordx4 v[188:189], off
	s_barrier
	s_setprio 1
	s_waitcnt lgkmcnt(3)
	v_mfma_f32_16x16x32_bf16 v[116:119], v[198:201], v[164:167], v[116:119]
	s_waitcnt lgkmcnt(1)
	v_mfma_f32_16x16x32_bf16 v[112:115], v[206:209], v[164:167], v[112:115]
	v_mfma_f32_16x16x32_bf16 v[100:103], v[198:201], v[172:175], v[100:103]
	v_mfma_f32_16x16x32_bf16 v[96:99], v[206:209], v[172:175], v[96:99]
	v_mfma_f32_16x16x32_bf16 v[84:87], v[198:201], v[180:183], v[84:87]
	v_mfma_f32_16x16x32_bf16 v[80:83], v[206:209], v[180:183], v[80:83]
	v_mfma_f32_16x16x32_bf16 v[68:71], v[198:201], v[190:193], v[68:71]
	v_mfma_f32_16x16x32_bf16 v[64:67], v[206:209], v[190:193], v[64:67]
	v_mfma_f32_16x16x32_bf16 v[116:119], v[202:205], v[168:171], v[116:119]
	s_waitcnt lgkmcnt(0)
	v_mfma_f32_16x16x32_bf16 v[112:115], v[210:213], v[168:171], v[112:115]
	v_mfma_f32_16x16x32_bf16 v[100:103], v[202:205], v[176:179], v[100:103]
	v_mfma_f32_16x16x32_bf16 v[96:99], v[210:213], v[176:179], v[96:99]
	v_mfma_f32_16x16x32_bf16 v[84:87], v[202:205], v[184:187], v[84:87]
	v_mfma_f32_16x16x32_bf16 v[80:83], v[210:213], v[184:187], v[80:83]
	v_mfma_f32_16x16x32_bf16 v[68:71], v[202:205], v[194:197], v[68:71]
	v_mfma_f32_16x16x32_bf16 v[64:67], v[210:213], v[194:197], v[64:67]
	s_setprio 0
	s_mov_b32 m0, s48
	v_lshl_add_u64 v[188:189], v[216:217], 0, s[6:7]
	s_barrier
; __device__ __forceinline__ float bflo(unsigned w) { return __uint_as_float(w << 16); }
; __device__ __forceinline__ float bfhi(unsigned w) { return __uint_as_float(w & 0xffff0000u); }
; __device__ __forceinline__ float sigmoidf_(float x) { return __builtin_amdgcn_rcpf(1.0f + __expf(-x)); }
; #define PG8_STAGE(bufoff, gbase, voff) do { _Pragma("unroll") for (int _i = 0; _i < 2; ++_i) \
;         __builtin_amdgcn_global_load_lds((const unsigned*)((const char*)(gbase) + (voff)[_i]), (LAS unsigned*)(lds + (bufoff) + ldsw + _i * 8192), 16, 0, 0); } while (0)
; #define PG8_LDA(dst, b, h) do { _Pragma("unroll") for (int m = 0; m < 4; ++m) _Pragma("unroll") for (int k = 0; k < 2; ++k) dst[m][k] = *(const LAS bf16x8*)(lds + PG8_SA(b, h) + aoff + m * 2048 + k * 1024); } while (0)
; #define PG8_MMA(ai, bj, At, Bt) do { __builtin_amdgcn_s_setprio(1); _Pragma("unroll") for (int m = 0; m < 4; ++m) _Pragma("unroll") for (int n = 0; n < 2; ++n) _Pragma("unroll") for (int k = 0; k < 2; ++k) \
;         acc[ai][bj][m][n] = __builtin_amdgcn_mfma_f32_16x16x32_bf16(Bt[n][k], At[m][k], acc[ai][bj][m][n], 0, 0, 0); __builtin_amdgcn_s_setprio(0); } while (0)
; #define PG8_WAIT_V(n) asm volatile("s_waitcnt vmcnt(" #n ")" ::: "memory")
; #define PG8_WAIT_L(n) asm volatile("s_waitcnt lgkmcnt(" #n ")" ::: "memory")
; #define PG8_BAR __builtin_amdgcn_s_barrier()
; template <class Epi>
; __device__ __forceinline__ void gemm_phase(LAS unsigned char* lds, const Gemm g, const StaticOrder& S, const Epi& E) {
;     ...
;             PG8_LDA(At, 1, 1); PG8_STAGE(PG8_SA(1, 0), a3, voffA);
;             PG8_BAR; PG8_WAIT_L(0); PG8_MMA(1, 0, At, B0); PG8_BAR; PG8_SCHED;
;             PG8_STAGE(PG8_SB(1, 1), b3 + hstepB, voffB);
;             PG8_WAIT_V(6); PG8_BAR; PG8_MMA(1, 1, At, B1); PG8_BAR;
;         }
;         E(acc, cur, wr, wc, fr, fq);
;     __device__ __forceinline__ void operator()(const AccT& acc, const Unit& u, int wr, int wc, int fr, int fq) const {
;     ...
;                     for (int n = 0; n < 2; ++n) { const size_t o = ro + bj * 128 + n * 16; const f32x4 h = *(const f32x4*)(H + o); const u32x2 pw = *(const u32x2*)(PP + o);
;                         const f32x4 a = acc[ai][bj][m][n]; f32x4 r;
;                         r[0] = h[0] + bflo(pw.x) * sigmoidf_(a[0]); r[1] = h[1] + bfhi(pw.x) * sigmoidf_(a[1]); r[2] = h[2] + bflo(pw.y) * sigmoidf_(a[2]); r[3] = h[3] + bfhi(pw.y) * sigmoidf_(a[3]);
	ds_read_b128 v[164:167], v153 offset:49152
	ds_read_b128 v[168:171], v153 offset:50176
	ds_read_b128 v[172:175], v153 offset:51200
	ds_read_b128 v[176:179], v153 offset:52224
	ds_read_b128 v[180:183], v153 offset:53248
	ds_read_b128 v[184:187], v153 offset:54272
	ds_read_b128 v[190:193], v153 offset:55296
	ds_read_b128 v[194:197], v153 offset:56320
	global_load_lds_dwordx4 v[188:189], off
	v_lshl_add_u64 v[188:189], v[218:219], 0, s[6:7]
	s_mov_b32 m0, s49
	s_nop 0
	global_load_lds_dwordx4 v[188:189], off
	s_barrier
	s_setprio 1
	s_waitcnt lgkmcnt(7)
	v_mfma_f32_16x16x32_bf16 v[60:63], v[140:143], v[164:167], v[60:63]
	v_mfma_f32_16x16x32_bf16 v[56:59], v[156:159], v[164:167], v[56:59]
	s_waitcnt lgkmcnt(5)
	v_mfma_f32_16x16x32_bf16 v[44:47], v[140:143], v[172:175], v[44:47]
	v_mfma_f32_16x16x32_bf16 v[40:43], v[156:159], v[172:175], v[40:43]
	s_waitcnt lgkmcnt(3)
	v_mfma_f32_16x16x32_bf16 v[28:31], v[140:143], v[180:183], v[28:31]
	v_mfma_f32_16x16x32_bf16 v[24:27], v[156:159], v[180:183], v[24:27]
	s_waitcnt lgkmcnt(1)
	v_mfma_f32_16x16x32_bf16 v[12:15], v[140:143], v[190:193], v[12:15]
	v_mfma_f32_16x16x32_bf16 v[8:11], v[156:159], v[190:193], v[8:11]
	v_mfma_f32_16x16x32_bf16 v[60:63], v[144:147], v[168:171], v[60:63]
	v_mfma_f32_16x16x32_bf16 v[56:59], v[160:163], v[168:171], v[56:59]
	v_mfma_f32_16x16x32_bf16 v[44:47], v[144:147], v[176:179], v[44:47]
	v_mfma_f32_16x16x32_bf16 v[40:43], v[160:163], v[176:179], v[40:43]
	v_mfma_f32_16x16x32_bf16 v[28:31], v[144:147], v[184:187], v[28:31]
	v_mfma_f32_16x16x32_bf16 v[24:27], v[160:163], v[184:187], v[24:27]
	s_waitcnt lgkmcnt(0)
	v_mfma_f32_16x16x32_bf16 v[12:15], v[144:147], v[194:197], v[12:15]
	v_mfma_f32_16x16x32_bf16 v[8:11], v[160:163], v[194:197], v[8:11]
	s_setprio 0
	s_barrier
	s_add_u32 s30, s30, 0x80080
	s_addc_u32 s31, s31, 0
	s_add_i32 s36, s36, s43
	v_lshl_add_u64 v[140:141], s[30:31], 0, v[128:129]
	s_mov_b32 m0, s36
	s_nop 0
	global_load_lds_dwordx4 v[140:141], off
	v_lshl_add_u64 v[140:141], s[30:31], 0, v[130:131]
	s_add_i32 m0, s36, 0x2000
	s_nop 0
	global_load_lds_dwordx4 v[140:141], off
	s_waitcnt vmcnt(6)
	s_barrier
	s_setprio 1
	v_mfma_f32_16x16x32_bf16 v[52:55], v[198:201], v[164:167], v[52:55]
	v_mfma_f32_16x16x32_bf16 v[48:51], v[206:209], v[164:167], v[48:51]
	v_mfma_f32_16x16x32_bf16 v[36:39], v[198:201], v[172:175], v[36:39]
	v_mfma_f32_16x16x32_bf16 v[32:35], v[206:209], v[172:175], v[32:35]
	v_mfma_f32_16x16x32_bf16 v[20:23], v[198:201], v[180:183], v[20:23]
	v_mfma_f32_16x16x32_bf16 v[16:19], v[206:209], v[180:183], v[16:19]
	v_mfma_f32_16x16x32_bf16 v[4:7], v[198:201], v[190:193], v[4:7]
	v_mfma_f32_16x16x32_bf16 v[0:3], v[206:209], v[190:193], v[0:3]
	v_mfma_f32_16x16x32_bf16 v[52:55], v[202:205], v[168:171], v[52:55]
	v_mfma_f32_16x16x32_bf16 v[48:51], v[210:213], v[168:171], v[48:51]
	v_mfma_f32_16x16x32_bf16 v[36:39], v[202:205], v[176:179], v[36:39]
	v_mfma_f32_16x16x32_bf16 v[32:35], v[210:213], v[176:179], v[32:35]
	v_mfma_f32_16x16x32_bf16 v[20:23], v[202:205], v[184:187], v[20:23]
	v_mfma_f32_16x16x32_bf16 v[16:19], v[210:213], v[184:187], v[16:19]
	v_mfma_f32_16x16x32_bf16 v[4:7], v[202:205], v[194:197], v[4:7]
	v_mfma_f32_16x16x32_bf16 v[0:3], v[210:213], v[194:197], v[0:3]
	s_setprio 0
	s_add_i32 s67, s67, 2
	s_add_u32 s28, s28, 0x100
	s_addc_u32 s29, s29, 0
	s_add_u32 s65, s65, 0x100
	s_addc_u32 s66, s66, 0
	s_cmp_gt_u32 s67, 29
	s_barrier
	s_cbranch_scc0 .LBB0_1240
	v_lshl_add_u32 v144, s26, 8, v149
	v_lshl_or_b32 v142, s62, 8, v151
	v_ashrrev_i32_e32 v145, 31, v144
	v_ashrrev_i32_e32 v143, 31, v142
	v_lshlrev_b64 v[140:141], 11, v[144:145]
	v_lshl_add_u64 v[140:141], v[140:141], 0, v[142:143]
	v_lshlrev_b64 v[160:161], 1, v[140:141]
	v_lshl_add_u64 v[146:147], s[0:1], 0, v[160:161]
	global_load_dwordx2 v[162:163], v[146:147], off
	v_lshl_add_u64 v[146:147], v[140:141], 2, s[54:55]
	global_load_dwordx4 v[156:159], v[146:147], off
	v_mul_f32_e32 v124, 0xbfb8aa3b, v124
	v_mul_f32_e32 v125, 0xbfb8aa3b, v125
	v_mul_f32_e32 v126, 0xbfb8aa3b, v126
	v_mul_f32_e32 v127, 0xbfb8aa3b, v127
	v_exp_f32_e32 v124, v124
	v_exp_f32_e32 v125, v125
	v_exp_f32_e32 v126, v126
	v_exp_f32_e32 v127, v127
	v_add_f32_e32 v145, 1.0, v124
	v_add_f32_e32 v155, 1.0, v125
	v_add_f32_e32 v164, 1.0, v126
	v_add_f32_e32 v165, 1.0, v127
	v_rcp_f32_e32 v126, v145
	v_rcp_f32_e32 v127, v155
	v_rcp_f32_e32 v164, v164
	v_rcp_f32_e32 v165, v165
	v_or_b32_e32 v124, 32, v160
	v_mov_b32_e32 v125, v161
	v_lshl_add_u64 v[166:167], s[0:1], 0, v[124:125]
	v_mul_f32_e32 v120, 0xbfb8aa3b, v120
	v_mul_f32_e32 v121, 0xbfb8aa3b, v121
	v_mul_f32_e32 v122, 0xbfb8aa3b, v122
	v_mul_f32_e32 v123, 0xbfb8aa3b, v123
	v_exp_f32_e32 v120, v120
	v_exp_f32_e32 v121, v121
	v_exp_f32_e32 v122, v122
	v_exp_f32_e32 v123, v123
	v_add_f32_e32 v145, 1.0, v120
	v_add_f32_e32 v155, 1.0, v121
	v_or_b32_e32 v120, 0x100, v160
	v_mov_b32_e32 v121, v161
	v_mul_f32_e32 v116, 0xbfb8aa3b, v116
	v_mul_f32_e32 v117, 0xbfb8aa3b, v117
	v_mul_f32_e32 v118, 0xbfb8aa3b, v118
	v_mul_f32_e32 v119, 0xbfb8aa3b, v119
	v_exp_f32_e32 v116, v116
	v_exp_f32_e32 v117, v117
	v_exp_f32_e32 v118, v118
	v_exp_f32_e32 v119, v119
	v_add_f32_e32 v116, 1.0, v116
	v_add_f32_e32 v117, 1.0, v117
	v_add_f32_e32 v118, 1.0, v118
	v_add_f32_e32 v119, 1.0, v119
	v_rcp_f32_e32 v116, v116
	v_rcp_f32_e32 v117, v117
	v_rcp_f32_e32 v118, v118
	v_rcp_f32_e32 v119, v119
	v_or_b32_e32 v160, 0x120, v160
	v_mul_f32_e32 v112, 0xbfb8aa3b, v112
	v_mul_f32_e32 v113, 0xbfb8aa3b, v113
	v_mul_f32_e32 v114, 0xbfb8aa3b, v114
	v_mul_f32_e32 v115, 0xbfb8aa3b, v115
	v_exp_f32_e32 v114, v114
	v_exp_f32_e32 v115, v115
	v_mul_f32_e32 v108, 0xbfb8aa3b, v108
	v_mul_f32_e32 v109, 0xbfb8aa3b, v109
	v_add_f32_e32 v114, 1.0, v114
	v_add_f32_e32 v115, 1.0, v115
	v_rcp_f32_e32 v114, v114
	v_rcp_f32_e32 v115, v115
	v_mul_f32_e32 v110, 0xbfb8aa3b, v110
	v_mul_f32_e32 v111, 0xbfb8aa3b, v111
	v_exp_f32_e32 v108, v108
	v_exp_f32_e32 v109, v109
	v_exp_f32_e32 v110, v110
	v_exp_f32_e32 v111, v111
	v_add_f32_e32 v108, 1.0, v108
	v_add_f32_e32 v109, 1.0, v109
	v_add_f32_e32 v110, 1.0, v110
	v_add_f32_e32 v111, 1.0, v111
	v_rcp_f32_e32 v108, v108
	v_rcp_f32_e32 v109, v109
	v_rcp_f32_e32 v110, v110
	v_rcp_f32_e32 v111, v111
	v_mul_f32_e32 v104, 0xbfb8aa3b, v104
	v_mul_f32_e32 v105, 0xbfb8aa3b, v105
	v_mul_f32_e32 v106, 0xbfb8aa3b, v106
	s_waitcnt vmcnt(0)
; __device__ __forceinline__ float bflo(unsigned w) { return __uint_as_float(w << 16); }
; __device__ __forceinline__ float bfhi(unsigned w) { return __uint_as_float(w & 0xffff0000u); }
; __device__ __forceinline__ float sigmoidf_(float x) { return __builtin_amdgcn_rcpf(1.0f + __expf(-x)); }
;     __device__ __forceinline__ void operator()(const AccT& acc, const Unit& u, int wr, int wc, int fr, int fq) const {
;     ...
; #pragma unroll
;         for (int ai = 0; ai < 2; ++ai)
; #pragma unroll
;             for (int m = 0; m < 4; ++m) { const size_t ro = (size_t)(row0 + ai * 128 + m * 16) * DM + col0;
; #pragma unroll
;                 for (int bj = 0; bj < 2; ++bj)
; #pragma unroll
;                     for (int n = 0; n < 2; ++n) { const size_t o = ro + bj * 128 + n * 16; const f32x4 h = *(const f32x4*)(H + o); const u32x2 pw = *(const u32x2*)(PP + o);
;                         const f32x4 a = acc[ai][bj][m][n]; f32x4 r;
;                         r[0] = h[0] + bflo(pw.x) * sigmoidf_(a[0]); r[1] = h[1] + bfhi(pw.x) * sigmoidf_(a[1]); r[2] = h[2] + bflo(pw.y) * sigmoidf_(a[2]); r[3] = h[3] + bfhi(pw.y) * sigmoidf_(a[3]);
;                         *(f32x4*)(H + o) = r; asm volatile("" ::: "memory"); } }
	v_lshlrev_b32_e32 v124, 16, v162
	v_and_b32_e32 v125, 0xffff0000, v162
	v_lshlrev_b32_e32 v162, 16, v163
	v_and_b32_e32 v163, 0xffff0000, v163
	v_pk_fma_f32 v[124:125], v[126:127], v[124:125], v[156:157]
	v_pk_fma_f32 v[126:127], v[164:165], v[162:163], v[158:159]
	global_store_dwordx4 v[146:147], v[124:127], off
	global_load_dwordx2 v[156:157], v[166:167], off
	global_load_dwordx4 v[124:127], v[146:147], off offset:64
	v_add_f32_e32 v158, 1.0, v122
	v_add_f32_e32 v159, 1.0, v123
	v_rcp_f32_e32 v122, v145
	v_rcp_f32_e32 v123, v155
	v_rcp_f32_e32 v158, v158
	v_rcp_f32_e32 v159, v159
	v_lshl_add_u64 v[162:163], s[0:1], 0, v[120:121]
	v_mul_f32_e32 v107, 0xbfb8aa3b, v107
	v_exp_f32_e32 v104, v104
	v_exp_f32_e32 v105, v105
	v_exp_f32_e32 v106, v106
	v_exp_f32_e32 v107, v107
	v_add_f32_e32 v104, 1.0, v104
	v_add_f32_e32 v105, 1.0, v105
	v_add_f32_e32 v106, 1.0, v106
	v_add_f32_e32 v107, 1.0, v107
	v_rcp_f32_e32 v104, v104
	v_rcp_f32_e32 v105, v105
	v_rcp_f32_e32 v106, v106
	v_rcp_f32_e32 v107, v107
	v_mul_f32_e32 v100, 0xbfb8aa3b, v100
	v_mul_f32_e32 v101, 0xbfb8aa3b, v101
	v_mul_f32_e32 v102, 0xbfb8aa3b, v102
	v_mul_f32_e32 v103, 0xbfb8aa3b, v103
	v_exp_f32_e32 v100, v100
	v_exp_f32_e32 v101, v101
	v_exp_f32_e32 v102, v102
	v_exp_f32_e32 v103, v103
	v_add_f32_e32 v100, 1.0, v100
	v_add_f32_e32 v101, 1.0, v101
	v_add_f32_e32 v102, 1.0, v102
	v_add_f32_e32 v103, 1.0, v103
	v_rcp_f32_e32 v100, v100
	v_rcp_f32_e32 v101, v101
	v_rcp_f32_e32 v102, v102
	v_rcp_f32_e32 v103, v103
	v_mul_f32_e32 v96, 0xbfb8aa3b, v96
	v_mul_f32_e32 v97, 0xbfb8aa3b, v97
	v_mul_f32_e32 v98, 0xbfb8aa3b, v98
	v_mul_f32_e32 v99, 0xbfb8aa3b, v99
	v_exp_f32_e32 v98, v98
	v_exp_f32_e32 v99, v99
	v_mul_f32_e32 v92, 0xbfb8aa3b, v92
	v_mul_f32_e32 v93, 0xbfb8aa3b, v93
	v_add_f32_e32 v98, 1.0, v98
	v_add_f32_e32 v99, 1.0, v99
	v_rcp_f32_e32 v98, v98
	v_rcp_f32_e32 v99, v99
	v_mul_f32_e32 v94, 0xbfb8aa3b, v94
	v_mul_f32_e32 v95, 0xbfb8aa3b, v95
	v_exp_f32_e32 v92, v92
	v_exp_f32_e32 v93, v93
	v_exp_f32_e32 v94, v94
	v_exp_f32_e32 v95, v95
	v_add_f32_e32 v92, 1.0, v92
	v_add_f32_e32 v93, 1.0, v93
	v_add_f32_e32 v94, 1.0, v94
	v_add_f32_e32 v95, 1.0, v95
	v_rcp_f32_e32 v92, v92
	v_rcp_f32_e32 v93, v93
	v_rcp_f32_e32 v94, v94
	v_rcp_f32_e32 v95, v95
	v_mul_f32_e32 v88, 0xbfb8aa3b, v88
	v_mul_f32_e32 v89, 0xbfb8aa3b, v89
	v_mul_f32_e32 v90, 0xbfb8aa3b, v90
	v_mul_f32_e32 v91, 0xbfb8aa3b, v91
	v_exp_f32_e32 v88, v88
	v_exp_f32_e32 v89, v89
	v_exp_f32_e32 v90, v90
	v_exp_f32_e32 v91, v91
	v_add_f32_e32 v88, 1.0, v88
	v_add_f32_e32 v89, 1.0, v89
	v_add_f32_e32 v90, 1.0, v90
	v_add_f32_e32 v91, 1.0, v91
	v_rcp_f32_e32 v88, v88
	v_rcp_f32_e32 v89, v89
	v_rcp_f32_e32 v90, v90
	v_rcp_f32_e32 v91, v91
	s_waitcnt vmcnt(0)
	v_lshlrev_b32_e32 v120, 16, v156
	v_and_b32_e32 v121, 0xffff0000, v156
	v_lshlrev_b32_e32 v156, 16, v157
	v_and_b32_e32 v157, 0xffff0000, v157
	v_pk_fma_f32 v[120:121], v[122:123], v[120:121], v[124:125]
	v_pk_fma_f32 v[122:123], v[158:159], v[156:157], v[126:127]
	global_store_dwordx4 v[146:147], v[120:123], off offset:64
	global_load_dwordx2 v[124:125], v[162:163], off
	global_load_dwordx4 v[120:123], v[146:147], off offset:512
	v_lshl_add_u64 v[126:127], s[0:1], 0, v[160:161]
	v_mul_f32_e32 v84, 0xbfb8aa3b, v84
	v_mul_f32_e32 v85, 0xbfb8aa3b, v85
	v_mul_f32_e32 v86, 0xbfb8aa3b, v86
	v_mul_f32_e32 v87, 0xbfb8aa3b, v87
	v_exp_f32_e32 v84, v84
	v_exp_f32_e32 v85, v85
	v_exp_f32_e32 v86, v86
	v_exp_f32_e32 v87, v87
	v_add_f32_e32 v84, 1.0, v84
	v_add_f32_e32 v85, 1.0, v85
	v_add_f32_e32 v86, 1.0, v86
	v_add_f32_e32 v87, 1.0, v87
	v_rcp_f32_e32 v84, v84
	v_rcp_f32_e32 v85, v85
	v_rcp_f32_e32 v86, v86
	v_rcp_f32_e32 v87, v87
	v_mul_f32_e32 v80, 0xbfb8aa3b, v80
	v_mul_f32_e32 v81, 0xbfb8aa3b, v81
	v_mul_f32_e32 v82, 0xbfb8aa3b, v82
	v_mul_f32_e32 v83, 0xbfb8aa3b, v83
	v_exp_f32_e32 v82, v82
	v_exp_f32_e32 v83, v83
	v_mul_f32_e32 v76, 0xbfb8aa3b, v76
	v_mul_f32_e32 v77, 0xbfb8aa3b, v77
	v_add_f32_e32 v82, 1.0, v82
	v_add_f32_e32 v83, 1.0, v83
	v_rcp_f32_e32 v82, v82
	v_rcp_f32_e32 v83, v83
	v_mul_f32_e32 v78, 0xbfb8aa3b, v78
	v_mul_f32_e32 v79, 0xbfb8aa3b, v79
	v_exp_f32_e32 v76, v76
	v_exp_f32_e32 v77, v77
	v_exp_f32_e32 v78, v78
	v_exp_f32_e32 v79, v79
	v_add_f32_e32 v76, 1.0, v76
	v_add_f32_e32 v77, 1.0, v77
	v_add_f32_e32 v78, 1.0, v78
	v_add_f32_e32 v79, 1.0, v79
	v_rcp_f32_e32 v76, v76
	v_rcp_f32_e32 v77, v77
	v_rcp_f32_e32 v78, v78
	v_rcp_f32_e32 v79, v79
	v_mul_f32_e32 v72, 0xbfb8aa3b, v72
	v_mul_f32_e32 v73, 0xbfb8aa3b, v73
	v_mul_f32_e32 v74, 0xbfb8aa3b, v74
	v_mul_f32_e32 v75, 0xbfb8aa3b, v75
	v_exp_f32_e32 v72, v72
	v_exp_f32_e32 v73, v73
	v_exp_f32_e32 v74, v74
	v_exp_f32_e32 v75, v75
	v_add_f32_e32 v72, 1.0, v72
	v_add_f32_e32 v73, 1.0, v73
	v_add_f32_e32 v74, 1.0, v74
	v_add_f32_e32 v75, 1.0, v75
	v_rcp_f32_e32 v72, v72
	v_rcp_f32_e32 v73, v73
	v_rcp_f32_e32 v74, v74
	v_rcp_f32_e32 v75, v75
	v_mul_f32_e32 v68, 0xbfb8aa3b, v68
	v_mul_f32_e32 v69, 0xbfb8aa3b, v69
	v_mul_f32_e32 v70, 0xbfb8aa3b, v70
	v_mul_f32_e32 v71, 0xbfb8aa3b, v71
	v_exp_f32_e32 v68, v68
	v_exp_f32_e32 v69, v69
	v_exp_f32_e32 v70, v70
	v_exp_f32_e32 v71, v71
	v_add_f32_e32 v68, 1.0, v68
	v_add_f32_e32 v69, 1.0, v69
	v_add_f32_e32 v70, 1.0, v70
	v_add_f32_e32 v71, 1.0, v71
	v_rcp_f32_e32 v68, v68
	v_rcp_f32_e32 v69, v69
	v_rcp_f32_e32 v70, v70
	v_rcp_f32_e32 v71, v71
	v_mul_f32_e32 v64, 0xbfb8aa3b, v64
	v_mul_f32_e32 v65, 0xbfb8aa3b, v65
	v_mul_f32_e32 v66, 0xbfb8aa3b, v66
	s_waitcnt vmcnt(0)
; __device__ __forceinline__ float bflo(unsigned w) { return __uint_as_float(w << 16); }
; __device__ __forceinline__ float bfhi(unsigned w) { return __uint_as_float(w & 0xffff0000u); }
; __device__ __forceinline__ float sigmoidf_(float x) { return __builtin_amdgcn_rcpf(1.0f + __expf(-x)); }
;     __device__ __forceinline__ void operator()(const AccT& acc, const Unit& u, int wr, int wc, int fr, int fq) const {
;     ...
; #pragma unroll
;         for (int ai = 0; ai < 2; ++ai)
; #pragma unroll
;             for (int m = 0; m < 4; ++m) { const size_t ro = (size_t)(row0 + ai * 128 + m * 16) * DM + col0;
; #pragma unroll
;                 for (int bj = 0; bj < 2; ++bj)
; #pragma unroll
;                     for (int n = 0; n < 2; ++n) { const size_t o = ro + bj * 128 + n * 16; const f32x4 h = *(const f32x4*)(H + o); const u32x2 pw = *(const u32x2*)(PP + o);
;                         const f32x4 a = acc[ai][bj][m][n]; f32x4 r;
;                         r[0] = h[0] + bflo(pw.x) * sigmoidf_(a[0]); r[1] = h[1] + bfhi(pw.x) * sigmoidf_(a[1]); r[2] = h[2] + bflo(pw.y) * sigmoidf_(a[2]); r[3] = h[3] + bfhi(pw.y) * sigmoidf_(a[3]);
;                         *(f32x4*)(H + o) = r; asm volatile("" ::: "memory"); } }
	v_lshlrev_b32_e32 v156, 16, v124
	v_and_b32_e32 v157, 0xffff0000, v124
	v_lshlrev_b32_e32 v124, 16, v125
	v_and_b32_e32 v125, 0xffff0000, v125
	v_pk_fma_f32 v[116:117], v[116:117], v[156:157], v[120:121]
	v_pk_fma_f32 v[118:119], v[118:119], v[124:125], v[122:123]
	global_store_dwordx4 v[146:147], v[116:119], off offset:512
	global_load_dwordx2 v[120:121], v[126:127], off
	global_load_dwordx4 v[116:119], v[146:147], off offset:576
	v_exp_f32_e32 v124, v112
	v_exp_f32_e32 v125, v113
	v_or_b32_e32 v112, 16, v144
	v_ashrrev_i32_e32 v113, 31, v112
	v_lshlrev_b64 v[112:113], 11, v[112:113]
	v_lshl_add_u64 v[122:123], v[112:113], 0, v[142:143]
	v_add_f32_e32 v112, 1.0, v124
	v_add_f32_e32 v113, 1.0, v125
	v_rcp_f32_e32 v112, v112
	v_rcp_f32_e32 v113, v113
	v_lshlrev_b64 v[124:125], 1, v[122:123]
	v_lshl_add_u64 v[126:127], s[0:1], 0, v[124:125]
	v_mul_f32_e32 v67, 0xbfb8aa3b, v67
	v_exp_f32_e32 v64, v64
	v_exp_f32_e32 v65, v65
	v_exp_f32_e32 v66, v66
	v_exp_f32_e32 v67, v67
	v_add_f32_e32 v64, 1.0, v64
	v_add_f32_e32 v65, 1.0, v65
	v_add_f32_e32 v66, 1.0, v66
	v_add_f32_e32 v67, 1.0, v67
	v_rcp_f32_e32 v64, v64
	v_rcp_f32_e32 v65, v65
	v_rcp_f32_e32 v66, v66
	v_rcp_f32_e32 v67, v67
	v_mul_f32_e32 v60, 0xbfb8aa3b, v60
	v_mul_f32_e32 v61, 0xbfb8aa3b, v61
	v_mul_f32_e32 v62, 0xbfb8aa3b, v62
	v_mul_f32_e32 v63, 0xbfb8aa3b, v63
	v_exp_f32_e32 v60, v60
	v_exp_f32_e32 v61, v61
	v_exp_f32_e32 v62, v62
	v_exp_f32_e32 v63, v63
	v_add_f32_e32 v60, 1.0, v60
	v_add_f32_e32 v61, 1.0, v61
	v_add_f32_e32 v62, 1.0, v62
	v_add_f32_e32 v63, 1.0, v63
	v_rcp_f32_e32 v60, v60
	v_rcp_f32_e32 v61, v61
	v_rcp_f32_e32 v62, v62
	v_rcp_f32_e32 v63, v63
	v_mul_f32_e32 v56, 0xbfb8aa3b, v56
	v_mul_f32_e32 v57, 0xbfb8aa3b, v57
	v_mul_f32_e32 v58, 0xbfb8aa3b, v58
	v_mul_f32_e32 v59, 0xbfb8aa3b, v59
	v_exp_f32_e32 v56, v56
	v_exp_f32_e32 v57, v57
	v_exp_f32_e32 v58, v58
	v_exp_f32_e32 v59, v59
	v_add_f32_e32 v56, 1.0, v56
	v_add_f32_e32 v57, 1.0, v57
	v_add_f32_e32 v58, 1.0, v58
	v_add_f32_e32 v59, 1.0, v59
	v_rcp_f32_e32 v56, v56
	v_rcp_f32_e32 v57, v57
	v_rcp_f32_e32 v58, v58
	v_rcp_f32_e32 v59, v59
	v_mul_f32_e32 v52, 0xbfb8aa3b, v52
	v_mul_f32_e32 v53, 0xbfb8aa3b, v53
	v_mul_f32_e32 v54, 0xbfb8aa3b, v54
	v_mul_f32_e32 v55, 0xbfb8aa3b, v55
	v_exp_f32_e32 v52, v52
	v_exp_f32_e32 v53, v53
	v_exp_f32_e32 v54, v54
	v_exp_f32_e32 v55, v55
	v_add_f32_e32 v52, 1.0, v52
	v_add_f32_e32 v53, 1.0, v53
	v_add_f32_e32 v54, 1.0, v54
	v_add_f32_e32 v55, 1.0, v55
	v_rcp_f32_e32 v52, v52
	v_rcp_f32_e32 v53, v53
	v_rcp_f32_e32 v54, v54
	v_rcp_f32_e32 v55, v55
	v_mul_f32_e32 v48, 0xbfb8aa3b, v48
	v_mul_f32_e32 v49, 0xbfb8aa3b, v49
	v_mul_f32_e32 v50, 0xbfb8aa3b, v50
	v_mul_f32_e32 v51, 0xbfb8aa3b, v51
	v_exp_f32_e32 v48, v48
	s_waitcnt vmcnt(0)
	v_lshlrev_b32_e32 v156, 16, v120
	v_and_b32_e32 v157, 0xffff0000, v120
	v_lshlrev_b32_e32 v120, 16, v121
	v_and_b32_e32 v121, 0xffff0000, v121
	v_pk_fma_f32 v[112:113], v[112:113], v[156:157], v[116:117]
	v_pk_fma_f32 v[114:115], v[114:115], v[120:121], v[118:119]
	global_store_dwordx4 v[146:147], v[112:115], off offset:576
	global_load_dwordx2 v[116:117], v[126:127], off
	v_lshl_add_u64 v[118:119], v[122:123], 2, s[54:55]
	global_load_dwordx4 v[112:115], v[118:119], off
	v_or_b32_e32 v120, 32, v124
	v_mov_b32_e32 v121, v125
	v_lshl_add_u64 v[120:121], s[0:1], 0, v[120:121]
	v_exp_f32_e32 v49, v49
	v_exp_f32_e32 v50, v50
	v_exp_f32_e32 v51, v51
	v_add_f32_e32 v48, 1.0, v48
	v_add_f32_e32 v49, 1.0, v49
	v_add_f32_e32 v50, 1.0, v50
	v_add_f32_e32 v51, 1.0, v51
	v_rcp_f32_e32 v48, v48
	v_rcp_f32_e32 v49, v49
	v_rcp_f32_e32 v50, v50
	v_rcp_f32_e32 v51, v51
	v_mul_f32_e32 v44, 0xbfb8aa3b, v44
	v_mul_f32_e32 v45, 0xbfb8aa3b, v45
	v_mul_f32_e32 v46, 0xbfb8aa3b, v46
	v_mul_f32_e32 v47, 0xbfb8aa3b, v47
	v_exp_f32_e32 v44, v44
	v_exp_f32_e32 v45, v45
	v_exp_f32_e32 v46, v46
	v_exp_f32_e32 v47, v47
	v_add_f32_e32 v44, 1.0, v44
	v_add_f32_e32 v45, 1.0, v45
	v_add_f32_e32 v46, 1.0, v46
	v_add_f32_e32 v47, 1.0, v47
	v_rcp_f32_e32 v44, v44
	v_rcp_f32_e32 v45, v45
	v_rcp_f32_e32 v46, v46
	v_rcp_f32_e32 v47, v47
	v_mul_f32_e32 v40, 0xbfb8aa3b, v40
	v_mul_f32_e32 v41, 0xbfb8aa3b, v41
	v_mul_f32_e32 v42, 0xbfb8aa3b, v42
	v_mul_f32_e32 v43, 0xbfb8aa3b, v43
	v_exp_f32_e32 v40, v40
	v_exp_f32_e32 v41, v41
	v_exp_f32_e32 v42, v42
	v_exp_f32_e32 v43, v43
	v_add_f32_e32 v40, 1.0, v40
	v_add_f32_e32 v41, 1.0, v41
	v_add_f32_e32 v42, 1.0, v42
	v_add_f32_e32 v43, 1.0, v43
	v_rcp_f32_e32 v40, v40
	v_rcp_f32_e32 v41, v41
	v_rcp_f32_e32 v42, v42
	v_rcp_f32_e32 v43, v43
	v_mul_f32_e32 v36, 0xbfb8aa3b, v36
	v_mul_f32_e32 v37, 0xbfb8aa3b, v37
	v_mul_f32_e32 v38, 0xbfb8aa3b, v38
	v_mul_f32_e32 v39, 0xbfb8aa3b, v39
	v_exp_f32_e32 v36, v36
	v_exp_f32_e32 v37, v37
	v_exp_f32_e32 v38, v38
	v_exp_f32_e32 v39, v39
	v_add_f32_e32 v36, 1.0, v36
	v_add_f32_e32 v37, 1.0, v37
	v_add_f32_e32 v38, 1.0, v38
	v_add_f32_e32 v39, 1.0, v39
	v_rcp_f32_e32 v36, v36
	v_rcp_f32_e32 v37, v37
	v_rcp_f32_e32 v38, v38
	v_rcp_f32_e32 v39, v39
	v_mul_f32_e32 v32, 0xbfb8aa3b, v32
	v_mul_f32_e32 v33, 0xbfb8aa3b, v33
	v_mul_f32_e32 v34, 0xbfb8aa3b, v34
	v_mul_f32_e32 v35, 0xbfb8aa3b, v35
	v_exp_f32_e32 v32, v32
	v_exp_f32_e32 v33, v33
	v_exp_f32_e32 v34, v34
	v_exp_f32_e32 v35, v35
	v_add_f32_e32 v32, 1.0, v32
	v_add_f32_e32 v33, 1.0, v33
	v_add_f32_e32 v34, 1.0, v34
	v_add_f32_e32 v35, 1.0, v35
	v_rcp_f32_e32 v32, v32
	v_rcp_f32_e32 v33, v33
	v_rcp_f32_e32 v34, v34
	s_waitcnt vmcnt(0)
; __device__ __forceinline__ float bflo(unsigned w) { return __uint_as_float(w << 16); }
; __device__ __forceinline__ float bfhi(unsigned w) { return __uint_as_float(w & 0xffff0000u); }
; __device__ __forceinline__ float sigmoidf_(float x) { return __builtin_amdgcn_rcpf(1.0f + __expf(-x)); }
; template <class Epi>
; __device__ __forceinline__ void gemm_phase(LAS unsigned char* lds, const Gemm g, const StaticOrder& S, const Epi& E) {
;     ...
;         cur = nxt; cA = nA; cB = nB; ++ui;
;     __device__ __forceinline__ void operator()(const AccT& acc, const Unit& u, int wr, int wc, int fr, int fq) const {
;     ...
; #pragma unroll
;         for (int ai = 0; ai < 2; ++ai)
; #pragma unroll
;             for (int m = 0; m < 4; ++m) { const size_t ro = (size_t)(row0 + ai * 128 + m * 16) * DM + col0;
; #pragma unroll
;                 for (int bj = 0; bj < 2; ++bj)
; #pragma unroll
;                     for (int n = 0; n < 2; ++n) { const size_t o = ro + bj * 128 + n * 16; const f32x4 h = *(const f32x4*)(H + o); const u32x2 pw = *(const u32x2*)(PP + o);
;                         const f32x4 a = acc[ai][bj][m][n]; f32x4 r;
;                         r[0] = h[0] + bflo(pw.x) * sigmoidf_(a[0]); r[1] = h[1] + bfhi(pw.x) * sigmoidf_(a[1]); r[2] = h[2] + bflo(pw.y) * sigmoidf_(a[2]); r[3] = h[3] + bfhi(pw.y) * sigmoidf_(a[3]);
;                         *(f32x4*)(H + o) = r; asm volatile("" ::: "memory"); } }
	v_lshlrev_b32_e32 v122, 16, v116
	v_and_b32_e32 v123, 0xffff0000, v116
	v_lshlrev_b32_e32 v116, 16, v117
	v_and_b32_e32 v117, 0xffff0000, v117
	v_pk_fma_f32 v[108:109], v[108:109], v[122:123], v[112:113]
	v_pk_fma_f32 v[110:111], v[110:111], v[116:117], v[114:115]
	global_store_dwordx4 v[118:119], v[108:111], off
	global_load_dwordx2 v[112:113], v[120:121], off
	global_load_dwordx4 v[108:111], v[118:119], off offset:64
	v_or_b32_e32 v114, 0x100, v124
	v_mov_b32_e32 v115, v125
	v_lshl_add_u64 v[114:115], s[0:1], 0, v[114:115]
	v_or_b32_e32 v124, 0x120, v124
	v_rcp_f32_e32 v35, v35
	v_mul_f32_e32 v28, 0xbfb8aa3b, v28
	v_mul_f32_e32 v29, 0xbfb8aa3b, v29
	v_mul_f32_e32 v30, 0xbfb8aa3b, v30
	v_mul_f32_e32 v31, 0xbfb8aa3b, v31
	v_exp_f32_e32 v28, v28
	v_exp_f32_e32 v29, v29
	v_exp_f32_e32 v30, v30
	v_exp_f32_e32 v31, v31
	v_add_f32_e32 v28, 1.0, v28
	v_add_f32_e32 v29, 1.0, v29
	v_add_f32_e32 v30, 1.0, v30
	v_add_f32_e32 v31, 1.0, v31
	v_rcp_f32_e32 v28, v28
	v_rcp_f32_e32 v29, v29
	v_rcp_f32_e32 v30, v30
	v_rcp_f32_e32 v31, v31
	v_mul_f32_e32 v24, 0xbfb8aa3b, v24
	v_mul_f32_e32 v25, 0xbfb8aa3b, v25
	v_mul_f32_e32 v26, 0xbfb8aa3b, v26
	v_mul_f32_e32 v27, 0xbfb8aa3b, v27
	v_exp_f32_e32 v24, v24
	v_exp_f32_e32 v25, v25
	v_exp_f32_e32 v26, v26
	v_exp_f32_e32 v27, v27
	v_add_f32_e32 v24, 1.0, v24
	v_add_f32_e32 v25, 1.0, v25
	v_add_f32_e32 v26, 1.0, v26
	v_add_f32_e32 v27, 1.0, v27
	v_rcp_f32_e32 v24, v24
	v_rcp_f32_e32 v25, v25
	v_rcp_f32_e32 v26, v26
	v_rcp_f32_e32 v27, v27
	v_mul_f32_e32 v20, 0xbfb8aa3b, v20
	v_mul_f32_e32 v21, 0xbfb8aa3b, v21
	v_mul_f32_e32 v22, 0xbfb8aa3b, v22
	v_mul_f32_e32 v23, 0xbfb8aa3b, v23
	v_exp_f32_e32 v20, v20
	v_exp_f32_e32 v21, v21
	v_exp_f32_e32 v22, v22
	v_exp_f32_e32 v23, v23
	v_add_f32_e32 v20, 1.0, v20
	v_add_f32_e32 v21, 1.0, v21
	v_add_f32_e32 v22, 1.0, v22
	v_add_f32_e32 v23, 1.0, v23
	v_rcp_f32_e32 v20, v20
	v_rcp_f32_e32 v21, v21
	v_rcp_f32_e32 v22, v22
	v_rcp_f32_e32 v23, v23
	v_mul_f32_e32 v16, 0xbfb8aa3b, v16
	v_mul_f32_e32 v17, 0xbfb8aa3b, v17
	v_mul_f32_e32 v18, 0xbfb8aa3b, v18
	v_mul_f32_e32 v19, 0xbfb8aa3b, v19
	v_exp_f32_e32 v16, v16
	v_exp_f32_e32 v17, v17
	v_exp_f32_e32 v18, v18
	v_exp_f32_e32 v19, v19
	v_add_f32_e32 v16, 1.0, v16
	v_add_f32_e32 v17, 1.0, v17
	v_add_f32_e32 v18, 1.0, v18
	v_add_f32_e32 v19, 1.0, v19
	v_rcp_f32_e32 v16, v16
	v_rcp_f32_e32 v17, v17
	v_rcp_f32_e32 v18, v18
	v_rcp_f32_e32 v19, v19
	v_mul_f32_e32 v12, 0xbfb8aa3b, v12
	v_mul_f32_e32 v13, 0xbfb8aa3b, v13
	v_mul_f32_e32 v14, 0xbfb8aa3b, v14
	v_mul_f32_e32 v15, 0xbfb8aa3b, v15
	v_exp_f32_e32 v12, v12
	v_exp_f32_e32 v13, v13
	v_exp_f32_e32 v14, v14
	v_exp_f32_e32 v15, v15
	v_add_f32_e32 v12, 1.0, v12
	s_waitcnt vmcnt(0)
	v_lshlrev_b32_e32 v116, 16, v112
	v_and_b32_e32 v117, 0xffff0000, v112
	v_lshlrev_b32_e32 v112, 16, v113
	v_and_b32_e32 v113, 0xffff0000, v113
	v_pk_fma_f32 v[104:105], v[104:105], v[116:117], v[108:109]
	v_pk_fma_f32 v[106:107], v[106:107], v[112:113], v[110:111]
	global_store_dwordx4 v[118:119], v[104:107], off offset:64
	global_load_dwordx2 v[108:109], v[114:115], off
	global_load_dwordx4 v[104:107], v[118:119], off offset:512
	v_lshl_add_u64 v[110:111], s[0:1], 0, v[124:125]
	v_add_f32_e32 v13, 1.0, v13
	v_add_f32_e32 v14, 1.0, v14
	v_add_f32_e32 v15, 1.0, v15
	v_rcp_f32_e32 v12, v12
	v_rcp_f32_e32 v13, v13
	v_rcp_f32_e32 v14, v14
	v_rcp_f32_e32 v15, v15
	v_mul_f32_e32 v8, 0xbfb8aa3b, v8
	v_mul_f32_e32 v9, 0xbfb8aa3b, v9
	v_mul_f32_e32 v10, 0xbfb8aa3b, v10
	v_mul_f32_e32 v11, 0xbfb8aa3b, v11
	v_exp_f32_e32 v8, v8
	v_exp_f32_e32 v9, v9
	v_exp_f32_e32 v10, v10
	v_exp_f32_e32 v11, v11
	v_add_f32_e32 v8, 1.0, v8
	v_add_f32_e32 v9, 1.0, v9
	v_add_f32_e32 v10, 1.0, v10
	v_add_f32_e32 v11, 1.0, v11
	v_rcp_f32_e32 v8, v8
	v_rcp_f32_e32 v9, v9
	v_rcp_f32_e32 v10, v10
	v_rcp_f32_e32 v11, v11
	v_mul_f32_e32 v4, 0xbfb8aa3b, v4
	v_mul_f32_e32 v5, 0xbfb8aa3b, v5
	v_mul_f32_e32 v6, 0xbfb8aa3b, v6
	v_mul_f32_e32 v7, 0xbfb8aa3b, v7
	v_exp_f32_e32 v4, v4
	v_exp_f32_e32 v5, v5
	v_exp_f32_e32 v6, v6
	v_exp_f32_e32 v7, v7
	v_add_f32_e32 v4, 1.0, v4
	v_add_f32_e32 v5, 1.0, v5
	v_add_f32_e32 v6, 1.0, v6
	v_add_f32_e32 v7, 1.0, v7
	v_rcp_f32_e32 v4, v4
	v_rcp_f32_e32 v5, v5
	v_rcp_f32_e32 v6, v6
	v_rcp_f32_e32 v7, v7
	v_mul_f32_e32 v0, 0xbfb8aa3b, v0
	v_mul_f32_e32 v1, 0xbfb8aa3b, v1
	v_mul_f32_e32 v2, 0xbfb8aa3b, v2
	v_mul_f32_e32 v3, 0xbfb8aa3b, v3
	v_exp_f32_e32 v0, v0
	v_exp_f32_e32 v1, v1
	v_exp_f32_e32 v2, v2
	v_exp_f32_e32 v3, v3
	v_add_f32_e32 v0, 1.0, v0
	v_add_f32_e32 v1, 1.0, v1
	v_add_f32_e32 v2, 1.0, v2
	v_add_f32_e32 v3, 1.0, v3
	v_rcp_f32_e32 v0, v0
	v_rcp_f32_e32 v1, v1
	v_rcp_f32_e32 v2, v2
	v_rcp_f32_e32 v3, v3
	s_and_b64 vcc, exec, s[4:5]
	s_mov_b32 s62, s18
	s_mov_b32 s26, s20
	s_mov_b64 s[30:31], s[24:25]
	s_mov_b64 s[28:29], s[22:23]
	s_waitcnt vmcnt(0)
	v_lshlrev_b32_e32 v112, 16, v108
	v_and_b32_e32 v113, 0xffff0000, v108
	v_lshlrev_b32_e32 v108, 16, v109
	v_and_b32_e32 v109, 0xffff0000, v109
	v_pk_fma_f32 v[100:101], v[100:101], v[112:113], v[104:105]
	v_pk_fma_f32 v[102:103], v[102:103], v[108:109], v[106:107]
	global_store_dwordx4 v[118:119], v[100:103], off offset:512
	global_load_dwordx2 v[104:105], v[110:111], off
	global_load_dwordx4 v[100:103], v[118:119], off offset:576
	v_exp_f32_e32 v108, v96
	v_exp_f32_e32 v109, v97
	v_or_b32_e32 v96, 32, v144
	v_ashrrev_i32_e32 v97, 31, v96
	v_lshlrev_b64 v[96:97], 11, v[96:97]
	v_lshl_add_u64 v[106:107], v[96:97], 0, v[142:143]
	v_add_f32_e32 v96, 1.0, v108
	v_add_f32_e32 v97, 1.0, v109
	v_rcp_f32_e32 v96, v96
	v_rcp_f32_e32 v97, v97
	v_lshlrev_b64 v[108:109], 1, v[106:107]
	v_lshl_add_u64 v[110:111], s[0:1], 0, v[108:109]
	s_waitcnt vmcnt(0)
; __device__ __forceinline__ float bflo(unsigned w) { return __uint_as_float(w << 16); }
; __device__ __forceinline__ float bfhi(unsigned w) { return __uint_as_float(w & 0xffff0000u); }
; __device__ __forceinline__ float sigmoidf_(float x) { return __builtin_amdgcn_rcpf(1.0f + __expf(-x)); }
;     __device__ __forceinline__ void operator()(const AccT& acc, const Unit& u, int wr, int wc, int fr, int fq) const {
;     ...
; #pragma unroll
;         for (int ai = 0; ai < 2; ++ai)
; #pragma unroll
;             for (int m = 0; m < 4; ++m) { const size_t ro = (size_t)(row0 + ai * 128 + m * 16) * DM + col0;
; #pragma unroll
;                 for (int bj = 0; bj < 2; ++bj)
; #pragma unroll
;                     for (int n = 0; n < 2; ++n) { const size_t o = ro + bj * 128 + n * 16; const f32x4 h = *(const f32x4*)(H + o); const u32x2 pw = *(const u32x2*)(PP + o);
;                         const f32x4 a = acc[ai][bj][m][n]; f32x4 r;
;                         r[0] = h[0] + bflo(pw.x) * sigmoidf_(a[0]); r[1] = h[1] + bfhi(pw.x) * sigmoidf_(a[1]); r[2] = h[2] + bflo(pw.y) * sigmoidf_(a[2]); r[3] = h[3] + bfhi(pw.y) * sigmoidf_(a[3]);
;                         *(f32x4*)(H + o) = r; asm volatile("" ::: "memory"); } }
	v_lshlrev_b32_e32 v112, 16, v104
	v_and_b32_e32 v113, 0xffff0000, v104
	v_lshlrev_b32_e32 v104, 16, v105
	v_and_b32_e32 v105, 0xffff0000, v105
	v_pk_fma_f32 v[96:97], v[96:97], v[112:113], v[100:101]
	v_pk_fma_f32 v[98:99], v[98:99], v[104:105], v[102:103]
	global_store_dwordx4 v[118:119], v[96:99], off offset:576
	global_load_dwordx2 v[100:101], v[110:111], off
	v_lshl_add_u64 v[102:103], v[106:107], 2, s[54:55]
	global_load_dwordx4 v[96:99], v[102:103], off
	v_or_b32_e32 v104, 32, v108
	v_mov_b32_e32 v105, v109
	v_lshl_add_u64 v[104:105], s[0:1], 0, v[104:105]
	s_waitcnt vmcnt(0)
	v_lshlrev_b32_e32 v106, 16, v100
	v_and_b32_e32 v107, 0xffff0000, v100
	v_lshlrev_b32_e32 v100, 16, v101
	v_and_b32_e32 v101, 0xffff0000, v101
	v_pk_fma_f32 v[92:93], v[92:93], v[106:107], v[96:97]
	v_pk_fma_f32 v[94:95], v[94:95], v[100:101], v[98:99]
	global_store_dwordx4 v[102:103], v[92:95], off
	global_load_dwordx2 v[96:97], v[104:105], off
	global_load_dwordx4 v[92:95], v[102:103], off offset:64
	v_or_b32_e32 v98, 0x100, v108
	v_mov_b32_e32 v99, v109
	v_lshl_add_u64 v[98:99], s[0:1], 0, v[98:99]
	v_or_b32_e32 v108, 0x120, v108
	s_waitcnt vmcnt(0)
	v_lshlrev_b32_e32 v100, 16, v96
	v_and_b32_e32 v101, 0xffff0000, v96
	v_lshlrev_b32_e32 v96, 16, v97
	v_and_b32_e32 v97, 0xffff0000, v97
	v_pk_fma_f32 v[88:89], v[88:89], v[100:101], v[92:93]
	v_pk_fma_f32 v[90:91], v[90:91], v[96:97], v[94:95]
	global_store_dwordx4 v[102:103], v[88:91], off offset:64
	global_load_dwordx2 v[92:93], v[98:99], off
	global_load_dwordx4 v[88:91], v[102:103], off offset:512
	v_lshl_add_u64 v[94:95], s[0:1], 0, v[108:109]
	s_waitcnt vmcnt(0)
	v_lshlrev_b32_e32 v96, 16, v92
	v_and_b32_e32 v97, 0xffff0000, v92
	v_lshlrev_b32_e32 v92, 16, v93
	v_and_b32_e32 v93, 0xffff0000, v93
	v_pk_fma_f32 v[84:85], v[84:85], v[96:97], v[88:89]
	v_pk_fma_f32 v[86:87], v[86:87], v[92:93], v[90:91]
	global_store_dwordx4 v[102:103], v[84:87], off offset:512
	global_load_dwordx2 v[88:89], v[94:95], off
	global_load_dwordx4 v[84:87], v[102:103], off offset:576
	v_exp_f32_e32 v92, v80
	v_exp_f32_e32 v93, v81
	v_or_b32_e32 v80, 48, v144
	v_ashrrev_i32_e32 v81, 31, v80
	v_lshlrev_b64 v[80:81], 11, v[80:81]
	v_lshl_add_u64 v[90:91], v[80:81], 0, v[142:143]
	v_add_f32_e32 v80, 1.0, v92
	v_add_f32_e32 v81, 1.0, v93
	v_rcp_f32_e32 v80, v80
	v_rcp_f32_e32 v81, v81
	v_lshlrev_b64 v[92:93], 1, v[90:91]
	v_lshl_add_u64 v[94:95], s[0:1], 0, v[92:93]
	s_waitcnt vmcnt(0)
	v_lshlrev_b32_e32 v96, 16, v88
	v_and_b32_e32 v97, 0xffff0000, v88
	v_lshlrev_b32_e32 v88, 16, v89
	v_and_b32_e32 v89, 0xffff0000, v89
	v_pk_fma_f32 v[80:81], v[80:81], v[96:97], v[84:85]
	v_pk_fma_f32 v[82:83], v[82:83], v[88:89], v[86:87]
	global_store_dwordx4 v[102:103], v[80:83], off offset:576
	global_load_dwordx2 v[84:85], v[94:95], off
	v_lshl_add_u64 v[86:87], v[90:91], 2, s[54:55]
	global_load_dwordx4 v[80:83], v[86:87], off
	v_or_b32_e32 v88, 32, v92
	v_mov_b32_e32 v89, v93
	v_lshl_add_u64 v[88:89], s[0:1], 0, v[88:89]
	s_waitcnt vmcnt(0)
	v_lshlrev_b32_e32 v90, 16, v84
	v_and_b32_e32 v91, 0xffff0000, v84
	v_lshlrev_b32_e32 v84, 16, v85
	v_and_b32_e32 v85, 0xffff0000, v85
	v_pk_fma_f32 v[76:77], v[76:77], v[90:91], v[80:81]
	v_pk_fma_f32 v[78:79], v[78:79], v[84:85], v[82:83]
	global_store_dwordx4 v[86:87], v[76:79], off
	global_load_dwordx2 v[80:81], v[88:89], off
	global_load_dwordx4 v[76:79], v[86:87], off offset:64
	v_or_b32_e32 v82, 0x100, v92
	v_mov_b32_e32 v83, v93
	v_lshl_add_u64 v[82:83], s[0:1], 0, v[82:83]
	v_or_b32_e32 v92, 0x120, v92
	s_waitcnt vmcnt(0)
	v_lshlrev_b32_e32 v84, 16, v80
	v_and_b32_e32 v85, 0xffff0000, v80
	v_lshlrev_b32_e32 v80, 16, v81
	v_and_b32_e32 v81, 0xffff0000, v81
	v_pk_fma_f32 v[72:73], v[72:73], v[84:85], v[76:77]
	v_pk_fma_f32 v[74:75], v[74:75], v[80:81], v[78:79]
	global_store_dwordx4 v[86:87], v[72:75], off offset:64
	global_load_dwordx2 v[76:77], v[82:83], off
	global_load_dwordx4 v[72:75], v[86:87], off offset:512
	v_lshl_add_u64 v[78:79], s[0:1], 0, v[92:93]
	s_waitcnt vmcnt(0)
	v_lshlrev_b32_e32 v80, 16, v76
	v_and_b32_e32 v81, 0xffff0000, v76
	v_lshlrev_b32_e32 v76, 16, v77
	v_and_b32_e32 v77, 0xffff0000, v77
	v_pk_fma_f32 v[68:69], v[68:69], v[80:81], v[72:73]
	v_pk_fma_f32 v[70:71], v[70:71], v[76:77], v[74:75]
	global_store_dwordx4 v[86:87], v[68:71], off offset:512
	global_load_dwordx2 v[72:73], v[78:79], off
	global_load_dwordx4 v[68:71], v[86:87], off offset:576
	v_lshl_add_u64 v[74:75], v[140:141], 0, s[8:9]
	v_lshlrev_b64 v[76:77], 1, v[74:75]
	v_lshl_add_u64 v[78:79], s[0:1], 0, v[76:77]
	s_waitcnt vmcnt(0)
	v_lshlrev_b32_e32 v80, 16, v72
	v_and_b32_e32 v81, 0xffff0000, v72
	v_lshlrev_b32_e32 v72, 16, v73
	v_and_b32_e32 v73, 0xffff0000, v73
	v_pk_fma_f32 v[64:65], v[64:65], v[80:81], v[68:69]
	v_pk_fma_f32 v[66:67], v[66:67], v[72:73], v[70:71]
	global_store_dwordx4 v[86:87], v[64:67], off offset:576
	global_load_dwordx2 v[68:69], v[78:79], off
	v_lshl_add_u64 v[70:71], v[74:75], 2, s[54:55]
	global_load_dwordx4 v[64:67], v[70:71], off
	v_or_b32_e32 v72, 32, v76
	v_mov_b32_e32 v73, v77
	v_lshl_add_u64 v[72:73], s[0:1], 0, v[72:73]
	s_waitcnt vmcnt(0)
	v_lshlrev_b32_e32 v74, 16, v68
	v_and_b32_e32 v75, 0xffff0000, v68
	v_lshlrev_b32_e32 v68, 16, v69
	v_and_b32_e32 v69, 0xffff0000, v69
	v_pk_fma_f32 v[60:61], v[60:61], v[74:75], v[64:65]
	v_pk_fma_f32 v[62:63], v[62:63], v[68:69], v[66:67]
	global_store_dwordx4 v[70:71], v[60:63], off
	global_load_dwordx2 v[64:65], v[72:73], off
	global_load_dwordx4 v[60:63], v[70:71], off offset:64
	v_or_b32_e32 v66, 0x100, v76
	v_mov_b32_e32 v67, v77
	v_lshl_add_u64 v[66:67], s[0:1], 0, v[66:67]
	v_or_b32_e32 v76, 0x120, v76
	s_waitcnt vmcnt(0)
; __device__ __forceinline__ float bflo(unsigned w) { return __uint_as_float(w << 16); }
; __device__ __forceinline__ float bfhi(unsigned w) { return __uint_as_float(w & 0xffff0000u); }
; __device__ __forceinline__ float sigmoidf_(float x) { return __builtin_amdgcn_rcpf(1.0f + __expf(-x)); }
;     __device__ __forceinline__ void operator()(const AccT& acc, const Unit& u, int wr, int wc, int fr, int fq) const {
;     ...
; #pragma unroll
;         for (int ai = 0; ai < 2; ++ai)
; #pragma unroll
;             for (int m = 0; m < 4; ++m) { const size_t ro = (size_t)(row0 + ai * 128 + m * 16) * DM + col0;
; #pragma unroll
;                 for (int bj = 0; bj < 2; ++bj)
; #pragma unroll
;                     for (int n = 0; n < 2; ++n) { const size_t o = ro + bj * 128 + n * 16; const f32x4 h = *(const f32x4*)(H + o); const u32x2 pw = *(const u32x2*)(PP + o);
;                         const f32x4 a = acc[ai][bj][m][n]; f32x4 r;
;                         r[0] = h[0] + bflo(pw.x) * sigmoidf_(a[0]); r[1] = h[1] + bfhi(pw.x) * sigmoidf_(a[1]); r[2] = h[2] + bflo(pw.y) * sigmoidf_(a[2]); r[3] = h[3] + bfhi(pw.y) * sigmoidf_(a[3]);
;                         *(f32x4*)(H + o) = r; asm volatile("" ::: "memory"); } }
	v_lshlrev_b32_e32 v68, 16, v64
	v_and_b32_e32 v69, 0xffff0000, v64
	v_lshlrev_b32_e32 v64, 16, v65
	v_and_b32_e32 v65, 0xffff0000, v65
	v_pk_fma_f32 v[56:57], v[56:57], v[68:69], v[60:61]
	v_pk_fma_f32 v[58:59], v[58:59], v[64:65], v[62:63]
	global_store_dwordx4 v[70:71], v[56:59], off offset:64
	global_load_dwordx2 v[60:61], v[66:67], off
	global_load_dwordx4 v[56:59], v[70:71], off offset:512
	v_lshl_add_u64 v[62:63], s[0:1], 0, v[76:77]
	s_waitcnt vmcnt(0)
	v_lshlrev_b32_e32 v64, 16, v60
	v_and_b32_e32 v65, 0xffff0000, v60
	v_lshlrev_b32_e32 v60, 16, v61
	v_and_b32_e32 v61, 0xffff0000, v61
	v_pk_fma_f32 v[52:53], v[52:53], v[64:65], v[56:57]
	v_pk_fma_f32 v[54:55], v[54:55], v[60:61], v[58:59]
	global_store_dwordx4 v[70:71], v[52:55], off offset:512
	global_load_dwordx2 v[56:57], v[62:63], off
	global_load_dwordx4 v[52:55], v[70:71], off offset:576
	v_lshl_add_u64 v[58:59], v[140:141], 0, s[12:13]
	v_lshlrev_b64 v[60:61], 1, v[58:59]
	v_lshl_add_u64 v[62:63], s[0:1], 0, v[60:61]
	s_waitcnt vmcnt(0)
	v_lshlrev_b32_e32 v64, 16, v56
	v_and_b32_e32 v65, 0xffff0000, v56
	v_lshlrev_b32_e32 v56, 16, v57
	v_and_b32_e32 v57, 0xffff0000, v57
	v_pk_fma_f32 v[48:49], v[48:49], v[64:65], v[52:53]
	v_pk_fma_f32 v[50:51], v[50:51], v[56:57], v[54:55]
	global_store_dwordx4 v[70:71], v[48:51], off offset:576
	global_load_dwordx2 v[52:53], v[62:63], off
	v_lshl_add_u64 v[54:55], v[58:59], 2, s[54:55]
	global_load_dwordx4 v[48:51], v[54:55], off
	v_or_b32_e32 v56, 32, v60
	v_mov_b32_e32 v57, v61
	v_lshl_add_u64 v[56:57], s[0:1], 0, v[56:57]
	s_waitcnt vmcnt(0)
	v_lshlrev_b32_e32 v58, 16, v52
	v_and_b32_e32 v59, 0xffff0000, v52
	v_lshlrev_b32_e32 v52, 16, v53
	v_and_b32_e32 v53, 0xffff0000, v53
	v_pk_fma_f32 v[44:45], v[44:45], v[58:59], v[48:49]
	v_pk_fma_f32 v[46:47], v[46:47], v[52:53], v[50:51]
	global_store_dwordx4 v[54:55], v[44:47], off
	global_load_dwordx2 v[48:49], v[56:57], off
	global_load_dwordx4 v[44:47], v[54:55], off offset:64
	v_or_b32_e32 v50, 0x100, v60
	v_mov_b32_e32 v51, v61
	v_lshl_add_u64 v[50:51], s[0:1], 0, v[50:51]
	v_or_b32_e32 v60, 0x120, v60
	s_waitcnt vmcnt(0)
	v_lshlrev_b32_e32 v52, 16, v48
	v_and_b32_e32 v53, 0xffff0000, v48
	v_lshlrev_b32_e32 v48, 16, v49
	v_and_b32_e32 v49, 0xffff0000, v49
	v_pk_fma_f32 v[40:41], v[40:41], v[52:53], v[44:45]
	v_pk_fma_f32 v[42:43], v[42:43], v[48:49], v[46:47]
	global_store_dwordx4 v[54:55], v[40:43], off offset:64
	global_load_dwordx2 v[44:45], v[50:51], off
	global_load_dwordx4 v[40:43], v[54:55], off offset:512
	v_lshl_add_u64 v[46:47], s[0:1], 0, v[60:61]
	s_waitcnt vmcnt(0)
	v_lshlrev_b32_e32 v48, 16, v44
	v_and_b32_e32 v49, 0xffff0000, v44
	v_lshlrev_b32_e32 v44, 16, v45
	v_and_b32_e32 v45, 0xffff0000, v45
	v_pk_fma_f32 v[36:37], v[36:37], v[48:49], v[40:41]
	v_pk_fma_f32 v[38:39], v[38:39], v[44:45], v[42:43]
	global_store_dwordx4 v[54:55], v[36:39], off offset:512
	global_load_dwordx2 v[40:41], v[46:47], off
	global_load_dwordx4 v[36:39], v[54:55], off offset:576
	v_lshl_add_u64 v[42:43], v[140:141], 0, s[14:15]
	v_lshlrev_b64 v[44:45], 1, v[42:43]
	v_lshl_add_u64 v[46:47], s[0:1], 0, v[44:45]
	s_waitcnt vmcnt(0)
	v_lshlrev_b32_e32 v48, 16, v40
	v_and_b32_e32 v49, 0xffff0000, v40
	v_lshlrev_b32_e32 v40, 16, v41
	v_and_b32_e32 v41, 0xffff0000, v41
	v_pk_fma_f32 v[32:33], v[32:33], v[48:49], v[36:37]
	v_pk_fma_f32 v[34:35], v[34:35], v[40:41], v[38:39]
	global_store_dwordx4 v[54:55], v[32:35], off offset:576
	global_load_dwordx2 v[36:37], v[46:47], off
	v_lshl_add_u64 v[38:39], v[42:43], 2, s[54:55]
	global_load_dwordx4 v[32:35], v[38:39], off
	v_or_b32_e32 v40, 32, v44
	v_mov_b32_e32 v41, v45
	v_lshl_add_u64 v[40:41], s[0:1], 0, v[40:41]
	s_waitcnt vmcnt(0)
; __device__ __forceinline__ float bflo(unsigned w) { return __uint_as_float(w << 16); }
; __device__ __forceinline__ float bfhi(unsigned w) { return __uint_as_float(w & 0xffff0000u); }
; __device__ __forceinline__ float sigmoidf_(float x) { return __builtin_amdgcn_rcpf(1.0f + __expf(-x)); }
; #define PG8_WAIT_V(n) asm volatile("s_waitcnt vmcnt(" #n ")" ::: "memory")
; #define PG8_BAR __builtin_amdgcn_s_barrier()
; template <class Epi>
; __device__ __forceinline__ void gemm_phase(LAS unsigned char* lds, const Gemm g, const StaticOrder& S, const Epi& E) {
;     ...
;         if (!has_next) break;
; #pragma unroll
;         for (int a = 0; a < 2; ++a)
; #pragma unroll
;             for (int b = 0; b < 2; ++b)
; #pragma unroll
;                 for (int m = 0; m < 4; ++m)
; #pragma unroll
;                     for (int n = 0; n < 2; ++n) acc[a][b][m][n] = (f32x4){0.f, 0.f, 0.f, 0.f};
;         cur = nxt; cA = nA; cB = nB; ++ui;
;     }
;     PG8_WAIT_V(0);
;     if (wr == 0) PG8_BAR;
;     PG8_BAR;
;     __device__ __forceinline__ void operator()(const AccT& acc, const Unit& u, int wr, int wc, int fr, int fq) const {
;     ...
; #pragma unroll
;         for (int ai = 0; ai < 2; ++ai)
; #pragma unroll
;             for (int m = 0; m < 4; ++m) { const size_t ro = (size_t)(row0 + ai * 128 + m * 16) * DM + col0;
; #pragma unroll
;                 for (int bj = 0; bj < 2; ++bj)
; #pragma unroll
;                     for (int n = 0; n < 2; ++n) { const size_t o = ro + bj * 128 + n * 16; const f32x4 h = *(const f32x4*)(H + o); const u32x2 pw = *(const u32x2*)(PP + o);
;                         const f32x4 a = acc[ai][bj][m][n]; f32x4 r;
;                         r[0] = h[0] + bflo(pw.x) * sigmoidf_(a[0]); r[1] = h[1] + bfhi(pw.x) * sigmoidf_(a[1]); r[2] = h[2] + bflo(pw.y) * sigmoidf_(a[2]); r[3] = h[3] + bfhi(pw.y) * sigmoidf_(a[3]);
;                         *(f32x4*)(H + o) = r; asm volatile("" ::: "memory"); } }
	v_lshlrev_b32_e32 v42, 16, v36
	v_and_b32_e32 v43, 0xffff0000, v36
	v_lshlrev_b32_e32 v36, 16, v37
	v_and_b32_e32 v37, 0xffff0000, v37
	v_pk_fma_f32 v[28:29], v[28:29], v[42:43], v[32:33]
	v_pk_fma_f32 v[30:31], v[30:31], v[36:37], v[34:35]
	global_store_dwordx4 v[38:39], v[28:31], off
	global_load_dwordx2 v[32:33], v[40:41], off
	global_load_dwordx4 v[28:31], v[38:39], off offset:64
	v_or_b32_e32 v34, 0x100, v44
	v_mov_b32_e32 v35, v45
	v_lshl_add_u64 v[34:35], s[0:1], 0, v[34:35]
	v_or_b32_e32 v44, 0x120, v44
	s_waitcnt vmcnt(0)
	v_lshlrev_b32_e32 v36, 16, v32
	v_and_b32_e32 v37, 0xffff0000, v32
	v_lshlrev_b32_e32 v32, 16, v33
	v_and_b32_e32 v33, 0xffff0000, v33
	v_pk_fma_f32 v[24:25], v[24:25], v[36:37], v[28:29]
	v_pk_fma_f32 v[26:27], v[26:27], v[32:33], v[30:31]
	global_store_dwordx4 v[38:39], v[24:27], off offset:64
	global_load_dwordx2 v[28:29], v[34:35], off
	global_load_dwordx4 v[24:27], v[38:39], off offset:512
	v_lshl_add_u64 v[30:31], s[0:1], 0, v[44:45]
	s_waitcnt vmcnt(0)
	v_lshlrev_b32_e32 v32, 16, v28
	v_and_b32_e32 v33, 0xffff0000, v28
	v_lshlrev_b32_e32 v28, 16, v29
	v_and_b32_e32 v29, 0xffff0000, v29
	v_pk_fma_f32 v[20:21], v[20:21], v[32:33], v[24:25]
	v_pk_fma_f32 v[22:23], v[22:23], v[28:29], v[26:27]
	global_store_dwordx4 v[38:39], v[20:23], off offset:512
	global_load_dwordx2 v[24:25], v[30:31], off
	global_load_dwordx4 v[20:23], v[38:39], off offset:576
	v_lshl_add_u64 v[26:27], v[140:141], 0, s[16:17]
	v_lshlrev_b64 v[28:29], 1, v[26:27]
	v_lshl_add_u64 v[30:31], s[0:1], 0, v[28:29]
	s_waitcnt vmcnt(0)
	v_lshlrev_b32_e32 v32, 16, v24
	v_and_b32_e32 v33, 0xffff0000, v24
	v_lshlrev_b32_e32 v24, 16, v25
	v_and_b32_e32 v25, 0xffff0000, v25
	v_pk_fma_f32 v[16:17], v[16:17], v[32:33], v[20:21]
	v_pk_fma_f32 v[18:19], v[18:19], v[24:25], v[22:23]
	global_store_dwordx4 v[38:39], v[16:19], off offset:576
	global_load_dwordx2 v[20:21], v[30:31], off
	v_lshl_add_u64 v[22:23], v[26:27], 2, s[54:55]
	global_load_dwordx4 v[16:19], v[22:23], off
	v_or_b32_e32 v24, 32, v28
	v_mov_b32_e32 v25, v29
	v_lshl_add_u64 v[24:25], s[0:1], 0, v[24:25]
	s_waitcnt vmcnt(0)
	v_lshlrev_b32_e32 v26, 16, v20
	v_and_b32_e32 v27, 0xffff0000, v20
	v_lshlrev_b32_e32 v20, 16, v21
	v_and_b32_e32 v21, 0xffff0000, v21
	v_pk_fma_f32 v[12:13], v[12:13], v[26:27], v[16:17]
	v_pk_fma_f32 v[14:15], v[14:15], v[20:21], v[18:19]
	global_store_dwordx4 v[22:23], v[12:15], off
	global_load_dwordx2 v[16:17], v[24:25], off
	global_load_dwordx4 v[12:15], v[22:23], off offset:64
	v_or_b32_e32 v18, 0x100, v28
	v_mov_b32_e32 v19, v29
	v_lshl_add_u64 v[18:19], s[0:1], 0, v[18:19]
	v_or_b32_e32 v28, 0x120, v28
	s_waitcnt vmcnt(0)
	v_lshlrev_b32_e32 v20, 16, v16
	v_and_b32_e32 v21, 0xffff0000, v16
	v_lshlrev_b32_e32 v16, 16, v17
	v_and_b32_e32 v17, 0xffff0000, v17
	v_pk_fma_f32 v[8:9], v[8:9], v[20:21], v[12:13]
	v_pk_fma_f32 v[10:11], v[10:11], v[16:17], v[14:15]
	global_store_dwordx4 v[22:23], v[8:11], off offset:64
	global_load_dwordx2 v[12:13], v[18:19], off
	global_load_dwordx4 v[8:11], v[22:23], off offset:512
	v_lshl_add_u64 v[14:15], s[0:1], 0, v[28:29]
	s_waitcnt vmcnt(0)
	v_lshlrev_b32_e32 v16, 16, v12
	v_and_b32_e32 v17, 0xffff0000, v12
	v_lshlrev_b32_e32 v12, 16, v13
	v_and_b32_e32 v13, 0xffff0000, v13
	v_pk_fma_f32 v[4:5], v[4:5], v[16:17], v[8:9]
	v_pk_fma_f32 v[6:7], v[6:7], v[12:13], v[10:11]
	global_store_dwordx4 v[22:23], v[4:7], off offset:512
	global_load_dwordx2 v[8:9], v[14:15], off
	global_load_dwordx4 v[4:7], v[22:23], off offset:576
	s_waitcnt vmcnt(0)
	v_lshlrev_b32_e32 v10, 16, v8
	v_and_b32_e32 v11, 0xffff0000, v8
	v_lshlrev_b32_e32 v8, 16, v9
	v_and_b32_e32 v9, 0xffff0000, v9
	v_pk_fma_f32 v[0:1], v[0:1], v[10:11], v[4:5]
	v_pk_fma_f32 v[2:3], v[2:3], v[8:9], v[6:7]
	global_store_dwordx4 v[22:23], v[0:3], off offset:576
	s_cbranch_vccz .LBB0_1233
	s_waitcnt vmcnt(0)
	s_cmpk_gt_u32 s3, 0xff
	s_cbranch_scc1 .LBB0_1244
	s_barrier
